# C pass static ring slots (x4 unroll), A2 pass LDS-DMA staging with 4-slot swizzled ring, EpiG1 rope-table prefetch, EpiUpConv conv weights via one wave fetch + LDS broadcast
# speedup vs baseline: 1.0338x; 1.0227x over previous
; __device__ __forceinline__ unsigned cvt_pk_bf16(float lo, float hi) { f32x2 v = {lo, hi}; bf16x2_t b = __builtin_convertvector(v, bf16x2_t); return __builtin_bit_cast(unsigned, b); }
; __device__ __forceinline__ float sigmoidf_(float v) { return __builtin_amdgcn_rcpf(1.0f + __builtin_amdgcn_exp2f(-1.4426950408889634f * v)); }
; __device__ __forceinline__ float dpp_shr1(float v) { return __builtin_bit_cast(float, __builtin_amdgcn_update_dpp(0, __builtin_bit_cast(int, v), 0x111, 0xf, 0xf, true)); }
;     __device__ __forceinline__ void operator()(const f32x4 (&acc)[2][2][4][2], const Unit& u, int wr, int wc, int fr, int fq) const {
;     ...
;         const size_t row0 = (size_t)256 * u.pm + 128 * wr + 8 * fr;
; #pragma unroll
;         for (int n = 0; n < 2; ++n) {
;             const int f0 = 128 * u.pn + 32 * wc + 8 * fq + 4 * n;
;             f32x4 wa[3], wg[3];
; #pragma unroll
;             for (int j = 0; j < 3; ++j) { wa[j] = *(const f32x4*)(cw + j * 5632 + f0); wg[j] = *(const f32x4*)(cw + j * 5632 + 2816 + f0); }
;             const f32x4 ba = *(const f32x4*)(cb + f0), bg = *(const f32x4*)(cb + 2816 + f0);
;             f32x4 pa, pg, na, ng;
; #pragma unroll
;             for (int e = 0; e < 4; ++e) { pa[e] = dpp_shr1(acc[1][0][3][n][e]); pg[e] = dpp_shr1(acc[1][1][3][n][e]); na[e] = dpp_shl1(acc[0][0][0][n][e]); ng[e] = dpp_shl1(acc[0][1][0][n][e]); }
; #pragma unroll
;             for (int k = 0; k < 8; ++k) {
;                 const f32x4 ua0 = (k == 0) ? pa : acc[(k - 1) >> 2][0][(k - 1) & 3][n], ua1 = acc[k >> 2][0][k & 3][n], ua2 = (k == 7) ? na : acc[(k + 1) >> 2][0][(k + 1) & 3][n];
;                 const f32x4 ug0 = (k == 0) ? pg : acc[(k - 1) >> 2][1][(k - 1) & 3][n], ug1 = acc[k >> 2][1][k & 3][n], ug2 = (k == 7) ? ng : acc[(k + 1) >> 2][1][(k + 1) & 3][n];
;                 const f32x4 ca = wa[0] * ua0 + wa[1] * ua1 + wa[2] * ua2 + ba, cg = wg[0] * ug0 + wg[1] * ug1 + wg[2] * ug2 + bg;
;                 u32x2 w; w.x = cvt_pk_bf16(cg[0] * sigmoidf_(cg[0]) * ca[0], cg[1] * sigmoidf_(cg[1]) * ca[1]); w.y = cvt_pk_bf16(cg[2] * sigmoidf_(cg[2]) * ca[2], cg[3] * sigmoidf_(cg[3]) * ca[3]);
;                 const bool edge = (k == 0 && fr == 0) || (k == 7 && fr == 15);
;                 if (!edge) *(u32x2*)(ACT + (row0 + k) * 2816 + f0) = w;
;             }
.LBB0_118:
	v_mov_b32_e32 v128, v212
	v_mov_b32_e32 v192, v197
	s_mov_b64 s[6:7], -1
	s_cmp_lg_u32 s2, 1
	v_lshl_add_u32 v215, v128, 3, s94
	s_cbranch_scc0 .LBB0_131
	v_mbcnt_lo_u32_b32 v222, -1, 0
	v_mbcnt_hi_u32_b32 v222, -1, v222
	v_lshrrev_b32_e32 v223, 3, v222
	v_lshlrev_b32_e32 v223, 3, v223
	v_add_u32_e32 v223, 0xa0, v223
	ds_bpermute_b32 v220, v223, v253
	v_add_u32_e32 v224, 4, v223
	ds_bpermute_b32 v221, v224, v253
	v_and_b32_e32 v224, 7, v222
	v_lshlrev_b32_e32 v224, 4, v224
	s_lshl_b32 s56, s18, 7
	s_add_i32 s56, s56, s94
	s_lshl_b32 s56, s56, 2
	v_add_u32_e32 v224, s56, v224
	v_mov_b32_e32 v225, 0
	s_waitcnt lgkmcnt(0)
	v_lshl_add_u64 v[220:221], v[224:225], 0, v[220:221]
	global_load_dwordx4 v[216:219], v[220:221], off
	s_add_i32 s57, s96, 0x20800
	v_lshl_add_u32 v224, v222, 4, s57
	v_lshl_add_u32 v223, v212, 5, s57
	s_ashr_i32 s1, s0, 31
	s_lshl_b64 s[2:3], s[0:1], 8
	s_add_u32 s2, s2, s35
	v_readlane_b32 s1, v254, 63
	s_addc_u32 s3, s3, s1
	s_lshl_b32 s1, s18, 7
	v_add_u32_e32 v172, s1, v215
	v_ashrrev_i32_e32 v173, 31, v172
	v_readlane_b32 s6, v253, 48
	v_lshlrev_b64 v[144:145], 2, v[172:173]
	v_readlane_b32 s7, v253, 49
	v_lshlrev_b32_e32 v174, 3, v192
	v_ashrrev_i32_e32 v175, 31, v174
	v_lshl_add_u64 v[128:129], s[6:7], 0, v[144:145]
	v_readlane_b32 s6, v253, 40
	v_readlane_b32 s7, v253, 41
	v_lshl_add_u64 v[174:175], s[2:3], 0, v[174:175]
	v_mov_b32_dpp v178, v76 row_shr:1 row_mask:0xf bank_mask:0xf bound_ctrl:1
	v_lshl_add_u64 v[132:133], s[6:7], 0, v[144:145]
	v_readlane_b32 s6, v253, 42
	v_readlane_b32 s7, v253, 43
	s_waitcnt vmcnt(0)
	ds_write_b128 v224, v[216:219]
	ds_read_b128 v[128:131], v223 offset:512
	s_nop 0
	ds_read_b128 v[136:139], v223
	v_lshl_add_u64 v[132:133], s[6:7], 0, v[144:145]
	v_readlane_b32 s6, v253, 44
	v_readlane_b32 s7, v253, 45
	v_mov_b32_dpp v182, v60 row_shr:1 row_mask:0xf bank_mask:0xf bound_ctrl:1
	v_mov_b32_dpp v188, v124 row_shl:1 row_mask:0xf bank_mask:0xf bound_ctrl:1
	v_lshl_add_u64 v[134:135], s[6:7], 0, v[144:145]
	v_readlane_b32 s6, v253, 46
	v_readlane_b32 s7, v253, 47
	ds_read_b128 v[140:143], v223 offset:128
	ds_read_b128 v[152:155], v223 offset:256
	v_lshl_add_u64 v[132:133], s[6:7], 0, v[144:145]
	v_readlane_b32 s6, v253, 50
	v_readlane_b32 s7, v253, 51
	v_mov_b32_dpp v198, v120 row_shl:1 row_mask:0xf bank_mask:0xf bound_ctrl:1
	v_mov_b32_dpp v179, v77 row_shr:1 row_mask:0xf bank_mask:0xf bound_ctrl:1
	v_lshl_add_u64 v[146:147], s[6:7], 0, v[144:145]
	v_readlane_b32 s6, v253, 52
	v_readlane_b32 s7, v253, 53
	ds_read_b128 v[132:135], v223 offset:384
	s_nop 0
	ds_read_b128 v[148:151], v223 offset:640
	v_lshl_add_u64 v[146:147], s[6:7], 0, v[144:145]
	v_readlane_b32 s6, v253, 54
	v_readlane_b32 s7, v253, 55
	v_mov_b32_dpp v183, v61 row_shr:1 row_mask:0xf bank_mask:0xf bound_ctrl:1
	v_mov_b32_dpp v189, v125 row_shl:1 row_mask:0xf bank_mask:0xf bound_ctrl:1
	v_lshl_add_u64 v[156:157], s[6:7], 0, v[144:145]
	ds_read_b128 v[144:147], v223 offset:768
	s_nop 0
	ds_read_b128 v[156:159], v223 offset:896
	v_mov_b32_dpp v199, v121 row_shl:1 row_mask:0xf bank_mask:0xf bound_ctrl:1
	v_mov_b32_dpp v180, v78 row_shr:1 row_mask:0xf bank_mask:0xf bound_ctrl:1
	v_mov_b32_dpp v184, v62 row_shr:1 row_mask:0xf bank_mask:0xf bound_ctrl:1
	v_mov_b32_dpp v186, v126 row_shl:1 row_mask:0xf bank_mask:0xf bound_ctrl:1
	v_mov_b32_dpp v190, v122 row_shl:1 row_mask:0xf bank_mask:0xf bound_ctrl:1
	v_mov_b32_dpp v181, v79 row_shr:1 row_mask:0xf bank_mask:0xf bound_ctrl:1
	v_mov_b32_dpp v185, v63 row_shr:1 row_mask:0xf bank_mask:0xf bound_ctrl:1
	v_mov_b32_dpp v187, v127 row_shl:1 row_mask:0xf bank_mask:0xf bound_ctrl:1
	v_mov_b32_dpp v191, v123 row_shl:1 row_mask:0xf bank_mask:0xf bound_ctrl:1
	v_cmp_ne_u32_e64 s[8:9], 0, v192
	s_and_saveexec_b64 s[2:3], s[8:9]
	s_xor_b64 s[6:7], exec, s[2:3]
	s_cbranch_execz .LBB0_121
	s_waitcnt lgkmcnt(0)
	v_pk_mul_f32 v[182:183], v[136:137], v[182:183]
	v_pk_mul_f32 v[176:177], v[138:139], v[184:185]
	v_pk_fma_f32 v[182:183], v[120:121], v[152:153], v[182:183]
	v_pk_mul_f32 v[178:179], v[128:129], v[178:179]
	v_pk_fma_f32 v[182:183], v[104:105], v[148:149], v[182:183]
	v_pk_fma_f32 v[178:179], v[124:125], v[140:141], v[178:179]
	v_pk_add_f32 v[182:183], v[156:157], v[182:183]
	v_pk_fma_f32 v[176:177], v[122:123], v[154:155], v[176:177]
	v_mul_f32_e32 v184, 0xbfb8aa3b, v182
	v_mul_f32_e32 v185, 0xbfb8aa3b, v183
	v_exp_f32_e32 v184, v184
	v_exp_f32_e32 v185, v185
	v_pk_fma_f32 v[178:179], v[116:117], v[132:133], v[178:179]
	v_pk_fma_f32 v[176:177], v[106:107], v[150:151], v[176:177]
	v_add_f32_e32 v184, 1.0, v184
	v_add_f32_e32 v185, 1.0, v185
	v_rcp_f32_e32 v184, v184
	v_rcp_f32_e32 v185, v185
	v_pk_add_f32 v[178:179], v[144:145], v[178:179]
	v_pk_add_f32 v[176:177], v[158:159], v[176:177]
	v_pk_mul_f32 v[180:181], v[130:131], v[180:181]
	v_pk_mul_f32 v[182:183], v[182:183], v[184:185]
	v_pk_fma_f32 v[180:181], v[126:127], v[142:143], v[180:181]
	v_pk_mul_f32 v[178:179], v[178:179], v[182:183]
	v_pk_fma_f32 v[180:181], v[118:119], v[134:135], v[180:181]
	v_cvt_pk_bf16_f32 v178, v178, v179
	v_mul_f32_e32 v179, 0xbfb8aa3b, v176
	v_exp_f32_e32 v179, v179
	v_pk_add_f32 v[180:181], v[146:147], v[180:181]
	s_movk_i32 s19, 0x1600
	v_add_f32_e32 v179, 1.0, v179
	v_rcp_f32_e32 v182, v179
	v_mul_f32_e32 v179, 0xbfb8aa3b, v177
	v_exp_f32_e32 v179, v179
	s_nop 0
	v_add_f32_e32 v179, 1.0, v179
	v_rcp_f32_e32 v183, v179
	s_nop 0
	v_pk_mul_f32 v[176:177], v[176:177], v[182:183]
	s_nop 0
	v_pk_mul_f32 v[176:177], v[180:181], v[176:177]
	s_nop 0
	v_cvt_pk_bf16_f32 v179, v176, v177
	v_mad_u64_u32 v[176:177], s[2:3], v174, s19, 0
	v_readlane_b32 s2, v254, 38
	v_readlane_b32 s3, v254, 39
	v_mad_i32_i24 v177, v175, s19, v177
	s_nop 0
	v_mov_b64_e32 v[180:181], s[2:3]
	v_mad_u64_u32 v[180:181], s[2:3], v174, s19, v[180:181]
	v_mad_i32_i24 v181, v175, s19, v181
	v_lshl_add_u64 v[174:175], v[172:173], 1, v[180:181]
	flat_store_dwordx2 v[174:175], v[178:179]
; __device__ __forceinline__ unsigned cvt_pk_bf16(float lo, float hi) { f32x2 v = {lo, hi}; bf16x2_t b = __builtin_convertvector(v, bf16x2_t); return __builtin_bit_cast(unsigned, b); }
; __device__ __forceinline__ float sigmoidf_(float v) { return __builtin_amdgcn_rcpf(1.0f + __builtin_amdgcn_exp2f(-1.4426950408889634f * v)); }
;     __device__ __forceinline__ void operator()(const f32x4 (&acc)[2][2][4][2], const Unit& u, int wr, int wc, int fr, int fq) const {
;     ...
;             for (int k = 0; k < 8; ++k) {
;                 const f32x4 ua0 = (k == 0) ? pa : acc[(k - 1) >> 2][0][(k - 1) & 3][n], ua1 = acc[k >> 2][0][k & 3][n], ua2 = (k == 7) ? na : acc[(k + 1) >> 2][0][(k + 1) & 3][n];
;                 const f32x4 ug0 = (k == 0) ? pg : acc[(k - 1) >> 2][1][(k - 1) & 3][n], ug1 = acc[k >> 2][1][k & 3][n], ug2 = (k == 7) ? ng : acc[(k + 1) >> 2][1][(k + 1) & 3][n];
;                 const f32x4 ca = wa[0] * ua0 + wa[1] * ua1 + wa[2] * ua2 + ba, cg = wg[0] * ug0 + wg[1] * ug1 + wg[2] * ug2 + bg;
;                 u32x2 w; w.x = cvt_pk_bf16(cg[0] * sigmoidf_(cg[0]) * ca[0], cg[1] * sigmoidf_(cg[1]) * ca[1]); w.y = cvt_pk_bf16(cg[2] * sigmoidf_(cg[2]) * ca[2], cg[3] * sigmoidf_(cg[3]) * ca[3]);
;                 const bool edge = (k == 0 && fr == 0) || (k == 7 && fr == 15);
;                 if (!edge) *(u32x2*)(ACT + (row0 + k) * 2816 + f0) = w;
;             }
.LBB0_121:
	s_andn2_saveexec_b64 s[6:7], s[6:7]
	s_movk_i32 s19, 0x1600
	v_mad_u64_u32 v[176:177], s[2:3], v174, s19, 0
	v_mad_i32_i24 v177, v175, s19, v177
	s_or_b64 exec, exec, s[6:7]
	s_waitcnt lgkmcnt(0)
	v_pk_mul_f32 v[178:179], v[104:105], v[152:153]
	v_pk_mul_f32 v[184:185], v[116:117], v[140:141]
	v_pk_fma_f32 v[178:179], v[120:121], v[136:137], v[178:179]
	v_pk_mul_f32 v[174:175], v[106:107], v[154:155]
	v_pk_fma_f32 v[178:179], v[100:101], v[148:149], v[178:179]
	v_pk_fma_f32 v[184:185], v[124:125], v[128:129], v[184:185]
	v_pk_add_f32 v[178:179], v[156:157], v[178:179]
	v_pk_fma_f32 v[174:175], v[122:123], v[138:139], v[174:175]
	v_mul_f32_e32 v180, 0xbfb8aa3b, v178
	v_mul_f32_e32 v181, 0xbfb8aa3b, v179
	v_exp_f32_e32 v180, v180
	v_exp_f32_e32 v181, v181
	v_pk_fma_f32 v[184:185], v[112:113], v[132:133], v[184:185]
	v_pk_fma_f32 v[174:175], v[102:103], v[150:151], v[174:175]
	v_add_f32_e32 v180, 1.0, v180
	v_add_f32_e32 v181, 1.0, v181
	v_rcp_f32_e32 v180, v180
	v_rcp_f32_e32 v181, v181
	v_pk_add_f32 v[184:185], v[144:145], v[184:185]
	v_pk_add_f32 v[174:175], v[158:159], v[174:175]
	v_pk_mul_f32 v[182:183], v[118:119], v[142:143]
	v_pk_mul_f32 v[178:179], v[178:179], v[180:181]
	v_pk_fma_f32 v[182:183], v[126:127], v[130:131], v[182:183]
	v_pk_mul_f32 v[178:179], v[184:185], v[178:179]
	v_pk_fma_f32 v[182:183], v[114:115], v[134:135], v[182:183]
	v_cvt_pk_bf16_f32 v178, v178, v179
	v_mul_f32_e32 v179, 0xbfb8aa3b, v174
	v_exp_f32_e32 v179, v179
	v_readlane_b32 s2, v254, 38
	v_pk_add_f32 v[182:183], v[146:147], v[182:183]
	v_readlane_b32 s3, v254, 39
	v_add_f32_e32 v179, 1.0, v179
	v_rcp_f32_e32 v180, v179
	v_mul_f32_e32 v179, 0xbfb8aa3b, v175
	v_exp_f32_e32 v179, v179
	v_lshl_add_u64 v[200:201], s[2:3], 0, v[176:177]
	s_mov_b64 s[2:3], 0x1600
	v_lshlrev_b64 v[202:203], 1, v[172:173]
	v_add_f32_e32 v179, 1.0, v179
	v_rcp_f32_e32 v181, v179
	v_pk_mul_f32 v[184:185], v[112:113], v[140:141]
	v_pk_mul_f32 v[204:205], v[108:109], v[140:141]
	v_pk_fma_f32 v[184:185], v[116:117], v[128:129], v[184:185]
	v_pk_mul_f32 v[174:175], v[174:175], v[180:181]
	v_pk_fma_f32 v[184:185], v[108:109], v[132:133], v[184:185]
	v_pk_mul_f32 v[174:175], v[182:183], v[174:175]
	v_pk_add_f32 v[184:185], v[144:145], v[184:185]
	v_cvt_pk_bf16_f32 v179, v174, v175
	v_lshl_add_u64 v[174:175], v[200:201], 0, s[2:3]
	v_lshl_add_u64 v[176:177], v[174:175], 0, v[202:203]
	flat_store_dwordx2 v[176:177], v[178:179]
	v_pk_mul_f32 v[178:179], v[100:101], v[152:153]
	v_pk_mul_f32 v[176:177], v[102:103], v[154:155]
	v_pk_fma_f32 v[178:179], v[104:105], v[136:137], v[178:179]
	v_pk_fma_f32 v[176:177], v[106:107], v[138:139], v[176:177]
	v_pk_fma_f32 v[178:179], v[96:97], v[148:149], v[178:179]
	v_pk_fma_f32 v[176:177], v[98:99], v[150:151], v[176:177]
	v_pk_add_f32 v[178:179], v[156:157], v[178:179]
	v_pk_add_f32 v[176:177], v[158:159], v[176:177]
	v_mul_f32_e32 v180, 0xbfb8aa3b, v178
	v_mul_f32_e32 v181, 0xbfb8aa3b, v179
	v_exp_f32_e32 v180, v180
	v_exp_f32_e32 v181, v181
	v_pk_mul_f32 v[182:183], v[114:115], v[142:143]
	s_mov_b64 s[2:3], 0x2c00
	v_add_f32_e32 v180, 1.0, v180
	v_add_f32_e32 v181, 1.0, v181
	v_rcp_f32_e32 v180, v180
	v_rcp_f32_e32 v181, v181
	v_pk_fma_f32 v[182:183], v[118:119], v[130:131], v[182:183]
	v_pk_fma_f32 v[204:205], v[112:113], v[128:129], v[204:205]
	v_pk_fma_f32 v[182:183], v[110:111], v[134:135], v[182:183]
	v_pk_mul_f32 v[178:179], v[178:179], v[180:181]
	v_pk_add_f32 v[182:183], v[146:147], v[182:183]
	v_pk_mul_f32 v[178:179], v[184:185], v[178:179]
	v_pk_fma_f32 v[204:205], v[92:93], v[132:133], v[204:205]
	v_cvt_pk_bf16_f32 v178, v178, v179
	v_mul_f32_e32 v179, 0xbfb8aa3b, v176
	v_exp_f32_e32 v179, v179
	v_pk_add_f32 v[204:205], v[144:145], v[204:205]
	v_pk_mul_f32 v[184:185], v[110:111], v[142:143]
	v_pk_mul_f32 v[206:207], v[92:93], v[140:141]
	v_add_f32_e32 v179, 1.0, v179
	v_rcp_f32_e32 v180, v179
	v_mul_f32_e32 v179, 0xbfb8aa3b, v177
	v_exp_f32_e32 v179, v179
	v_pk_fma_f32 v[184:185], v[114:115], v[130:131], v[184:185]
	v_pk_fma_f32 v[206:207], v[108:109], v[128:129], v[206:207]
	v_pk_fma_f32 v[184:185], v[94:95], v[134:135], v[184:185]
	v_add_f32_e32 v179, 1.0, v179
	v_rcp_f32_e32 v181, v179
	v_pk_add_f32 v[184:185], v[146:147], v[184:185]
	v_pk_fma_f32 v[206:207], v[84:85], v[132:133], v[206:207]
	v_pk_mul_f32 v[208:209], v[84:85], v[140:141]
	v_pk_mul_f32 v[176:177], v[176:177], v[180:181]
	v_pk_add_f32 v[206:207], v[144:145], v[206:207]
	v_pk_mul_f32 v[176:177], v[182:183], v[176:177]
	v_pk_fma_f32 v[208:209], v[92:93], v[128:129], v[208:209]
	v_cvt_pk_bf16_f32 v179, v176, v177
	v_lshl_add_u64 v[176:177], v[200:201], 0, s[2:3]
	v_lshl_add_u64 v[180:181], v[176:177], 0, v[202:203]
	flat_store_dwordx2 v[180:181], v[178:179]
	v_pk_mul_f32 v[180:181], v[96:97], v[152:153]
	v_pk_mul_f32 v[178:179], v[98:99], v[154:155]
	v_pk_fma_f32 v[180:181], v[100:101], v[136:137], v[180:181]
	v_pk_fma_f32 v[178:179], v[102:103], v[138:139], v[178:179]
	v_pk_fma_f32 v[180:181], v[88:89], v[148:149], v[180:181]
	v_pk_fma_f32 v[178:179], v[90:91], v[150:151], v[178:179]
	v_pk_add_f32 v[180:181], v[156:157], v[180:181]
	v_pk_add_f32 v[178:179], v[158:159], v[178:179]
	v_mul_f32_e32 v182, 0xbfb8aa3b, v180
	v_mul_f32_e32 v183, 0xbfb8aa3b, v181
	v_exp_f32_e32 v182, v182
	v_exp_f32_e32 v183, v183
	s_mov_b64 s[2:3], 0x4200
	v_pk_fma_f32 v[208:209], v[80:81], v[132:133], v[208:209]
	v_add_f32_e32 v182, 1.0, v182
	v_add_f32_e32 v183, 1.0, v183
	v_rcp_f32_e32 v182, v182
	v_rcp_f32_e32 v183, v183
	v_pk_add_f32 v[208:209], v[144:145], v[208:209]
	v_pk_mul_f32 v[210:211], v[80:81], v[140:141]
	v_cmp_ne_u32_e64 s[6:7], 15, v192
	v_pk_mul_f32 v[180:181], v[180:181], v[182:183]
; __device__ __forceinline__ unsigned cvt_pk_bf16(float lo, float hi) { f32x2 v = {lo, hi}; bf16x2_t b = __builtin_convertvector(v, bf16x2_t); return __builtin_bit_cast(unsigned, b); }
; __device__ __forceinline__ float sigmoidf_(float v) { return __builtin_amdgcn_rcpf(1.0f + __builtin_amdgcn_exp2f(-1.4426950408889634f * v)); }
;     __device__ __forceinline__ void operator()(const f32x4 (&acc)[2][2][4][2], const Unit& u, int wr, int wc, int fr, int fq) const {
;     ...
;             for (int k = 0; k < 8; ++k) {
;                 const f32x4 ua0 = (k == 0) ? pa : acc[(k - 1) >> 2][0][(k - 1) & 3][n], ua1 = acc[k >> 2][0][k & 3][n], ua2 = (k == 7) ? na : acc[(k + 1) >> 2][0][(k + 1) & 3][n];
;                 const f32x4 ug0 = (k == 0) ? pg : acc[(k - 1) >> 2][1][(k - 1) & 3][n], ug1 = acc[k >> 2][1][k & 3][n], ug2 = (k == 7) ? ng : acc[(k + 1) >> 2][1][(k + 1) & 3][n];
;                 const f32x4 ca = wa[0] * ua0 + wa[1] * ua1 + wa[2] * ua2 + ba, cg = wg[0] * ug0 + wg[1] * ug1 + wg[2] * ug2 + bg;
;                 u32x2 w; w.x = cvt_pk_bf16(cg[0] * sigmoidf_(cg[0]) * ca[0], cg[1] * sigmoidf_(cg[1]) * ca[1]); w.y = cvt_pk_bf16(cg[2] * sigmoidf_(cg[2]) * ca[2], cg[3] * sigmoidf_(cg[3]) * ca[3]);
;                 const bool edge = (k == 0 && fr == 0) || (k == 7 && fr == 15);
;                 if (!edge) *(u32x2*)(ACT + (row0 + k) * 2816 + f0) = w;
;             }
	v_pk_fma_f32 v[210:211], v[84:85], v[128:129], v[210:211]
	v_pk_mul_f32 v[180:181], v[204:205], v[180:181]
	v_pk_mul_f32 v[204:205], v[94:95], v[142:143]
	v_cvt_pk_bf16_f32 v180, v180, v181
	v_mul_f32_e32 v181, 0xbfb8aa3b, v178
	v_exp_f32_e32 v181, v181
	v_pk_fma_f32 v[204:205], v[110:111], v[130:131], v[204:205]
	v_pk_fma_f32 v[210:211], v[76:77], v[132:133], v[210:211]
	v_pk_fma_f32 v[204:205], v[86:87], v[134:135], v[204:205]
	v_add_f32_e32 v181, 1.0, v181
	v_rcp_f32_e32 v182, v181
	v_mul_f32_e32 v181, 0xbfb8aa3b, v179
	v_exp_f32_e32 v181, v181
	v_pk_add_f32 v[204:205], v[146:147], v[204:205]
	v_pk_add_f32 v[210:211], v[144:145], v[210:211]
	v_add_f32_e32 v181, 1.0, v181
	v_rcp_f32_e32 v183, v181
	s_nop 0
	v_pk_mul_f32 v[178:179], v[178:179], v[182:183]
	s_nop 0
	v_pk_mul_f32 v[178:179], v[184:185], v[178:179]
	s_nop 0
	v_cvt_pk_bf16_f32 v181, v178, v179
	v_lshl_add_u64 v[178:179], v[200:201], 0, s[2:3]
	v_lshl_add_u64 v[182:183], v[178:179], 0, v[202:203]
	flat_store_dwordx2 v[182:183], v[180:181]
	v_pk_mul_f32 v[182:183], v[88:89], v[152:153]
	v_pk_mul_f32 v[180:181], v[90:91], v[154:155]
	v_pk_fma_f32 v[182:183], v[96:97], v[136:137], v[182:183]
	v_pk_fma_f32 v[180:181], v[98:99], v[138:139], v[180:181]
	v_pk_fma_f32 v[182:183], v[72:73], v[148:149], v[182:183]
	v_pk_fma_f32 v[180:181], v[74:75], v[150:151], v[180:181]
	v_pk_add_f32 v[182:183], v[156:157], v[182:183]
	v_pk_add_f32 v[180:181], v[158:159], v[180:181]
	v_mul_f32_e32 v184, 0xbfb8aa3b, v182
	v_mul_f32_e32 v185, 0xbfb8aa3b, v183
	v_exp_f32_e32 v184, v184
	v_exp_f32_e32 v185, v185
	s_mov_b64 s[2:3], 0x5800
	v_add_f32_e32 v184, 1.0, v184
	v_add_f32_e32 v185, 1.0, v185
	v_rcp_f32_e32 v184, v184
	v_rcp_f32_e32 v185, v185
	s_nop 0
	v_pk_mul_f32 v[182:183], v[182:183], v[184:185]
	s_nop 0
	v_pk_mul_f32 v[182:183], v[206:207], v[182:183]
	v_pk_mul_f32 v[206:207], v[86:87], v[142:143]
	v_cvt_pk_bf16_f32 v182, v182, v183
	v_mul_f32_e32 v183, 0xbfb8aa3b, v180
	v_exp_f32_e32 v183, v183
	v_pk_fma_f32 v[206:207], v[94:95], v[130:131], v[206:207]
	v_add_f32_e32 v183, 1.0, v183
	v_rcp_f32_e32 v184, v183
	v_mul_f32_e32 v183, 0xbfb8aa3b, v181
	v_exp_f32_e32 v183, v183
	v_pk_fma_f32 v[206:207], v[82:83], v[134:135], v[206:207]
	v_add_f32_e32 v183, 1.0, v183
	v_rcp_f32_e32 v185, v183
	v_pk_add_f32 v[206:207], v[146:147], v[206:207]
	v_pk_mul_f32 v[180:181], v[180:181], v[184:185]
	s_nop 0
	v_pk_mul_f32 v[180:181], v[204:205], v[180:181]
	s_nop 0
	v_cvt_pk_bf16_f32 v183, v180, v181
	v_lshl_add_u64 v[180:181], v[200:201], 0, s[2:3]
	v_lshl_add_u64 v[184:185], v[180:181], 0, v[202:203]
	flat_store_dwordx2 v[184:185], v[182:183]
	v_pk_mul_f32 v[184:185], v[72:73], v[152:153]
	v_pk_mul_f32 v[182:183], v[74:75], v[154:155]
	v_pk_fma_f32 v[184:185], v[88:89], v[136:137], v[184:185]
	v_pk_fma_f32 v[182:183], v[90:91], v[138:139], v[182:183]
	v_pk_fma_f32 v[184:185], v[68:69], v[148:149], v[184:185]
	v_pk_fma_f32 v[182:183], v[70:71], v[150:151], v[182:183]
	v_pk_add_f32 v[184:185], v[156:157], v[184:185]
	v_pk_add_f32 v[182:183], v[158:159], v[182:183]
	v_mul_f32_e32 v204, 0xbfb8aa3b, v184
	v_mul_f32_e32 v205, 0xbfb8aa3b, v185
	v_exp_f32_e32 v204, v204
	v_exp_f32_e32 v205, v205
	s_mov_b64 s[2:3], 0x6e00
	v_add_f32_e32 v204, 1.0, v204
	v_add_f32_e32 v205, 1.0, v205
	v_rcp_f32_e32 v204, v204
	v_rcp_f32_e32 v205, v205
	s_nop 0
	v_pk_mul_f32 v[184:185], v[184:185], v[204:205]
	s_nop 0
	v_pk_mul_f32 v[184:185], v[208:209], v[184:185]
	v_pk_mul_f32 v[208:209], v[82:83], v[142:143]
	v_cvt_pk_bf16_f32 v184, v184, v185
	v_mul_f32_e32 v185, 0xbfb8aa3b, v182
	v_exp_f32_e32 v185, v185
	v_pk_fma_f32 v[208:209], v[86:87], v[130:131], v[208:209]
	v_add_f32_e32 v185, 1.0, v185
	v_rcp_f32_e32 v204, v185
	v_mul_f32_e32 v185, 0xbfb8aa3b, v183
	v_exp_f32_e32 v185, v185
	v_pk_fma_f32 v[208:209], v[78:79], v[134:135], v[208:209]
	v_add_f32_e32 v185, 1.0, v185
	v_rcp_f32_e32 v205, v185
	v_pk_add_f32 v[208:209], v[146:147], v[208:209]
	v_pk_mul_f32 v[182:183], v[182:183], v[204:205]
	s_nop 0
	v_pk_mul_f32 v[182:183], v[206:207], v[182:183]
	s_nop 0
	v_cvt_pk_bf16_f32 v185, v182, v183
	v_lshl_add_u64 v[182:183], v[200:201], 0, s[2:3]
	v_lshl_add_u64 v[204:205], v[182:183], 0, v[202:203]
	flat_store_dwordx2 v[204:205], v[184:185]
	v_pk_mul_f32 v[204:205], v[68:69], v[152:153]
	v_pk_mul_f32 v[184:185], v[70:71], v[154:155]
	v_pk_fma_f32 v[204:205], v[72:73], v[136:137], v[204:205]
	v_pk_fma_f32 v[184:185], v[74:75], v[138:139], v[184:185]
	v_pk_fma_f32 v[204:205], v[60:61], v[148:149], v[204:205]
	v_pk_fma_f32 v[184:185], v[62:63], v[150:151], v[184:185]
	v_pk_add_f32 v[204:205], v[156:157], v[204:205]
	v_pk_add_f32 v[184:185], v[158:159], v[184:185]
	v_mul_f32_e32 v206, 0xbfb8aa3b, v204
	v_mul_f32_e32 v207, 0xbfb8aa3b, v205
	v_exp_f32_e32 v206, v206
	v_exp_f32_e32 v207, v207
	s_mov_b64 s[2:3], 0x8400
	v_add_f32_e32 v206, 1.0, v206
	v_add_f32_e32 v207, 1.0, v207
	v_rcp_f32_e32 v206, v206
	v_rcp_f32_e32 v207, v207
	s_nop 0
	v_pk_mul_f32 v[204:205], v[204:205], v[206:207]
	s_nop 0
	v_pk_mul_f32 v[204:205], v[210:211], v[204:205]
	s_nop 0
	v_cvt_pk_bf16_f32 v204, v204, v205
	v_mul_f32_e32 v205, 0xbfb8aa3b, v184
	v_exp_f32_e32 v205, v205
	s_nop 0
	v_add_f32_e32 v205, 1.0, v205
	v_rcp_f32_e32 v206, v205
	v_mul_f32_e32 v205, 0xbfb8aa3b, v185
	v_exp_f32_e32 v205, v205
	s_nop 0
	v_add_f32_e32 v205, 1.0, v205
	v_rcp_f32_e32 v207, v205
	s_nop 0
	v_pk_mul_f32 v[184:185], v[184:185], v[206:207]
	s_nop 0
	v_pk_mul_f32 v[184:185], v[208:209], v[184:185]
	s_nop 0
	v_cvt_pk_bf16_f32 v205, v184, v185
	v_lshl_add_u64 v[184:185], v[200:201], 0, s[2:3]
	v_lshl_add_u64 v[202:203], v[184:185], 0, v[202:203]
	flat_store_dwordx2 v[202:203], v[204:205]
	s_and_saveexec_b64 s[28:29], s[6:7]
	s_cbranch_execz .LBB0_125
; __device__ __forceinline__ unsigned cvt_pk_bf16(float lo, float hi) { f32x2 v = {lo, hi}; bf16x2_t b = __builtin_convertvector(v, bf16x2_t); return __builtin_bit_cast(unsigned, b); }
; __device__ __forceinline__ float sigmoidf_(float v) { return __builtin_amdgcn_rcpf(1.0f + __builtin_amdgcn_exp2f(-1.4426950408889634f * v)); }
; __device__ __forceinline__ float dpp_shr1(float v) { return __builtin_bit_cast(float, __builtin_amdgcn_update_dpp(0, __builtin_bit_cast(int, v), 0x111, 0xf, 0xf, true)); }
; __device__ __forceinline__ float dpp_shl1(float v) { return __builtin_bit_cast(float, __builtin_amdgcn_update_dpp(0, __builtin_bit_cast(int, v), 0x101, 0xf, 0xf, true)); }
;     __device__ __forceinline__ void operator()(const f32x4 (&acc)[2][2][4][2], const Unit& u, int wr, int wc, int fr, int fq) const {
;     ...
;         for (int n = 0; n < 2; ++n) {
;             const int f0 = 128 * u.pn + 32 * wc + 8 * fq + 4 * n;
;             f32x4 wa[3], wg[3];
; #pragma unroll
;             for (int j = 0; j < 3; ++j) { wa[j] = *(const f32x4*)(cw + j * 5632 + f0); wg[j] = *(const f32x4*)(cw + j * 5632 + 2816 + f0); }
;             const f32x4 ba = *(const f32x4*)(cb + f0), bg = *(const f32x4*)(cb + 2816 + f0);
;             f32x4 pa, pg, na, ng;
; #pragma unroll
;             for (int e = 0; e < 4; ++e) { pa[e] = dpp_shr1(acc[1][0][3][n][e]); pg[e] = dpp_shr1(acc[1][1][3][n][e]); na[e] = dpp_shl1(acc[0][0][0][n][e]); ng[e] = dpp_shl1(acc[0][1][0][n][e]); }
; #pragma unroll
;             for (int k = 0; k < 8; ++k) {
;                 const f32x4 ua0 = (k == 0) ? pa : acc[(k - 1) >> 2][0][(k - 1) & 3][n], ua1 = acc[k >> 2][0][k & 3][n], ua2 = (k == 7) ? na : acc[(k + 1) >> 2][0][(k + 1) & 3][n];
;                 const f32x4 ug0 = (k == 0) ? pg : acc[(k - 1) >> 2][1][(k - 1) & 3][n], ug1 = acc[k >> 2][1][k & 3][n], ug2 = (k == 7) ? ng : acc[(k + 1) >> 2][1][(k + 1) & 3][n];
;                 const f32x4 ca = wa[0] * ua0 + wa[1] * ua1 + wa[2] * ua2 + ba, cg = wg[0] * ug0 + wg[1] * ug1 + wg[2] * ug2 + bg;
;                 u32x2 w; w.x = cvt_pk_bf16(cg[0] * sigmoidf_(cg[0]) * ca[0], cg[1] * sigmoidf_(cg[1]) * ca[1]); w.y = cvt_pk_bf16(cg[2] * sigmoidf_(cg[2]) * ca[2], cg[3] * sigmoidf_(cg[3]) * ca[3]);
;                 const bool edge = (k == 0 && fr == 0) || (k == 7 && fr == 15);
;                 if (!edge) *(u32x2*)(ACT + (row0 + k) * 2816 + f0) = w;
;             }
	v_pk_mul_f32 v[152:153], v[60:61], v[152:153]
	v_pk_mul_f32 v[154:155], v[62:63], v[154:155]
	v_pk_fma_f32 v[136:137], v[68:69], v[136:137], v[152:153]
	v_pk_fma_f32 v[138:139], v[70:71], v[138:139], v[154:155]
	v_pk_fma_f32 v[136:137], v[148:149], v[198:199], v[136:137]
	v_pk_mul_f32 v[140:141], v[76:77], v[140:141]
	v_pk_add_f32 v[136:137], v[156:157], v[136:137]
	v_pk_fma_f32 v[138:139], v[150:151], v[190:191], v[138:139]
	v_pk_mul_f32 v[142:143], v[78:79], v[142:143]
	v_pk_fma_f32 v[128:129], v[80:81], v[128:129], v[140:141]
	v_pk_add_f32 v[138:139], v[158:159], v[138:139]
	v_pk_fma_f32 v[130:131], v[82:83], v[130:131], v[142:143]
	v_pk_fma_f32 v[128:129], v[132:133], v[188:189], v[128:129]
	v_mul_f32_e32 v132, 0xbfb8aa3b, v137
	v_mul_f32_e32 v148, 0xbfb8aa3b, v136
	v_exp_f32_e32 v132, v132
	v_pk_fma_f32 v[130:131], v[134:135], v[186:187], v[130:131]
	v_mul_f32_e32 v133, 0xbfb8aa3b, v138
	v_mul_f32_e32 v134, 0xbfb8aa3b, v139
	v_exp_f32_e32 v148, v148
	v_exp_f32_e32 v133, v133
	v_exp_f32_e32 v134, v134
	v_add_f32_e32 v132, 1.0, v132
	v_add_f32_e32 v148, 1.0, v148
	v_rcp_f32_e32 v149, v132
	v_add_f32_e32 v132, 1.0, v133
	v_add_f32_e32 v133, 1.0, v134
	v_rcp_f32_e32 v148, v148
	v_rcp_f32_e32 v132, v132
	v_rcp_f32_e32 v133, v133
	v_pk_add_f32 v[130:131], v[146:147], v[130:131]
	v_pk_add_f32 v[128:129], v[144:145], v[128:129]
	v_pk_mul_f32 v[134:135], v[136:137], v[148:149]
	v_pk_mul_f32 v[132:133], v[138:139], v[132:133]
	v_pk_mul_f32 v[128:129], v[128:129], v[134:135]
	v_pk_mul_f32 v[130:131], v[130:131], v[132:133]
	v_cvt_pk_bf16_f32 v128, v128, v129
	v_cvt_pk_bf16_f32 v129, v130, v131
	v_lshl_add_u64 v[130:131], v[172:173], 1, v[200:201]
	v_add_co_u32_e32 v130, vcc, 0x9000, v130
	s_nop 1
	v_addc_co_u32_e32 v131, vcc, 0, v131, vcc
	flat_store_dwordx2 v[130:131], v[128:129] offset:2560
.LBB0_125:
	s_or_b64 exec, exec, s[28:29]
	v_add3_u32 v202, v215, s1, 4
	v_ashrrev_i32_e32 v203, 31, v202
	v_readlane_b32 s2, v253, 48
	v_lshlrev_b64 v[144:145], 2, v[202:203]
	v_readlane_b32 s3, v253, 49
	v_mov_b32_dpp v204, v12 row_shr:1 row_mask:0xf bank_mask:0xf bound_ctrl:1
	v_mov_b32_dpp v208, v0 row_shr:1 row_mask:0xf bank_mask:0xf bound_ctrl:1
	v_lshl_add_u64 v[128:129], s[2:3], 0, v[144:145]
	v_readlane_b32 s2, v253, 40
	v_readlane_b32 s3, v253, 41
	v_mov_b32_dpp v188, v64 row_shl:1 row_mask:0xf bank_mask:0xf bound_ctrl:1
	v_mov_b32_dpp v198, v56 row_shl:1 row_mask:0xf bank_mask:0xf bound_ctrl:1
	v_lshl_add_u64 v[132:133], s[2:3], 0, v[144:145]
	v_readlane_b32 s2, v253, 42
	v_readlane_b32 s3, v253, 43
	ds_read_b128 v[128:131], v223 offset:528
	s_nop 0
	ds_read_b128 v[136:139], v223 offset:16
	v_lshl_add_u64 v[132:133], s[2:3], 0, v[144:145]
	v_readlane_b32 s2, v253, 44
	v_readlane_b32 s3, v253, 45
	v_mov_b32_dpp v205, v13 row_shr:1 row_mask:0xf bank_mask:0xf bound_ctrl:1
	v_mov_b32_dpp v209, v1 row_shr:1 row_mask:0xf bank_mask:0xf bound_ctrl:1
	v_lshl_add_u64 v[134:135], s[2:3], 0, v[144:145]
	v_readlane_b32 s2, v253, 46
	v_readlane_b32 s3, v253, 47
	ds_read_b128 v[140:143], v223 offset:144
	ds_read_b128 v[152:155], v223 offset:272
	v_lshl_add_u64 v[132:133], s[2:3], 0, v[144:145]
	v_readlane_b32 s2, v253, 50
	v_readlane_b32 s3, v253, 51
	v_mov_b32_dpp v189, v65 row_shl:1 row_mask:0xf bank_mask:0xf bound_ctrl:1
	v_mov_b32_dpp v199, v57 row_shl:1 row_mask:0xf bank_mask:0xf bound_ctrl:1
	v_lshl_add_u64 v[146:147], s[2:3], 0, v[144:145]
	v_readlane_b32 s2, v253, 52
	v_readlane_b32 s3, v253, 53
	ds_read_b128 v[132:135], v223 offset:400
	s_nop 0
	ds_read_b128 v[148:151], v223 offset:656
	v_lshl_add_u64 v[146:147], s[2:3], 0, v[144:145]
	v_readlane_b32 s2, v253, 54
	v_readlane_b32 s3, v253, 55
	v_mov_b32_dpp v206, v14 row_shr:1 row_mask:0xf bank_mask:0xf bound_ctrl:1
	v_mov_b32_dpp v210, v2 row_shr:1 row_mask:0xf bank_mask:0xf bound_ctrl:1
	v_lshl_add_u64 v[156:157], s[2:3], 0, v[144:145]
	ds_read_b128 v[144:147], v223 offset:784
	s_nop 0
	ds_read_b128 v[156:159], v223 offset:912
	v_mov_b32_dpp v186, v66 row_shl:1 row_mask:0xf bank_mask:0xf bound_ctrl:1
	v_mov_b32_dpp v190, v58 row_shl:1 row_mask:0xf bank_mask:0xf bound_ctrl:1
	v_mov_b32_dpp v207, v15 row_shr:1 row_mask:0xf bank_mask:0xf bound_ctrl:1
	v_mov_b32_dpp v211, v3 row_shr:1 row_mask:0xf bank_mask:0xf bound_ctrl:1
	v_mov_b32_dpp v187, v67 row_shl:1 row_mask:0xf bank_mask:0xf bound_ctrl:1
	v_mov_b32_dpp v191, v59 row_shl:1 row_mask:0xf bank_mask:0xf bound_ctrl:1
	v_lshl_add_u64 v[172:173], v[202:203], 1, v[200:201]
	s_and_saveexec_b64 s[28:29], s[8:9]
	s_cbranch_execz .LBB0_127
	s_waitcnt lgkmcnt(0)
	v_pk_mul_f32 v[208:209], v[136:137], v[208:209]
	v_pk_mul_f32 v[200:201], v[138:139], v[210:211]
	v_pk_fma_f32 v[208:209], v[56:57], v[152:153], v[208:209]
	v_pk_mul_f32 v[204:205], v[128:129], v[204:205]
	v_pk_fma_f32 v[208:209], v[40:41], v[148:149], v[208:209]
	v_pk_fma_f32 v[204:205], v[64:65], v[140:141], v[204:205]
	v_pk_add_f32 v[208:209], v[156:157], v[208:209]
	v_pk_fma_f32 v[200:201], v[58:59], v[154:155], v[200:201]
	v_mul_f32_e32 v210, 0xbfb8aa3b, v208
	v_mul_f32_e32 v211, 0xbfb8aa3b, v209
	v_exp_f32_e32 v210, v210
	v_exp_f32_e32 v211, v211
	v_pk_fma_f32 v[204:205], v[52:53], v[132:133], v[204:205]
	v_pk_fma_f32 v[200:201], v[42:43], v[150:151], v[200:201]
	v_add_f32_e32 v210, 1.0, v210
	v_add_f32_e32 v211, 1.0, v211
	v_rcp_f32_e32 v210, v210
	v_rcp_f32_e32 v211, v211
	v_pk_add_f32 v[204:205], v[144:145], v[204:205]
	v_pk_add_f32 v[200:201], v[158:159], v[200:201]
	v_pk_mul_f32 v[206:207], v[130:131], v[206:207]
	v_pk_mul_f32 v[208:209], v[208:209], v[210:211]
	v_pk_fma_f32 v[206:207], v[66:67], v[142:143], v[206:207]
	v_pk_mul_f32 v[204:205], v[204:205], v[208:209]
	v_pk_fma_f32 v[206:207], v[54:55], v[134:135], v[206:207]
	v_cvt_pk_bf16_f32 v204, v204, v205
	v_mul_f32_e32 v205, 0xbfb8aa3b, v200
	v_exp_f32_e32 v205, v205
	v_pk_add_f32 v[206:207], v[146:147], v[206:207]
	v_add_f32_e32 v205, 1.0, v205
	v_rcp_f32_e32 v208, v205
	v_mul_f32_e32 v205, 0xbfb8aa3b, v201
	v_exp_f32_e32 v205, v205
	s_nop 0
	v_add_f32_e32 v205, 1.0, v205
	v_rcp_f32_e32 v209, v205
	s_nop 0
	v_pk_mul_f32 v[200:201], v[200:201], v[208:209]
	s_nop 0
	v_pk_mul_f32 v[200:201], v[206:207], v[200:201]
	s_nop 0
	v_cvt_pk_bf16_f32 v205, v200, v201
	flat_store_dwordx2 v[172:173], v[204:205]
; __device__ __forceinline__ unsigned cvt_pk_bf16(float lo, float hi) { f32x2 v = {lo, hi}; bf16x2_t b = __builtin_convertvector(v, bf16x2_t); return __builtin_bit_cast(unsigned, b); }
; __device__ __forceinline__ float sigmoidf_(float v) { return __builtin_amdgcn_rcpf(1.0f + __builtin_amdgcn_exp2f(-1.4426950408889634f * v)); }
;     __device__ __forceinline__ void operator()(const f32x4 (&acc)[2][2][4][2], const Unit& u, int wr, int wc, int fr, int fq) const {
;     ...
;             for (int k = 0; k < 8; ++k) {
;                 const f32x4 ua0 = (k == 0) ? pa : acc[(k - 1) >> 2][0][(k - 1) & 3][n], ua1 = acc[k >> 2][0][k & 3][n], ua2 = (k == 7) ? na : acc[(k + 1) >> 2][0][(k + 1) & 3][n];
;                 const f32x4 ug0 = (k == 0) ? pg : acc[(k - 1) >> 2][1][(k - 1) & 3][n], ug1 = acc[k >> 2][1][k & 3][n], ug2 = (k == 7) ? ng : acc[(k + 1) >> 2][1][(k + 1) & 3][n];
;                 const f32x4 ca = wa[0] * ua0 + wa[1] * ua1 + wa[2] * ua2 + ba, cg = wg[0] * ug0 + wg[1] * ug1 + wg[2] * ug2 + bg;
;                 u32x2 w; w.x = cvt_pk_bf16(cg[0] * sigmoidf_(cg[0]) * ca[0], cg[1] * sigmoidf_(cg[1]) * ca[1]); w.y = cvt_pk_bf16(cg[2] * sigmoidf_(cg[2]) * ca[2], cg[3] * sigmoidf_(cg[3]) * ca[3]);
;                 const bool edge = (k == 0 && fr == 0) || (k == 7 && fr == 15);
;                 if (!edge) *(u32x2*)(ACT + (row0 + k) * 2816 + f0) = w;
;             }
.LBB0_127:
	s_or_b64 exec, exec, s[28:29]
	s_waitcnt lgkmcnt(0)
	v_pk_mul_f32 v[204:205], v[40:41], v[152:153]
	v_pk_mul_f32 v[210:211], v[52:53], v[140:141]
	v_pk_fma_f32 v[204:205], v[56:57], v[136:137], v[204:205]
	v_pk_mul_f32 v[200:201], v[42:43], v[154:155]
	v_pk_fma_f32 v[204:205], v[36:37], v[148:149], v[204:205]
	v_pk_fma_f32 v[210:211], v[64:65], v[128:129], v[210:211]
	v_pk_add_f32 v[204:205], v[156:157], v[204:205]
	v_pk_fma_f32 v[200:201], v[58:59], v[138:139], v[200:201]
	v_mul_f32_e32 v206, 0xbfb8aa3b, v204
	v_mul_f32_e32 v207, 0xbfb8aa3b, v205
	v_exp_f32_e32 v206, v206
	v_exp_f32_e32 v207, v207
	v_pk_fma_f32 v[210:211], v[48:49], v[132:133], v[210:211]
	v_pk_fma_f32 v[200:201], v[38:39], v[150:151], v[200:201]
	v_add_f32_e32 v206, 1.0, v206
	v_add_f32_e32 v207, 1.0, v207
	v_rcp_f32_e32 v206, v206
	v_rcp_f32_e32 v207, v207
	v_pk_add_f32 v[210:211], v[144:145], v[210:211]
	v_pk_add_f32 v[200:201], v[158:159], v[200:201]
	v_pk_mul_f32 v[208:209], v[54:55], v[142:143]
	v_pk_mul_f32 v[204:205], v[204:205], v[206:207]
	v_pk_fma_f32 v[208:209], v[66:67], v[130:131], v[208:209]
	v_pk_mul_f32 v[204:205], v[210:211], v[204:205]
	v_pk_fma_f32 v[208:209], v[50:51], v[134:135], v[208:209]
	v_cvt_pk_bf16_f32 v204, v204, v205
	v_mul_f32_e32 v205, 0xbfb8aa3b, v200
	v_exp_f32_e32 v205, v205
	v_pk_add_f32 v[208:209], v[146:147], v[208:209]
	v_add_f32_e32 v205, 1.0, v205
	v_rcp_f32_e32 v206, v205
	v_mul_f32_e32 v205, 0xbfb8aa3b, v201
	v_exp_f32_e32 v205, v205
	s_nop 0
	v_add_f32_e32 v205, 1.0, v205
	v_rcp_f32_e32 v207, v205
	s_nop 0
	v_pk_mul_f32 v[200:201], v[200:201], v[206:207]
	s_nop 0
	v_pk_mul_f32 v[200:201], v[208:209], v[200:201]
	v_pk_mul_f32 v[208:209], v[48:49], v[140:141]
	v_cvt_pk_bf16_f32 v205, v200, v201
	v_lshlrev_b64 v[200:201], 1, v[202:203]
	v_pk_mul_f32 v[202:203], v[36:37], v[152:153]
	v_lshl_add_u64 v[174:175], v[174:175], 0, v[200:201]
	v_pk_fma_f32 v[202:203], v[40:41], v[136:137], v[202:203]
	flat_store_dwordx2 v[174:175], v[204:205]
	v_pk_fma_f32 v[202:203], v[32:33], v[148:149], v[202:203]
	v_pk_mul_f32 v[174:175], v[38:39], v[154:155]
	v_pk_add_f32 v[202:203], v[156:157], v[202:203]
	v_pk_fma_f32 v[208:209], v[52:53], v[128:129], v[208:209]
	v_mul_f32_e32 v204, 0xbfb8aa3b, v202
	v_mul_f32_e32 v205, 0xbfb8aa3b, v203
	v_exp_f32_e32 v204, v204
	v_exp_f32_e32 v205, v205
	v_pk_fma_f32 v[174:175], v[42:43], v[138:139], v[174:175]
	v_pk_fma_f32 v[208:209], v[44:45], v[132:133], v[208:209]
	v_add_f32_e32 v204, 1.0, v204
	v_add_f32_e32 v205, 1.0, v205
	v_rcp_f32_e32 v204, v204
	v_rcp_f32_e32 v205, v205
	v_pk_fma_f32 v[174:175], v[34:35], v[150:151], v[174:175]
	v_pk_add_f32 v[208:209], v[144:145], v[208:209]
	v_pk_add_f32 v[174:175], v[158:159], v[174:175]
	v_pk_mul_f32 v[202:203], v[202:203], v[204:205]
	v_pk_mul_f32 v[206:207], v[50:51], v[142:143]
	v_pk_mul_f32 v[202:203], v[208:209], v[202:203]
	v_pk_fma_f32 v[206:207], v[54:55], v[130:131], v[206:207]
	v_cvt_pk_bf16_f32 v202, v202, v203
	v_mul_f32_e32 v203, 0xbfb8aa3b, v174
	v_exp_f32_e32 v203, v203
	v_pk_fma_f32 v[206:207], v[46:47], v[134:135], v[206:207]
	v_add_f32_e32 v203, 1.0, v203
	v_rcp_f32_e32 v204, v203
	v_mul_f32_e32 v203, 0xbfb8aa3b, v175
	v_exp_f32_e32 v203, v203
	v_pk_add_f32 v[206:207], v[146:147], v[206:207]
	v_add_f32_e32 v203, 1.0, v203
	v_rcp_f32_e32 v205, v203
	s_nop 0
	v_pk_mul_f32 v[174:175], v[174:175], v[204:205]
	s_nop 0
	v_pk_mul_f32 v[174:175], v[206:207], v[174:175]
	v_pk_mul_f32 v[206:207], v[44:45], v[140:141]
	v_cvt_pk_bf16_f32 v203, v174, v175
	v_lshl_add_u64 v[174:175], v[176:177], 0, v[200:201]
	v_pk_mul_f32 v[176:177], v[32:33], v[152:153]
	flat_store_dwordx2 v[174:175], v[202:203]
	v_pk_fma_f32 v[176:177], v[36:37], v[136:137], v[176:177]
	v_pk_mul_f32 v[174:175], v[34:35], v[154:155]
	v_pk_fma_f32 v[176:177], v[24:25], v[148:149], v[176:177]
	v_pk_fma_f32 v[206:207], v[48:49], v[128:129], v[206:207]
	v_pk_add_f32 v[176:177], v[156:157], v[176:177]
	v_pk_fma_f32 v[174:175], v[38:39], v[138:139], v[174:175]
	v_mul_f32_e32 v202, 0xbfb8aa3b, v176
	v_mul_f32_e32 v203, 0xbfb8aa3b, v177
	v_exp_f32_e32 v202, v202
	v_exp_f32_e32 v203, v203
	v_pk_fma_f32 v[206:207], v[28:29], v[132:133], v[206:207]
	v_pk_fma_f32 v[174:175], v[26:27], v[150:151], v[174:175]
	v_add_f32_e32 v202, 1.0, v202
	v_add_f32_e32 v203, 1.0, v203
	v_rcp_f32_e32 v202, v202
	v_rcp_f32_e32 v203, v203
	v_pk_add_f32 v[206:207], v[144:145], v[206:207]
	v_pk_add_f32 v[174:175], v[158:159], v[174:175]
	v_pk_mul_f32 v[204:205], v[46:47], v[142:143]
	v_pk_mul_f32 v[176:177], v[176:177], v[202:203]
	v_pk_fma_f32 v[204:205], v[50:51], v[130:131], v[204:205]
	v_pk_mul_f32 v[176:177], v[206:207], v[176:177]
	v_pk_fma_f32 v[204:205], v[30:31], v[134:135], v[204:205]
	v_cvt_pk_bf16_f32 v176, v176, v177
	v_mul_f32_e32 v177, 0xbfb8aa3b, v174
	v_exp_f32_e32 v177, v177
	v_pk_add_f32 v[204:205], v[146:147], v[204:205]
	v_add_f32_e32 v177, 1.0, v177
	v_rcp_f32_e32 v202, v177
	v_mul_f32_e32 v177, 0xbfb8aa3b, v175
	v_exp_f32_e32 v177, v177
	s_nop 0
	v_add_f32_e32 v177, 1.0, v177
	v_rcp_f32_e32 v203, v177
	s_nop 0
	v_pk_mul_f32 v[174:175], v[174:175], v[202:203]
	s_nop 0
	v_pk_mul_f32 v[174:175], v[204:205], v[174:175]
	v_pk_mul_f32 v[204:205], v[28:29], v[140:141]
	v_cvt_pk_bf16_f32 v177, v174, v175
	v_lshl_add_u64 v[174:175], v[178:179], 0, v[200:201]
	flat_store_dwordx2 v[174:175], v[176:177]
	v_pk_mul_f32 v[176:177], v[24:25], v[152:153]
	v_pk_mul_f32 v[174:175], v[26:27], v[154:155]
	v_pk_fma_f32 v[176:177], v[32:33], v[136:137], v[176:177]
	v_pk_fma_f32 v[204:205], v[44:45], v[128:129], v[204:205]
	v_pk_fma_f32 v[176:177], v[8:9], v[148:149], v[176:177]
	v_pk_fma_f32 v[174:175], v[34:35], v[138:139], v[174:175]
; __device__ __forceinline__ unsigned cvt_pk_bf16(float lo, float hi) { f32x2 v = {lo, hi}; bf16x2_t b = __builtin_convertvector(v, bf16x2_t); return __builtin_bit_cast(unsigned, b); }
; __device__ __forceinline__ float sigmoidf_(float v) { return __builtin_amdgcn_rcpf(1.0f + __builtin_amdgcn_exp2f(-1.4426950408889634f * v)); }
;     __device__ __forceinline__ void operator()(const f32x4 (&acc)[2][2][4][2], const Unit& u, int wr, int wc, int fr, int fq) const {
;     ...
;             for (int k = 0; k < 8; ++k) {
;                 const f32x4 ua0 = (k == 0) ? pa : acc[(k - 1) >> 2][0][(k - 1) & 3][n], ua1 = acc[k >> 2][0][k & 3][n], ua2 = (k == 7) ? na : acc[(k + 1) >> 2][0][(k + 1) & 3][n];
;                 const f32x4 ug0 = (k == 0) ? pg : acc[(k - 1) >> 2][1][(k - 1) & 3][n], ug1 = acc[k >> 2][1][k & 3][n], ug2 = (k == 7) ? ng : acc[(k + 1) >> 2][1][(k + 1) & 3][n];
;                 const f32x4 ca = wa[0] * ua0 + wa[1] * ua1 + wa[2] * ua2 + ba, cg = wg[0] * ug0 + wg[1] * ug1 + wg[2] * ug2 + bg;
;                 u32x2 w; w.x = cvt_pk_bf16(cg[0] * sigmoidf_(cg[0]) * ca[0], cg[1] * sigmoidf_(cg[1]) * ca[1]); w.y = cvt_pk_bf16(cg[2] * sigmoidf_(cg[2]) * ca[2], cg[3] * sigmoidf_(cg[3]) * ca[3]);
;                 const bool edge = (k == 0 && fr == 0) || (k == 7 && fr == 15);
;                 if (!edge) *(u32x2*)(ACT + (row0 + k) * 2816 + f0) = w;
;             }
	v_pk_add_f32 v[176:177], v[156:157], v[176:177]
	v_pk_fma_f32 v[204:205], v[20:21], v[132:133], v[204:205]
	v_mul_f32_e32 v178, 0xbfb8aa3b, v176
	v_mul_f32_e32 v179, 0xbfb8aa3b, v177
	v_exp_f32_e32 v178, v178
	v_exp_f32_e32 v179, v179
	v_pk_fma_f32 v[174:175], v[10:11], v[150:151], v[174:175]
	v_pk_add_f32 v[204:205], v[144:145], v[204:205]
	v_add_f32_e32 v178, 1.0, v178
	v_add_f32_e32 v179, 1.0, v179
	v_rcp_f32_e32 v178, v178
	v_rcp_f32_e32 v179, v179
	v_pk_add_f32 v[174:175], v[158:159], v[174:175]
	v_pk_mul_f32 v[202:203], v[30:31], v[142:143]
	v_pk_mul_f32 v[176:177], v[176:177], v[178:179]
	s_nop 0
	v_pk_mul_f32 v[176:177], v[204:205], v[176:177]
	v_pk_fma_f32 v[202:203], v[46:47], v[130:131], v[202:203]
	v_cvt_pk_bf16_f32 v176, v176, v177
	v_mul_f32_e32 v177, 0xbfb8aa3b, v174
	v_exp_f32_e32 v177, v177
	v_pk_fma_f32 v[202:203], v[22:23], v[134:135], v[202:203]
	v_add_f32_e32 v177, 1.0, v177
	v_rcp_f32_e32 v178, v177
	v_mul_f32_e32 v177, 0xbfb8aa3b, v175
	v_exp_f32_e32 v177, v177
	v_pk_add_f32 v[202:203], v[146:147], v[202:203]
	v_add_f32_e32 v177, 1.0, v177
	v_rcp_f32_e32 v179, v177
	s_nop 0
	v_pk_mul_f32 v[174:175], v[174:175], v[178:179]
	s_nop 0
	v_pk_mul_f32 v[174:175], v[202:203], v[174:175]
	v_pk_mul_f32 v[202:203], v[20:21], v[140:141]
	v_cvt_pk_bf16_f32 v177, v174, v175
	v_lshl_add_u64 v[174:175], v[180:181], 0, v[200:201]
	flat_store_dwordx2 v[174:175], v[176:177]
	v_pk_mul_f32 v[176:177], v[8:9], v[152:153]
	v_pk_mul_f32 v[174:175], v[10:11], v[154:155]
	v_pk_fma_f32 v[176:177], v[24:25], v[136:137], v[176:177]
	v_pk_fma_f32 v[202:203], v[28:29], v[128:129], v[202:203]
	v_pk_fma_f32 v[176:177], v[4:5], v[148:149], v[176:177]
	v_pk_fma_f32 v[174:175], v[26:27], v[138:139], v[174:175]
	v_pk_add_f32 v[176:177], v[156:157], v[176:177]
	v_pk_fma_f32 v[202:203], v[16:17], v[132:133], v[202:203]
	v_mul_f32_e32 v178, 0xbfb8aa3b, v176
	v_mul_f32_e32 v179, 0xbfb8aa3b, v177
	v_exp_f32_e32 v178, v178
	v_exp_f32_e32 v179, v179
	v_pk_fma_f32 v[174:175], v[6:7], v[150:151], v[174:175]
	v_pk_add_f32 v[202:203], v[144:145], v[202:203]
	v_add_f32_e32 v178, 1.0, v178
	v_add_f32_e32 v179, 1.0, v179
	v_rcp_f32_e32 v178, v178
	v_rcp_f32_e32 v179, v179
	v_pk_add_f32 v[174:175], v[158:159], v[174:175]
	v_pk_mul_f32 v[180:181], v[22:23], v[142:143]
	v_pk_mul_f32 v[176:177], v[176:177], v[178:179]
	s_nop 0
	v_pk_mul_f32 v[176:177], v[202:203], v[176:177]
	v_pk_fma_f32 v[180:181], v[30:31], v[130:131], v[180:181]
	v_cvt_pk_bf16_f32 v176, v176, v177
	v_mul_f32_e32 v177, 0xbfb8aa3b, v174
	v_exp_f32_e32 v177, v177
	v_pk_fma_f32 v[180:181], v[18:19], v[134:135], v[180:181]
	v_add_f32_e32 v177, 1.0, v177
	v_rcp_f32_e32 v178, v177
	v_mul_f32_e32 v177, 0xbfb8aa3b, v175
	v_exp_f32_e32 v177, v177
	v_pk_add_f32 v[180:181], v[146:147], v[180:181]
	v_add_f32_e32 v177, 1.0, v177
	v_rcp_f32_e32 v179, v177
	s_nop 0
	v_pk_mul_f32 v[174:175], v[174:175], v[178:179]
	s_nop 0
	v_pk_mul_f32 v[174:175], v[180:181], v[174:175]
	v_pk_mul_f32 v[180:181], v[18:19], v[142:143]
	v_cvt_pk_bf16_f32 v177, v174, v175
	v_lshl_add_u64 v[174:175], v[182:183], 0, v[200:201]
	flat_store_dwordx2 v[174:175], v[176:177]
	v_pk_mul_f32 v[176:177], v[4:5], v[152:153]
	v_pk_mul_f32 v[182:183], v[16:17], v[140:141]
	v_pk_fma_f32 v[176:177], v[8:9], v[136:137], v[176:177]
	v_pk_mul_f32 v[174:175], v[6:7], v[154:155]
	v_pk_fma_f32 v[176:177], v[0:1], v[148:149], v[176:177]
	v_pk_fma_f32 v[182:183], v[20:21], v[128:129], v[182:183]
	v_pk_add_f32 v[176:177], v[156:157], v[176:177]
	v_pk_fma_f32 v[174:175], v[10:11], v[138:139], v[174:175]
	v_mul_f32_e32 v178, 0xbfb8aa3b, v176
	v_mul_f32_e32 v179, 0xbfb8aa3b, v177
	v_exp_f32_e32 v178, v178
	v_exp_f32_e32 v179, v179
	v_pk_fma_f32 v[182:183], v[12:13], v[132:133], v[182:183]
	v_pk_fma_f32 v[174:175], v[2:3], v[150:151], v[174:175]
	v_add_f32_e32 v178, 1.0, v178
	v_add_f32_e32 v179, 1.0, v179
	v_rcp_f32_e32 v178, v178
	v_rcp_f32_e32 v179, v179
	v_pk_add_f32 v[182:183], v[144:145], v[182:183]
	v_pk_add_f32 v[174:175], v[158:159], v[174:175]
	v_pk_fma_f32 v[180:181], v[22:23], v[130:131], v[180:181]
	v_pk_mul_f32 v[176:177], v[176:177], v[178:179]
	v_pk_fma_f32 v[180:181], v[14:15], v[134:135], v[180:181]
	v_pk_mul_f32 v[176:177], v[182:183], v[176:177]
	v_pk_add_f32 v[180:181], v[146:147], v[180:181]
	v_cvt_pk_bf16_f32 v176, v176, v177
	v_mul_f32_e32 v177, 0xbfb8aa3b, v174
	v_exp_f32_e32 v177, v177
	s_nop 0
	v_add_f32_e32 v177, 1.0, v177
	v_rcp_f32_e32 v178, v177
	v_mul_f32_e32 v177, 0xbfb8aa3b, v175
	v_exp_f32_e32 v177, v177
	s_nop 0
	v_add_f32_e32 v177, 1.0, v177
	v_rcp_f32_e32 v179, v177
	s_nop 0
	v_pk_mul_f32 v[174:175], v[174:175], v[178:179]
	s_nop 0
	v_pk_mul_f32 v[174:175], v[180:181], v[174:175]
	s_nop 0
	v_cvt_pk_bf16_f32 v177, v174, v175
	v_lshl_add_u64 v[174:175], v[184:185], 0, v[200:201]
	flat_store_dwordx2 v[174:175], v[176:177]
	s_and_saveexec_b64 s[8:9], s[6:7]
	s_cbranch_execz .LBB0_129
	v_pk_mul_f32 v[152:153], v[0:1], v[152:153]
	v_pk_mul_f32 v[154:155], v[2:3], v[154:155]
	v_pk_fma_f32 v[136:137], v[4:5], v[136:137], v[152:153]
	v_pk_fma_f32 v[138:139], v[6:7], v[138:139], v[154:155]
	v_pk_fma_f32 v[136:137], v[148:149], v[198:199], v[136:137]
	v_pk_mul_f32 v[140:141], v[12:13], v[140:141]
	v_pk_add_f32 v[136:137], v[156:157], v[136:137]
	v_pk_fma_f32 v[138:139], v[150:151], v[190:191], v[138:139]
	v_pk_mul_f32 v[142:143], v[14:15], v[142:143]
	v_pk_fma_f32 v[128:129], v[16:17], v[128:129], v[140:141]
	v_pk_add_f32 v[138:139], v[158:159], v[138:139]
	v_pk_fma_f32 v[130:131], v[18:19], v[130:131], v[142:143]
	v_pk_fma_f32 v[128:129], v[132:133], v[188:189], v[128:129]
	v_mul_f32_e32 v132, 0xbfb8aa3b, v137
	v_mul_f32_e32 v148, 0xbfb8aa3b, v136
	v_exp_f32_e32 v132, v132
	v_pk_fma_f32 v[130:131], v[134:135], v[186:187], v[130:131]
	v_mul_f32_e32 v133, 0xbfb8aa3b, v138
	v_mul_f32_e32 v134, 0xbfb8aa3b, v139
	v_exp_f32_e32 v148, v148
	v_exp_f32_e32 v133, v133
	v_exp_f32_e32 v134, v134
	v_add_f32_e32 v132, 1.0, v132
	v_add_f32_e32 v148, 1.0, v148
	v_rcp_f32_e32 v149, v132
	v_add_f32_e32 v132, 1.0, v133
	v_add_f32_e32 v133, 1.0, v134
	v_rcp_f32_e32 v148, v148
	v_rcp_f32_e32 v132, v132
	v_rcp_f32_e32 v133, v133
	v_pk_add_f32 v[130:131], v[146:147], v[130:131]
	v_pk_add_f32 v[128:129], v[144:145], v[128:129]
	v_pk_mul_f32 v[134:135], v[136:137], v[148:149]
	v_pk_mul_f32 v[132:133], v[138:139], v[132:133]
	v_pk_mul_f32 v[128:129], v[128:129], v[134:135]
	v_pk_mul_f32 v[130:131], v[130:131], v[132:133]
	v_cvt_pk_bf16_f32 v128, v128, v129
	v_cvt_pk_bf16_f32 v129, v130, v131
	v_add_co_u32_e32 v130, vcc, 0x9000, v172
	s_nop 1
	v_addc_co_u32_e32 v131, vcc, 0, v173, vcc
	flat_store_dwordx2 v[130:131], v[128:129] offset:2560

; __device__ __forceinline__ float bf2f(unsigned short b) { return __uint_as_float((unsigned)b << 16); }
; __device__ __forceinline__ float sum_x32(float v) { auto rr = __builtin_amdgcn_permlane32_swap(__float_as_uint(v), __float_as_uint(v), false, false); return __uint_as_float(rr[0]) + __uint_as_float(rr[1]); }
; template <int DV>
; __device__ __forceinline__ void attn_pass(const int tid, unsigned char* smem, const bf16_t* Q0, int qpitch, const bf16_t* Kb, int kpitch, const bf16_t* Vb, int vpitch,
;                                           int b, int ntiles, float kmax, f32x16 (&o)[DV / 32], float& linv) {
;     ...
;     { const bf16_t* qp = Q0 + (size_t)(wid * 32 + r32) * qpitch + 8 * hi;
; #pragma unroll
;       for (int ds = 0; ds < 4; ++ds) qf[ds] = *(const bf16x8*)(qp + 16 * ds); }
;     float ssq = 0.f;
; #pragma unroll
;     for (int ds = 0; ds < 4; ++ds)
; #pragma unroll
;         for (int j = 0; j < 8; ++j) { const float f = bf2f((unsigned short)qf[ds][j]); ssq += f * f; }
;     ssq = sum_x32(ssq);
;     const float nshift = -sqrtf(ssq) * kmax;
; #pragma unroll
;     for (int d0 = 0; d0 < DV / 32; ++d0)
; #pragma unroll
;         for (int r = 0; r < 16; ++r) o[d0][r] = 0.f;
;     float lsum = 0.f;
;     const int krow = tid >> 3, kch = tid & 7;
;     u32x4 kreg, vreg[NV];
;     auto tile_row = [&](int kt) -> size_t { return kt < 4 ? (size_t)(NLAT + 256 * b + 64 * kt) : (size_t)(SEQ * b + 64 * (kt - 4)); };
;     auto gload = [&](int kt) {
;         const size_t rb = tile_row(kt);
;         kreg = *(const u32x4*)(Kb + (rb + krow) * kpitch + 8 * kch);
; #pragma unroll
;         for (int i = 0; i < NV; ++i) { const int item = tid + 512 * i; const int vr = (DV == 64) ? (item >> 3) : (item >> 4), vc = (DV == 64) ? (item & 7) : (item & 15);
;             vreg[i] = *(const u32x4*)(Vb + (rb + vr) * vpitch + 8 * vc); }
;     };
;     auto lwrite = [&](int buf) {
;         unsigned char* Ks = smem + buf * BUF; unsigned char* Vs = Ks + KBYTES;
;         *(u32x4*)(Ks + krow * KP + 16 * kch) = kreg;
; #pragma unroll
;         for (int i = 0; i < NV; ++i) { const int item = tid + 512 * i; const int vr = (DV == 64) ? (item >> 3) : (item >> 4), vc = (DV == 64) ? (item & 7) : (item & 15);
;             *(u32x4*)(Vs + vr * VP + 16 * vc) = vreg[i]; }
;     };
;     gload(0); lwrite(0); __syncthreads();
.LBB0_405:
	s_xor_b64 s[14:15], s[16:17], -1
	s_lshl_b64 s[0:1], s[0:1], 1
	s_add_u32 s2, s28, s0
	s_addc_u32 s3, s29, s1
	s_add_u32 s16, s30, s0
	v_readfirstlane_b32 s0, v197
	s_addc_u32 s17, s31, s1
	s_ashr_i32 s0, s0, 1
	s_andn2_b32 s0, s0, 31
	v_or_b32_e32 v0, s0, v218
	v_ashrrev_i32_e32 v1, 31, v0
	v_lshlrev_b64 v[0:1], 11, v[0:1]
	v_lshl_add_u64 v[0:1], s[2:3], 0, v[0:1]
	v_lshl_add_u64 v[0:1], v[0:1], 0, v[192:193]
	global_load_dwordx4 v[96:99], v[0:1], off
	global_load_dwordx4 v[100:103], v[0:1], off offset:32
	global_load_dwordx4 v[104:107], v[0:1], off offset:64
	global_load_dwordx4 v[108:111], v[0:1], off offset:96
	s_mov_b32 s0, 0xf800000
	v_mov_b32_e32 v169, v193
	v_readlane_b32 s68, v251, 29
	v_readlane_b32 s69, v251, 30
	s_lshl_b32 s2, s26, 8
	s_add_u32 s68, s68, s2
	s_addc_u32 s69, s69, 0
	s_mov_b64 s[66:67], s[16:17]
	s_lshl_b32 s2, s10, 8
	s_add_i32 s65, s2, 0x8000
	s_lshl_b32 s2, s10, 13
	s_add_i32 s32, s2, 0xffffff00
	s_lshr_b32 s56, s27, 6
	s_lshl_b32 s56, s56, 10
	v_bfe_u32 v234, v136, 1, 3
	v_and_b32_e32 v235, 7, v197
	v_xor_b32_e32 v234, v234, v235
	v_lshlrev_b32_e32 v234, 4, v234
	v_lshl_add_u32 v166, v136, 10, v234
	v_and_b32_e32 v236, 3, v134
	v_lshlrev_b32_e32 v236, 2, v236
	v_and_b32_e32 v237, 15, v197
	v_xor_b32_e32 v236, v236, v237
	v_lshlrev_b32_e32 v236, 4, v236
	v_lshl_add_u32 v167, v134, 10, v236
	v_add_u32_e32 v132, 0x8000, v167
	s_mov_b32 s70, 0
	s_cmp_lt_u32 s70, 4
	s_cselect_b32 s2, s65, s32
	s_lshl_b32 s3, s70, 6
	s_add_i32 s2, s2, s3
	s_lshl_b32 s2, s2, 10
	s_add_u32 s60, s66, s2
	s_addc_u32 s61, s67, 0
	s_cmp_lt_u32 s70, 4
	s_cselect_b32 s2, s65, s32
	s_lshl_b32 s3, s70, 6
	s_add_i32 s2, s2, s3
	s_lshl_b32 s2, s2, 10
	s_add_u32 s62, s68, s2
	s_addc_u32 s63, s69, 0
	s_mov_b32 m0, s56
	s_nop 0
	global_load_lds_dwordx4 v166, s[60:61]
	s_mov_b32 s70, 1
	s_cmp_lt_u32 s70, 4
	s_cselect_b32 s2, s65, s32
	s_lshl_b32 s3, s70, 6
	s_add_i32 s2, s2, s3
	s_lshl_b32 s2, s2, 10
	s_add_u32 s60, s66, s2
	s_addc_u32 s61, s67, 0
	s_add_i32 m0, s56, 0x6000
	s_nop 0
	global_load_lds_dwordx4 v166, s[60:61]
	s_add_i32 m0, s56, 0x8000
	s_nop 0
	global_load_lds_dwordx4 v167, s[62:63]
	s_add_i32 m0, s56, 0xa000
	s_nop 0
	global_load_lds_dwordx4 v132, s[62:63]
	s_cmp_lt_u32 s70, 4
	s_cselect_b32 s2, s65, s32
	s_lshl_b32 s3, s70, 6
	s_add_i32 s2, s2, s3
	s_lshl_b32 s2, s2, 10
	s_add_u32 s62, s68, s2
	s_addc_u32 s63, s69, 0
	s_mov_b32 s70, 2
	s_cmp_lt_u32 s70, 4
	s_cselect_b32 s2, s65, s32
	s_lshl_b32 s3, s70, 6
	s_add_i32 s2, s2, s3
	s_lshl_b32 s2, s2, 10
	s_add_u32 s60, s66, s2
	s_addc_u32 s61, s67, 0
	s_add_i32 m0, s56, 0xc000
	s_nop 0
	global_load_lds_dwordx4 v166, s[60:61]
	s_add_i32 m0, s56, 0xe000
	s_nop 0
	global_load_lds_dwordx4 v167, s[62:63]
	s_add_i32 m0, s56, 0x10000
	s_nop 0
	global_load_lds_dwordx4 v132, s[62:63]
	v_mov_b32_e32 v63, v193
	s_waitcnt vmcnt(10)
	v_and_b32_e32 v1, 0xffff0000, v96
	v_lshlrev_b32_e32 v0, 16, v96
	v_mul_f32_e32 v2, v1, v1
	v_fmac_f32_e32 v2, v0, v0
	v_lshlrev_b32_e32 v0, 16, v97
	v_fmac_f32_e32 v2, v0, v0
	v_and_b32_e32 v0, 0xffff0000, v97
	v_fmac_f32_e32 v2, v0, v0
	v_lshlrev_b32_e32 v0, 16, v98
	v_fmac_f32_e32 v2, v0, v0
	v_and_b32_e32 v0, 0xffff0000, v98
	v_fmac_f32_e32 v2, v0, v0
	v_lshlrev_b32_e32 v0, 16, v99
	v_fmac_f32_e32 v2, v0, v0
	v_and_b32_e32 v0, 0xffff0000, v99
	v_fmac_f32_e32 v2, v0, v0
	s_waitcnt vmcnt(9)
	v_lshlrev_b32_e32 v0, 16, v100
	v_fmac_f32_e32 v2, v0, v0
	v_and_b32_e32 v0, 0xffff0000, v100
	v_fmac_f32_e32 v2, v0, v0
	v_lshlrev_b32_e32 v0, 16, v101
	v_fmac_f32_e32 v2, v0, v0
	v_and_b32_e32 v0, 0xffff0000, v101
	v_fmac_f32_e32 v2, v0, v0
	v_lshlrev_b32_e32 v0, 16, v102
	v_fmac_f32_e32 v2, v0, v0
	v_and_b32_e32 v0, 0xffff0000, v102
	v_fmac_f32_e32 v2, v0, v0
	v_lshlrev_b32_e32 v0, 16, v103
	v_fmac_f32_e32 v2, v0, v0
	v_and_b32_e32 v0, 0xffff0000, v103
	v_fmac_f32_e32 v2, v0, v0
	s_waitcnt vmcnt(8)
	v_lshlrev_b32_e32 v0, 16, v104
	v_fmac_f32_e32 v2, v0, v0
	v_and_b32_e32 v0, 0xffff0000, v104
	v_fmac_f32_e32 v2, v0, v0
	v_lshlrev_b32_e32 v0, 16, v105
	v_fmac_f32_e32 v2, v0, v0
	v_and_b32_e32 v0, 0xffff0000, v105
	v_fmac_f32_e32 v2, v0, v0
	v_lshlrev_b32_e32 v0, 16, v106
	v_fmac_f32_e32 v2, v0, v0
	v_and_b32_e32 v0, 0xffff0000, v106
	v_fmac_f32_e32 v2, v0, v0
	v_lshlrev_b32_e32 v0, 16, v107
	v_fmac_f32_e32 v2, v0, v0
	v_and_b32_e32 v0, 0xffff0000, v107
	v_fmac_f32_e32 v2, v0, v0
	s_waitcnt vmcnt(7)
; __device__ __forceinline__ float bf2f(unsigned short b) { return __uint_as_float((unsigned)b << 16); }
; __device__ __forceinline__ float sum_x32(float v) { auto rr = __builtin_amdgcn_permlane32_swap(__float_as_uint(v), __float_as_uint(v), false, false); return __uint_as_float(rr[0]) + __uint_as_float(rr[1]); }
; template <int DV>
; __device__ __forceinline__ void attn_pass(const int tid, unsigned char* smem, const bf16_t* Q0, int qpitch, const bf16_t* Kb, int kpitch, const bf16_t* Vb, int vpitch,
;                                           int b, int ntiles, float kmax, f32x16 (&o)[DV / 32], float& linv) {
;     ...
;     float ssq = 0.f;
; #pragma unroll
;     for (int ds = 0; ds < 4; ++ds)
; #pragma unroll
;         for (int j = 0; j < 8; ++j) { const float f = bf2f((unsigned short)qf[ds][j]); ssq += f * f; }
;     ssq = sum_x32(ssq);
;     const float nshift = -sqrtf(ssq) * kmax;
; #pragma unroll
;     for (int d0 = 0; d0 < DV / 32; ++d0)
; #pragma unroll
;         for (int r = 0; r < 16; ++r) o[d0][r] = 0.f;
;     float lsum = 0.f;
;     const int krow = tid >> 3, kch = tid & 7;
;     u32x4 kreg, vreg[NV];
;     auto tile_row = [&](int kt) -> size_t { return kt < 4 ? (size_t)(NLAT + 256 * b + 64 * kt) : (size_t)(SEQ * b + 64 * (kt - 4)); };
;     auto gload = [&](int kt) {
;         const size_t rb = tile_row(kt);
;         kreg = *(const u32x4*)(Kb + (rb + krow) * kpitch + 8 * kch);
; #pragma unroll
;         for (int i = 0; i < NV; ++i) { const int item = tid + 512 * i; const int vr = (DV == 64) ? (item >> 3) : (item >> 4), vc = (DV == 64) ? (item & 7) : (item & 15);
;             vreg[i] = *(const u32x4*)(Vb + (rb + vr) * vpitch + 8 * vc); }
;     };
;     auto lwrite = [&](int buf) {
;         unsigned char* Ks = smem + buf * BUF; unsigned char* Vs = Ks + KBYTES;
;         *(u32x4*)(Ks + krow * KP + 16 * kch) = kreg;
; #pragma unroll
;         for (int i = 0; i < NV; ++i) { const int item = tid + 512 * i; const int vr = (DV == 64) ? (item >> 3) : (item >> 4), vc = (DV == 64) ? (item & 7) : (item & 15);
;             *(u32x4*)(Vs + vr * VP + 16 * vc) = vreg[i]; }
;     };
;     gload(0); lwrite(0); __syncthreads();
;     const int nhalf = (lane >> 4) & 1, q4 = (lane & 15) >> 2, p4 = lane & 3;
	v_lshlrev_b32_e32 v0, 16, v108
	v_fmac_f32_e32 v2, v0, v0
	v_and_b32_e32 v0, 0xffff0000, v108
	v_fmac_f32_e32 v2, v0, v0
	v_lshlrev_b32_e32 v0, 16, v109
	v_fmac_f32_e32 v2, v0, v0
	v_and_b32_e32 v0, 0xffff0000, v109
	v_fmac_f32_e32 v2, v0, v0
	v_and_b32_e32 v1, 0xffff0000, v110
	v_lshlrev_b32_e32 v0, 16, v110
	v_pk_mul_f32 v[0:1], v[0:1], v[0:1]
	s_nop 0
	v_add_f32_e32 v0, v0, v2
	v_add_f32_e32 v2, v1, v0
	v_and_b32_e32 v1, 0xffff0000, v111
	v_lshlrev_b32_e32 v0, 16, v111
	v_pk_mul_f32 v[0:1], v[0:1], v[0:1]
	s_nop 0
	v_add_f32_e32 v0, v0, v2
	v_add_f32_e32 v0, v1, v0
	v_mov_b32_e32 v1, v0
	s_nop 1
	v_permlane32_swap_b32_e32 v0, v1
	v_add_f32_e32 v0, v0, v1
	v_cmp_gt_f32_e32 vcc, s0, v0
	v_mul_f32_e32 v1, 0x4f800000, v0
	s_nop 0
	v_cndmask_b32_e32 v0, v0, v1, vcc
	v_sqrt_f32_e32 v1, v0
	s_nop 0
	v_add_u32_e32 v2, -1, v1
	v_fma_f32 v3, -v2, v1, v0
	v_cmp_ge_f32_e64 s[0:1], 0, v3
	v_add_u32_e32 v3, 1, v1
	s_nop 0
	v_cndmask_b32_e64 v2, v1, v2, s[0:1]
	v_fma_f32 v1, -v3, v1, v0
	v_cmp_lt_f32_e64 s[0:1], 0, v1
	s_nop 1
	v_cndmask_b32_e64 v1, v2, v3, s[0:1]
	v_mul_f32_e32 v2, 0x37800000, v1
	v_cndmask_b32_e32 v1, v1, v2, vcc
	v_cmp_class_f32_e32 vcc, v0, v227
	s_nop 1
	v_cndmask_b32_e32 v0, v1, v0, vcc
	v_mul_f32_e64 v32, v214, -v0
	v_mov_b32_e32 v33, v32
	v_mov_b32_e32 v34, v32
	v_mov_b32_e32 v35, v32
	v_mov_b32_e32 v36, v32
	v_mov_b32_e32 v37, v32
	v_mov_b32_e32 v38, v32
	v_mov_b32_e32 v39, v32
	v_mov_b32_e32 v40, v32
	v_mov_b32_e32 v41, v32
	v_mov_b32_e32 v42, v32
	v_mov_b32_e32 v43, v32
	v_mov_b32_e32 v44, v32
	v_mov_b32_e32 v45, v32
	v_mov_b32_e32 v46, v32
	v_mov_b32_e32 v47, v32
	v_mov_b32_e32 v0, 0
	v_mov_b32_e32 v1, 0
	v_mov_b32_e32 v2, 0
	v_mov_b32_e32 v3, 0
	v_mov_b32_e32 v4, 0
	v_mov_b32_e32 v5, 0
	v_mov_b32_e32 v6, 0
	v_mov_b32_e32 v7, 0
	v_mov_b32_e32 v8, 0
	v_mov_b32_e32 v9, 0
	v_mov_b32_e32 v10, 0
	v_mov_b32_e32 v11, 0
	v_mov_b32_e32 v12, 0
	v_mov_b32_e32 v13, 0
	v_mov_b32_e32 v14, 0
	v_mov_b32_e32 v15, 0
	v_mov_b32_e32 v16, 0
	v_mov_b32_e32 v17, 0
	v_mov_b32_e32 v18, 0
	v_mov_b32_e32 v19, 0
	v_mov_b32_e32 v20, 0
	v_mov_b32_e32 v21, 0
	v_mov_b32_e32 v22, 0
	v_mov_b32_e32 v23, 0
	v_mov_b32_e32 v24, 0
	v_mov_b32_e32 v25, 0
	v_mov_b32_e32 v26, 0
	v_mov_b32_e32 v27, 0
	v_mov_b32_e32 v28, 0
	v_mov_b32_e32 v29, 0
	v_mov_b32_e32 v30, 0
	v_mov_b32_e32 v31, 0
	v_mov_b32_e32 v48, 0
	v_mov_b32_e32 v49, 0
	v_mov_b32_e32 v50, 0
	v_mov_b32_e32 v51, 0
	v_mov_b32_e32 v52, 0
	v_mov_b32_e32 v53, 0
	v_mov_b32_e32 v54, 0
	v_mov_b32_e32 v55, 0
	v_mov_b32_e32 v56, 0
	v_mov_b32_e32 v57, 0
	v_mov_b32_e32 v58, 0
	v_mov_b32_e32 v59, 0
	v_mov_b32_e32 v60, 0
	v_mov_b32_e32 v61, 0
	v_mov_b32_e32 v62, 0
	v_mov_b32_e32 v63, 0
	v_mov_b32_e32 v64, 0
	v_mov_b32_e32 v65, 0
	v_mov_b32_e32 v66, 0
	v_mov_b32_e32 v67, 0
	v_mov_b32_e32 v68, 0
	v_mov_b32_e32 v69, 0
	v_mov_b32_e32 v70, 0
	v_mov_b32_e32 v71, 0
	v_mov_b32_e32 v72, 0
	v_mov_b32_e32 v73, 0
	v_mov_b32_e32 v74, 0
	v_mov_b32_e32 v75, 0
	v_mov_b32_e32 v76, 0
	v_mov_b32_e32 v77, 0
	v_mov_b32_e32 v78, 0
	v_mov_b32_e32 v79, 0
	v_mov_b32_e32 v169, 0
	v_bfe_u32 v234, v218, 1, 3
	v_lshrrev_b32_e32 v235, 4, v138
	v_xor_b32_e32 v234, v234, v235
	v_xor_b32_e32 v235, 0, v234
	v_lshlrev_b32_e32 v235, 4, v235
	v_lshl_or_b32 v174, v218, 7, v235
	v_add_u32_e32 v128, 0xc000, v174
	v_xor_b32_e32 v235, 2, v234
	v_lshlrev_b32_e32 v235, 4, v235
	v_lshl_or_b32 v175, v218, 7, v235
	v_add_u32_e32 v129, 0xc000, v175
	v_xor_b32_e32 v235, 4, v234
	v_lshlrev_b32_e32 v235, 4, v235
	v_lshl_or_b32 v210, v218, 7, v235
	v_add_u32_e32 v130, 0xc000, v210
	v_xor_b32_e32 v235, 6, v234
	v_lshlrev_b32_e32 v235, 4, v235
	v_lshl_or_b32 v211, v218, 7, v235
	v_add_u32_e32 v131, 0xc000, v211
	v_and_b32_e32 v236, 3, v215
	v_xor_b32_e32 v237, 0, v236
	v_lshl_add_u32 v237, v237, 6, v221
	v_lshl_add_u32 v142, v215, 8, v237
	v_add_u32_e32 v170, 0xc000, v142
	v_xor_b32_e32 v237, 1, v236
	v_lshl_add_u32 v237, v237, 6, v221
	v_lshl_add_u32 v143, v215, 8, v237
	v_add_u32_e32 v171, 0xc000, v143
	v_xor_b32_e32 v237, 2, v236
	v_lshl_add_u32 v237, v237, 6, v221
	v_lshl_add_u32 v146, v215, 8, v237
	v_add_u32_e32 v172, 0xc000, v146
	v_xor_b32_e32 v237, 3, v236
	v_lshl_add_u32 v237, v237, 6, v221
	v_lshl_add_u32 v147, v215, 8, v237
	v_add_u32_e32 v173, 0xc000, v147
	s_mov_b32 s59, 0
	s_waitcnt vmcnt(3)
	s_barrier
; template <int DV>
; __device__ __forceinline__ void attn_pass(const int tid, unsigned char* smem, const bf16_t* Q0, int qpitch, const bf16_t* Kb, int kpitch, const bf16_t* Vb, int vpitch,
;                                           int b, int ntiles, float kmax, f32x16 (&o)[DV / 32], float& linv) {
;     ...
;     for (int kt = 0; kt < ntiles; ++kt) {
;         if (kt + 1 < ntiles) gload(kt + 1);
;         const unsigned char* Ks = smem + (kt & 1) * BUF; const unsigned char* Vs = Ks + KBYTES;
;         const unsigned char* kp = Ks + r32 * KP + hi * 16;
;         bf16x8 pf[2][2];
; #pragma unroll
;         for (int kb = 0; kb < 2; ++kb) {
;             f32x16 s;
; #pragma unroll
;             for (int r = 0; r < 16; ++r) s[r] = nshift;
; #pragma unroll
;             for (int ds = 0; ds < 4; ++ds) {
;                 const bf16x8 kf = *(const bf16x8*)(kp + kb * 32 * KP + ds * 32);
;                 s = __builtin_amdgcn_mfma_f32_32x32x16_bf16(kf, qf[ds], s, 0, 0, 0);
;             }
;             float ls = 0.f;
; #pragma unroll
;             for (int r = 0; r < 16; ++r) { s[r] = __builtin_amdgcn_exp2f(s[r]); ls += s[r]; }
;             lsum += ls;
; #pragma unroll
;             for (int j = 0; j < 2; ++j) {
;                 u32x4 w0;
;                 w0.x = cvt_pk_bf16(s[8 * j + 0], s[8 * j + 1]); w0.y = cvt_pk_bf16(s[8 * j + 2], s[8 * j + 3]); w0.z = cvt_pk_bf16(s[8 * j + 4], s[8 * j + 5]); w0.w = cvt_pk_bf16(s[8 * j + 6], s[8 * j + 7]);
;                 pf[kb][j] = __builtin_bit_cast(bf16x8, w0);
;             }
;         }
;         const unsigned char* vp = Vs + (4 * hi + q4) * VP + (16 * nhalf + 4 * p4) * 2;
; #pragma unroll
;         for (int d0 = 0; d0 < DV / 32; ++d0) {
; #pragma unroll
;             for (int kb = 0; kb < 2; ++kb)
; #pragma unroll
;                 for (int j = 0; j < 2; ++j) {
;                     const unsigned char* a = vp + (32 * kb + 16 * j) * VP + d0 * 64;
;                     const s16x4 lo = ld_tr(a), h4 = ld_tr(a + 8 * VP);
;                     const bf16x8 vf = (bf16x8){lo[0], lo[1], lo[2], lo[3], h4[0], h4[1], h4[2], h4[3]};
;                     o[d0] = __builtin_amdgcn_mfma_f32_32x32x16_bf16(vf, pf[kb][j], o[d0], 0, 0, 0);
;                 }
;             if (d0 & 1) __builtin_amdgcn_sched_barrier(0);
;         }
;         if (kt + 1 < ntiles) lwrite((kt + 1) & 1);
;         __syncthreads();
;     }
	ds_read_b128 v[198:201], v174
	ds_read_b128 v[202:205], v175
	ds_read_b128 v[206:209], v210
	ds_read_b128 v[150:153], v211
	s_waitcnt lgkmcnt(3)
	v_mfma_f32_32x32x16_bf16 v[80:95], v[198:201], v[96:99], v[32:47]
	ds_read_b128 v[198:201], v174 offset:4096
	s_add_i32 s71, s25, -1
	s_add_i32 s70, s59, 3
	s_min_u32 s70, s70, s71
	s_cmp_lt_u32 s70, 4
	s_cselect_b32 s2, s65, s32
	s_lshl_b32 s3, s70, 6
	s_add_i32 s2, s2, s3
	s_lshl_b32 s2, s2, 10
	s_add_u32 s60, s66, s2
	s_addc_u32 s61, s67, 0
	s_add_i32 s70, s59, 2
	s_min_u32 s70, s70, s71
	s_cmp_lt_u32 s70, 4
	s_cselect_b32 s2, s65, s32
	s_lshl_b32 s3, s70, 6
	s_add_i32 s2, s2, s3
	s_lshl_b32 s2, s2, 10
	s_add_u32 s62, s68, s2
	s_addc_u32 s63, s69, 0
	s_waitcnt lgkmcnt(3)
	v_mfma_f32_32x32x16_bf16 v[80:95], v[202:205], v[100:103], v[80:95]
	ds_read_b128 v[202:205], v175 offset:4096
	s_add_i32 m0, s56, 0x12000
	s_nop 0
	global_load_lds_dwordx4 v166, s[60:61]
	s_waitcnt lgkmcnt(3)
	v_mfma_f32_32x32x16_bf16 v[80:95], v[206:209], v[104:107], v[80:95]
	ds_read_b128 v[206:209], v210 offset:4096
	s_add_i32 m0, s56, 0x14000
	s_nop 0
	global_load_lds_dwordx4 v167, s[62:63]
	s_add_i32 m0, s56, 0x16000
	s_nop 0
	global_load_lds_dwordx4 v132, s[62:63]
	s_waitcnt lgkmcnt(3)
	v_mfma_f32_32x32x16_bf16 v[80:95], v[150:153], v[108:111], v[80:95]
	ds_read_b128 v[150:153], v211 offset:4096
	s_nop 7
	s_waitcnt lgkmcnt(3)
	v_mfma_f32_32x32x16_bf16 v[112:127], v[198:201], v[96:99], v[32:47]
	ds_read_b128 v[198:201], v174 offset:24576
	ds_read_b64_tr_b16 v[154:155], v142 offset:32768
	ds_read_b64_tr_b16 v[156:157], v142 offset:34816
	v_exp_f32_e32 v80, v80
	v_exp_f32_e32 v81, v81
	v_exp_f32_e32 v82, v82
	v_add_f32_e32 v169, v169, v80
	v_exp_f32_e32 v83, v83
	v_add_f32_e32 v169, v169, v81
	v_cvt_pk_bf16_f32 v176, v80, v81
	v_exp_f32_e32 v84, v84
	v_add_f32_e32 v169, v169, v82
	v_exp_f32_e32 v85, v85
	v_add_f32_e32 v169, v169, v83
	v_cvt_pk_bf16_f32 v177, v82, v83
	v_exp_f32_e32 v86, v86
	s_waitcnt lgkmcnt(5)
	v_mfma_f32_32x32x16_bf16 v[112:127], v[202:205], v[100:103], v[112:127]
	ds_read_b128 v[202:205], v175 offset:24576
	ds_read_b64_tr_b16 v[158:159], v143 offset:32768
	ds_read_b64_tr_b16 v[160:161], v143 offset:34816
	v_add_f32_e32 v169, v169, v84
	v_exp_f32_e32 v87, v87
	v_add_f32_e32 v169, v169, v85
	v_cvt_pk_bf16_f32 v178, v84, v85
	v_exp_f32_e32 v88, v88
	v_add_f32_e32 v169, v169, v86
	v_exp_f32_e32 v89, v89
	v_add_f32_e32 v169, v169, v87
	v_cvt_pk_bf16_f32 v179, v86, v87
	v_exp_f32_e32 v90, v90
	v_add_f32_e32 v169, v169, v88
	v_exp_f32_e32 v91, v91
	v_add_f32_e32 v169, v169, v89
	s_waitcnt lgkmcnt(7)
	v_mfma_f32_32x32x16_bf16 v[112:127], v[206:209], v[104:107], v[112:127]
	ds_read_b128 v[206:209], v210 offset:24576
	ds_read_b64_tr_b16 v[162:163], v146 offset:32768
	ds_read_b64_tr_b16 v[164:165], v146 offset:34816
	v_cvt_pk_bf16_f32 v180, v88, v89
	v_exp_f32_e32 v92, v92
	v_add_f32_e32 v169, v169, v90
	v_exp_f32_e32 v93, v93
	v_add_f32_e32 v169, v169, v91
	v_cvt_pk_bf16_f32 v181, v90, v91
	v_exp_f32_e32 v94, v94
	v_add_f32_e32 v169, v169, v92
	v_exp_f32_e32 v95, v95
	v_add_f32_e32 v169, v169, v93
	v_cvt_pk_bf16_f32 v182, v92, v93
	v_add_f32_e32 v169, v169, v94
	v_add_f32_e32 v169, v169, v95
	v_cvt_pk_bf16_f32 v183, v94, v95
	s_waitcnt lgkmcnt(9)
	v_mfma_f32_32x32x16_bf16 v[112:127], v[150:153], v[108:111], v[112:127]
	ds_read_b128 v[150:153], v211 offset:24576
	ds_read_b64_tr_b16 v[230:231], v147 offset:32768
	ds_read_b64_tr_b16 v[232:233], v147 offset:34816
	s_add_i32 s59, s59, 1
	s_nop 3
	s_waitcnt vmcnt(3) lgkmcnt(0)
	s_barrier
	s_add_i32 s71, s25, -6
	s_cmp_lt_i32 s59, s71
	s_cbranch_scc0 .Lcattn_tail
.Lcattn_loop:
	v_mfma_f32_32x32x16_bf16 v[80:95], v[198:201], v[96:99], v[32:47]
	ds_read_b128 v[198:201], v174 offset:28672
	v_exp_f32_e32 v112, v112
	v_exp_f32_e32 v113, v113
	v_exp_f32_e32 v114, v114
	v_mfma_f32_32x32x16_bf16 v[80:95], v[202:205], v[100:103], v[80:95]
	ds_read_b128 v[202:205], v175 offset:28672
	v_add_f32_e32 v169, v169, v112
	v_exp_f32_e32 v115, v115
	v_add_f32_e32 v169, v169, v113
	v_cvt_pk_bf16_f32 v184, v112, v113
	v_mfma_f32_32x32x16_bf16 v[80:95], v[206:209], v[104:107], v[80:95]
	ds_read_b128 v[206:209], v210 offset:28672
	v_exp_f32_e32 v116, v116
	v_add_f32_e32 v169, v169, v114
	v_exp_f32_e32 v117, v117
	v_mfma_f32_32x32x16_bf16 v[80:95], v[150:153], v[108:111], v[80:95]
	ds_read_b128 v[150:153], v211 offset:28672
	v_add_f32_e32 v169, v169, v115
	v_cvt_pk_bf16_f32 v185, v114, v115
	v_exp_f32_e32 v118, v118
	v_add_f32_e32 v169, v169, v116
	s_waitcnt lgkmcnt(10)
	v_mfma_f32_32x32x16_bf16 v[0:15], v[154:157], v[176:179], v[0:15]
	ds_read_b64_tr_b16 v[154:155], v142 offset:36864
	ds_read_b64_tr_b16 v[156:157], v142 offset:38912
	s_add_i32 s71, s25, -1
	s_add_i32 s70, s59, 3
	s_min_u32 s70, s70, s71
	s_cmp_lt_u32 s70, 4
	s_cselect_b32 s2, s65, s32
	s_lshl_b32 s3, s70, 6
	s_add_i32 s2, s2, s3
	s_lshl_b32 s2, s2, 10
	s_add_u32 s60, s66, s2
	s_addc_u32 s61, s67, 0
	s_add_i32 s70, s59, 2
	s_min_u32 s70, s70, s71
	s_cmp_lt_u32 s70, 4
	s_cselect_b32 s2, s65, s32
	s_lshl_b32 s3, s70, 6
	s_add_i32 s2, s2, s3
	s_lshl_b32 s2, s2, 10
	s_add_u32 s62, s68, s2
	s_addc_u32 s63, s69, 0
	v_exp_f32_e32 v119, v119
	v_add_f32_e32 v169, v169, v117
	v_cvt_pk_bf16_f32 v186, v116, v117
	v_exp_f32_e32 v120, v120
	s_waitcnt lgkmcnt(10)
	v_mfma_f32_32x32x16_bf16 v[16:31], v[158:161], v[176:179], v[16:31]
	ds_read_b64_tr_b16 v[158:159], v143 offset:36864
	ds_read_b64_tr_b16 v[160:161], v143 offset:38912
	s_mov_b32 m0, s56
	s_nop 0
	global_load_lds_dwordx4 v166, s[60:61]
	v_add_f32_e32 v169, v169, v118
	v_exp_f32_e32 v121, v121
	v_add_f32_e32 v169, v169, v119
	s_waitcnt lgkmcnt(10)
; template <int DV>
; __device__ __forceinline__ void attn_pass(const int tid, unsigned char* smem, const bf16_t* Q0, int qpitch, const bf16_t* Kb, int kpitch, const bf16_t* Vb, int vpitch,
;                                           int b, int ntiles, float kmax, f32x16 (&o)[DV / 32], float& linv) {
;     ...
;     for (int kt = 0; kt < ntiles; ++kt) {
;         if (kt + 1 < ntiles) gload(kt + 1);
;         const unsigned char* Ks = smem + (kt & 1) * BUF; const unsigned char* Vs = Ks + KBYTES;
;         const unsigned char* kp = Ks + r32 * KP + hi * 16;
;         bf16x8 pf[2][2];
; #pragma unroll
;         for (int kb = 0; kb < 2; ++kb) {
;             f32x16 s;
; #pragma unroll
;             for (int r = 0; r < 16; ++r) s[r] = nshift;
; #pragma unroll
;             for (int ds = 0; ds < 4; ++ds) {
;                 const bf16x8 kf = *(const bf16x8*)(kp + kb * 32 * KP + ds * 32);
;                 s = __builtin_amdgcn_mfma_f32_32x32x16_bf16(kf, qf[ds], s, 0, 0, 0);
;             }
;             float ls = 0.f;
; #pragma unroll
;             for (int r = 0; r < 16; ++r) { s[r] = __builtin_amdgcn_exp2f(s[r]); ls += s[r]; }
;             lsum += ls;
; #pragma unroll
;             for (int j = 0; j < 2; ++j) {
;                 u32x4 w0;
;                 w0.x = cvt_pk_bf16(s[8 * j + 0], s[8 * j + 1]); w0.y = cvt_pk_bf16(s[8 * j + 2], s[8 * j + 3]); w0.z = cvt_pk_bf16(s[8 * j + 4], s[8 * j + 5]); w0.w = cvt_pk_bf16(s[8 * j + 6], s[8 * j + 7]);
;                 pf[kb][j] = __builtin_bit_cast(bf16x8, w0);
;             }
;         }
;         const unsigned char* vp = Vs + (4 * hi + q4) * VP + (16 * nhalf + 4 * p4) * 2;
; #pragma unroll
;         for (int d0 = 0; d0 < DV / 32; ++d0) {
; #pragma unroll
;             for (int kb = 0; kb < 2; ++kb)
; #pragma unroll
;                 for (int j = 0; j < 2; ++j) {
;                     const unsigned char* a = vp + (32 * kb + 16 * j) * VP + d0 * 64;
;                     const s16x4 lo = ld_tr(a), h4 = ld_tr(a + 8 * VP);
;                     const bf16x8 vf = (bf16x8){lo[0], lo[1], lo[2], lo[3], h4[0], h4[1], h4[2], h4[3]};
;                     o[d0] = __builtin_amdgcn_mfma_f32_32x32x16_bf16(vf, pf[kb][j], o[d0], 0, 0, 0);
;                 }
;             if (d0 & 1) __builtin_amdgcn_sched_barrier(0);
;         }
;         if (kt + 1 < ntiles) lwrite((kt + 1) & 1);
;         __syncthreads();
;     }
	v_mfma_f32_32x32x16_bf16 v[48:63], v[162:165], v[176:179], v[48:63]
	ds_read_b64_tr_b16 v[162:163], v146 offset:36864
	ds_read_b64_tr_b16 v[164:165], v146 offset:38912
	s_add_i32 m0, s56, 0x2000
	s_nop 0
	global_load_lds_dwordx4 v167, s[62:63]
	s_add_i32 m0, s56, 0x4000
	s_nop 0
	global_load_lds_dwordx4 v132, s[62:63]
	v_cvt_pk_bf16_f32 v187, v118, v119
	v_exp_f32_e32 v122, v122
	v_add_f32_e32 v169, v169, v120
	v_exp_f32_e32 v123, v123
	s_waitcnt lgkmcnt(10)
	v_mfma_f32_32x32x16_bf16 v[64:79], v[230:233], v[176:179], v[64:79]
	ds_read_b64_tr_b16 v[230:231], v147 offset:36864
	ds_read_b64_tr_b16 v[232:233], v147 offset:38912
	v_add_f32_e32 v169, v169, v121
	v_cvt_pk_bf16_f32 v188, v120, v121
	v_exp_f32_e32 v124, v124
	s_waitcnt lgkmcnt(6)
	v_mfma_f32_32x32x16_bf16 v[0:15], v[154:157], v[180:183], v[0:15]
	ds_read_b64_tr_b16 v[154:155], v142 offset:40960
	ds_read_b64_tr_b16 v[156:157], v142 offset:43008
	v_add_f32_e32 v169, v169, v122
	v_exp_f32_e32 v125, v125
	v_add_f32_e32 v169, v169, v123
	v_cvt_pk_bf16_f32 v189, v122, v123
	s_waitcnt lgkmcnt(6)
	v_mfma_f32_32x32x16_bf16 v[16:31], v[158:161], v[180:183], v[16:31]
	ds_read_b64_tr_b16 v[158:159], v143 offset:40960
	ds_read_b64_tr_b16 v[160:161], v143 offset:43008
	v_exp_f32_e32 v126, v126
	v_add_f32_e32 v169, v169, v124
	v_exp_f32_e32 v127, v127
	s_waitcnt lgkmcnt(6)
	v_mfma_f32_32x32x16_bf16 v[48:63], v[162:165], v[180:183], v[48:63]
	ds_read_b64_tr_b16 v[162:163], v146 offset:40960
	ds_read_b64_tr_b16 v[164:165], v146 offset:43008
	v_add_f32_e32 v169, v169, v125
	v_cvt_pk_bf16_f32 v190, v124, v125
	v_add_f32_e32 v169, v169, v126
	v_add_f32_e32 v169, v169, v127
	v_cvt_pk_bf16_f32 v191, v126, v127
	s_waitcnt lgkmcnt(6)
	v_mfma_f32_32x32x16_bf16 v[64:79], v[230:233], v[180:183], v[64:79]
	ds_read_b64_tr_b16 v[230:231], v147 offset:40960
	ds_read_b64_tr_b16 v[232:233], v147 offset:43008
	v_mfma_f32_32x32x16_bf16 v[112:127], v[198:201], v[96:99], v[32:47]
	ds_read_b128 v[198:201], v128
	v_exp_f32_e32 v80, v80
	v_exp_f32_e32 v81, v81
	v_exp_f32_e32 v82, v82
	v_mfma_f32_32x32x16_bf16 v[112:127], v[202:205], v[100:103], v[112:127]
	ds_read_b128 v[202:205], v129
	v_add_f32_e32 v169, v169, v80
	v_exp_f32_e32 v83, v83
	v_add_f32_e32 v169, v169, v81
	v_cvt_pk_bf16_f32 v176, v80, v81
	v_mfma_f32_32x32x16_bf16 v[112:127], v[206:209], v[104:107], v[112:127]
	ds_read_b128 v[206:209], v130
	v_exp_f32_e32 v84, v84
	v_add_f32_e32 v169, v169, v82
	v_exp_f32_e32 v85, v85
	v_mfma_f32_32x32x16_bf16 v[112:127], v[150:153], v[108:111], v[112:127]
	ds_read_b128 v[150:153], v131
	v_add_f32_e32 v169, v169, v83
	v_cvt_pk_bf16_f32 v177, v82, v83
	v_exp_f32_e32 v86, v86
	v_add_f32_e32 v169, v169, v84
	s_waitcnt lgkmcnt(10)
	v_mfma_f32_32x32x16_bf16 v[0:15], v[154:157], v[184:187], v[0:15]
	ds_read_b64_tr_b16 v[154:155], v142 offset:45056
	ds_read_b64_tr_b16 v[156:157], v142 offset:47104
	v_exp_f32_e32 v87, v87
	v_add_f32_e32 v169, v169, v85
	v_cvt_pk_bf16_f32 v178, v84, v85
	v_exp_f32_e32 v88, v88
	s_waitcnt lgkmcnt(10)
	v_mfma_f32_32x32x16_bf16 v[16:31], v[158:161], v[184:187], v[16:31]
	ds_read_b64_tr_b16 v[158:159], v143 offset:45056
	ds_read_b64_tr_b16 v[160:161], v143 offset:47104
	v_add_f32_e32 v169, v169, v86
	v_exp_f32_e32 v89, v89
	v_add_f32_e32 v169, v169, v87
	s_waitcnt lgkmcnt(10)
	v_mfma_f32_32x32x16_bf16 v[48:63], v[162:165], v[184:187], v[48:63]
	ds_read_b64_tr_b16 v[162:163], v146 offset:45056
	ds_read_b64_tr_b16 v[164:165], v146 offset:47104
	v_cvt_pk_bf16_f32 v179, v86, v87
	v_exp_f32_e32 v90, v90
	v_add_f32_e32 v169, v169, v88
	v_exp_f32_e32 v91, v91
	s_waitcnt lgkmcnt(10)
	v_mfma_f32_32x32x16_bf16 v[64:79], v[230:233], v[184:187], v[64:79]
	ds_read_b64_tr_b16 v[230:231], v147 offset:45056
	ds_read_b64_tr_b16 v[232:233], v147 offset:47104
	v_add_f32_e32 v169, v169, v89
	v_cvt_pk_bf16_f32 v180, v88, v89
	v_exp_f32_e32 v92, v92
	s_waitcnt lgkmcnt(6)
	v_mfma_f32_32x32x16_bf16 v[0:15], v[154:157], v[188:191], v[0:15]
	ds_read_b64_tr_b16 v[154:155], v170 offset:8192
	ds_read_b64_tr_b16 v[156:157], v170 offset:10240
	v_add_f32_e32 v169, v169, v90
	v_exp_f32_e32 v93, v93
	v_add_f32_e32 v169, v169, v91
	v_cvt_pk_bf16_f32 v181, v90, v91
	s_waitcnt lgkmcnt(6)
	v_mfma_f32_32x32x16_bf16 v[16:31], v[158:161], v[188:191], v[16:31]
	ds_read_b64_tr_b16 v[158:159], v171 offset:8192
	ds_read_b64_tr_b16 v[160:161], v171 offset:10240
	v_exp_f32_e32 v94, v94
	v_add_f32_e32 v169, v169, v92
	v_exp_f32_e32 v95, v95
	s_waitcnt lgkmcnt(6)
	v_mfma_f32_32x32x16_bf16 v[48:63], v[162:165], v[188:191], v[48:63]
	ds_read_b64_tr_b16 v[162:163], v172 offset:8192
	ds_read_b64_tr_b16 v[164:165], v172 offset:10240
	s_add_i32 s59, s59, 1
	v_add_f32_e32 v169, v169, v93
	v_cvt_pk_bf16_f32 v182, v92, v93
	v_add_f32_e32 v169, v169, v94
	v_add_f32_e32 v169, v169, v95
	v_cvt_pk_bf16_f32 v183, v94, v95
	s_waitcnt lgkmcnt(6)
	v_mfma_f32_32x32x16_bf16 v[64:79], v[230:233], v[188:191], v[64:79]
	ds_read_b64_tr_b16 v[230:231], v173 offset:8192
	ds_read_b64_tr_b16 v[232:233], v173 offset:10240
	s_waitcnt vmcnt(3) lgkmcnt(8)
	s_barrier
; template <int DV>
; __device__ __forceinline__ void attn_pass(const int tid, unsigned char* smem, const bf16_t* Q0, int qpitch, const bf16_t* Kb, int kpitch, const bf16_t* Vb, int vpitch,
;                                           int b, int ntiles, float kmax, f32x16 (&o)[DV / 32], float& linv) {
;     ...
;     for (int kt = 0; kt < ntiles; ++kt) {
;         if (kt + 1 < ntiles) gload(kt + 1);
;         const unsigned char* Ks = smem + (kt & 1) * BUF; const unsigned char* Vs = Ks + KBYTES;
;         const unsigned char* kp = Ks + r32 * KP + hi * 16;
;         bf16x8 pf[2][2];
; #pragma unroll
;         for (int kb = 0; kb < 2; ++kb) {
;             f32x16 s;
; #pragma unroll
;             for (int r = 0; r < 16; ++r) s[r] = nshift;
; #pragma unroll
;             for (int ds = 0; ds < 4; ++ds) {
;                 const bf16x8 kf = *(const bf16x8*)(kp + kb * 32 * KP + ds * 32);
;                 s = __builtin_amdgcn_mfma_f32_32x32x16_bf16(kf, qf[ds], s, 0, 0, 0);
;             }
;             float ls = 0.f;
; #pragma unroll
;             for (int r = 0; r < 16; ++r) { s[r] = __builtin_amdgcn_exp2f(s[r]); ls += s[r]; }
;             lsum += ls;
; #pragma unroll
;             for (int j = 0; j < 2; ++j) {
;                 u32x4 w0;
;                 w0.x = cvt_pk_bf16(s[8 * j + 0], s[8 * j + 1]); w0.y = cvt_pk_bf16(s[8 * j + 2], s[8 * j + 3]); w0.z = cvt_pk_bf16(s[8 * j + 4], s[8 * j + 5]); w0.w = cvt_pk_bf16(s[8 * j + 6], s[8 * j + 7]);
;                 pf[kb][j] = __builtin_bit_cast(bf16x8, w0);
;             }
;         }
;         const unsigned char* vp = Vs + (4 * hi + q4) * VP + (16 * nhalf + 4 * p4) * 2;
; #pragma unroll
;         for (int d0 = 0; d0 < DV / 32; ++d0) {
; #pragma unroll
;             for (int kb = 0; kb < 2; ++kb)
; #pragma unroll
;                 for (int j = 0; j < 2; ++j) {
;                     const unsigned char* a = vp + (32 * kb + 16 * j) * VP + d0 * 64;
;                     const s16x4 lo = ld_tr(a), h4 = ld_tr(a + 8 * VP);
;                     const bf16x8 vf = (bf16x8){lo[0], lo[1], lo[2], lo[3], h4[0], h4[1], h4[2], h4[3]};
;                     o[d0] = __builtin_amdgcn_mfma_f32_32x32x16_bf16(vf, pf[kb][j], o[d0], 0, 0, 0);
;                 }
;             if (d0 & 1) __builtin_amdgcn_sched_barrier(0);
;         }
;         if (kt + 1 < ntiles) lwrite((kt + 1) & 1);
;         __syncthreads();
;     }
	v_mfma_f32_32x32x16_bf16 v[80:95], v[198:201], v[96:99], v[32:47]
	ds_read_b128 v[198:201], v128 offset:4096
	v_exp_f32_e32 v112, v112
	v_exp_f32_e32 v113, v113
	v_exp_f32_e32 v114, v114
	v_mfma_f32_32x32x16_bf16 v[80:95], v[202:205], v[100:103], v[80:95]
	ds_read_b128 v[202:205], v129 offset:4096
	v_add_f32_e32 v169, v169, v112
	v_exp_f32_e32 v115, v115
	v_add_f32_e32 v169, v169, v113
	v_cvt_pk_bf16_f32 v184, v112, v113
	v_mfma_f32_32x32x16_bf16 v[80:95], v[206:209], v[104:107], v[80:95]
	ds_read_b128 v[206:209], v130 offset:4096
	v_exp_f32_e32 v116, v116
	v_add_f32_e32 v169, v169, v114
	v_exp_f32_e32 v117, v117
	v_mfma_f32_32x32x16_bf16 v[80:95], v[150:153], v[108:111], v[80:95]
	ds_read_b128 v[150:153], v131 offset:4096
	v_add_f32_e32 v169, v169, v115
	v_cvt_pk_bf16_f32 v185, v114, v115
	v_exp_f32_e32 v118, v118
	v_add_f32_e32 v169, v169, v116
	s_waitcnt lgkmcnt(10)
	v_mfma_f32_32x32x16_bf16 v[0:15], v[154:157], v[176:179], v[0:15]
	ds_read_b64_tr_b16 v[154:155], v170 offset:12288
	ds_read_b64_tr_b16 v[156:157], v170 offset:14336
	s_add_i32 s71, s25, -1
	s_add_i32 s70, s59, 3
	s_min_u32 s70, s70, s71
	s_cmp_lt_u32 s70, 4
	s_cselect_b32 s2, s65, s32
	s_lshl_b32 s3, s70, 6
	s_add_i32 s2, s2, s3
	s_lshl_b32 s2, s2, 10
	s_add_u32 s60, s66, s2
	s_addc_u32 s61, s67, 0
	s_add_i32 s70, s59, 2
	s_min_u32 s70, s70, s71
	s_cmp_lt_u32 s70, 4
	s_cselect_b32 s2, s65, s32
	s_lshl_b32 s3, s70, 6
	s_add_i32 s2, s2, s3
	s_lshl_b32 s2, s2, 10
	s_add_u32 s62, s68, s2
	s_addc_u32 s63, s69, 0
	v_exp_f32_e32 v119, v119
	v_add_f32_e32 v169, v169, v117
	v_cvt_pk_bf16_f32 v186, v116, v117
	v_exp_f32_e32 v120, v120
	s_waitcnt lgkmcnt(10)
	v_mfma_f32_32x32x16_bf16 v[16:31], v[158:161], v[176:179], v[16:31]
	ds_read_b64_tr_b16 v[158:159], v171 offset:12288
	ds_read_b64_tr_b16 v[160:161], v171 offset:14336
	s_add_i32 m0, s56, 0x6000
	s_nop 0
	global_load_lds_dwordx4 v166, s[60:61]
	v_add_f32_e32 v169, v169, v118
	v_exp_f32_e32 v121, v121
	v_add_f32_e32 v169, v169, v119
	s_waitcnt lgkmcnt(10)
	v_mfma_f32_32x32x16_bf16 v[48:63], v[162:165], v[176:179], v[48:63]
	ds_read_b64_tr_b16 v[162:163], v172 offset:12288
	ds_read_b64_tr_b16 v[164:165], v172 offset:14336
	s_add_i32 m0, s56, 0x8000
	s_nop 0
	global_load_lds_dwordx4 v167, s[62:63]
	s_add_i32 m0, s56, 0xa000
	s_nop 0
	global_load_lds_dwordx4 v132, s[62:63]
	v_cvt_pk_bf16_f32 v187, v118, v119
	v_exp_f32_e32 v122, v122
	v_add_f32_e32 v169, v169, v120
	v_exp_f32_e32 v123, v123
	s_waitcnt lgkmcnt(10)
	v_mfma_f32_32x32x16_bf16 v[64:79], v[230:233], v[176:179], v[64:79]
	ds_read_b64_tr_b16 v[230:231], v173 offset:12288
	ds_read_b64_tr_b16 v[232:233], v173 offset:14336
	v_add_f32_e32 v169, v169, v121
	v_cvt_pk_bf16_f32 v188, v120, v121
	v_exp_f32_e32 v124, v124
	s_waitcnt lgkmcnt(6)
	v_mfma_f32_32x32x16_bf16 v[0:15], v[154:157], v[180:183], v[0:15]
	ds_read_b64_tr_b16 v[154:155], v170 offset:16384
	ds_read_b64_tr_b16 v[156:157], v170 offset:18432
	v_add_f32_e32 v169, v169, v122
	v_exp_f32_e32 v125, v125
	v_add_f32_e32 v169, v169, v123
	v_cvt_pk_bf16_f32 v189, v122, v123
	s_waitcnt lgkmcnt(6)
	v_mfma_f32_32x32x16_bf16 v[16:31], v[158:161], v[180:183], v[16:31]
	ds_read_b64_tr_b16 v[158:159], v171 offset:16384
	ds_read_b64_tr_b16 v[160:161], v171 offset:18432
	v_exp_f32_e32 v126, v126
	v_add_f32_e32 v169, v169, v124
	v_exp_f32_e32 v127, v127
	s_waitcnt lgkmcnt(6)
	v_mfma_f32_32x32x16_bf16 v[48:63], v[162:165], v[180:183], v[48:63]
	ds_read_b64_tr_b16 v[162:163], v172 offset:16384
	ds_read_b64_tr_b16 v[164:165], v172 offset:18432
	v_add_f32_e32 v169, v169, v125
	v_cvt_pk_bf16_f32 v190, v124, v125
	v_add_f32_e32 v169, v169, v126
	v_add_f32_e32 v169, v169, v127
	v_cvt_pk_bf16_f32 v191, v126, v127
	s_waitcnt lgkmcnt(6)
	v_mfma_f32_32x32x16_bf16 v[64:79], v[230:233], v[180:183], v[64:79]
	ds_read_b64_tr_b16 v[230:231], v173 offset:16384
	ds_read_b64_tr_b16 v[232:233], v173 offset:18432
	v_mfma_f32_32x32x16_bf16 v[112:127], v[198:201], v[96:99], v[32:47]
	ds_read_b128 v[198:201], v128 offset:24576
	v_exp_f32_e32 v80, v80
	v_exp_f32_e32 v81, v81
	v_exp_f32_e32 v82, v82
	v_mfma_f32_32x32x16_bf16 v[112:127], v[202:205], v[100:103], v[112:127]
	ds_read_b128 v[202:205], v129 offset:24576
	v_add_f32_e32 v169, v169, v80
	v_exp_f32_e32 v83, v83
	v_add_f32_e32 v169, v169, v81
	v_cvt_pk_bf16_f32 v176, v80, v81
	v_mfma_f32_32x32x16_bf16 v[112:127], v[206:209], v[104:107], v[112:127]
	ds_read_b128 v[206:209], v130 offset:24576
	v_exp_f32_e32 v84, v84
	v_add_f32_e32 v169, v169, v82
	v_exp_f32_e32 v85, v85
	v_mfma_f32_32x32x16_bf16 v[112:127], v[150:153], v[108:111], v[112:127]
	ds_read_b128 v[150:153], v131 offset:24576
	v_add_f32_e32 v169, v169, v83
	v_cvt_pk_bf16_f32 v177, v82, v83
	v_exp_f32_e32 v86, v86
	v_add_f32_e32 v169, v169, v84
	s_waitcnt lgkmcnt(10)
	v_mfma_f32_32x32x16_bf16 v[0:15], v[154:157], v[184:187], v[0:15]
	ds_read_b64_tr_b16 v[154:155], v170 offset:20480
	ds_read_b64_tr_b16 v[156:157], v170 offset:22528
	v_exp_f32_e32 v87, v87
	v_add_f32_e32 v169, v169, v85
	v_cvt_pk_bf16_f32 v178, v84, v85
	v_exp_f32_e32 v88, v88
	s_waitcnt lgkmcnt(10)
	v_mfma_f32_32x32x16_bf16 v[16:31], v[158:161], v[184:187], v[16:31]
	ds_read_b64_tr_b16 v[158:159], v171 offset:20480
	ds_read_b64_tr_b16 v[160:161], v171 offset:22528
	v_add_f32_e32 v169, v169, v86
	v_exp_f32_e32 v89, v89
	v_add_f32_e32 v169, v169, v87
	s_waitcnt lgkmcnt(10)
	v_mfma_f32_32x32x16_bf16 v[48:63], v[162:165], v[184:187], v[48:63]
	ds_read_b64_tr_b16 v[162:163], v172 offset:20480
	ds_read_b64_tr_b16 v[164:165], v172 offset:22528
	v_cvt_pk_bf16_f32 v179, v86, v87
	v_exp_f32_e32 v90, v90
	v_add_f32_e32 v169, v169, v88
	v_exp_f32_e32 v91, v91
	s_waitcnt lgkmcnt(10)
; template <int DV>
; __device__ __forceinline__ void attn_pass(const int tid, unsigned char* smem, const bf16_t* Q0, int qpitch, const bf16_t* Kb, int kpitch, const bf16_t* Vb, int vpitch,
;                                           int b, int ntiles, float kmax, f32x16 (&o)[DV / 32], float& linv) {
;     ...
;     for (int kt = 0; kt < ntiles; ++kt) {
;         if (kt + 1 < ntiles) gload(kt + 1);
;         const unsigned char* Ks = smem + (kt & 1) * BUF; const unsigned char* Vs = Ks + KBYTES;
;         const unsigned char* kp = Ks + r32 * KP + hi * 16;
;         bf16x8 pf[2][2];
; #pragma unroll
;         for (int kb = 0; kb < 2; ++kb) {
;             f32x16 s;
; #pragma unroll
;             for (int r = 0; r < 16; ++r) s[r] = nshift;
; #pragma unroll
;             for (int ds = 0; ds < 4; ++ds) {
;                 const bf16x8 kf = *(const bf16x8*)(kp + kb * 32 * KP + ds * 32);
;                 s = __builtin_amdgcn_mfma_f32_32x32x16_bf16(kf, qf[ds], s, 0, 0, 0);
;             }
;             float ls = 0.f;
; #pragma unroll
;             for (int r = 0; r < 16; ++r) { s[r] = __builtin_amdgcn_exp2f(s[r]); ls += s[r]; }
;             lsum += ls;
; #pragma unroll
;             for (int j = 0; j < 2; ++j) {
;                 u32x4 w0;
;                 w0.x = cvt_pk_bf16(s[8 * j + 0], s[8 * j + 1]); w0.y = cvt_pk_bf16(s[8 * j + 2], s[8 * j + 3]); w0.z = cvt_pk_bf16(s[8 * j + 4], s[8 * j + 5]); w0.w = cvt_pk_bf16(s[8 * j + 6], s[8 * j + 7]);
;                 pf[kb][j] = __builtin_bit_cast(bf16x8, w0);
;             }
;         }
;         const unsigned char* vp = Vs + (4 * hi + q4) * VP + (16 * nhalf + 4 * p4) * 2;
; #pragma unroll
;         for (int d0 = 0; d0 < DV / 32; ++d0) {
; #pragma unroll
;             for (int kb = 0; kb < 2; ++kb)
; #pragma unroll
;                 for (int j = 0; j < 2; ++j) {
;                     const unsigned char* a = vp + (32 * kb + 16 * j) * VP + d0 * 64;
;                     const s16x4 lo = ld_tr(a), h4 = ld_tr(a + 8 * VP);
;                     const bf16x8 vf = (bf16x8){lo[0], lo[1], lo[2], lo[3], h4[0], h4[1], h4[2], h4[3]};
;                     o[d0] = __builtin_amdgcn_mfma_f32_32x32x16_bf16(vf, pf[kb][j], o[d0], 0, 0, 0);
;                 }
;             if (d0 & 1) __builtin_amdgcn_sched_barrier(0);
;         }
;         if (kt + 1 < ntiles) lwrite((kt + 1) & 1);
;         __syncthreads();
;     }
	v_mfma_f32_32x32x16_bf16 v[64:79], v[230:233], v[184:187], v[64:79]
	ds_read_b64_tr_b16 v[230:231], v173 offset:20480
	ds_read_b64_tr_b16 v[232:233], v173 offset:22528
	v_add_f32_e32 v169, v169, v89
	v_cvt_pk_bf16_f32 v180, v88, v89
	v_exp_f32_e32 v92, v92
	s_waitcnt lgkmcnt(6)
	v_mfma_f32_32x32x16_bf16 v[0:15], v[154:157], v[188:191], v[0:15]
	ds_read_b64_tr_b16 v[154:155], v170 offset:32768
	ds_read_b64_tr_b16 v[156:157], v170 offset:34816
	v_add_f32_e32 v169, v169, v90
	v_exp_f32_e32 v93, v93
	v_add_f32_e32 v169, v169, v91
	v_cvt_pk_bf16_f32 v181, v90, v91
	s_waitcnt lgkmcnt(6)
	v_mfma_f32_32x32x16_bf16 v[16:31], v[158:161], v[188:191], v[16:31]
	ds_read_b64_tr_b16 v[158:159], v171 offset:32768
	ds_read_b64_tr_b16 v[160:161], v171 offset:34816
	v_exp_f32_e32 v94, v94
	v_add_f32_e32 v169, v169, v92
	v_exp_f32_e32 v95, v95
	s_waitcnt lgkmcnt(6)
	v_mfma_f32_32x32x16_bf16 v[48:63], v[162:165], v[188:191], v[48:63]
	ds_read_b64_tr_b16 v[162:163], v172 offset:32768
	ds_read_b64_tr_b16 v[164:165], v172 offset:34816
	s_add_i32 s59, s59, 1
	v_add_f32_e32 v169, v169, v93
	v_cvt_pk_bf16_f32 v182, v92, v93
	v_add_f32_e32 v169, v169, v94
	v_add_f32_e32 v169, v169, v95
	v_cvt_pk_bf16_f32 v183, v94, v95
	s_waitcnt lgkmcnt(6)
	v_mfma_f32_32x32x16_bf16 v[64:79], v[230:233], v[188:191], v[64:79]
	ds_read_b64_tr_b16 v[230:231], v173 offset:32768
	ds_read_b64_tr_b16 v[232:233], v173 offset:34816
	s_waitcnt vmcnt(3) lgkmcnt(8)
	s_barrier
	v_mfma_f32_32x32x16_bf16 v[80:95], v[198:201], v[96:99], v[32:47]
	ds_read_b128 v[198:201], v128 offset:28672
	v_exp_f32_e32 v112, v112
	v_exp_f32_e32 v113, v113
	v_exp_f32_e32 v114, v114
	v_mfma_f32_32x32x16_bf16 v[80:95], v[202:205], v[100:103], v[80:95]
	ds_read_b128 v[202:205], v129 offset:28672
	v_add_f32_e32 v169, v169, v112
	v_exp_f32_e32 v115, v115
	v_add_f32_e32 v169, v169, v113
	v_cvt_pk_bf16_f32 v184, v112, v113
	v_mfma_f32_32x32x16_bf16 v[80:95], v[206:209], v[104:107], v[80:95]
	ds_read_b128 v[206:209], v130 offset:28672
	v_exp_f32_e32 v116, v116
	v_add_f32_e32 v169, v169, v114
	v_exp_f32_e32 v117, v117
	v_mfma_f32_32x32x16_bf16 v[80:95], v[150:153], v[108:111], v[80:95]
	ds_read_b128 v[150:153], v131 offset:28672
	v_add_f32_e32 v169, v169, v115
	v_cvt_pk_bf16_f32 v185, v114, v115
	v_exp_f32_e32 v118, v118
	v_add_f32_e32 v169, v169, v116
	s_waitcnt lgkmcnt(10)
	v_mfma_f32_32x32x16_bf16 v[0:15], v[154:157], v[176:179], v[0:15]
	ds_read_b64_tr_b16 v[154:155], v170 offset:36864
	ds_read_b64_tr_b16 v[156:157], v170 offset:38912
	s_add_i32 s71, s25, -1
	s_add_i32 s70, s59, 3
	s_min_u32 s70, s70, s71
	s_cmp_lt_u32 s70, 4
	s_cselect_b32 s2, s65, s32
	s_lshl_b32 s3, s70, 6
	s_add_i32 s2, s2, s3
	s_lshl_b32 s2, s2, 10
	s_add_u32 s60, s66, s2
	s_addc_u32 s61, s67, 0
	s_add_i32 s70, s59, 2
	s_min_u32 s70, s70, s71
	s_cmp_lt_u32 s70, 4
	s_cselect_b32 s2, s65, s32
	s_lshl_b32 s3, s70, 6
	s_add_i32 s2, s2, s3
	s_lshl_b32 s2, s2, 10
	s_add_u32 s62, s68, s2
	s_addc_u32 s63, s69, 0
	v_exp_f32_e32 v119, v119
	v_add_f32_e32 v169, v169, v117
	v_cvt_pk_bf16_f32 v186, v116, v117
	v_exp_f32_e32 v120, v120
	s_waitcnt lgkmcnt(10)
	v_mfma_f32_32x32x16_bf16 v[16:31], v[158:161], v[176:179], v[16:31]
	ds_read_b64_tr_b16 v[158:159], v171 offset:36864
	ds_read_b64_tr_b16 v[160:161], v171 offset:38912
	s_add_i32 m0, s56, 0xc000
	s_nop 0
	global_load_lds_dwordx4 v166, s[60:61]
	v_add_f32_e32 v169, v169, v118
	v_exp_f32_e32 v121, v121
	v_add_f32_e32 v169, v169, v119
	s_waitcnt lgkmcnt(10)
	v_mfma_f32_32x32x16_bf16 v[48:63], v[162:165], v[176:179], v[48:63]
	ds_read_b64_tr_b16 v[162:163], v172 offset:36864
	ds_read_b64_tr_b16 v[164:165], v172 offset:38912
	s_add_i32 m0, s56, 0xe000
	s_nop 0
	global_load_lds_dwordx4 v167, s[62:63]
	s_add_i32 m0, s56, 0x10000
	s_nop 0
	global_load_lds_dwordx4 v132, s[62:63]
	v_cvt_pk_bf16_f32 v187, v118, v119
	v_exp_f32_e32 v122, v122
	v_add_f32_e32 v169, v169, v120
	v_exp_f32_e32 v123, v123
	s_waitcnt lgkmcnt(10)
	v_mfma_f32_32x32x16_bf16 v[64:79], v[230:233], v[176:179], v[64:79]
	ds_read_b64_tr_b16 v[230:231], v173 offset:36864
	ds_read_b64_tr_b16 v[232:233], v173 offset:38912
	v_add_f32_e32 v169, v169, v121
	v_cvt_pk_bf16_f32 v188, v120, v121
	v_exp_f32_e32 v124, v124
	s_waitcnt lgkmcnt(6)
	v_mfma_f32_32x32x16_bf16 v[0:15], v[154:157], v[180:183], v[0:15]
	ds_read_b64_tr_b16 v[154:155], v170 offset:40960
	ds_read_b64_tr_b16 v[156:157], v170 offset:43008
	v_add_f32_e32 v169, v169, v122
	v_exp_f32_e32 v125, v125
	v_add_f32_e32 v169, v169, v123
	v_cvt_pk_bf16_f32 v189, v122, v123
	s_waitcnt lgkmcnt(6)
	v_mfma_f32_32x32x16_bf16 v[16:31], v[158:161], v[180:183], v[16:31]
	ds_read_b64_tr_b16 v[158:159], v171 offset:40960
	ds_read_b64_tr_b16 v[160:161], v171 offset:43008
	v_exp_f32_e32 v126, v126
	v_add_f32_e32 v169, v169, v124
	v_exp_f32_e32 v127, v127
	s_waitcnt lgkmcnt(6)
	v_mfma_f32_32x32x16_bf16 v[48:63], v[162:165], v[180:183], v[48:63]
	ds_read_b64_tr_b16 v[162:163], v172 offset:40960
	ds_read_b64_tr_b16 v[164:165], v172 offset:43008
	v_add_f32_e32 v169, v169, v125
	v_cvt_pk_bf16_f32 v190, v124, v125
	v_add_f32_e32 v169, v169, v126
	v_add_f32_e32 v169, v169, v127
	v_cvt_pk_bf16_f32 v191, v126, v127
	s_waitcnt lgkmcnt(6)
; template <int DV>
; __device__ __forceinline__ void attn_pass(const int tid, unsigned char* smem, const bf16_t* Q0, int qpitch, const bf16_t* Kb, int kpitch, const bf16_t* Vb, int vpitch,
;                                           int b, int ntiles, float kmax, f32x16 (&o)[DV / 32], float& linv) {
;     ...
;     for (int kt = 0; kt < ntiles; ++kt) {
;         if (kt + 1 < ntiles) gload(kt + 1);
;         const unsigned char* Ks = smem + (kt & 1) * BUF; const unsigned char* Vs = Ks + KBYTES;
;         const unsigned char* kp = Ks + r32 * KP + hi * 16;
;         bf16x8 pf[2][2];
; #pragma unroll
;         for (int kb = 0; kb < 2; ++kb) {
;             f32x16 s;
; #pragma unroll
;             for (int r = 0; r < 16; ++r) s[r] = nshift;
; #pragma unroll
;             for (int ds = 0; ds < 4; ++ds) {
;                 const bf16x8 kf = *(const bf16x8*)(kp + kb * 32 * KP + ds * 32);
;                 s = __builtin_amdgcn_mfma_f32_32x32x16_bf16(kf, qf[ds], s, 0, 0, 0);
;             }
;             float ls = 0.f;
; #pragma unroll
;             for (int r = 0; r < 16; ++r) { s[r] = __builtin_amdgcn_exp2f(s[r]); ls += s[r]; }
;             lsum += ls;
; #pragma unroll
;             for (int j = 0; j < 2; ++j) {
;                 u32x4 w0;
;                 w0.x = cvt_pk_bf16(s[8 * j + 0], s[8 * j + 1]); w0.y = cvt_pk_bf16(s[8 * j + 2], s[8 * j + 3]); w0.z = cvt_pk_bf16(s[8 * j + 4], s[8 * j + 5]); w0.w = cvt_pk_bf16(s[8 * j + 6], s[8 * j + 7]);
;                 pf[kb][j] = __builtin_bit_cast(bf16x8, w0);
;             }
;         }
;         const unsigned char* vp = Vs + (4 * hi + q4) * VP + (16 * nhalf + 4 * p4) * 2;
; #pragma unroll
;         for (int d0 = 0; d0 < DV / 32; ++d0) {
; #pragma unroll
;             for (int kb = 0; kb < 2; ++kb)
; #pragma unroll
;                 for (int j = 0; j < 2; ++j) {
;                     const unsigned char* a = vp + (32 * kb + 16 * j) * VP + d0 * 64;
;                     const s16x4 lo = ld_tr(a), h4 = ld_tr(a + 8 * VP);
;                     const bf16x8 vf = (bf16x8){lo[0], lo[1], lo[2], lo[3], h4[0], h4[1], h4[2], h4[3]};
;                     o[d0] = __builtin_amdgcn_mfma_f32_32x32x16_bf16(vf, pf[kb][j], o[d0], 0, 0, 0);
;                 }
;             if (d0 & 1) __builtin_amdgcn_sched_barrier(0);
;         }
;         if (kt + 1 < ntiles) lwrite((kt + 1) & 1);
;         __syncthreads();
;     }
	v_mfma_f32_32x32x16_bf16 v[64:79], v[230:233], v[180:183], v[64:79]
	ds_read_b64_tr_b16 v[230:231], v173 offset:40960
	ds_read_b64_tr_b16 v[232:233], v173 offset:43008
	v_mfma_f32_32x32x16_bf16 v[112:127], v[198:201], v[96:99], v[32:47]
	ds_read_b128 v[198:201], v174
	v_exp_f32_e32 v80, v80
	v_exp_f32_e32 v81, v81
	v_exp_f32_e32 v82, v82
	v_mfma_f32_32x32x16_bf16 v[112:127], v[202:205], v[100:103], v[112:127]
	ds_read_b128 v[202:205], v175
	v_add_f32_e32 v169, v169, v80
	v_exp_f32_e32 v83, v83
	v_add_f32_e32 v169, v169, v81
	v_cvt_pk_bf16_f32 v176, v80, v81
	v_mfma_f32_32x32x16_bf16 v[112:127], v[206:209], v[104:107], v[112:127]
	ds_read_b128 v[206:209], v210
	v_exp_f32_e32 v84, v84
	v_add_f32_e32 v169, v169, v82
	v_exp_f32_e32 v85, v85
	v_mfma_f32_32x32x16_bf16 v[112:127], v[150:153], v[108:111], v[112:127]
	ds_read_b128 v[150:153], v211
	v_add_f32_e32 v169, v169, v83
	v_cvt_pk_bf16_f32 v177, v82, v83
	v_exp_f32_e32 v86, v86
	v_add_f32_e32 v169, v169, v84
	s_waitcnt lgkmcnt(10)
	v_mfma_f32_32x32x16_bf16 v[0:15], v[154:157], v[184:187], v[0:15]
	ds_read_b64_tr_b16 v[154:155], v170 offset:45056
	ds_read_b64_tr_b16 v[156:157], v170 offset:47104
	v_exp_f32_e32 v87, v87
	v_add_f32_e32 v169, v169, v85
	v_cvt_pk_bf16_f32 v178, v84, v85
	v_exp_f32_e32 v88, v88
	s_waitcnt lgkmcnt(10)
	v_mfma_f32_32x32x16_bf16 v[16:31], v[158:161], v[184:187], v[16:31]
	ds_read_b64_tr_b16 v[158:159], v171 offset:45056
	ds_read_b64_tr_b16 v[160:161], v171 offset:47104
	v_add_f32_e32 v169, v169, v86
	v_exp_f32_e32 v89, v89
	v_add_f32_e32 v169, v169, v87
	s_waitcnt lgkmcnt(10)
	v_mfma_f32_32x32x16_bf16 v[48:63], v[162:165], v[184:187], v[48:63]
	ds_read_b64_tr_b16 v[162:163], v172 offset:45056
	ds_read_b64_tr_b16 v[164:165], v172 offset:47104
	v_cvt_pk_bf16_f32 v179, v86, v87
	v_exp_f32_e32 v90, v90
	v_add_f32_e32 v169, v169, v88
	v_exp_f32_e32 v91, v91
	s_waitcnt lgkmcnt(10)
	v_mfma_f32_32x32x16_bf16 v[64:79], v[230:233], v[184:187], v[64:79]
	ds_read_b64_tr_b16 v[230:231], v173 offset:45056
	ds_read_b64_tr_b16 v[232:233], v173 offset:47104
	v_add_f32_e32 v169, v169, v89
	v_cvt_pk_bf16_f32 v180, v88, v89
	v_exp_f32_e32 v92, v92
	s_waitcnt lgkmcnt(6)
	v_mfma_f32_32x32x16_bf16 v[0:15], v[154:157], v[188:191], v[0:15]
	ds_read_b64_tr_b16 v[154:155], v142 offset:8192
	ds_read_b64_tr_b16 v[156:157], v142 offset:10240
	v_add_f32_e32 v169, v169, v90
	v_exp_f32_e32 v93, v93
	v_add_f32_e32 v169, v169, v91
	v_cvt_pk_bf16_f32 v181, v90, v91
	s_waitcnt lgkmcnt(6)
	v_mfma_f32_32x32x16_bf16 v[16:31], v[158:161], v[188:191], v[16:31]
	ds_read_b64_tr_b16 v[158:159], v143 offset:8192
	ds_read_b64_tr_b16 v[160:161], v143 offset:10240
	v_exp_f32_e32 v94, v94
	v_add_f32_e32 v169, v169, v92
	v_exp_f32_e32 v95, v95
	s_waitcnt lgkmcnt(6)
	v_mfma_f32_32x32x16_bf16 v[48:63], v[162:165], v[188:191], v[48:63]
	ds_read_b64_tr_b16 v[162:163], v146 offset:8192
	ds_read_b64_tr_b16 v[164:165], v146 offset:10240
	s_add_i32 s59, s59, 1
	v_add_f32_e32 v169, v169, v93
	v_cvt_pk_bf16_f32 v182, v92, v93
	v_add_f32_e32 v169, v169, v94
	v_add_f32_e32 v169, v169, v95
	v_cvt_pk_bf16_f32 v183, v94, v95
	s_waitcnt lgkmcnt(6)
	v_mfma_f32_32x32x16_bf16 v[64:79], v[230:233], v[188:191], v[64:79]
	ds_read_b64_tr_b16 v[230:231], v147 offset:8192
	ds_read_b64_tr_b16 v[232:233], v147 offset:10240
	s_waitcnt vmcnt(3) lgkmcnt(8)
	s_barrier
	v_mfma_f32_32x32x16_bf16 v[80:95], v[198:201], v[96:99], v[32:47]
	ds_read_b128 v[198:201], v174 offset:4096
	v_exp_f32_e32 v112, v112
	v_exp_f32_e32 v113, v113
	v_exp_f32_e32 v114, v114
	v_mfma_f32_32x32x16_bf16 v[80:95], v[202:205], v[100:103], v[80:95]
	ds_read_b128 v[202:205], v175 offset:4096
	v_add_f32_e32 v169, v169, v112
	v_exp_f32_e32 v115, v115
	v_add_f32_e32 v169, v169, v113
	v_cvt_pk_bf16_f32 v184, v112, v113
	v_mfma_f32_32x32x16_bf16 v[80:95], v[206:209], v[104:107], v[80:95]
	ds_read_b128 v[206:209], v210 offset:4096
	v_exp_f32_e32 v116, v116
	v_add_f32_e32 v169, v169, v114
	v_exp_f32_e32 v117, v117
	v_mfma_f32_32x32x16_bf16 v[80:95], v[150:153], v[108:111], v[80:95]
	ds_read_b128 v[150:153], v211 offset:4096
	v_add_f32_e32 v169, v169, v115
	v_cvt_pk_bf16_f32 v185, v114, v115
	v_exp_f32_e32 v118, v118
	v_add_f32_e32 v169, v169, v116
	s_waitcnt lgkmcnt(10)
	v_mfma_f32_32x32x16_bf16 v[0:15], v[154:157], v[176:179], v[0:15]
	ds_read_b64_tr_b16 v[154:155], v142 offset:12288
	ds_read_b64_tr_b16 v[156:157], v142 offset:14336
	s_add_i32 s71, s25, -1
	s_add_i32 s70, s59, 3
	s_min_u32 s70, s70, s71
	s_cmp_lt_u32 s70, 4
	s_cselect_b32 s2, s65, s32
	s_lshl_b32 s3, s70, 6
	s_add_i32 s2, s2, s3
	s_lshl_b32 s2, s2, 10
	s_add_u32 s60, s66, s2
	s_addc_u32 s61, s67, 0
	s_add_i32 s70, s59, 2
	s_min_u32 s70, s70, s71
	s_cmp_lt_u32 s70, 4
	s_cselect_b32 s2, s65, s32
	s_lshl_b32 s3, s70, 6
	s_add_i32 s2, s2, s3
	s_lshl_b32 s2, s2, 10
	s_add_u32 s62, s68, s2
	s_addc_u32 s63, s69, 0
	v_exp_f32_e32 v119, v119
	v_add_f32_e32 v169, v169, v117
	v_cvt_pk_bf16_f32 v186, v116, v117
	v_exp_f32_e32 v120, v120
	s_waitcnt lgkmcnt(10)
	v_mfma_f32_32x32x16_bf16 v[16:31], v[158:161], v[176:179], v[16:31]
	ds_read_b64_tr_b16 v[158:159], v143 offset:12288
	ds_read_b64_tr_b16 v[160:161], v143 offset:14336
	s_add_i32 m0, s56, 0x12000
	s_nop 0
	global_load_lds_dwordx4 v166, s[60:61]
	v_add_f32_e32 v169, v169, v118
	v_exp_f32_e32 v121, v121
	v_add_f32_e32 v169, v169, v119
	s_waitcnt lgkmcnt(10)
	v_mfma_f32_32x32x16_bf16 v[48:63], v[162:165], v[176:179], v[48:63]
	ds_read_b64_tr_b16 v[162:163], v146 offset:12288
	ds_read_b64_tr_b16 v[164:165], v146 offset:14336
	s_add_i32 m0, s56, 0x14000
	s_nop 0
	global_load_lds_dwordx4 v167, s[62:63]
	s_add_i32 m0, s56, 0x16000
	s_nop 0
	global_load_lds_dwordx4 v132, s[62:63]
	v_cvt_pk_bf16_f32 v187, v118, v119
	v_exp_f32_e32 v122, v122
	v_add_f32_e32 v169, v169, v120
	v_exp_f32_e32 v123, v123
	s_waitcnt lgkmcnt(10)
; template <int DV>
; __device__ __forceinline__ void attn_pass(const int tid, unsigned char* smem, const bf16_t* Q0, int qpitch, const bf16_t* Kb, int kpitch, const bf16_t* Vb, int vpitch,
;                                           int b, int ntiles, float kmax, f32x16 (&o)[DV / 32], float& linv) {
;     ...
;     for (int kt = 0; kt < ntiles; ++kt) {
;         if (kt + 1 < ntiles) gload(kt + 1);
;         const unsigned char* Ks = smem + (kt & 1) * BUF; const unsigned char* Vs = Ks + KBYTES;
;         const unsigned char* kp = Ks + r32 * KP + hi * 16;
;         bf16x8 pf[2][2];
; #pragma unroll
;         for (int kb = 0; kb < 2; ++kb) {
;             f32x16 s;
; #pragma unroll
;             for (int r = 0; r < 16; ++r) s[r] = nshift;
; #pragma unroll
;             for (int ds = 0; ds < 4; ++ds) {
;                 const bf16x8 kf = *(const bf16x8*)(kp + kb * 32 * KP + ds * 32);
;                 s = __builtin_amdgcn_mfma_f32_32x32x16_bf16(kf, qf[ds], s, 0, 0, 0);
;             }
;             float ls = 0.f;
; #pragma unroll
;             for (int r = 0; r < 16; ++r) { s[r] = __builtin_amdgcn_exp2f(s[r]); ls += s[r]; }
;             lsum += ls;
; #pragma unroll
;             for (int j = 0; j < 2; ++j) {
;                 u32x4 w0;
;                 w0.x = cvt_pk_bf16(s[8 * j + 0], s[8 * j + 1]); w0.y = cvt_pk_bf16(s[8 * j + 2], s[8 * j + 3]); w0.z = cvt_pk_bf16(s[8 * j + 4], s[8 * j + 5]); w0.w = cvt_pk_bf16(s[8 * j + 6], s[8 * j + 7]);
;                 pf[kb][j] = __builtin_bit_cast(bf16x8, w0);
;             }
;         }
;         const unsigned char* vp = Vs + (4 * hi + q4) * VP + (16 * nhalf + 4 * p4) * 2;
; #pragma unroll
;         for (int d0 = 0; d0 < DV / 32; ++d0) {
; #pragma unroll
;             for (int kb = 0; kb < 2; ++kb)
; #pragma unroll
;                 for (int j = 0; j < 2; ++j) {
;                     const unsigned char* a = vp + (32 * kb + 16 * j) * VP + d0 * 64;
;                     const s16x4 lo = ld_tr(a), h4 = ld_tr(a + 8 * VP);
;                     const bf16x8 vf = (bf16x8){lo[0], lo[1], lo[2], lo[3], h4[0], h4[1], h4[2], h4[3]};
;                     o[d0] = __builtin_amdgcn_mfma_f32_32x32x16_bf16(vf, pf[kb][j], o[d0], 0, 0, 0);
;                 }
;             if (d0 & 1) __builtin_amdgcn_sched_barrier(0);
;         }
;         if (kt + 1 < ntiles) lwrite((kt + 1) & 1);
;         __syncthreads();
;     }
	v_mfma_f32_32x32x16_bf16 v[64:79], v[230:233], v[176:179], v[64:79]
	ds_read_b64_tr_b16 v[230:231], v147 offset:12288
	ds_read_b64_tr_b16 v[232:233], v147 offset:14336
	v_add_f32_e32 v169, v169, v121
	v_cvt_pk_bf16_f32 v188, v120, v121
	v_exp_f32_e32 v124, v124
	s_waitcnt lgkmcnt(6)
	v_mfma_f32_32x32x16_bf16 v[0:15], v[154:157], v[180:183], v[0:15]
	ds_read_b64_tr_b16 v[154:155], v142 offset:16384
	ds_read_b64_tr_b16 v[156:157], v142 offset:18432
	v_add_f32_e32 v169, v169, v122
	v_exp_f32_e32 v125, v125
	v_add_f32_e32 v169, v169, v123
	v_cvt_pk_bf16_f32 v189, v122, v123
	s_waitcnt lgkmcnt(6)
	v_mfma_f32_32x32x16_bf16 v[16:31], v[158:161], v[180:183], v[16:31]
	ds_read_b64_tr_b16 v[158:159], v143 offset:16384
	ds_read_b64_tr_b16 v[160:161], v143 offset:18432
	v_exp_f32_e32 v126, v126
	v_add_f32_e32 v169, v169, v124
	v_exp_f32_e32 v127, v127
	s_waitcnt lgkmcnt(6)
	v_mfma_f32_32x32x16_bf16 v[48:63], v[162:165], v[180:183], v[48:63]
	ds_read_b64_tr_b16 v[162:163], v146 offset:16384
	ds_read_b64_tr_b16 v[164:165], v146 offset:18432
	v_add_f32_e32 v169, v169, v125
	v_cvt_pk_bf16_f32 v190, v124, v125
	v_add_f32_e32 v169, v169, v126
	v_add_f32_e32 v169, v169, v127
	v_cvt_pk_bf16_f32 v191, v126, v127
	s_waitcnt lgkmcnt(6)
	v_mfma_f32_32x32x16_bf16 v[64:79], v[230:233], v[180:183], v[64:79]
	ds_read_b64_tr_b16 v[230:231], v147 offset:16384
	ds_read_b64_tr_b16 v[232:233], v147 offset:18432
	v_mfma_f32_32x32x16_bf16 v[112:127], v[198:201], v[96:99], v[32:47]
	ds_read_b128 v[198:201], v174 offset:24576
	v_exp_f32_e32 v80, v80
	v_exp_f32_e32 v81, v81
	v_exp_f32_e32 v82, v82
	v_mfma_f32_32x32x16_bf16 v[112:127], v[202:205], v[100:103], v[112:127]
	ds_read_b128 v[202:205], v175 offset:24576
	v_add_f32_e32 v169, v169, v80
	v_exp_f32_e32 v83, v83
	v_add_f32_e32 v169, v169, v81
	v_cvt_pk_bf16_f32 v176, v80, v81
	v_mfma_f32_32x32x16_bf16 v[112:127], v[206:209], v[104:107], v[112:127]
	ds_read_b128 v[206:209], v210 offset:24576
	v_exp_f32_e32 v84, v84
	v_add_f32_e32 v169, v169, v82
	v_exp_f32_e32 v85, v85
	v_mfma_f32_32x32x16_bf16 v[112:127], v[150:153], v[108:111], v[112:127]
	ds_read_b128 v[150:153], v211 offset:24576
	v_add_f32_e32 v169, v169, v83
	v_cvt_pk_bf16_f32 v177, v82, v83
	v_exp_f32_e32 v86, v86
	v_add_f32_e32 v169, v169, v84
	s_waitcnt lgkmcnt(10)
	v_mfma_f32_32x32x16_bf16 v[0:15], v[154:157], v[184:187], v[0:15]
	ds_read_b64_tr_b16 v[154:155], v142 offset:20480
	ds_read_b64_tr_b16 v[156:157], v142 offset:22528
	v_exp_f32_e32 v87, v87
	v_add_f32_e32 v169, v169, v85
	v_cvt_pk_bf16_f32 v178, v84, v85
	v_exp_f32_e32 v88, v88
	s_waitcnt lgkmcnt(10)
	v_mfma_f32_32x32x16_bf16 v[16:31], v[158:161], v[184:187], v[16:31]
	ds_read_b64_tr_b16 v[158:159], v143 offset:20480
	ds_read_b64_tr_b16 v[160:161], v143 offset:22528
	v_add_f32_e32 v169, v169, v86
	v_exp_f32_e32 v89, v89
	v_add_f32_e32 v169, v169, v87
	s_waitcnt lgkmcnt(10)
	v_mfma_f32_32x32x16_bf16 v[48:63], v[162:165], v[184:187], v[48:63]
	ds_read_b64_tr_b16 v[162:163], v146 offset:20480
	ds_read_b64_tr_b16 v[164:165], v146 offset:22528
	v_cvt_pk_bf16_f32 v179, v86, v87
	v_exp_f32_e32 v90, v90
	v_add_f32_e32 v169, v169, v88
	v_exp_f32_e32 v91, v91
	s_waitcnt lgkmcnt(10)
	v_mfma_f32_32x32x16_bf16 v[64:79], v[230:233], v[184:187], v[64:79]
	ds_read_b64_tr_b16 v[230:231], v147 offset:20480
	ds_read_b64_tr_b16 v[232:233], v147 offset:22528
	v_add_f32_e32 v169, v169, v89
	v_cvt_pk_bf16_f32 v180, v88, v89
	v_exp_f32_e32 v92, v92
	s_waitcnt lgkmcnt(6)
	v_mfma_f32_32x32x16_bf16 v[0:15], v[154:157], v[188:191], v[0:15]
	ds_read_b64_tr_b16 v[154:155], v142 offset:32768
	ds_read_b64_tr_b16 v[156:157], v142 offset:34816
	v_add_f32_e32 v169, v169, v90
	v_exp_f32_e32 v93, v93
	v_add_f32_e32 v169, v169, v91
	v_cvt_pk_bf16_f32 v181, v90, v91
	s_waitcnt lgkmcnt(6)
	v_mfma_f32_32x32x16_bf16 v[16:31], v[158:161], v[188:191], v[16:31]
	ds_read_b64_tr_b16 v[158:159], v143 offset:32768
	ds_read_b64_tr_b16 v[160:161], v143 offset:34816
	v_exp_f32_e32 v94, v94
	v_add_f32_e32 v169, v169, v92
	v_exp_f32_e32 v95, v95
	s_waitcnt lgkmcnt(6)
	v_mfma_f32_32x32x16_bf16 v[48:63], v[162:165], v[188:191], v[48:63]
	ds_read_b64_tr_b16 v[162:163], v146 offset:32768
	ds_read_b64_tr_b16 v[164:165], v146 offset:34816
	s_add_i32 s59, s59, 1
	v_add_f32_e32 v169, v169, v93
	v_cvt_pk_bf16_f32 v182, v92, v93
	v_add_f32_e32 v169, v169, v94
	v_add_f32_e32 v169, v169, v95
	v_cvt_pk_bf16_f32 v183, v94, v95
	s_waitcnt lgkmcnt(6)
	v_mfma_f32_32x32x16_bf16 v[64:79], v[230:233], v[188:191], v[64:79]
	ds_read_b64_tr_b16 v[230:231], v147 offset:32768
	ds_read_b64_tr_b16 v[232:233], v147 offset:34816
	s_add_i32 s71, s25, -6
	s_cmp_lt_i32 s59, s71
	s_waitcnt vmcnt(3) lgkmcnt(8)
	s_barrier
	s_cbranch_scc1 .Lcattn_loop
; template <int DV>
; __device__ __forceinline__ void attn_pass(const int tid, unsigned char* smem, const bf16_t* Q0, int qpitch, const bf16_t* Kb, int kpitch, const bf16_t* Vb, int vpitch,
;                                           int b, int ntiles, float kmax, f32x16 (&o)[DV / 32], float& linv) {
;     ...
;     for (int kt = 0; kt < ntiles; ++kt) {
;         if (kt + 1 < ntiles) gload(kt + 1);
;         const unsigned char* Ks = smem + (kt & 1) * BUF; const unsigned char* Vs = Ks + KBYTES;
;         const unsigned char* kp = Ks + r32 * KP + hi * 16;
;         bf16x8 pf[2][2];
; #pragma unroll
;         for (int kb = 0; kb < 2; ++kb) {
;             f32x16 s;
; #pragma unroll
;             for (int r = 0; r < 16; ++r) s[r] = nshift;
; #pragma unroll
;             for (int ds = 0; ds < 4; ++ds) {
;                 const bf16x8 kf = *(const bf16x8*)(kp + kb * 32 * KP + ds * 32);
;                 s = __builtin_amdgcn_mfma_f32_32x32x16_bf16(kf, qf[ds], s, 0, 0, 0);
;             }
;             float ls = 0.f;
; #pragma unroll
;             for (int r = 0; r < 16; ++r) { s[r] = __builtin_amdgcn_exp2f(s[r]); ls += s[r]; }
;             lsum += ls;
; #pragma unroll
;             for (int j = 0; j < 2; ++j) {
;                 u32x4 w0;
;                 w0.x = cvt_pk_bf16(s[8 * j + 0], s[8 * j + 1]); w0.y = cvt_pk_bf16(s[8 * j + 2], s[8 * j + 3]); w0.z = cvt_pk_bf16(s[8 * j + 4], s[8 * j + 5]); w0.w = cvt_pk_bf16(s[8 * j + 6], s[8 * j + 7]);
;                 pf[kb][j] = __builtin_bit_cast(bf16x8, w0);
;             }
;         }
;         const unsigned char* vp = Vs + (4 * hi + q4) * VP + (16 * nhalf + 4 * p4) * 2;
; #pragma unroll
;         for (int d0 = 0; d0 < DV / 32; ++d0) {
; #pragma unroll
;             for (int kb = 0; kb < 2; ++kb)
; #pragma unroll
;                 for (int j = 0; j < 2; ++j) {
;                     const unsigned char* a = vp + (32 * kb + 16 * j) * VP + d0 * 64;
;                     const s16x4 lo = ld_tr(a), h4 = ld_tr(a + 8 * VP);
;                     const bf16x8 vf = (bf16x8){lo[0], lo[1], lo[2], lo[3], h4[0], h4[1], h4[2], h4[3]};
;                     o[d0] = __builtin_amdgcn_mfma_f32_32x32x16_bf16(vf, pf[kb][j], o[d0], 0, 0, 0);
;                 }
;             if (d0 & 1) __builtin_amdgcn_sched_barrier(0);
;         }
;         if (kt + 1 < ntiles) lwrite((kt + 1) & 1);
;         __syncthreads();
;     }
.Lcattn_tail:
	v_mfma_f32_32x32x16_bf16 v[80:95], v[198:201], v[96:99], v[32:47]
	ds_read_b128 v[198:201], v174 offset:28672
	v_exp_f32_e32 v112, v112
	v_exp_f32_e32 v113, v113
	v_exp_f32_e32 v114, v114
	v_mfma_f32_32x32x16_bf16 v[80:95], v[202:205], v[100:103], v[80:95]
	ds_read_b128 v[202:205], v175 offset:28672
	v_add_f32_e32 v169, v169, v112
	v_exp_f32_e32 v115, v115
	v_add_f32_e32 v169, v169, v113
	v_cvt_pk_bf16_f32 v184, v112, v113
	v_mfma_f32_32x32x16_bf16 v[80:95], v[206:209], v[104:107], v[80:95]
	ds_read_b128 v[206:209], v210 offset:28672
	v_exp_f32_e32 v116, v116
	v_add_f32_e32 v169, v169, v114
	v_exp_f32_e32 v117, v117
	v_mfma_f32_32x32x16_bf16 v[80:95], v[150:153], v[108:111], v[80:95]
	ds_read_b128 v[150:153], v211 offset:28672
	v_add_f32_e32 v169, v169, v115
	v_cvt_pk_bf16_f32 v185, v114, v115
	v_exp_f32_e32 v118, v118
	v_add_f32_e32 v169, v169, v116
	s_waitcnt lgkmcnt(10)
	v_mfma_f32_32x32x16_bf16 v[0:15], v[154:157], v[176:179], v[0:15]
	ds_read_b64_tr_b16 v[154:155], v142 offset:36864
	ds_read_b64_tr_b16 v[156:157], v142 offset:38912
	s_add_i32 s71, s25, -1
	s_add_i32 s70, s59, 3
	s_min_u32 s70, s70, s71
	s_cmp_lt_u32 s70, 4
	s_cselect_b32 s2, s65, s32
	s_lshl_b32 s3, s70, 6
	s_add_i32 s2, s2, s3
	s_lshl_b32 s2, s2, 10
	s_add_u32 s60, s66, s2
	s_addc_u32 s61, s67, 0
	s_add_i32 s70, s59, 2
	s_min_u32 s70, s70, s71
	s_cmp_lt_u32 s70, 4
	s_cselect_b32 s2, s65, s32
	s_lshl_b32 s3, s70, 6
	s_add_i32 s2, s2, s3
	s_lshl_b32 s2, s2, 10
	s_add_u32 s62, s68, s2
	s_addc_u32 s63, s69, 0
	v_exp_f32_e32 v119, v119
	v_add_f32_e32 v169, v169, v117
	v_cvt_pk_bf16_f32 v186, v116, v117
	v_exp_f32_e32 v120, v120
	s_waitcnt lgkmcnt(10)
	v_mfma_f32_32x32x16_bf16 v[16:31], v[158:161], v[176:179], v[16:31]
	ds_read_b64_tr_b16 v[158:159], v143 offset:36864
	ds_read_b64_tr_b16 v[160:161], v143 offset:38912
	s_mov_b32 m0, s56
	s_nop 0
	global_load_lds_dwordx4 v166, s[60:61]
	v_add_f32_e32 v169, v169, v118
	v_exp_f32_e32 v121, v121
	v_add_f32_e32 v169, v169, v119
	s_waitcnt lgkmcnt(10)
	v_mfma_f32_32x32x16_bf16 v[48:63], v[162:165], v[176:179], v[48:63]
	ds_read_b64_tr_b16 v[162:163], v146 offset:36864
	ds_read_b64_tr_b16 v[164:165], v146 offset:38912
	s_add_i32 m0, s56, 0x2000
	s_nop 0
	global_load_lds_dwordx4 v167, s[62:63]
	s_add_i32 m0, s56, 0x4000
	s_nop 0
	global_load_lds_dwordx4 v132, s[62:63]
	v_cvt_pk_bf16_f32 v187, v118, v119
	v_exp_f32_e32 v122, v122
	v_add_f32_e32 v169, v169, v120
	v_exp_f32_e32 v123, v123
	s_waitcnt lgkmcnt(10)
	v_mfma_f32_32x32x16_bf16 v[64:79], v[230:233], v[176:179], v[64:79]
	ds_read_b64_tr_b16 v[230:231], v147 offset:36864
	ds_read_b64_tr_b16 v[232:233], v147 offset:38912
	v_add_f32_e32 v169, v169, v121
	v_cvt_pk_bf16_f32 v188, v120, v121
	v_exp_f32_e32 v124, v124
	s_waitcnt lgkmcnt(6)
	v_mfma_f32_32x32x16_bf16 v[0:15], v[154:157], v[180:183], v[0:15]
	ds_read_b64_tr_b16 v[154:155], v142 offset:40960
	ds_read_b64_tr_b16 v[156:157], v142 offset:43008
	v_add_f32_e32 v169, v169, v122
	v_exp_f32_e32 v125, v125
	v_add_f32_e32 v169, v169, v123
	v_cvt_pk_bf16_f32 v189, v122, v123
	s_waitcnt lgkmcnt(6)
	v_mfma_f32_32x32x16_bf16 v[16:31], v[158:161], v[180:183], v[16:31]
	ds_read_b64_tr_b16 v[158:159], v143 offset:40960
	ds_read_b64_tr_b16 v[160:161], v143 offset:43008
	v_exp_f32_e32 v126, v126
	v_add_f32_e32 v169, v169, v124
	v_exp_f32_e32 v127, v127
	s_waitcnt lgkmcnt(6)
	v_mfma_f32_32x32x16_bf16 v[48:63], v[162:165], v[180:183], v[48:63]
	ds_read_b64_tr_b16 v[162:163], v146 offset:40960
	ds_read_b64_tr_b16 v[164:165], v146 offset:43008
	v_add_f32_e32 v169, v169, v125
	v_cvt_pk_bf16_f32 v190, v124, v125
	v_add_f32_e32 v169, v169, v126
	v_add_f32_e32 v169, v169, v127
	v_cvt_pk_bf16_f32 v191, v126, v127
	s_waitcnt lgkmcnt(6)
	v_mfma_f32_32x32x16_bf16 v[64:79], v[230:233], v[180:183], v[64:79]
	ds_read_b64_tr_b16 v[230:231], v147 offset:40960
	ds_read_b64_tr_b16 v[232:233], v147 offset:43008
	v_mfma_f32_32x32x16_bf16 v[112:127], v[198:201], v[96:99], v[32:47]
	ds_read_b128 v[198:201], v128
	v_exp_f32_e32 v80, v80
	v_exp_f32_e32 v81, v81
	v_exp_f32_e32 v82, v82
	v_mfma_f32_32x32x16_bf16 v[112:127], v[202:205], v[100:103], v[112:127]
	ds_read_b128 v[202:205], v129
	v_add_f32_e32 v169, v169, v80
	v_exp_f32_e32 v83, v83
	v_add_f32_e32 v169, v169, v81
	v_cvt_pk_bf16_f32 v176, v80, v81
	v_mfma_f32_32x32x16_bf16 v[112:127], v[206:209], v[104:107], v[112:127]
	ds_read_b128 v[206:209], v130
	v_exp_f32_e32 v84, v84
	v_add_f32_e32 v169, v169, v82
	v_exp_f32_e32 v85, v85
	v_mfma_f32_32x32x16_bf16 v[112:127], v[150:153], v[108:111], v[112:127]
	ds_read_b128 v[150:153], v131
	v_add_f32_e32 v169, v169, v83
	v_cvt_pk_bf16_f32 v177, v82, v83
	v_exp_f32_e32 v86, v86
	v_add_f32_e32 v169, v169, v84
	s_waitcnt lgkmcnt(10)
	v_mfma_f32_32x32x16_bf16 v[0:15], v[154:157], v[184:187], v[0:15]
	ds_read_b64_tr_b16 v[154:155], v142 offset:45056
	ds_read_b64_tr_b16 v[156:157], v142 offset:47104
	v_exp_f32_e32 v87, v87
	v_add_f32_e32 v169, v169, v85
	v_cvt_pk_bf16_f32 v178, v84, v85
	v_exp_f32_e32 v88, v88
	s_waitcnt lgkmcnt(10)
	v_mfma_f32_32x32x16_bf16 v[16:31], v[158:161], v[184:187], v[16:31]
	ds_read_b64_tr_b16 v[158:159], v143 offset:45056
	ds_read_b64_tr_b16 v[160:161], v143 offset:47104
	v_add_f32_e32 v169, v169, v86
	v_exp_f32_e32 v89, v89
	v_add_f32_e32 v169, v169, v87
	s_waitcnt lgkmcnt(10)
	v_mfma_f32_32x32x16_bf16 v[48:63], v[162:165], v[184:187], v[48:63]
	ds_read_b64_tr_b16 v[162:163], v146 offset:45056
	ds_read_b64_tr_b16 v[164:165], v146 offset:47104
	v_cvt_pk_bf16_f32 v179, v86, v87
	v_exp_f32_e32 v90, v90
	v_add_f32_e32 v169, v169, v88
	v_exp_f32_e32 v91, v91
	s_waitcnt lgkmcnt(10)
	v_mfma_f32_32x32x16_bf16 v[64:79], v[230:233], v[184:187], v[64:79]
	ds_read_b64_tr_b16 v[230:231], v147 offset:45056
	ds_read_b64_tr_b16 v[232:233], v147 offset:47104
	v_add_f32_e32 v169, v169, v89
	v_cvt_pk_bf16_f32 v180, v88, v89
	v_exp_f32_e32 v92, v92
	s_waitcnt lgkmcnt(6)
	v_mfma_f32_32x32x16_bf16 v[0:15], v[154:157], v[188:191], v[0:15]
	ds_read_b64_tr_b16 v[154:155], v170 offset:8192
	ds_read_b64_tr_b16 v[156:157], v170 offset:10240
	v_add_f32_e32 v169, v169, v90
	v_exp_f32_e32 v93, v93
	v_add_f32_e32 v169, v169, v91
	v_cvt_pk_bf16_f32 v181, v90, v91
	s_waitcnt lgkmcnt(6)
	v_mfma_f32_32x32x16_bf16 v[16:31], v[158:161], v[188:191], v[16:31]
	ds_read_b64_tr_b16 v[158:159], v171 offset:8192
	ds_read_b64_tr_b16 v[160:161], v171 offset:10240
	v_exp_f32_e32 v94, v94
	v_add_f32_e32 v169, v169, v92
	v_exp_f32_e32 v95, v95
	s_waitcnt lgkmcnt(6)
	v_mfma_f32_32x32x16_bf16 v[48:63], v[162:165], v[188:191], v[48:63]
	ds_read_b64_tr_b16 v[162:163], v172 offset:8192
	ds_read_b64_tr_b16 v[164:165], v172 offset:10240
	s_add_i32 s59, s59, 1
	v_add_f32_e32 v169, v169, v93
	v_cvt_pk_bf16_f32 v182, v92, v93
	v_add_f32_e32 v169, v169, v94
	v_add_f32_e32 v169, v169, v95
	v_cvt_pk_bf16_f32 v183, v94, v95
	s_waitcnt lgkmcnt(6)
	v_mfma_f32_32x32x16_bf16 v[64:79], v[230:233], v[188:191], v[64:79]
	ds_read_b64_tr_b16 v[230:231], v173 offset:8192
	ds_read_b64_tr_b16 v[232:233], v173 offset:10240
	s_waitcnt vmcnt(3) lgkmcnt(8)
	s_barrier
; template <int DV>
; __device__ __forceinline__ void attn_pass(const int tid, unsigned char* smem, const bf16_t* Q0, int qpitch, const bf16_t* Kb, int kpitch, const bf16_t* Vb, int vpitch,
;                                           int b, int ntiles, float kmax, f32x16 (&o)[DV / 32], float& linv) {
;     ...
;     for (int kt = 0; kt < ntiles; ++kt) {
;         if (kt + 1 < ntiles) gload(kt + 1);
;         const unsigned char* Ks = smem + (kt & 1) * BUF; const unsigned char* Vs = Ks + KBYTES;
;         const unsigned char* kp = Ks + r32 * KP + hi * 16;
;         bf16x8 pf[2][2];
; #pragma unroll
;         for (int kb = 0; kb < 2; ++kb) {
;             f32x16 s;
; #pragma unroll
;             for (int r = 0; r < 16; ++r) s[r] = nshift;
; #pragma unroll
;             for (int ds = 0; ds < 4; ++ds) {
;                 const bf16x8 kf = *(const bf16x8*)(kp + kb * 32 * KP + ds * 32);
;                 s = __builtin_amdgcn_mfma_f32_32x32x16_bf16(kf, qf[ds], s, 0, 0, 0);
;             }
;             float ls = 0.f;
; #pragma unroll
;             for (int r = 0; r < 16; ++r) { s[r] = __builtin_amdgcn_exp2f(s[r]); ls += s[r]; }
;             lsum += ls;
; #pragma unroll
;             for (int j = 0; j < 2; ++j) {
;                 u32x4 w0;
;                 w0.x = cvt_pk_bf16(s[8 * j + 0], s[8 * j + 1]); w0.y = cvt_pk_bf16(s[8 * j + 2], s[8 * j + 3]); w0.z = cvt_pk_bf16(s[8 * j + 4], s[8 * j + 5]); w0.w = cvt_pk_bf16(s[8 * j + 6], s[8 * j + 7]);
;                 pf[kb][j] = __builtin_bit_cast(bf16x8, w0);
;             }
;         }
;         const unsigned char* vp = Vs + (4 * hi + q4) * VP + (16 * nhalf + 4 * p4) * 2;
; #pragma unroll
;         for (int d0 = 0; d0 < DV / 32; ++d0) {
; #pragma unroll
;             for (int kb = 0; kb < 2; ++kb)
; #pragma unroll
;                 for (int j = 0; j < 2; ++j) {
;                     const unsigned char* a = vp + (32 * kb + 16 * j) * VP + d0 * 64;
;                     const s16x4 lo = ld_tr(a), h4 = ld_tr(a + 8 * VP);
;                     const bf16x8 vf = (bf16x8){lo[0], lo[1], lo[2], lo[3], h4[0], h4[1], h4[2], h4[3]};
;                     o[d0] = __builtin_amdgcn_mfma_f32_32x32x16_bf16(vf, pf[kb][j], o[d0], 0, 0, 0);
;                 }
;             if (d0 & 1) __builtin_amdgcn_sched_barrier(0);
;         }
;         if (kt + 1 < ntiles) lwrite((kt + 1) & 1);
;         __syncthreads();
;     }
	v_mfma_f32_32x32x16_bf16 v[80:95], v[198:201], v[96:99], v[32:47]
	ds_read_b128 v[198:201], v128 offset:4096
	v_exp_f32_e32 v112, v112
	v_exp_f32_e32 v113, v113
	v_exp_f32_e32 v114, v114
	v_mfma_f32_32x32x16_bf16 v[80:95], v[202:205], v[100:103], v[80:95]
	ds_read_b128 v[202:205], v129 offset:4096
	v_add_f32_e32 v169, v169, v112
	v_exp_f32_e32 v115, v115
	v_add_f32_e32 v169, v169, v113
	v_cvt_pk_bf16_f32 v184, v112, v113
	v_mfma_f32_32x32x16_bf16 v[80:95], v[206:209], v[104:107], v[80:95]
	ds_read_b128 v[206:209], v130 offset:4096
	v_exp_f32_e32 v116, v116
	v_add_f32_e32 v169, v169, v114
	v_exp_f32_e32 v117, v117
	v_mfma_f32_32x32x16_bf16 v[80:95], v[150:153], v[108:111], v[80:95]
	ds_read_b128 v[150:153], v131 offset:4096
	v_add_f32_e32 v169, v169, v115
	v_cvt_pk_bf16_f32 v185, v114, v115
	v_exp_f32_e32 v118, v118
	v_add_f32_e32 v169, v169, v116
	s_waitcnt lgkmcnt(10)
	v_mfma_f32_32x32x16_bf16 v[0:15], v[154:157], v[176:179], v[0:15]
	ds_read_b64_tr_b16 v[154:155], v170 offset:12288
	ds_read_b64_tr_b16 v[156:157], v170 offset:14336
	s_add_i32 s71, s25, -1
	s_add_i32 s70, s59, 3
	s_min_u32 s70, s70, s71
	s_cmp_lt_u32 s70, 4
	s_cselect_b32 s2, s65, s32
	s_lshl_b32 s3, s70, 6
	s_add_i32 s2, s2, s3
	s_lshl_b32 s2, s2, 10
	s_add_u32 s60, s66, s2
	s_addc_u32 s61, s67, 0
	s_add_i32 s70, s59, 2
	s_min_u32 s70, s70, s71
	s_cmp_lt_u32 s70, 4
	s_cselect_b32 s2, s65, s32
	s_lshl_b32 s3, s70, 6
	s_add_i32 s2, s2, s3
	s_lshl_b32 s2, s2, 10
	s_add_u32 s62, s68, s2
	s_addc_u32 s63, s69, 0
	v_exp_f32_e32 v119, v119
	v_add_f32_e32 v169, v169, v117
	v_cvt_pk_bf16_f32 v186, v116, v117
	v_exp_f32_e32 v120, v120
	s_waitcnt lgkmcnt(10)
	v_mfma_f32_32x32x16_bf16 v[16:31], v[158:161], v[176:179], v[16:31]
	ds_read_b64_tr_b16 v[158:159], v171 offset:12288
	ds_read_b64_tr_b16 v[160:161], v171 offset:14336
	s_add_i32 m0, s56, 0x6000
	s_nop 0
	global_load_lds_dwordx4 v166, s[60:61]
	v_add_f32_e32 v169, v169, v118
	v_exp_f32_e32 v121, v121
	v_add_f32_e32 v169, v169, v119
	s_waitcnt lgkmcnt(10)
	v_mfma_f32_32x32x16_bf16 v[48:63], v[162:165], v[176:179], v[48:63]
	ds_read_b64_tr_b16 v[162:163], v172 offset:12288
	ds_read_b64_tr_b16 v[164:165], v172 offset:14336
	s_add_i32 m0, s56, 0x8000
	s_nop 0
	global_load_lds_dwordx4 v167, s[62:63]
	s_add_i32 m0, s56, 0xa000
	s_nop 0
	global_load_lds_dwordx4 v132, s[62:63]
	v_cvt_pk_bf16_f32 v187, v118, v119
	v_exp_f32_e32 v122, v122
	v_add_f32_e32 v169, v169, v120
	v_exp_f32_e32 v123, v123
	s_waitcnt lgkmcnt(10)
	v_mfma_f32_32x32x16_bf16 v[64:79], v[230:233], v[176:179], v[64:79]
	ds_read_b64_tr_b16 v[230:231], v173 offset:12288
	ds_read_b64_tr_b16 v[232:233], v173 offset:14336
	v_add_f32_e32 v169, v169, v121
	v_cvt_pk_bf16_f32 v188, v120, v121
	v_exp_f32_e32 v124, v124
	s_waitcnt lgkmcnt(6)
	v_mfma_f32_32x32x16_bf16 v[0:15], v[154:157], v[180:183], v[0:15]
	ds_read_b64_tr_b16 v[154:155], v170 offset:16384
	ds_read_b64_tr_b16 v[156:157], v170 offset:18432
	v_add_f32_e32 v169, v169, v122
	v_exp_f32_e32 v125, v125
	v_add_f32_e32 v169, v169, v123
	v_cvt_pk_bf16_f32 v189, v122, v123
	s_waitcnt lgkmcnt(6)
	v_mfma_f32_32x32x16_bf16 v[16:31], v[158:161], v[180:183], v[16:31]
	ds_read_b64_tr_b16 v[158:159], v171 offset:16384
	ds_read_b64_tr_b16 v[160:161], v171 offset:18432
	v_exp_f32_e32 v126, v126
	v_add_f32_e32 v169, v169, v124
	v_exp_f32_e32 v127, v127
	s_waitcnt lgkmcnt(6)
	v_mfma_f32_32x32x16_bf16 v[48:63], v[162:165], v[180:183], v[48:63]
	ds_read_b64_tr_b16 v[162:163], v172 offset:16384
	ds_read_b64_tr_b16 v[164:165], v172 offset:18432
	v_add_f32_e32 v169, v169, v125
	v_cvt_pk_bf16_f32 v190, v124, v125
	v_add_f32_e32 v169, v169, v126
	v_add_f32_e32 v169, v169, v127
	v_cvt_pk_bf16_f32 v191, v126, v127
	s_waitcnt lgkmcnt(6)
	v_mfma_f32_32x32x16_bf16 v[64:79], v[230:233], v[180:183], v[64:79]
	ds_read_b64_tr_b16 v[230:231], v173 offset:16384
	ds_read_b64_tr_b16 v[232:233], v173 offset:18432
	v_mfma_f32_32x32x16_bf16 v[112:127], v[198:201], v[96:99], v[32:47]
	ds_read_b128 v[198:201], v128 offset:24576
	v_exp_f32_e32 v80, v80
	v_exp_f32_e32 v81, v81
	v_exp_f32_e32 v82, v82
	v_mfma_f32_32x32x16_bf16 v[112:127], v[202:205], v[100:103], v[112:127]
	ds_read_b128 v[202:205], v129 offset:24576
	v_add_f32_e32 v169, v169, v80
	v_exp_f32_e32 v83, v83
	v_add_f32_e32 v169, v169, v81
	v_cvt_pk_bf16_f32 v176, v80, v81
	v_mfma_f32_32x32x16_bf16 v[112:127], v[206:209], v[104:107], v[112:127]
	ds_read_b128 v[206:209], v130 offset:24576
	v_exp_f32_e32 v84, v84
	v_add_f32_e32 v169, v169, v82
	v_exp_f32_e32 v85, v85
	v_mfma_f32_32x32x16_bf16 v[112:127], v[150:153], v[108:111], v[112:127]
	ds_read_b128 v[150:153], v131 offset:24576
	v_add_f32_e32 v169, v169, v83
	v_cvt_pk_bf16_f32 v177, v82, v83
	v_exp_f32_e32 v86, v86
	v_add_f32_e32 v169, v169, v84
	s_waitcnt lgkmcnt(10)
	v_mfma_f32_32x32x16_bf16 v[0:15], v[154:157], v[184:187], v[0:15]
	ds_read_b64_tr_b16 v[154:155], v170 offset:20480
	ds_read_b64_tr_b16 v[156:157], v170 offset:22528
	v_exp_f32_e32 v87, v87
	v_add_f32_e32 v169, v169, v85
	v_cvt_pk_bf16_f32 v178, v84, v85
	v_exp_f32_e32 v88, v88
	s_waitcnt lgkmcnt(10)
	v_mfma_f32_32x32x16_bf16 v[16:31], v[158:161], v[184:187], v[16:31]
	ds_read_b64_tr_b16 v[158:159], v171 offset:20480
	ds_read_b64_tr_b16 v[160:161], v171 offset:22528
	v_add_f32_e32 v169, v169, v86
	v_exp_f32_e32 v89, v89
	v_add_f32_e32 v169, v169, v87
	s_waitcnt lgkmcnt(10)
	v_mfma_f32_32x32x16_bf16 v[48:63], v[162:165], v[184:187], v[48:63]
	ds_read_b64_tr_b16 v[162:163], v172 offset:20480
	ds_read_b64_tr_b16 v[164:165], v172 offset:22528
	v_cvt_pk_bf16_f32 v179, v86, v87
	v_exp_f32_e32 v90, v90
	v_add_f32_e32 v169, v169, v88
	v_exp_f32_e32 v91, v91
	s_waitcnt lgkmcnt(10)
; template <int DV>
; __device__ __forceinline__ void attn_pass(const int tid, unsigned char* smem, const bf16_t* Q0, int qpitch, const bf16_t* Kb, int kpitch, const bf16_t* Vb, int vpitch,
;                                           int b, int ntiles, float kmax, f32x16 (&o)[DV / 32], float& linv) {
;     ...
;     for (int kt = 0; kt < ntiles; ++kt) {
;         if (kt + 1 < ntiles) gload(kt + 1);
;         const unsigned char* Ks = smem + (kt & 1) * BUF; const unsigned char* Vs = Ks + KBYTES;
;         const unsigned char* kp = Ks + r32 * KP + hi * 16;
;         bf16x8 pf[2][2];
; #pragma unroll
;         for (int kb = 0; kb < 2; ++kb) {
;             f32x16 s;
; #pragma unroll
;             for (int r = 0; r < 16; ++r) s[r] = nshift;
; #pragma unroll
;             for (int ds = 0; ds < 4; ++ds) {
;                 const bf16x8 kf = *(const bf16x8*)(kp + kb * 32 * KP + ds * 32);
;                 s = __builtin_amdgcn_mfma_f32_32x32x16_bf16(kf, qf[ds], s, 0, 0, 0);
;             }
;             float ls = 0.f;
; #pragma unroll
;             for (int r = 0; r < 16; ++r) { s[r] = __builtin_amdgcn_exp2f(s[r]); ls += s[r]; }
;             lsum += ls;
; #pragma unroll
;             for (int j = 0; j < 2; ++j) {
;                 u32x4 w0;
;                 w0.x = cvt_pk_bf16(s[8 * j + 0], s[8 * j + 1]); w0.y = cvt_pk_bf16(s[8 * j + 2], s[8 * j + 3]); w0.z = cvt_pk_bf16(s[8 * j + 4], s[8 * j + 5]); w0.w = cvt_pk_bf16(s[8 * j + 6], s[8 * j + 7]);
;                 pf[kb][j] = __builtin_bit_cast(bf16x8, w0);
;             }
;         }
;         const unsigned char* vp = Vs + (4 * hi + q4) * VP + (16 * nhalf + 4 * p4) * 2;
; #pragma unroll
;         for (int d0 = 0; d0 < DV / 32; ++d0) {
; #pragma unroll
;             for (int kb = 0; kb < 2; ++kb)
; #pragma unroll
;                 for (int j = 0; j < 2; ++j) {
;                     const unsigned char* a = vp + (32 * kb + 16 * j) * VP + d0 * 64;
;                     const s16x4 lo = ld_tr(a), h4 = ld_tr(a + 8 * VP);
;                     const bf16x8 vf = (bf16x8){lo[0], lo[1], lo[2], lo[3], h4[0], h4[1], h4[2], h4[3]};
;                     o[d0] = __builtin_amdgcn_mfma_f32_32x32x16_bf16(vf, pf[kb][j], o[d0], 0, 0, 0);
;                 }
;             if (d0 & 1) __builtin_amdgcn_sched_barrier(0);
;         }
;         if (kt + 1 < ntiles) lwrite((kt + 1) & 1);
;         __syncthreads();
;     }
	v_mfma_f32_32x32x16_bf16 v[64:79], v[230:233], v[184:187], v[64:79]
	ds_read_b64_tr_b16 v[230:231], v173 offset:20480
	ds_read_b64_tr_b16 v[232:233], v173 offset:22528
	v_add_f32_e32 v169, v169, v89
	v_cvt_pk_bf16_f32 v180, v88, v89
	v_exp_f32_e32 v92, v92
	s_waitcnt lgkmcnt(6)
	v_mfma_f32_32x32x16_bf16 v[0:15], v[154:157], v[188:191], v[0:15]
	ds_read_b64_tr_b16 v[154:155], v170 offset:32768
	ds_read_b64_tr_b16 v[156:157], v170 offset:34816
	v_add_f32_e32 v169, v169, v90
	v_exp_f32_e32 v93, v93
	v_add_f32_e32 v169, v169, v91
	v_cvt_pk_bf16_f32 v181, v90, v91
	s_waitcnt lgkmcnt(6)
	v_mfma_f32_32x32x16_bf16 v[16:31], v[158:161], v[188:191], v[16:31]
	ds_read_b64_tr_b16 v[158:159], v171 offset:32768
	ds_read_b64_tr_b16 v[160:161], v171 offset:34816
	v_exp_f32_e32 v94, v94
	v_add_f32_e32 v169, v169, v92
	v_exp_f32_e32 v95, v95
	s_waitcnt lgkmcnt(6)
	v_mfma_f32_32x32x16_bf16 v[48:63], v[162:165], v[188:191], v[48:63]
	ds_read_b64_tr_b16 v[162:163], v172 offset:32768
	ds_read_b64_tr_b16 v[164:165], v172 offset:34816
	s_add_i32 s59, s59, 1
	v_add_f32_e32 v169, v169, v93
	v_cvt_pk_bf16_f32 v182, v92, v93
	v_add_f32_e32 v169, v169, v94
	v_add_f32_e32 v169, v169, v95
	v_cvt_pk_bf16_f32 v183, v94, v95
	s_waitcnt lgkmcnt(6)
	v_mfma_f32_32x32x16_bf16 v[64:79], v[230:233], v[188:191], v[64:79]
	ds_read_b64_tr_b16 v[230:231], v173 offset:32768
	ds_read_b64_tr_b16 v[232:233], v173 offset:34816
	s_waitcnt vmcnt(3) lgkmcnt(8)
	s_barrier
	v_mfma_f32_32x32x16_bf16 v[80:95], v[198:201], v[96:99], v[32:47]
	ds_read_b128 v[198:201], v128 offset:28672
	v_exp_f32_e32 v112, v112
	v_exp_f32_e32 v113, v113
	v_exp_f32_e32 v114, v114
	v_mfma_f32_32x32x16_bf16 v[80:95], v[202:205], v[100:103], v[80:95]
	ds_read_b128 v[202:205], v129 offset:28672
	v_add_f32_e32 v169, v169, v112
	v_exp_f32_e32 v115, v115
	v_add_f32_e32 v169, v169, v113
	v_cvt_pk_bf16_f32 v184, v112, v113
	v_mfma_f32_32x32x16_bf16 v[80:95], v[206:209], v[104:107], v[80:95]
	ds_read_b128 v[206:209], v130 offset:28672
	v_exp_f32_e32 v116, v116
	v_add_f32_e32 v169, v169, v114
	v_exp_f32_e32 v117, v117
	v_mfma_f32_32x32x16_bf16 v[80:95], v[150:153], v[108:111], v[80:95]
	ds_read_b128 v[150:153], v131 offset:28672
	v_add_f32_e32 v169, v169, v115
	v_cvt_pk_bf16_f32 v185, v114, v115
	v_exp_f32_e32 v118, v118
	v_add_f32_e32 v169, v169, v116
	s_waitcnt lgkmcnt(10)
	v_mfma_f32_32x32x16_bf16 v[0:15], v[154:157], v[176:179], v[0:15]
	ds_read_b64_tr_b16 v[154:155], v170 offset:36864
	ds_read_b64_tr_b16 v[156:157], v170 offset:38912
	v_exp_f32_e32 v119, v119
	v_add_f32_e32 v169, v169, v117
	v_cvt_pk_bf16_f32 v186, v116, v117
	v_exp_f32_e32 v120, v120
	s_waitcnt lgkmcnt(10)
	v_mfma_f32_32x32x16_bf16 v[16:31], v[158:161], v[176:179], v[16:31]
	ds_read_b64_tr_b16 v[158:159], v171 offset:36864
	ds_read_b64_tr_b16 v[160:161], v171 offset:38912
	v_add_f32_e32 v169, v169, v118
	v_exp_f32_e32 v121, v121
	v_add_f32_e32 v169, v169, v119
	s_waitcnt lgkmcnt(10)
	v_mfma_f32_32x32x16_bf16 v[48:63], v[162:165], v[176:179], v[48:63]
	ds_read_b64_tr_b16 v[162:163], v172 offset:36864
	ds_read_b64_tr_b16 v[164:165], v172 offset:38912
	v_cvt_pk_bf16_f32 v187, v118, v119
	v_exp_f32_e32 v122, v122
	v_add_f32_e32 v169, v169, v120
	v_exp_f32_e32 v123, v123
	s_waitcnt lgkmcnt(10)
	v_mfma_f32_32x32x16_bf16 v[64:79], v[230:233], v[176:179], v[64:79]
	ds_read_b64_tr_b16 v[230:231], v173 offset:36864
	ds_read_b64_tr_b16 v[232:233], v173 offset:38912
	v_add_f32_e32 v169, v169, v121
	v_cvt_pk_bf16_f32 v188, v120, v121
	v_exp_f32_e32 v124, v124
	s_waitcnt lgkmcnt(6)
	v_mfma_f32_32x32x16_bf16 v[0:15], v[154:157], v[180:183], v[0:15]
	ds_read_b64_tr_b16 v[154:155], v170 offset:40960
	ds_read_b64_tr_b16 v[156:157], v170 offset:43008
	v_add_f32_e32 v169, v169, v122
	v_exp_f32_e32 v125, v125
	v_add_f32_e32 v169, v169, v123
	v_cvt_pk_bf16_f32 v189, v122, v123
	s_waitcnt lgkmcnt(6)
	v_mfma_f32_32x32x16_bf16 v[16:31], v[158:161], v[180:183], v[16:31]
	ds_read_b64_tr_b16 v[158:159], v171 offset:40960
	ds_read_b64_tr_b16 v[160:161], v171 offset:43008
	v_exp_f32_e32 v126, v126
	v_add_f32_e32 v169, v169, v124
	v_exp_f32_e32 v127, v127
	s_waitcnt lgkmcnt(6)
	v_mfma_f32_32x32x16_bf16 v[48:63], v[162:165], v[180:183], v[48:63]
	ds_read_b64_tr_b16 v[162:163], v172 offset:40960
	ds_read_b64_tr_b16 v[164:165], v172 offset:43008
	v_add_f32_e32 v169, v169, v125
	v_cvt_pk_bf16_f32 v190, v124, v125
	v_add_f32_e32 v169, v169, v126
	v_add_f32_e32 v169, v169, v127
	v_cvt_pk_bf16_f32 v191, v126, v127
	s_waitcnt lgkmcnt(6)
	v_mfma_f32_32x32x16_bf16 v[64:79], v[230:233], v[180:183], v[64:79]
	ds_read_b64_tr_b16 v[230:231], v173 offset:40960
	ds_read_b64_tr_b16 v[232:233], v173 offset:43008
	v_mfma_f32_32x32x16_bf16 v[112:127], v[198:201], v[96:99], v[32:47]
	v_exp_f32_e32 v80, v80
	v_exp_f32_e32 v81, v81
	v_exp_f32_e32 v82, v82
	v_mfma_f32_32x32x16_bf16 v[112:127], v[202:205], v[100:103], v[112:127]
	v_add_f32_e32 v169, v169, v80
	v_exp_f32_e32 v83, v83
	v_add_f32_e32 v169, v169, v81
	v_cvt_pk_bf16_f32 v176, v80, v81
	v_mfma_f32_32x32x16_bf16 v[112:127], v[206:209], v[104:107], v[112:127]
	v_exp_f32_e32 v84, v84
	v_add_f32_e32 v169, v169, v82
	v_exp_f32_e32 v85, v85
	v_mfma_f32_32x32x16_bf16 v[112:127], v[150:153], v[108:111], v[112:127]
	v_add_f32_e32 v169, v169, v83
	v_cvt_pk_bf16_f32 v177, v82, v83
	v_exp_f32_e32 v86, v86
	v_add_f32_e32 v169, v169, v84
	s_waitcnt lgkmcnt(6)
	v_mfma_f32_32x32x16_bf16 v[0:15], v[154:157], v[184:187], v[0:15]
	ds_read_b64_tr_b16 v[154:155], v170 offset:45056
	ds_read_b64_tr_b16 v[156:157], v170 offset:47104
	v_exp_f32_e32 v87, v87
	v_add_f32_e32 v169, v169, v85
	v_cvt_pk_bf16_f32 v178, v84, v85
	v_exp_f32_e32 v88, v88
	s_waitcnt lgkmcnt(6)
; __device__ __forceinline__ float sum_x32(float v) { auto rr = __builtin_amdgcn_permlane32_swap(__float_as_uint(v), __float_as_uint(v), false, false); return __uint_as_float(rr[0]) + __uint_as_float(rr[1]); }
; __device__ __forceinline__ s16x4 ld_tr(const unsigned char* p) { return __builtin_bit_cast(s16x4, __builtin_amdgcn_ds_read_tr16_b64_v4i16((LAS s16x4*)p)); }
; template <int DV>
; __device__ __forceinline__ void attn_pass(const int tid, unsigned char* smem, const bf16_t* Q0, int qpitch, const bf16_t* Kb, int kpitch, const bf16_t* Vb, int vpitch,
;                                           int b, int ntiles, float kmax, f32x16 (&o)[DV / 32], float& linv) {
;     ...
;         const unsigned char* vp = Vs + (4 * hi + q4) * VP + (16 * nhalf + 4 * p4) * 2;
; #pragma unroll
;         for (int d0 = 0; d0 < DV / 32; ++d0) {
; #pragma unroll
;             for (int kb = 0; kb < 2; ++kb)
; #pragma unroll
;                 for (int j = 0; j < 2; ++j) {
;                     const unsigned char* a = vp + (32 * kb + 16 * j) * VP + d0 * 64;
;                     const s16x4 lo = ld_tr(a), h4 = ld_tr(a + 8 * VP);
;                     const bf16x8 vf = (bf16x8){lo[0], lo[1], lo[2], lo[3], h4[0], h4[1], h4[2], h4[3]};
;                     o[d0] = __builtin_amdgcn_mfma_f32_32x32x16_bf16(vf, pf[kb][j], o[d0], 0, 0, 0);
;                 }
;             if (d0 & 1) __builtin_amdgcn_sched_barrier(0);
;         }
;         if (kt + 1 < ntiles) lwrite((kt + 1) & 1);
;         __syncthreads();
;     }
;     lsum = sum_x32(lsum);
;     linv = 1.0f / lsum;
	v_mfma_f32_32x32x16_bf16 v[16:31], v[158:161], v[184:187], v[16:31]
	ds_read_b64_tr_b16 v[158:159], v171 offset:45056
	ds_read_b64_tr_b16 v[160:161], v171 offset:47104
	v_add_f32_e32 v169, v169, v86
	v_exp_f32_e32 v89, v89
	v_add_f32_e32 v169, v169, v87
	s_waitcnt lgkmcnt(6)
	v_mfma_f32_32x32x16_bf16 v[48:63], v[162:165], v[184:187], v[48:63]
	ds_read_b64_tr_b16 v[162:163], v172 offset:45056
	ds_read_b64_tr_b16 v[164:165], v172 offset:47104
	v_cvt_pk_bf16_f32 v179, v86, v87
	v_exp_f32_e32 v90, v90
	v_add_f32_e32 v169, v169, v88
	v_exp_f32_e32 v91, v91
	s_waitcnt lgkmcnt(6)
	v_mfma_f32_32x32x16_bf16 v[64:79], v[230:233], v[184:187], v[64:79]
	ds_read_b64_tr_b16 v[230:231], v173 offset:45056
	ds_read_b64_tr_b16 v[232:233], v173 offset:47104
	v_add_f32_e32 v169, v169, v89
	v_cvt_pk_bf16_f32 v180, v88, v89
	v_exp_f32_e32 v92, v92
	s_waitcnt lgkmcnt(6)
	v_mfma_f32_32x32x16_bf16 v[0:15], v[154:157], v[188:191], v[0:15]
	ds_read_b64_tr_b16 v[154:155], v142 offset:8192
	ds_read_b64_tr_b16 v[156:157], v142 offset:10240
	v_add_f32_e32 v169, v169, v90
	v_exp_f32_e32 v93, v93
	v_add_f32_e32 v169, v169, v91
	v_cvt_pk_bf16_f32 v181, v90, v91
	s_waitcnt lgkmcnt(6)
	v_mfma_f32_32x32x16_bf16 v[16:31], v[158:161], v[188:191], v[16:31]
	ds_read_b64_tr_b16 v[158:159], v143 offset:8192
	ds_read_b64_tr_b16 v[160:161], v143 offset:10240
	v_exp_f32_e32 v94, v94
	v_add_f32_e32 v169, v169, v92
	v_exp_f32_e32 v95, v95
	s_waitcnt lgkmcnt(6)
	v_mfma_f32_32x32x16_bf16 v[48:63], v[162:165], v[188:191], v[48:63]
	ds_read_b64_tr_b16 v[162:163], v146 offset:8192
	ds_read_b64_tr_b16 v[164:165], v146 offset:10240
	s_add_i32 s59, s59, 1
	v_add_f32_e32 v169, v169, v93
	v_cvt_pk_bf16_f32 v182, v92, v93
	v_add_f32_e32 v169, v169, v94
	v_add_f32_e32 v169, v169, v95
	v_cvt_pk_bf16_f32 v183, v94, v95
	s_waitcnt lgkmcnt(6)
	v_mfma_f32_32x32x16_bf16 v[64:79], v[230:233], v[188:191], v[64:79]
	ds_read_b64_tr_b16 v[230:231], v147 offset:8192
	ds_read_b64_tr_b16 v[232:233], v147 offset:10240
	s_waitcnt lgkmcnt(8)
	s_barrier
	s_waitcnt lgkmcnt(6)
	v_mfma_f32_32x32x16_bf16 v[0:15], v[154:157], v[176:179], v[0:15]
	ds_read_b64_tr_b16 v[154:155], v142 offset:12288
	ds_read_b64_tr_b16 v[156:157], v142 offset:14336
	v_exp_f32_e32 v112, v112
	v_exp_f32_e32 v113, v113
	v_exp_f32_e32 v114, v114
	v_add_f32_e32 v169, v169, v112
	v_exp_f32_e32 v115, v115
	s_waitcnt lgkmcnt(6)
	v_mfma_f32_32x32x16_bf16 v[16:31], v[158:161], v[176:179], v[16:31]
	ds_read_b64_tr_b16 v[158:159], v143 offset:12288
	ds_read_b64_tr_b16 v[160:161], v143 offset:14336
	v_add_f32_e32 v169, v169, v113
	v_cvt_pk_bf16_f32 v184, v112, v113
	v_exp_f32_e32 v116, v116
	v_add_f32_e32 v169, v169, v114
	v_exp_f32_e32 v117, v117
	s_waitcnt lgkmcnt(6)
	v_mfma_f32_32x32x16_bf16 v[48:63], v[162:165], v[176:179], v[48:63]
	ds_read_b64_tr_b16 v[162:163], v146 offset:12288
	ds_read_b64_tr_b16 v[164:165], v146 offset:14336
	v_add_f32_e32 v169, v169, v115
	v_cvt_pk_bf16_f32 v185, v114, v115
	v_exp_f32_e32 v118, v118
	v_add_f32_e32 v169, v169, v116
	v_exp_f32_e32 v119, v119
	v_add_f32_e32 v169, v169, v117
	s_waitcnt lgkmcnt(6)
	v_mfma_f32_32x32x16_bf16 v[64:79], v[230:233], v[176:179], v[64:79]
	ds_read_b64_tr_b16 v[230:231], v147 offset:12288
	ds_read_b64_tr_b16 v[232:233], v147 offset:14336
	v_cvt_pk_bf16_f32 v186, v116, v117
	v_exp_f32_e32 v120, v120
	v_add_f32_e32 v169, v169, v118
	v_exp_f32_e32 v121, v121
	v_add_f32_e32 v169, v169, v119
	v_cvt_pk_bf16_f32 v187, v118, v119
	s_waitcnt lgkmcnt(6)
	v_mfma_f32_32x32x16_bf16 v[0:15], v[154:157], v[180:183], v[0:15]
	ds_read_b64_tr_b16 v[154:155], v142 offset:16384
	ds_read_b64_tr_b16 v[156:157], v142 offset:18432
	v_exp_f32_e32 v122, v122
	v_add_f32_e32 v169, v169, v120
	v_exp_f32_e32 v123, v123
	v_add_f32_e32 v169, v169, v121
	v_cvt_pk_bf16_f32 v188, v120, v121
	v_exp_f32_e32 v124, v124
	s_waitcnt lgkmcnt(6)
	v_mfma_f32_32x32x16_bf16 v[16:31], v[158:161], v[180:183], v[16:31]
	ds_read_b64_tr_b16 v[158:159], v143 offset:16384
	ds_read_b64_tr_b16 v[160:161], v143 offset:18432
	v_add_f32_e32 v169, v169, v122
	v_exp_f32_e32 v125, v125
	v_add_f32_e32 v169, v169, v123
	v_cvt_pk_bf16_f32 v189, v122, v123
	v_exp_f32_e32 v126, v126
	s_waitcnt lgkmcnt(6)
	v_mfma_f32_32x32x16_bf16 v[48:63], v[162:165], v[180:183], v[48:63]
	ds_read_b64_tr_b16 v[162:163], v146 offset:16384
	ds_read_b64_tr_b16 v[164:165], v146 offset:18432
	v_add_f32_e32 v169, v169, v124
	v_exp_f32_e32 v127, v127
	v_add_f32_e32 v169, v169, v125
	v_cvt_pk_bf16_f32 v190, v124, v125
	v_add_f32_e32 v169, v169, v126
	v_add_f32_e32 v169, v169, v127
	v_cvt_pk_bf16_f32 v191, v126, v127
	s_waitcnt lgkmcnt(6)
	v_mfma_f32_32x32x16_bf16 v[64:79], v[230:233], v[180:183], v[64:79]
	ds_read_b64_tr_b16 v[230:231], v147 offset:16384
	ds_read_b64_tr_b16 v[232:233], v147 offset:18432
	s_waitcnt lgkmcnt(6)
	v_mfma_f32_32x32x16_bf16 v[0:15], v[154:157], v[184:187], v[0:15]
	ds_read_b64_tr_b16 v[154:155], v142 offset:20480
	ds_read_b64_tr_b16 v[156:157], v142 offset:22528
	s_waitcnt lgkmcnt(6)
	v_mfma_f32_32x32x16_bf16 v[16:31], v[158:161], v[184:187], v[16:31]
	ds_read_b64_tr_b16 v[158:159], v143 offset:20480
	ds_read_b64_tr_b16 v[160:161], v143 offset:22528
	s_waitcnt lgkmcnt(6)
	v_mfma_f32_32x32x16_bf16 v[48:63], v[162:165], v[184:187], v[48:63]
	ds_read_b64_tr_b16 v[162:163], v146 offset:20480
	ds_read_b64_tr_b16 v[164:165], v146 offset:22528
	s_waitcnt lgkmcnt(6)
	v_mfma_f32_32x32x16_bf16 v[64:79], v[230:233], v[184:187], v[64:79]
	ds_read_b64_tr_b16 v[230:231], v147 offset:20480
	ds_read_b64_tr_b16 v[232:233], v147 offset:22528
	s_waitcnt lgkmcnt(6)
	v_mfma_f32_32x32x16_bf16 v[0:15], v[154:157], v[188:191], v[0:15]
	s_waitcnt lgkmcnt(4)
	v_mfma_f32_32x32x16_bf16 v[16:31], v[158:161], v[188:191], v[16:31]
	s_waitcnt lgkmcnt(2)
	v_mfma_f32_32x32x16_bf16 v[48:63], v[162:165], v[188:191], v[48:63]
	s_waitcnt lgkmcnt(0)
	v_mfma_f32_32x32x16_bf16 v[64:79], v[230:233], v[188:191], v[64:79]
	s_waitcnt lgkmcnt(0)
	s_barrier
	s_waitcnt vmcnt(0)

; __device__ __forceinline__ float bf2f(unsigned short b) { return __uint_as_float((unsigned)b << 16); }
; __device__ __forceinline__ float sum_x32(float v) { auto rr = __builtin_amdgcn_permlane32_swap(__float_as_uint(v), __float_as_uint(v), false, false); return __uint_as_float(rr[0]) + __uint_as_float(rr[1]); }
; __device__ __forceinline__ void attn_pass_A2(const int tid, unsigned char* smem, const bf16_t* Q0w, int qpitch, const bf16_t* Kb, int kpitch, const bf16_t* Vb, int vpitch,
;                                              int b, int ntiles, float kmax, f32x16 (&o)[2][2], float (&linv)[2]) {
;     ...
;     unsigned char* qs = smem + 2 * BUF + ((tid >> 6) * 64 + r32) * KP + hi * 16;
; #pragma unroll
;     for (int qb = 0; qb < 2; ++qb) {
;         const bf16_t* qp = Q0w + (size_t)(32 * qb + r32) * qpitch + 8 * hi; float ssq = 0.f;
; #pragma unroll
;         for (int ds = 0; ds < 4; ++ds) { const bf16x8 qv = *(const bf16x8*)(qp + 16 * ds); *(bf16x8*)(qs + qb * 32 * KP + ds * 32) = qv;
; #pragma unroll
;             for (int j = 0; j < 8; ++j) { const float f = bf2f((unsigned short)qv[j]); ssq += f * f; } }
;         nshift[qb] = -sqrtf(sum_x32(ssq)) * kmax;
; #pragma unroll
;         for (int d0 = 0; d0 < 2; ++d0)
; #pragma unroll
;             for (int r = 0; r < 16; ++r) o[qb][d0][r] = 0.f;
;     }
.LBB0_417:
	s_and_b64 vcc, exec, s[0:1]
	s_cbranch_vccz .LBB0_394
	s_and_b32 s0, s27, 0xffffffc0
	s_add_i32 s1, s0, 0xffffff00
	s_cmp_lt_i32 s0, s11
	s_cselect_b32 s0, s0, s1
	s_ashr_i32 s1, s0, 31
	s_add_u32 s0, s8, s0
	s_addc_u32 s1, s9, s1
	s_lshl_b64 s[0:1], s[0:1], 11
	v_readlane_b32 s2, v253, 22
	v_readlane_b32 s3, v253, 23
	s_add_u32 s2, s2, s0
	s_addc_u32 s3, s3, s1
	s_lshl_b32 s0, s26, 6
	s_ashr_i32 s1, s0, 31
	s_lshl_b64 s[12:13], s[0:1], 1
	s_add_u32 s0, s2, s12
	s_addc_u32 s1, s3, s13
	v_mov_b32_e32 v139, v193
	v_lshl_add_u64 v[0:1], s[0:1], 0, v[138:139]
	v_lshlrev_b32_e32 v192, 11, v218
	v_lshl_add_u64 v[0:1], v[0:1], 0, v[192:193]
	global_load_dwordx4 v[20:23], v[0:1], off
	global_load_dwordx4 v[24:27], v[0:1], off offset:32
	global_load_dwordx4 v[28:31], v[0:1], off offset:64
	global_load_dwordx4 v[32:35], v[0:1], off offset:96
	s_mov_b32 s0, 0x10000
	v_add_co_u32_e32 v10, vcc, s0, v0
	s_movk_i32 s0, 0x90
	s_nop 0
	v_addc_co_u32_e32 v11, vcc, 0, v1, vcc
	global_load_dwordx4 v[16:19], v[10:11], off
	v_and_b32_e32 v1, 0xfffffdf, v197
	v_mul_lo_u32 v1, v1, s0
	v_add_u32_e32 v1, 0, v1
	v_add_u32_e32 v139, v1, v138
	global_load_dwordx4 v[2:5], v[10:11], off offset:32
	global_load_dwordx4 v[6:9], v[10:11], off offset:64
	s_nop 0
	global_load_dwordx4 v[10:13], v[10:11], off offset:96
	s_lshl_b32 s0, s26, 4
	s_andn2_b32 s0, s0, 63
	s_ashr_i32 s1, s0, 31
	s_lshl_b64 s[0:1], s[0:1], 1
	v_readlane_b32 s2, v251, 33
	s_add_u32 s14, s2, s0
	v_readlane_b32 s2, v251, 34
	s_addc_u32 s15, s2, s1
	v_readlane_b32 s2, v251, 35
	s_add_u32 s16, s2, s0
	s_mov_b32 s2, 0xf800000
	v_readlane_b32 s0, v251, 36
	s_addc_u32 s17, s0, s1
	v_and_b32_e32 v192, 0x70, v217
	v_mov_b32_e32 v0, 0
	s_mov_b32 s3, 0
	v_lshl_add_u64 v[140:141], s[14:15], 0, v[192:193]
	v_lshl_add_u64 v[142:143], s[16:17], 0, v[192:193]
	v_mul_u32_u24_e32 v173, 0xc0, v215
	v_lshlrev_b32_e32 v174, 1, v216
	v_mov_b32_e32 v52, v0
	v_mov_b32_e32 v53, v0
	v_mov_b32_e32 v54, v0
	v_mov_b32_e32 v55, v0
	v_mov_b32_e32 v56, v0
	v_mov_b32_e32 v57, v0
	v_mov_b32_e32 v58, v0
	v_mov_b32_e32 v59, v0
	v_mov_b32_e32 v60, v0
	v_mov_b32_e32 v61, v0
	v_mov_b32_e32 v62, v0
	v_mov_b32_e32 v63, v0
	v_mov_b32_e32 v64, v0
	v_mov_b32_e32 v65, v0
	v_mov_b32_e32 v66, v0
	v_mov_b32_e32 v67, v0
	v_mov_b32_e32 v68, v0
	v_mov_b32_e32 v69, v0
	v_mov_b32_e32 v70, v0
	v_mov_b32_e32 v71, v0
	v_mov_b32_e32 v72, v0
	v_mov_b32_e32 v73, v0
	v_mov_b32_e32 v74, v0
	v_mov_b32_e32 v75, v0
	v_mov_b32_e32 v76, v0
	v_mov_b32_e32 v77, v0
	v_mov_b32_e32 v78, v0
	v_mov_b32_e32 v79, v0
	v_mov_b32_e32 v144, v0
	v_mov_b32_e32 v145, v0
	s_waitcnt vmcnt(7)
	v_and_b32_e32 v36, 0xffff0000, v20
	v_lshlrev_b32_e32 v1, 16, v20
	v_lshlrev_b32_e32 v37, 16, v21
	s_waitcnt vmcnt(4)
	ds_write_b128 v139, v[32:35] offset:43104
	v_and_b32_e32 v15, 0xffff0000, v34
	v_lshlrev_b32_e32 v14, 16, v34
	v_mul_f32_e32 v34, v36, v36
	v_fmac_f32_e32 v34, v1, v1
	v_and_b32_e32 v38, 0xffff0000, v21
	v_fmac_f32_e32 v34, v37, v37
	v_lshlrev_b32_e32 v39, 16, v22
	v_fmac_f32_e32 v34, v38, v38
	ds_write_b128 v139, v[20:23] offset:43008
	v_and_b32_e32 v22, 0xffff0000, v22
	v_fmac_f32_e32 v34, v39, v39
	v_lshlrev_b32_e32 v40, 16, v23
	v_fmac_f32_e32 v34, v22, v22
	v_and_b32_e32 v23, 0xffff0000, v23
	v_fmac_f32_e32 v34, v40, v40
	v_lshlrev_b32_e32 v41, 16, v24
	v_fmac_f32_e32 v34, v23, v23
	ds_write_b128 v139, v[24:27] offset:43040
	v_and_b32_e32 v24, 0xffff0000, v24
	v_fmac_f32_e32 v34, v41, v41
	v_lshlrev_b32_e32 v42, 16, v25
	v_fmac_f32_e32 v34, v24, v24
	v_and_b32_e32 v25, 0xffff0000, v25
	v_fmac_f32_e32 v34, v42, v42
	v_lshlrev_b32_e32 v43, 16, v26
	v_fmac_f32_e32 v34, v25, v25
	v_and_b32_e32 v26, 0xffff0000, v26
	v_fmac_f32_e32 v34, v43, v43
	v_lshlrev_b32_e32 v44, 16, v27
	v_fmac_f32_e32 v34, v26, v26
	v_and_b32_e32 v27, 0xffff0000, v27
	v_fmac_f32_e32 v34, v44, v44
	v_lshlrev_b32_e32 v45, 16, v28
	v_fmac_f32_e32 v34, v27, v27
	ds_write_b128 v139, v[28:31] offset:43072
	v_and_b32_e32 v28, 0xffff0000, v28
	v_fmac_f32_e32 v34, v45, v45
	v_lshlrev_b32_e32 v46, 16, v29
	v_fmac_f32_e32 v34, v28, v28
	v_and_b32_e32 v29, 0xffff0000, v29
	v_fmac_f32_e32 v34, v46, v46
	v_lshlrev_b32_e32 v47, 16, v30
	v_fmac_f32_e32 v34, v29, v29
	v_and_b32_e32 v30, 0xffff0000, v30
	v_fmac_f32_e32 v34, v47, v47
	v_lshlrev_b32_e32 v48, 16, v31
	v_fmac_f32_e32 v34, v30, v30
	v_and_b32_e32 v31, 0xffff0000, v31
	v_fmac_f32_e32 v34, v48, v48
	v_lshlrev_b32_e32 v49, 16, v32
	v_fmac_f32_e32 v34, v31, v31
	v_and_b32_e32 v32, 0xffff0000, v32
	v_fmac_f32_e32 v34, v49, v49
	v_lshlrev_b32_e32 v50, 16, v33
	v_fmac_f32_e32 v34, v32, v32
	v_and_b32_e32 v33, 0xffff0000, v33
	v_fmac_f32_e32 v34, v50, v50
	v_pk_mul_f32 v[14:15], v[14:15], v[14:15]
	v_fmac_f32_e32 v34, v33, v33
	v_and_b32_e32 v21, 0xffff0000, v35
	v_lshlrev_b32_e32 v20, 16, v35
	v_add_f32_e32 v14, v14, v34
	v_pk_mul_f32 v[20:21], v[20:21], v[20:21]
	v_add_f32_e32 v14, v15, v14
	v_add_f32_e32 v14, v20, v14
	v_add_f32_e32 v14, v21, v14
	v_mov_b32_e32 v15, v14
	s_nop 1
	v_permlane32_swap_b32_e32 v14, v15
	v_add_f32_e32 v14, v14, v15
	v_mul_f32_e32 v15, 0x4f800000, v14
	v_cmp_gt_f32_e32 vcc, s2, v14
	s_waitcnt vmcnt(3)
; __device__ __forceinline__ float bf2f(unsigned short b) { return __uint_as_float((unsigned)b << 16); }
; __device__ __forceinline__ float sum_x32(float v) { auto rr = __builtin_amdgcn_permlane32_swap(__float_as_uint(v), __float_as_uint(v), false, false); return __uint_as_float(rr[0]) + __uint_as_float(rr[1]); }
; __device__ __forceinline__ void attn_pass_A2(const int tid, unsigned char* smem, const bf16_t* Q0w, int qpitch, const bf16_t* Kb, int kpitch, const bf16_t* Vb, int vpitch,
;                                              int b, int ntiles, float kmax, f32x16 (&o)[2][2], float (&linv)[2]) {
;     ...
;     for (int qb = 0; qb < 2; ++qb) {
;         const bf16_t* qp = Q0w + (size_t)(32 * qb + r32) * qpitch + 8 * hi; float ssq = 0.f;
; #pragma unroll
;         for (int ds = 0; ds < 4; ++ds) { const bf16x8 qv = *(const bf16x8*)(qp + 16 * ds); *(bf16x8*)(qs + qb * 32 * KP + ds * 32) = qv;
; #pragma unroll
;             for (int j = 0; j < 8; ++j) { const float f = bf2f((unsigned short)qv[j]); ssq += f * f; } }
;         nshift[qb] = -sqrtf(sum_x32(ssq)) * kmax;
; #pragma unroll
;         for (int d0 = 0; d0 < 2; ++d0)
; #pragma unroll
;             for (int r = 0; r < 16; ++r) o[qb][d0][r] = 0.f;
;     }
;     const int krow = tid >> 3, kch = tid & 7;
;     u32x4 kreg, vreg;
;     auto gload = [&](int kt) {
;         const size_t rb = kt < 4 ? (size_t)(NLAT + 256 * b + 64 * kt) : (size_t)(SEQ * b + 64 * (kt - 4));
;         kreg = *(const u32x4*)(Kb + (rb + krow) * kpitch + 8 * kch); vreg = *(const u32x4*)(Vb + (rb + krow) * vpitch + 8 * kch);
;     };
;     auto lwrite = [&](int buf) { unsigned char* Ks = smem + buf * BUF; *(u32x4*)(Ks + krow * KP + 16 * kch) = kreg; *(u32x4*)(Ks + KBYTES + krow * VP + 16 * kch) = vreg; };
;     gload(0); lwrite(0); __syncthreads();
	ds_write_b128 v139, v[16:19] offset:47616
	v_lshlrev_b32_e32 v35, 16, v16
	v_cndmask_b32_e32 v14, v14, v15, vcc
	v_sqrt_f32_e32 v15, v14
	v_and_b32_e32 v16, 0xffff0000, v16
	v_mul_f32_e32 v1, v16, v16
	v_lshlrev_b32_e32 v36, 16, v17
	v_fmac_f32_e32 v1, v35, v35
	v_and_b32_e32 v17, 0xffff0000, v17
	v_fmac_f32_e32 v1, v36, v36
	v_add_u32_e32 v16, -1, v15
	v_fmac_f32_e32 v1, v17, v17
	v_add_u32_e32 v17, 1, v15
	v_fma_f32 v20, -v16, v15, v14
	v_fma_f32 v21, -v17, v15, v14
	v_cmp_ge_f32_e64 s[0:1], 0, v20
	v_lshlrev_b32_e32 v51, 16, v18
	v_fmac_f32_e32 v1, v51, v51
	v_cndmask_b32_e64 v15, v15, v16, s[0:1]
	v_cmp_lt_f32_e64 s[0:1], 0, v21
	v_mov_b32_e32 v32, v0
	v_mov_b32_e32 v33, v0
	v_cndmask_b32_e64 v15, v15, v17, s[0:1]
	v_mul_f32_e32 v16, 0x37800000, v15
	v_cndmask_b32_e32 v15, v15, v16, vcc
	v_cmp_class_f32_e32 vcc, v14, v227
	s_lshl_b32 s0, s10, 8
	s_add_i32 s0, s0, 0x8000
	v_cndmask_b32_e32 v14, v15, v14, vcc
	v_mul_f32_e64 v16, v214, -v14
	v_and_b32_e32 v14, 0xffff0000, v18
	v_fmac_f32_e32 v1, v14, v14
	v_lshlrev_b32_e32 v14, 16, v19
	s_ashr_i32 s1, s0, 31
	v_fmac_f32_e32 v1, v14, v14
	v_lshl_add_u64 v[14:15], s[0:1], 0, v[136:137]
	v_lshlrev_b64 v[14:15], 8, v[14:15]
	v_and_b32_e32 v17, 0xffff0000, v19
	v_lshl_add_u64 v[18:19], s[14:15], 0, v[14:15]
	v_lshl_add_u64 v[18:19], v[18:19], 0, v[192:193]
	v_lshl_add_u64 v[14:15], s[16:17], 0, v[14:15]
	global_load_dwordx4 v[128:131], v[18:19], off
	v_lshl_add_u64 v[14:15], v[14:15], 0, v[192:193]
	global_load_dwordx4 v[132:135], v[14:15], off
	v_fmac_f32_e32 v1, v17, v17
	s_waitcnt vmcnt(4)
	v_lshlrev_b32_e32 v14, 16, v2
	v_fmac_f32_e32 v1, v14, v14
	v_and_b32_e32 v14, 0xffff0000, v2
	v_fmac_f32_e32 v1, v14, v14
	v_lshlrev_b32_e32 v14, 16, v3
	v_fmac_f32_e32 v1, v14, v14
	v_and_b32_e32 v14, 0xffff0000, v3
	v_fmac_f32_e32 v1, v14, v14
	v_lshlrev_b32_e32 v14, 16, v4
	v_fmac_f32_e32 v1, v14, v14
	v_and_b32_e32 v14, 0xffff0000, v4
	v_fmac_f32_e32 v1, v14, v14
	v_lshlrev_b32_e32 v14, 16, v5
	v_fmac_f32_e32 v1, v14, v14
	v_and_b32_e32 v14, 0xffff0000, v5
	v_fmac_f32_e32 v1, v14, v14
	s_waitcnt vmcnt(3)
	v_lshlrev_b32_e32 v14, 16, v6
	v_fmac_f32_e32 v1, v14, v14
	v_and_b32_e32 v14, 0xffff0000, v6
	v_fmac_f32_e32 v1, v14, v14
	v_lshlrev_b32_e32 v14, 16, v7
	v_fmac_f32_e32 v1, v14, v14
	v_and_b32_e32 v14, 0xffff0000, v7
	v_fmac_f32_e32 v1, v14, v14
	v_lshlrev_b32_e32 v14, 16, v8
	v_fmac_f32_e32 v1, v14, v14
	v_and_b32_e32 v14, 0xffff0000, v8
	v_fmac_f32_e32 v1, v14, v14
	v_lshlrev_b32_e32 v14, 16, v9
	v_fmac_f32_e32 v1, v14, v14
	v_and_b32_e32 v14, 0xffff0000, v9
	v_fmac_f32_e32 v1, v14, v14
	s_waitcnt vmcnt(2)
	v_lshlrev_b32_e32 v14, 16, v10
	v_fmac_f32_e32 v1, v14, v14
	v_and_b32_e32 v14, 0xffff0000, v10
	v_fmac_f32_e32 v1, v14, v14
	v_lshlrev_b32_e32 v14, 16, v11
	v_fmac_f32_e32 v1, v14, v14
	v_and_b32_e32 v14, 0xffff0000, v11
	v_fmac_f32_e32 v1, v14, v14
	v_and_b32_e32 v15, 0xffff0000, v12
	v_lshlrev_b32_e32 v14, 16, v12
	v_pk_mul_f32 v[14:15], v[14:15], v[14:15]
	ds_write_b128 v139, v[2:5] offset:47648
	ds_write_b128 v139, v[6:9] offset:47680
	ds_write_b128 v139, v[10:13] offset:47712
	v_add_f32_e32 v1, v14, v1
	v_add_f32_e32 v1, v15, v1
	v_and_b32_e32 v15, 0xffff0000, v13
	v_lshlrev_b32_e32 v14, 16, v13
	v_pk_mul_f32 v[14:15], v[14:15], v[14:15]
	v_mov_b32_e32 v17, v16
	v_add_f32_e32 v1, v14, v1
	v_add_f32_e32 v1, v15, v1
	v_mov_b32_e32 v14, v1
	s_nop 1
	v_permlane32_swap_b32_e32 v1, v14
	v_add_f32_e32 v1, v1, v14
	v_mul_f32_e32 v14, 0x4f800000, v1
	v_cmp_gt_f32_e32 vcc, s2, v1
	v_mov_b32_e32 v18, v16
	v_mov_b32_e32 v19, v16
	v_cndmask_b32_e32 v1, v1, v14, vcc
	v_sqrt_f32_e32 v14, v1
	v_mov_b32_e32 v20, v16
	v_mov_b32_e32 v21, v16
	v_mov_b32_e32 v22, v16
	v_add_u32_e32 v2, -1, v14
	v_fma_f32 v3, -v2, v14, v1
	v_cmp_ge_f32_e64 s[0:1], 0, v3
	v_add_u32_e32 v3, 1, v14
	v_fma_f32 v4, -v3, v14, v1
	v_cndmask_b32_e64 v2, v14, v2, s[0:1]
	v_cmp_lt_f32_e64 s[0:1], 0, v4
	v_mov_b32_e32 v23, v16
	v_mov_b32_e32 v24, v16
	v_cndmask_b32_e64 v2, v2, v3, s[0:1]
	v_mul_f32_e32 v3, 0x37800000, v2
	v_cndmask_b32_e32 v2, v2, v3, vcc
	v_cmp_class_f32_e32 vcc, v1, v227
	s_movk_i32 s0, 0xc0
	v_mul_lo_u32 v172, v136, s0
	v_cndmask_b32_e32 v1, v2, v1, vcc
	v_add3_u32 v2, 0, v212, v192
	v_mul_f32_e64 v80, v214, -v1
	s_waitcnt vmcnt(1)
	ds_write_b128 v2, v[128:131]
	v_mad_u64_u32 v[2:3], s[0:1], v136, 48, v[2:3]
	s_waitcnt vmcnt(0)
	ds_write_b128 v2, v[132:135] offset:9216
	v_mov_b32_e32 v25, v16
	v_mov_b32_e32 v26, v16
	v_mov_b32_e32 v27, v16
	v_mov_b32_e32 v28, v16
	v_mov_b32_e32 v29, v16
	v_mov_b32_e32 v30, v16
	v_mov_b32_e32 v31, v16
	v_mov_b32_e32 v81, v80
	v_mov_b32_e32 v82, v80
	v_mov_b32_e32 v83, v80
	v_mov_b32_e32 v84, v80
	v_mov_b32_e32 v85, v80
	v_mov_b32_e32 v86, v80
	v_mov_b32_e32 v87, v80
	v_mov_b32_e32 v88, v80
	v_mov_b32_e32 v89, v80
	v_mov_b32_e32 v90, v80
	v_mov_b32_e32 v91, v80
	v_mov_b32_e32 v92, v80
	v_mov_b32_e32 v93, v80
	v_mov_b32_e32 v94, v80
	v_mov_b32_e32 v95, v80
	s_mov_b32 s2, 64
	v_mov_b32_e32 v1, v0
	v_mov_b32_e32 v2, v0
	v_mov_b32_e32 v3, v0
	v_mov_b32_e32 v4, v0
	v_mov_b32_e32 v5, v0
	v_mov_b32_e32 v6, v0
	v_mov_b32_e32 v7, v0
	v_mov_b32_e32 v8, v0
	v_mov_b32_e32 v9, v0
	v_mov_b32_e32 v10, v0
	v_mov_b32_e32 v11, v0
	v_mov_b32_e32 v12, v0
	v_mov_b32_e32 v13, v0
	v_mov_b32_e32 v14, v0
	v_mov_b32_e32 v15, v0
	v_mov_b32_e32 v34, v0
	v_mov_b32_e32 v35, v0
	v_mov_b32_e32 v36, v0
	v_mov_b32_e32 v37, v0
	v_mov_b32_e32 v38, v0
	v_mov_b32_e32 v39, v0
	v_mov_b32_e32 v40, v0
	v_mov_b32_e32 v41, v0
	v_mov_b32_e32 v42, v0
	v_mov_b32_e32 v43, v0
	v_mov_b32_e32 v44, v0
	v_mov_b32_e32 v45, v0
	v_mov_b32_e32 v46, v0
	v_mov_b32_e32 v47, v0
	v_mov_b32_e32 v48, v0
	v_mov_b32_e32 v49, v0
	v_mov_b32_e32 v50, v0
	v_mov_b32_e32 v51, v0
	s_waitcnt lgkmcnt(0)
	s_barrier
; __device__ __forceinline__ void attn_pass_A2(const int tid, unsigned char* smem, const bf16_t* Q0w, int qpitch, const bf16_t* Kb, int kpitch, const bf16_t* Vb, int vpitch,
;                                              int b, int ntiles, float kmax, f32x16 (&o)[2][2], float (&linv)[2]) {
;     ...
;     const int krow = tid >> 3, kch = tid & 7;
;     u32x4 kreg, vreg;
;     auto gload = [&](int kt) {
;         const size_t rb = kt < 4 ? (size_t)(NLAT + 256 * b + 64 * kt) : (size_t)(SEQ * b + 64 * (kt - 4));
;         kreg = *(const u32x4*)(Kb + (rb + krow) * kpitch + 8 * kch); vreg = *(const u32x4*)(Vb + (rb + krow) * vpitch + 8 * kch);
;     };
;     auto lwrite = [&](int buf) { unsigned char* Ks = smem + buf * BUF; *(u32x4*)(Ks + krow * KP + 16 * kch) = kreg; *(u32x4*)(Ks + KBYTES + krow * VP + 16 * kch) = vreg; };
;     gload(0); lwrite(0); __syncthreads();
;     const int nhalf = (lane >> 4) & 1, q4 = (lane & 15) >> 2, p4 = lane & 3;
;     for (int kt = 0; kt < ntiles; ++kt) {
;         if (kt + 1 < ntiles) gload(kt + 1);
;         const unsigned char* Ks = smem + (kt & 1) * BUF; const unsigned char* Vs = Ks + KBYTES;
;         const unsigned char* kp = Ks + r32 * KP + hi * 16;
;         const unsigned char* vp = Vs + (4 * hi + q4) * VP + (16 * nhalf + 4 * p4) * 2;
; #pragma unroll
;         for (int kb = 0; kb < 2; ++kb) {
;             bf16x8 pf[2][2];
;             {
;                 f32x16 s0, s1;
; #pragma unroll
;                 for (int r = 0; r < 16; ++r) { s0[r] = nshift[0]; s1[r] = nshift[1]; }
; #pragma unroll
;                 for (int ds = 0; ds < 4; ++ds) {
;                     const bf16x8 kf = *(const bf16x8*)(kp + kb * 32 * KP + ds * 32);
;                     const bf16x8 q0 = *(const bf16x8*)(qs + ds * 32), q1 = *(const bf16x8*)(qs + 32 * KP + ds * 32);
;                     s0 = __builtin_amdgcn_mfma_f32_32x32x16_bf16(kf, q0, s0, 0, 0, 0);
;                     s1 = __builtin_amdgcn_mfma_f32_32x32x16_bf16(kf, q1, s1, 0, 0, 0);
;                 }
	s_mov_b64 s[66:67], s[14:15]
	s_mov_b64 s[68:69], s[16:17]
	s_lshl_b32 s2, s10, 8
	s_add_i32 s65, s2, 0x8000
	s_lshl_b32 s2, s10, 13
	s_add_i32 s32, s2, 0xffffff00
	s_lshr_b32 s56, s27, 6
	s_lshl_b32 s56, s56, 10
	v_and_b32_e32 v132, 7, v197
	v_bfe_u32 v133, v136, 1, 3
	v_xor_b32_e32 v133, v133, v132
	v_lshlrev_b32_e32 v133, 4, v133
	v_lshl_add_u32 v236, v136, 8, v133
	v_bfe_u32 v134, v136, 1, 1
	v_lshlrev_b32_e32 v134, 2, v134
	v_xor_b32_e32 v134, v134, v132
	v_lshlrev_b32_e32 v134, 4, v134
	v_lshl_add_u32 v234, v136, 8, v134
	s_mov_b32 s59, 0
	s_waitcnt vmcnt(0)
	s_add_i32 s70, s59, 0
	s_cmp_lt_u32 s70, 4
	s_cselect_b32 s2, s65, s32
	s_lshl_b32 s3, s70, 6
	s_add_i32 s2, s2, s3
	s_lshl_b32 s2, s2, 8
	s_add_u32 s60, s66, s2
	s_addc_u32 s61, s67, 0
	s_add_u32 s62, s68, s2
	s_addc_u32 s63, s69, 0
	s_mov_b32 m0, s56
	s_nop 0
	global_load_lds_dwordx4 v236, s[60:61]
	s_add_i32 m0, s56, 0x2000
	s_nop 0
	global_load_lds_dwordx4 v234, s[62:63]
	s_add_i32 s70, s59, 1
	s_cmp_lt_u32 s70, 4
	s_cselect_b32 s2, s65, s32
	s_lshl_b32 s3, s70, 6
	s_add_i32 s2, s2, s3
	s_lshl_b32 s2, s2, 8
	s_add_u32 s60, s66, s2
	s_addc_u32 s61, s67, 0
	s_add_u32 s62, s68, s2
	s_addc_u32 s63, s69, 0
	s_add_i32 m0, s56, 0x4000
	s_nop 0
	global_load_lds_dwordx4 v236, s[60:61]
	s_add_i32 m0, s56, 0x6000
	s_nop 0
	global_load_lds_dwordx4 v234, s[62:63]
	v_min_f32_e32 v16, v16, v80
	v_mov_b32_e32 v17, v16
	v_mov_b32_e32 v18, v16
	v_mov_b32_e32 v19, v16
	v_mov_b32_e32 v20, v16
	v_mov_b32_e32 v21, v16
	v_mov_b32_e32 v22, v16
	v_mov_b32_e32 v23, v16
	v_mov_b32_e32 v24, v16
	v_mov_b32_e32 v25, v16
	v_mov_b32_e32 v26, v16
	v_mov_b32_e32 v27, v16
	v_mov_b32_e32 v28, v16
	v_mov_b32_e32 v29, v16
	v_mov_b32_e32 v30, v16
	v_mov_b32_e32 v31, v16
	ds_read_b128 v[146:149], v139 offset:43008
	ds_read_b128 v[150:153], v139 offset:43040
	ds_read_b128 v[154:157], v139 offset:43072
	ds_read_b128 v[158:161], v139 offset:43104
	ds_read_b128 v[176:179], v139 offset:47616
	ds_read_b128 v[180:183], v139 offset:47648
	ds_read_b128 v[184:187], v139 offset:47680
	ds_read_b128 v[188:191], v139 offset:47712
	v_bfe_u32 v132, v218, 1, 3
	v_lshrrev_b32_e32 v133, 4, v138
	v_xor_b32_e32 v132, v132, v133
	v_xor_b32_e32 v133, 0, v132
	v_lshlrev_b32_e32 v133, 4, v133
	v_lshl_or_b32 v170, v218, 7, v133
	v_xor_b32_e32 v133, 2, v132
	v_lshlrev_b32_e32 v133, 4, v133
	v_lshl_or_b32 v171, v218, 7, v133
	v_xor_b32_e32 v133, 4, v132
	v_lshlrev_b32_e32 v133, 4, v133
	v_lshl_or_b32 v210, v218, 7, v133
	v_xor_b32_e32 v133, 6, v132
	v_lshlrev_b32_e32 v133, 4, v133
	v_lshl_or_b32 v222, v218, 7, v133
	v_bfe_u32 v134, v215, 1, 1
	v_xor_b32_e32 v135, 0, v134
	v_lshl_add_u32 v135, v135, 6, v174
	v_lshl_add_u32 v223, v215, 7, v135
	v_xor_b32_e32 v135, 1, v134
	v_lshl_add_u32 v135, v135, 6, v174
	v_lshl_add_u32 v224, v215, 7, v135
	s_waitcnt vmcnt(0) lgkmcnt(0)
	s_barrier
	s_add_i32 s70, s59, 2
	s_cmp_lt_u32 s70, 4
	s_cselect_b32 s2, s65, s32
	s_lshl_b32 s3, s70, 6
	s_add_i32 s2, s2, s3
	s_lshl_b32 s2, s2, 8
	s_add_u32 s60, s66, s2
	s_addc_u32 s61, s67, 0
	s_add_u32 s62, s68, s2
	s_addc_u32 s63, s69, 0
	s_add_i32 m0, s56, 0x8000
	s_nop 0
	global_load_lds_dwordx4 v236, s[60:61]
	s_add_i32 m0, s56, 0xa000
	s_nop 0
	global_load_lds_dwordx4 v234, s[62:63]
	ds_read_b128 v[198:201], v170
	ds_read_b128 v[202:205], v171
	ds_read_b128 v[206:209], v210
	ds_read_b128 v[128:131], v222
	s_waitcnt lgkmcnt(3)
	v_mfma_f32_32x32x16_bf16 v[80:95], v[198:201], v[146:149], v[16:31]
	s_waitcnt lgkmcnt(2)
	v_mfma_f32_32x32x16_bf16 v[80:95], v[202:205], v[150:153], v[80:95]
	s_waitcnt lgkmcnt(1)
	v_mfma_f32_32x32x16_bf16 v[80:95], v[206:209], v[154:157], v[80:95]
	s_waitcnt lgkmcnt(0)
	v_mfma_f32_32x32x16_bf16 v[80:95], v[128:131], v[158:161], v[80:95]
	s_nop 7
	s_nop 3
	v_mfma_f32_32x32x16_bf16 v[96:111], v[198:201], v[176:179], v[16:31]
	ds_read_b128 v[198:201], v170 offset:4096
	v_exp_f32_e32 v80, v80
	v_exp_f32_e32 v81, v81
	v_exp_f32_e32 v82, v82
	v_add_f32_e32 v144, v144, v80
	v_exp_f32_e32 v83, v83
	v_add_f32_e32 v144, v144, v81
	v_cvt_pk_bf16_f32 v112, v80, v81
	v_exp_f32_e32 v84, v84
	v_add_f32_e32 v144, v144, v82
	v_exp_f32_e32 v85, v85
	v_add_f32_e32 v144, v144, v83
	v_cvt_pk_bf16_f32 v113, v82, v83
	v_exp_f32_e32 v86, v86
	v_mfma_f32_32x32x16_bf16 v[96:111], v[202:205], v[180:183], v[96:111]
	ds_read_b128 v[202:205], v171 offset:4096
	v_add_f32_e32 v144, v144, v84
	v_exp_f32_e32 v87, v87
	v_add_f32_e32 v144, v144, v85
	v_cvt_pk_bf16_f32 v114, v84, v85
	v_exp_f32_e32 v88, v88
	v_add_f32_e32 v144, v144, v86
	v_exp_f32_e32 v89, v89
	v_add_f32_e32 v144, v144, v87
	v_cvt_pk_bf16_f32 v115, v86, v87
	v_exp_f32_e32 v90, v90
	v_add_f32_e32 v144, v144, v88
	v_exp_f32_e32 v91, v91
	v_add_f32_e32 v144, v144, v89
	v_mfma_f32_32x32x16_bf16 v[96:111], v[206:209], v[184:187], v[96:111]
	ds_read_b128 v[206:209], v210 offset:4096
	v_cvt_pk_bf16_f32 v116, v88, v89
	v_exp_f32_e32 v92, v92
	v_add_f32_e32 v144, v144, v90
	v_exp_f32_e32 v93, v93
	v_add_f32_e32 v144, v144, v91
	v_cvt_pk_bf16_f32 v117, v90, v91
	v_exp_f32_e32 v94, v94
	v_add_f32_e32 v144, v144, v92
	v_exp_f32_e32 v95, v95
	v_add_f32_e32 v144, v144, v93
	v_cvt_pk_bf16_f32 v118, v92, v93
	v_add_f32_e32 v144, v144, v94
	v_add_f32_e32 v144, v144, v95
	v_cvt_pk_bf16_f32 v119, v94, v95
	v_mfma_f32_32x32x16_bf16 v[96:111], v[128:131], v[188:191], v[96:111]
	ds_read_b128 v[128:131], v222 offset:4096
	ds_read_b64_tr_b16 v[162:163], v223 offset:8192
	ds_read_b64_tr_b16 v[164:165], v223 offset:9216
	ds_read_b64_tr_b16 v[166:167], v224 offset:8192
	ds_read_b64_tr_b16 v[168:169], v224 offset:9216
	ds_read_b64_tr_b16 v[214:215], v223 offset:10240
	ds_read_b64_tr_b16 v[216:217], v223 offset:11264
	ds_read_b64_tr_b16 v[218:219], v224 offset:10240
	ds_read_b64_tr_b16 v[220:221], v224 offset:11264
	s_waitcnt lgkmcnt(8)
	s_nop 3
	s_add_i32 s71, s25, -7
	s_cmp_lt_i32 s59, s71
	s_cbranch_scc0 .Laattn_tail
; __device__ __forceinline__ void attn_pass_A2(const int tid, unsigned char* smem, const bf16_t* Q0w, int qpitch, const bf16_t* Kb, int kpitch, const bf16_t* Vb, int vpitch,
;                                              int b, int ntiles, float kmax, f32x16 (&o)[2][2], float (&linv)[2]) {
;     ...
;     for (int kt = 0; kt < ntiles; ++kt) {
;         if (kt + 1 < ntiles) gload(kt + 1);
;         const unsigned char* Ks = smem + (kt & 1) * BUF; const unsigned char* Vs = Ks + KBYTES;
;         const unsigned char* kp = Ks + r32 * KP + hi * 16;
;         const unsigned char* vp = Vs + (4 * hi + q4) * VP + (16 * nhalf + 4 * p4) * 2;
; #pragma unroll
;         for (int kb = 0; kb < 2; ++kb) {
;             bf16x8 pf[2][2];
;             {
;                 f32x16 s0, s1;
; #pragma unroll
;                 for (int r = 0; r < 16; ++r) { s0[r] = nshift[0]; s1[r] = nshift[1]; }
; #pragma unroll
;                 for (int ds = 0; ds < 4; ++ds) {
;                     const bf16x8 kf = *(const bf16x8*)(kp + kb * 32 * KP + ds * 32);
;                     const bf16x8 q0 = *(const bf16x8*)(qs + ds * 32), q1 = *(const bf16x8*)(qs + 32 * KP + ds * 32);
;                     s0 = __builtin_amdgcn_mfma_f32_32x32x16_bf16(kf, q0, s0, 0, 0, 0);
;                     s1 = __builtin_amdgcn_mfma_f32_32x32x16_bf16(kf, q1, s1, 0, 0, 0);
;                 }
;                 float l0 = 0.f, l1 = 0.f;
; #pragma unroll
;                 for (int r = 0; r < 16; ++r) { s0[r] = __builtin_amdgcn_exp2f(s0[r]); l0 += s0[r]; }
; #pragma unroll
;                 for (int r = 0; r < 16; ++r) { s1[r] = __builtin_amdgcn_exp2f(s1[r]); l1 += s1[r]; }
;                 lsum[0] += l0; lsum[1] += l1;
; #pragma unroll
;                 for (int j = 0; j < 2; ++j) {
;                     u32x4 w0, w1;
;                     w0.x = cvt_pk_bf16(s0[8 * j + 0], s0[8 * j + 1]); w0.y = cvt_pk_bf16(s0[8 * j + 2], s0[8 * j + 3]); w0.z = cvt_pk_bf16(s0[8 * j + 4], s0[8 * j + 5]); w0.w = cvt_pk_bf16(s0[8 * j + 6], s0[8 * j + 7]);
;                     w1.x = cvt_pk_bf16(s1[8 * j + 0], s1[8 * j + 1]); w1.y = cvt_pk_bf16(s1[8 * j + 2], s1[8 * j + 3]); w1.z = cvt_pk_bf16(s1[8 * j + 4], s1[8 * j + 5]); w1.w = cvt_pk_bf16(s1[8 * j + 6], s1[8 * j + 7]);
;                     pf[0][j] = __builtin_bit_cast(bf16x8, w0); pf[1][j] = __builtin_bit_cast(bf16x8, w1);
;                 }
;             }
.Laattn_loop:
	v_mfma_f32_32x32x16_bf16 v[80:95], v[198:201], v[146:149], v[16:31]
	v_exp_f32_e32 v96, v96
	v_exp_f32_e32 v97, v97
	v_exp_f32_e32 v98, v98
	v_add_f32_e32 v145, v145, v96
	v_exp_f32_e32 v99, v99
	v_mfma_f32_32x32x16_bf16 v[80:95], v[202:205], v[150:153], v[80:95]
	s_add_i32 s70, s59, 3
	s_cmp_lt_u32 s70, 4
	s_cselect_b32 s2, s65, s32
	s_lshl_b32 s3, s70, 6
	s_add_i32 s2, s2, s3
	s_lshl_b32 s2, s2, 8
	s_add_u32 s60, s66, s2
	s_addc_u32 s61, s67, 0
	s_add_u32 s62, s68, s2
	s_addc_u32 s63, s69, 0
	v_add_f32_e32 v145, v145, v97
	v_cvt_pk_bf16_f32 v120, v96, v97
	v_exp_f32_e32 v100, v100
	v_add_f32_e32 v145, v145, v98
	v_exp_f32_e32 v101, v101
	v_mfma_f32_32x32x16_bf16 v[80:95], v[206:209], v[154:157], v[80:95]
	v_add_f32_e32 v145, v145, v99
	v_cvt_pk_bf16_f32 v121, v98, v99
	v_exp_f32_e32 v102, v102
	v_add_f32_e32 v145, v145, v100
	v_exp_f32_e32 v103, v103
	v_add_f32_e32 v145, v145, v101
	v_mfma_f32_32x32x16_bf16 v[80:95], v[128:131], v[158:161], v[80:95]
	s_add_i32 m0, s56, 0xc000
	s_nop 0
	global_load_lds_dwordx4 v236, s[60:61]
	v_cvt_pk_bf16_f32 v122, v100, v101
	v_exp_f32_e32 v104, v104
	v_add_f32_e32 v145, v145, v102
	v_exp_f32_e32 v105, v105
	v_add_f32_e32 v145, v145, v103
	v_cvt_pk_bf16_f32 v123, v102, v103
	s_waitcnt lgkmcnt(6)
	v_mfma_f32_32x32x16_bf16 v[64:79], v[162:165], v[112:115], v[64:79]
	v_exp_f32_e32 v106, v106
	v_add_f32_e32 v145, v145, v104
	v_exp_f32_e32 v107, v107
	v_add_f32_e32 v145, v145, v105
	v_cvt_pk_bf16_f32 v124, v104, v105
	v_exp_f32_e32 v108, v108
	s_waitcnt lgkmcnt(4)
	v_mfma_f32_32x32x16_bf16 v[48:63], v[166:169], v[112:115], v[48:63]
	s_add_i32 m0, s56, 0xe000
	s_nop 0
	global_load_lds_dwordx4 v234, s[62:63]
	v_add_f32_e32 v145, v145, v106
	v_exp_f32_e32 v109, v109
	v_add_f32_e32 v145, v145, v107
	v_cvt_pk_bf16_f32 v125, v106, v107
	v_exp_f32_e32 v110, v110
	s_waitcnt lgkmcnt(2)
	v_mfma_f32_32x32x16_bf16 v[64:79], v[214:217], v[116:119], v[64:79]
	v_add_f32_e32 v145, v145, v108
	v_exp_f32_e32 v111, v111
	v_add_f32_e32 v145, v145, v109
	v_cvt_pk_bf16_f32 v126, v108, v109
	v_add_f32_e32 v145, v145, v110
	v_add_f32_e32 v145, v145, v111
	v_cvt_pk_bf16_f32 v127, v110, v111
	s_waitcnt lgkmcnt(0)
	v_mfma_f32_32x32x16_bf16 v[48:63], v[218:221], v[116:119], v[48:63]
	v_mfma_f32_32x32x16_bf16 v[96:111], v[198:201], v[176:179], v[16:31]
	ds_read_b128 v[198:201], v170 offset:16384
	v_exp_f32_e32 v80, v80
	v_exp_f32_e32 v81, v81
	v_exp_f32_e32 v82, v82
	v_add_f32_e32 v144, v144, v80
	v_exp_f32_e32 v83, v83
	v_mfma_f32_32x32x16_bf16 v[96:111], v[202:205], v[180:183], v[96:111]
	ds_read_b128 v[202:205], v171 offset:16384
	v_add_f32_e32 v144, v144, v81
	v_cvt_pk_bf16_f32 v112, v80, v81
	v_exp_f32_e32 v84, v84
	v_add_f32_e32 v144, v144, v82
	v_exp_f32_e32 v85, v85
	v_mfma_f32_32x32x16_bf16 v[96:111], v[206:209], v[184:187], v[96:111]
	ds_read_b128 v[206:209], v210 offset:16384
	v_add_f32_e32 v144, v144, v83
	v_cvt_pk_bf16_f32 v113, v82, v83
	v_exp_f32_e32 v86, v86
	v_add_f32_e32 v144, v144, v84
	v_exp_f32_e32 v87, v87
	v_add_f32_e32 v144, v144, v85
	v_mfma_f32_32x32x16_bf16 v[96:111], v[128:131], v[188:191], v[96:111]
	ds_read_b128 v[128:131], v222 offset:16384
	v_cvt_pk_bf16_f32 v114, v84, v85
	v_exp_f32_e32 v88, v88
	v_add_f32_e32 v144, v144, v86
	v_exp_f32_e32 v89, v89
	v_add_f32_e32 v144, v144, v87
	v_cvt_pk_bf16_f32 v115, v86, v87
	v_mfma_f32_32x32x16_bf16 v[32:47], v[162:165], v[120:123], v[32:47]
	ds_read_b64_tr_b16 v[162:163], v223 offset:12288
	ds_read_b64_tr_b16 v[164:165], v223 offset:13312
	v_exp_f32_e32 v90, v90
	v_add_f32_e32 v144, v144, v88
	v_exp_f32_e32 v91, v91
	v_add_f32_e32 v144, v144, v89
	v_cvt_pk_bf16_f32 v116, v88, v89
	v_exp_f32_e32 v92, v92
	v_mfma_f32_32x32x16_bf16 v[0:15], v[166:169], v[120:123], v[0:15]
	ds_read_b64_tr_b16 v[166:167], v224 offset:12288
	ds_read_b64_tr_b16 v[168:169], v224 offset:13312
	v_add_f32_e32 v144, v144, v90
	v_exp_f32_e32 v93, v93
	v_add_f32_e32 v144, v144, v91
	v_cvt_pk_bf16_f32 v117, v90, v91
	v_exp_f32_e32 v94, v94
	v_mfma_f32_32x32x16_bf16 v[32:47], v[214:217], v[124:127], v[32:47]
	ds_read_b64_tr_b16 v[214:215], v223 offset:14336
	ds_read_b64_tr_b16 v[216:217], v223 offset:15360
	v_add_f32_e32 v144, v144, v92
	v_exp_f32_e32 v95, v95
	v_add_f32_e32 v144, v144, v93
	v_cvt_pk_bf16_f32 v118, v92, v93
	v_add_f32_e32 v144, v144, v94
	v_add_f32_e32 v144, v144, v95
	v_cvt_pk_bf16_f32 v119, v94, v95
	v_mfma_f32_32x32x16_bf16 v[0:15], v[218:221], v[124:127], v[0:15]
	ds_read_b64_tr_b16 v[218:219], v224 offset:14336
	ds_read_b64_tr_b16 v[220:221], v224 offset:15360
	s_waitcnt lgkmcnt(11)
	v_mfma_f32_32x32x16_bf16 v[80:95], v[198:201], v[146:149], v[16:31]
	v_exp_f32_e32 v96, v96
	v_exp_f32_e32 v97, v97
	v_exp_f32_e32 v98, v98
	v_add_f32_e32 v145, v145, v96
	v_exp_f32_e32 v99, v99
	s_waitcnt lgkmcnt(10)
	v_mfma_f32_32x32x16_bf16 v[80:95], v[202:205], v[150:153], v[80:95]
	v_add_f32_e32 v145, v145, v97
	v_cvt_pk_bf16_f32 v120, v96, v97
	v_exp_f32_e32 v100, v100
	v_add_f32_e32 v145, v145, v98
	v_exp_f32_e32 v101, v101
	s_waitcnt lgkmcnt(9)
	v_mfma_f32_32x32x16_bf16 v[80:95], v[206:209], v[154:157], v[80:95]
	v_add_f32_e32 v145, v145, v99
	v_cvt_pk_bf16_f32 v121, v98, v99
	v_exp_f32_e32 v102, v102
	v_add_f32_e32 v145, v145, v100
	v_exp_f32_e32 v103, v103
	v_add_f32_e32 v145, v145, v101
	s_waitcnt lgkmcnt(8)
	v_mfma_f32_32x32x16_bf16 v[80:95], v[128:131], v[158:161], v[80:95]
	v_cvt_pk_bf16_f32 v122, v100, v101
	v_exp_f32_e32 v104, v104
	v_add_f32_e32 v145, v145, v102
	v_exp_f32_e32 v105, v105
	v_add_f32_e32 v145, v145, v103
	v_cvt_pk_bf16_f32 v123, v102, v103
	s_waitcnt lgkmcnt(6)
; __device__ __forceinline__ void attn_pass_A2(const int tid, unsigned char* smem, const bf16_t* Q0w, int qpitch, const bf16_t* Kb, int kpitch, const bf16_t* Vb, int vpitch,
;                                              int b, int ntiles, float kmax, f32x16 (&o)[2][2], float (&linv)[2]) {
;     ...
;     for (int kt = 0; kt < ntiles; ++kt) {
;         if (kt + 1 < ntiles) gload(kt + 1);
;         const unsigned char* Ks = smem + (kt & 1) * BUF; const unsigned char* Vs = Ks + KBYTES;
;         const unsigned char* kp = Ks + r32 * KP + hi * 16;
;         const unsigned char* vp = Vs + (4 * hi + q4) * VP + (16 * nhalf + 4 * p4) * 2;
; #pragma unroll
;         for (int kb = 0; kb < 2; ++kb) {
;             bf16x8 pf[2][2];
;             {
;                 f32x16 s0, s1;
; #pragma unroll
;                 for (int r = 0; r < 16; ++r) { s0[r] = nshift[0]; s1[r] = nshift[1]; }
; #pragma unroll
;                 for (int ds = 0; ds < 4; ++ds) {
;                     const bf16x8 kf = *(const bf16x8*)(kp + kb * 32 * KP + ds * 32);
;                     const bf16x8 q0 = *(const bf16x8*)(qs + ds * 32), q1 = *(const bf16x8*)(qs + 32 * KP + ds * 32);
;                     s0 = __builtin_amdgcn_mfma_f32_32x32x16_bf16(kf, q0, s0, 0, 0, 0);
;                     s1 = __builtin_amdgcn_mfma_f32_32x32x16_bf16(kf, q1, s1, 0, 0, 0);
;                 }
;                 float l0 = 0.f, l1 = 0.f;
; #pragma unroll
;                 for (int r = 0; r < 16; ++r) { s0[r] = __builtin_amdgcn_exp2f(s0[r]); l0 += s0[r]; }
; #pragma unroll
;                 for (int r = 0; r < 16; ++r) { s1[r] = __builtin_amdgcn_exp2f(s1[r]); l1 += s1[r]; }
;                 lsum[0] += l0; lsum[1] += l1;
; #pragma unroll
;                 for (int j = 0; j < 2; ++j) {
;                     u32x4 w0, w1;
;                     w0.x = cvt_pk_bf16(s0[8 * j + 0], s0[8 * j + 1]); w0.y = cvt_pk_bf16(s0[8 * j + 2], s0[8 * j + 3]); w0.z = cvt_pk_bf16(s0[8 * j + 4], s0[8 * j + 5]); w0.w = cvt_pk_bf16(s0[8 * j + 6], s0[8 * j + 7]);
;                     w1.x = cvt_pk_bf16(s1[8 * j + 0], s1[8 * j + 1]); w1.y = cvt_pk_bf16(s1[8 * j + 2], s1[8 * j + 3]); w1.z = cvt_pk_bf16(s1[8 * j + 4], s1[8 * j + 5]); w1.w = cvt_pk_bf16(s1[8 * j + 6], s1[8 * j + 7]);
;                     pf[0][j] = __builtin_bit_cast(bf16x8, w0); pf[1][j] = __builtin_bit_cast(bf16x8, w1);
;                 }
;             }
	v_mfma_f32_32x32x16_bf16 v[64:79], v[162:165], v[112:115], v[64:79]
	v_exp_f32_e32 v106, v106
	v_add_f32_e32 v145, v145, v104
	v_exp_f32_e32 v107, v107
	v_add_f32_e32 v145, v145, v105
	v_cvt_pk_bf16_f32 v124, v104, v105
	v_exp_f32_e32 v108, v108
	s_waitcnt lgkmcnt(4)
	v_mfma_f32_32x32x16_bf16 v[48:63], v[166:169], v[112:115], v[48:63]
	v_add_f32_e32 v145, v145, v106
	v_exp_f32_e32 v109, v109
	v_add_f32_e32 v145, v145, v107
	v_cvt_pk_bf16_f32 v125, v106, v107
	v_exp_f32_e32 v110, v110
	s_waitcnt lgkmcnt(2)
	v_mfma_f32_32x32x16_bf16 v[64:79], v[214:217], v[116:119], v[64:79]
	v_add_f32_e32 v145, v145, v108
	v_exp_f32_e32 v111, v111
	v_add_f32_e32 v145, v145, v109
	v_cvt_pk_bf16_f32 v126, v108, v109
	v_add_f32_e32 v145, v145, v110
	v_add_f32_e32 v145, v145, v111
	v_cvt_pk_bf16_f32 v127, v110, v111
	s_waitcnt lgkmcnt(0)
	v_mfma_f32_32x32x16_bf16 v[48:63], v[218:221], v[116:119], v[48:63]
	v_mfma_f32_32x32x16_bf16 v[96:111], v[198:201], v[176:179], v[16:31]
	ds_read_b128 v[198:201], v170 offset:20480
	v_exp_f32_e32 v80, v80
	v_exp_f32_e32 v81, v81
	v_exp_f32_e32 v82, v82
	v_add_f32_e32 v144, v144, v80
	v_exp_f32_e32 v83, v83
	v_mfma_f32_32x32x16_bf16 v[96:111], v[202:205], v[180:183], v[96:111]
	ds_read_b128 v[202:205], v171 offset:20480
	v_add_f32_e32 v144, v144, v81
	v_cvt_pk_bf16_f32 v112, v80, v81
	v_exp_f32_e32 v84, v84
	v_add_f32_e32 v144, v144, v82
	v_exp_f32_e32 v85, v85
	v_mfma_f32_32x32x16_bf16 v[96:111], v[206:209], v[184:187], v[96:111]
	ds_read_b128 v[206:209], v210 offset:20480
	v_add_f32_e32 v144, v144, v83
	v_cvt_pk_bf16_f32 v113, v82, v83
	v_exp_f32_e32 v86, v86
	v_add_f32_e32 v144, v144, v84
	v_exp_f32_e32 v87, v87
	v_add_f32_e32 v144, v144, v85
	v_mfma_f32_32x32x16_bf16 v[96:111], v[128:131], v[188:191], v[96:111]
	ds_read_b128 v[128:131], v222 offset:20480
	v_cvt_pk_bf16_f32 v114, v84, v85
	v_exp_f32_e32 v88, v88
	v_add_f32_e32 v144, v144, v86
	v_exp_f32_e32 v89, v89
	v_add_f32_e32 v144, v144, v87
	v_cvt_pk_bf16_f32 v115, v86, v87
	v_mfma_f32_32x32x16_bf16 v[32:47], v[162:165], v[120:123], v[32:47]
	ds_read_b64_tr_b16 v[162:163], v223 offset:24576
	ds_read_b64_tr_b16 v[164:165], v223 offset:25600
	v_exp_f32_e32 v90, v90
	v_add_f32_e32 v144, v144, v88
	v_exp_f32_e32 v91, v91
	v_add_f32_e32 v144, v144, v89
	v_cvt_pk_bf16_f32 v116, v88, v89
	v_exp_f32_e32 v92, v92
	v_mfma_f32_32x32x16_bf16 v[0:15], v[166:169], v[120:123], v[0:15]
	ds_read_b64_tr_b16 v[166:167], v224 offset:24576
	ds_read_b64_tr_b16 v[168:169], v224 offset:25600
	s_add_i32 s59, s59, 1
	v_add_f32_e32 v144, v144, v90
	v_exp_f32_e32 v93, v93
	v_add_f32_e32 v144, v144, v91
	v_cvt_pk_bf16_f32 v117, v90, v91
	v_exp_f32_e32 v94, v94
	v_mfma_f32_32x32x16_bf16 v[32:47], v[214:217], v[124:127], v[32:47]
	ds_read_b64_tr_b16 v[214:215], v223 offset:26624
	ds_read_b64_tr_b16 v[216:217], v223 offset:27648
	v_add_f32_e32 v144, v144, v92
	v_exp_f32_e32 v95, v95
	v_add_f32_e32 v144, v144, v93
	v_cvt_pk_bf16_f32 v118, v92, v93
	v_add_f32_e32 v144, v144, v94
	v_add_f32_e32 v144, v144, v95
	v_cvt_pk_bf16_f32 v119, v94, v95
	v_mfma_f32_32x32x16_bf16 v[0:15], v[218:221], v[124:127], v[0:15]
	ds_read_b64_tr_b16 v[218:219], v224 offset:26624
	ds_read_b64_tr_b16 v[220:221], v224 offset:27648
	s_waitcnt vmcnt(2) lgkmcnt(8)
	s_barrier
	v_mfma_f32_32x32x16_bf16 v[80:95], v[198:201], v[146:149], v[16:31]
	v_exp_f32_e32 v96, v96
	v_exp_f32_e32 v97, v97
	v_exp_f32_e32 v98, v98
	v_add_f32_e32 v145, v145, v96
	v_exp_f32_e32 v99, v99
	v_mfma_f32_32x32x16_bf16 v[80:95], v[202:205], v[150:153], v[80:95]
	s_add_i32 s70, s59, 3
	s_cmp_lt_u32 s70, 4
	s_cselect_b32 s2, s65, s32
	s_lshl_b32 s3, s70, 6
	s_add_i32 s2, s2, s3
	s_lshl_b32 s2, s2, 8
	s_add_u32 s60, s66, s2
	s_addc_u32 s61, s67, 0
	s_add_u32 s62, s68, s2
	s_addc_u32 s63, s69, 0
	v_add_f32_e32 v145, v145, v97
	v_cvt_pk_bf16_f32 v120, v96, v97
	v_exp_f32_e32 v100, v100
	v_add_f32_e32 v145, v145, v98
	v_exp_f32_e32 v101, v101
	v_mfma_f32_32x32x16_bf16 v[80:95], v[206:209], v[154:157], v[80:95]
	v_add_f32_e32 v145, v145, v99
	v_cvt_pk_bf16_f32 v121, v98, v99
	v_exp_f32_e32 v102, v102
	v_add_f32_e32 v145, v145, v100
	v_exp_f32_e32 v103, v103
	v_add_f32_e32 v145, v145, v101
	v_mfma_f32_32x32x16_bf16 v[80:95], v[128:131], v[158:161], v[80:95]
	s_mov_b32 m0, s56
	s_nop 0
	global_load_lds_dwordx4 v236, s[60:61]
	v_cvt_pk_bf16_f32 v122, v100, v101
	v_exp_f32_e32 v104, v104
	v_add_f32_e32 v145, v145, v102
	v_exp_f32_e32 v105, v105
	v_add_f32_e32 v145, v145, v103
	v_cvt_pk_bf16_f32 v123, v102, v103
	s_waitcnt lgkmcnt(6)
	v_mfma_f32_32x32x16_bf16 v[64:79], v[162:165], v[112:115], v[64:79]
	v_exp_f32_e32 v106, v106
	v_add_f32_e32 v145, v145, v104
	v_exp_f32_e32 v107, v107
	v_add_f32_e32 v145, v145, v105
	v_cvt_pk_bf16_f32 v124, v104, v105
	v_exp_f32_e32 v108, v108
	s_waitcnt lgkmcnt(4)
	v_mfma_f32_32x32x16_bf16 v[48:63], v[166:169], v[112:115], v[48:63]
	s_add_i32 m0, s56, 0x2000
	s_nop 0
	global_load_lds_dwordx4 v234, s[62:63]
	v_add_f32_e32 v145, v145, v106
	v_exp_f32_e32 v109, v109
	v_add_f32_e32 v145, v145, v107
	v_cvt_pk_bf16_f32 v125, v106, v107
	v_exp_f32_e32 v110, v110
	s_waitcnt lgkmcnt(2)
	v_mfma_f32_32x32x16_bf16 v[64:79], v[214:217], v[116:119], v[64:79]
	v_add_f32_e32 v145, v145, v108
	v_exp_f32_e32 v111, v111
	v_add_f32_e32 v145, v145, v109
	v_cvt_pk_bf16_f32 v126, v108, v109
	v_add_f32_e32 v145, v145, v110
	v_add_f32_e32 v145, v145, v111
	v_cvt_pk_bf16_f32 v127, v110, v111
	s_waitcnt lgkmcnt(0)
; __device__ __forceinline__ void attn_pass_A2(const int tid, unsigned char* smem, const bf16_t* Q0w, int qpitch, const bf16_t* Kb, int kpitch, const bf16_t* Vb, int vpitch,
;                                              int b, int ntiles, float kmax, f32x16 (&o)[2][2], float (&linv)[2]) {
;     ...
;     for (int kt = 0; kt < ntiles; ++kt) {
;         if (kt + 1 < ntiles) gload(kt + 1);
;         const unsigned char* Ks = smem + (kt & 1) * BUF; const unsigned char* Vs = Ks + KBYTES;
;         const unsigned char* kp = Ks + r32 * KP + hi * 16;
;         const unsigned char* vp = Vs + (4 * hi + q4) * VP + (16 * nhalf + 4 * p4) * 2;
; #pragma unroll
;         for (int kb = 0; kb < 2; ++kb) {
;             bf16x8 pf[2][2];
;             {
;                 f32x16 s0, s1;
; #pragma unroll
;                 for (int r = 0; r < 16; ++r) { s0[r] = nshift[0]; s1[r] = nshift[1]; }
; #pragma unroll
;                 for (int ds = 0; ds < 4; ++ds) {
;                     const bf16x8 kf = *(const bf16x8*)(kp + kb * 32 * KP + ds * 32);
;                     const bf16x8 q0 = *(const bf16x8*)(qs + ds * 32), q1 = *(const bf16x8*)(qs + 32 * KP + ds * 32);
;                     s0 = __builtin_amdgcn_mfma_f32_32x32x16_bf16(kf, q0, s0, 0, 0, 0);
;                     s1 = __builtin_amdgcn_mfma_f32_32x32x16_bf16(kf, q1, s1, 0, 0, 0);
;                 }
;                 float l0 = 0.f, l1 = 0.f;
; #pragma unroll
;                 for (int r = 0; r < 16; ++r) { s0[r] = __builtin_amdgcn_exp2f(s0[r]); l0 += s0[r]; }
; #pragma unroll
;                 for (int r = 0; r < 16; ++r) { s1[r] = __builtin_amdgcn_exp2f(s1[r]); l1 += s1[r]; }
;                 lsum[0] += l0; lsum[1] += l1;
; #pragma unroll
;                 for (int j = 0; j < 2; ++j) {
;                     u32x4 w0, w1;
;                     w0.x = cvt_pk_bf16(s0[8 * j + 0], s0[8 * j + 1]); w0.y = cvt_pk_bf16(s0[8 * j + 2], s0[8 * j + 3]); w0.z = cvt_pk_bf16(s0[8 * j + 4], s0[8 * j + 5]); w0.w = cvt_pk_bf16(s0[8 * j + 6], s0[8 * j + 7]);
;                     w1.x = cvt_pk_bf16(s1[8 * j + 0], s1[8 * j + 1]); w1.y = cvt_pk_bf16(s1[8 * j + 2], s1[8 * j + 3]); w1.z = cvt_pk_bf16(s1[8 * j + 4], s1[8 * j + 5]); w1.w = cvt_pk_bf16(s1[8 * j + 6], s1[8 * j + 7]);
;                     pf[0][j] = __builtin_bit_cast(bf16x8, w0); pf[1][j] = __builtin_bit_cast(bf16x8, w1);
;                 }
;             }
	v_mfma_f32_32x32x16_bf16 v[48:63], v[218:221], v[116:119], v[48:63]
	v_mfma_f32_32x32x16_bf16 v[96:111], v[198:201], v[176:179], v[16:31]
	ds_read_b128 v[198:201], v170 offset:32768
	v_exp_f32_e32 v80, v80
	v_exp_f32_e32 v81, v81
	v_exp_f32_e32 v82, v82
	v_add_f32_e32 v144, v144, v80
	v_exp_f32_e32 v83, v83
	v_mfma_f32_32x32x16_bf16 v[96:111], v[202:205], v[180:183], v[96:111]
	ds_read_b128 v[202:205], v171 offset:32768
	v_add_f32_e32 v144, v144, v81
	v_cvt_pk_bf16_f32 v112, v80, v81
	v_exp_f32_e32 v84, v84
	v_add_f32_e32 v144, v144, v82
	v_exp_f32_e32 v85, v85
	v_mfma_f32_32x32x16_bf16 v[96:111], v[206:209], v[184:187], v[96:111]
	ds_read_b128 v[206:209], v210 offset:32768
	v_add_f32_e32 v144, v144, v83
	v_cvt_pk_bf16_f32 v113, v82, v83
	v_exp_f32_e32 v86, v86
	v_add_f32_e32 v144, v144, v84
	v_exp_f32_e32 v87, v87
	v_add_f32_e32 v144, v144, v85
	v_mfma_f32_32x32x16_bf16 v[96:111], v[128:131], v[188:191], v[96:111]
	ds_read_b128 v[128:131], v222 offset:32768
	v_cvt_pk_bf16_f32 v114, v84, v85
	v_exp_f32_e32 v88, v88
	v_add_f32_e32 v144, v144, v86
	v_exp_f32_e32 v89, v89
	v_add_f32_e32 v144, v144, v87
	v_cvt_pk_bf16_f32 v115, v86, v87
	v_mfma_f32_32x32x16_bf16 v[32:47], v[162:165], v[120:123], v[32:47]
	ds_read_b64_tr_b16 v[162:163], v223 offset:28672
	ds_read_b64_tr_b16 v[164:165], v223 offset:29696
	v_exp_f32_e32 v90, v90
	v_add_f32_e32 v144, v144, v88
	v_exp_f32_e32 v91, v91
	v_add_f32_e32 v144, v144, v89
	v_cvt_pk_bf16_f32 v116, v88, v89
	v_exp_f32_e32 v92, v92
	v_mfma_f32_32x32x16_bf16 v[0:15], v[166:169], v[120:123], v[0:15]
	ds_read_b64_tr_b16 v[166:167], v224 offset:28672
	ds_read_b64_tr_b16 v[168:169], v224 offset:29696
	v_add_f32_e32 v144, v144, v90
	v_exp_f32_e32 v93, v93
	v_add_f32_e32 v144, v144, v91
	v_cvt_pk_bf16_f32 v117, v90, v91
	v_exp_f32_e32 v94, v94
	v_mfma_f32_32x32x16_bf16 v[32:47], v[214:217], v[124:127], v[32:47]
	ds_read_b64_tr_b16 v[214:215], v223 offset:30720
	ds_read_b64_tr_b16 v[216:217], v223 offset:31744
	v_add_f32_e32 v144, v144, v92
	v_exp_f32_e32 v95, v95
	v_add_f32_e32 v144, v144, v93
	v_cvt_pk_bf16_f32 v118, v92, v93
	v_add_f32_e32 v144, v144, v94
	v_add_f32_e32 v144, v144, v95
	v_cvt_pk_bf16_f32 v119, v94, v95
	v_mfma_f32_32x32x16_bf16 v[0:15], v[218:221], v[124:127], v[0:15]
	ds_read_b64_tr_b16 v[218:219], v224 offset:30720
	ds_read_b64_tr_b16 v[220:221], v224 offset:31744
	s_waitcnt lgkmcnt(11)
	v_mfma_f32_32x32x16_bf16 v[80:95], v[198:201], v[146:149], v[16:31]
	v_exp_f32_e32 v96, v96
	v_exp_f32_e32 v97, v97
	v_exp_f32_e32 v98, v98
	v_add_f32_e32 v145, v145, v96
	v_exp_f32_e32 v99, v99
	s_waitcnt lgkmcnt(10)
	v_mfma_f32_32x32x16_bf16 v[80:95], v[202:205], v[150:153], v[80:95]
	v_add_f32_e32 v145, v145, v97
	v_cvt_pk_bf16_f32 v120, v96, v97
	v_exp_f32_e32 v100, v100
	v_add_f32_e32 v145, v145, v98
	v_exp_f32_e32 v101, v101
	s_waitcnt lgkmcnt(9)
	v_mfma_f32_32x32x16_bf16 v[80:95], v[206:209], v[154:157], v[80:95]
	v_add_f32_e32 v145, v145, v99
	v_cvt_pk_bf16_f32 v121, v98, v99
	v_exp_f32_e32 v102, v102
	v_add_f32_e32 v145, v145, v100
	v_exp_f32_e32 v103, v103
	v_add_f32_e32 v145, v145, v101
	s_waitcnt lgkmcnt(8)
	v_mfma_f32_32x32x16_bf16 v[80:95], v[128:131], v[158:161], v[80:95]
	v_cvt_pk_bf16_f32 v122, v100, v101
	v_exp_f32_e32 v104, v104
	v_add_f32_e32 v145, v145, v102
	v_exp_f32_e32 v105, v105
	v_add_f32_e32 v145, v145, v103
	v_cvt_pk_bf16_f32 v123, v102, v103
	s_waitcnt lgkmcnt(6)
	v_mfma_f32_32x32x16_bf16 v[64:79], v[162:165], v[112:115], v[64:79]
	v_exp_f32_e32 v106, v106
	v_add_f32_e32 v145, v145, v104
	v_exp_f32_e32 v107, v107
	v_add_f32_e32 v145, v145, v105
	v_cvt_pk_bf16_f32 v124, v104, v105
	v_exp_f32_e32 v108, v108
	s_waitcnt lgkmcnt(4)
	v_mfma_f32_32x32x16_bf16 v[48:63], v[166:169], v[112:115], v[48:63]
	v_add_f32_e32 v145, v145, v106
	v_exp_f32_e32 v109, v109
	v_add_f32_e32 v145, v145, v107
	v_cvt_pk_bf16_f32 v125, v106, v107
	v_exp_f32_e32 v110, v110
	s_waitcnt lgkmcnt(2)
	v_mfma_f32_32x32x16_bf16 v[64:79], v[214:217], v[116:119], v[64:79]
	v_add_f32_e32 v145, v145, v108
	v_exp_f32_e32 v111, v111
	v_add_f32_e32 v145, v145, v109
	v_cvt_pk_bf16_f32 v126, v108, v109
	v_add_f32_e32 v145, v145, v110
	v_add_f32_e32 v145, v145, v111
	v_cvt_pk_bf16_f32 v127, v110, v111
	s_waitcnt lgkmcnt(0)
	v_mfma_f32_32x32x16_bf16 v[48:63], v[218:221], v[116:119], v[48:63]
	v_mfma_f32_32x32x16_bf16 v[96:111], v[198:201], v[176:179], v[16:31]
	ds_read_b128 v[198:201], v170 offset:36864
	v_exp_f32_e32 v80, v80
	v_exp_f32_e32 v81, v81
	v_exp_f32_e32 v82, v82
	v_add_f32_e32 v144, v144, v80
	v_exp_f32_e32 v83, v83
	v_mfma_f32_32x32x16_bf16 v[96:111], v[202:205], v[180:183], v[96:111]
	ds_read_b128 v[202:205], v171 offset:36864
	v_add_f32_e32 v144, v144, v81
	v_cvt_pk_bf16_f32 v112, v80, v81
	v_exp_f32_e32 v84, v84
	v_add_f32_e32 v144, v144, v82
	v_exp_f32_e32 v85, v85
	v_mfma_f32_32x32x16_bf16 v[96:111], v[206:209], v[184:187], v[96:111]
	ds_read_b128 v[206:209], v210 offset:36864
	v_add_f32_e32 v144, v144, v83
	v_cvt_pk_bf16_f32 v113, v82, v83
	v_exp_f32_e32 v86, v86
	v_add_f32_e32 v144, v144, v84
	v_exp_f32_e32 v87, v87
	v_add_f32_e32 v144, v144, v85
	v_mfma_f32_32x32x16_bf16 v[96:111], v[128:131], v[188:191], v[96:111]
	ds_read_b128 v[128:131], v222 offset:36864
	v_cvt_pk_bf16_f32 v114, v84, v85
	v_exp_f32_e32 v88, v88
	v_add_f32_e32 v144, v144, v86
	v_exp_f32_e32 v89, v89
	v_add_f32_e32 v144, v144, v87
	v_cvt_pk_bf16_f32 v115, v86, v87
	v_mfma_f32_32x32x16_bf16 v[32:47], v[162:165], v[120:123], v[32:47]
	ds_read_b64_tr_b16 v[162:163], v223 offset:40960
	ds_read_b64_tr_b16 v[164:165], v223 offset:41984
	v_exp_f32_e32 v90, v90
	v_add_f32_e32 v144, v144, v88
	v_exp_f32_e32 v91, v91
	v_add_f32_e32 v144, v144, v89
	v_cvt_pk_bf16_f32 v116, v88, v89
	v_exp_f32_e32 v92, v92
	v_mfma_f32_32x32x16_bf16 v[0:15], v[166:169], v[120:123], v[0:15]
	ds_read_b64_tr_b16 v[166:167], v224 offset:40960
	ds_read_b64_tr_b16 v[168:169], v224 offset:41984
	s_add_i32 s59, s59, 1
	v_add_f32_e32 v144, v144, v90
	v_exp_f32_e32 v93, v93
	v_add_f32_e32 v144, v144, v91
	v_cvt_pk_bf16_f32 v117, v90, v91
	v_exp_f32_e32 v94, v94
	v_mfma_f32_32x32x16_bf16 v[32:47], v[214:217], v[124:127], v[32:47]
	ds_read_b64_tr_b16 v[214:215], v223 offset:43008
	ds_read_b64_tr_b16 v[216:217], v223 offset:44032
	v_add_f32_e32 v144, v144, v92
	v_exp_f32_e32 v95, v95
	v_add_f32_e32 v144, v144, v93
	v_cvt_pk_bf16_f32 v118, v92, v93
	v_add_f32_e32 v144, v144, v94
	v_add_f32_e32 v144, v144, v95
	v_cvt_pk_bf16_f32 v119, v94, v95
	v_mfma_f32_32x32x16_bf16 v[0:15], v[218:221], v[124:127], v[0:15]
	ds_read_b64_tr_b16 v[218:219], v224 offset:43008
	ds_read_b64_tr_b16 v[220:221], v224 offset:44032
	s_waitcnt vmcnt(2) lgkmcnt(8)
	s_barrier
; __device__ __forceinline__ void attn_pass_A2(const int tid, unsigned char* smem, const bf16_t* Q0w, int qpitch, const bf16_t* Kb, int kpitch, const bf16_t* Vb, int vpitch,
;                                              int b, int ntiles, float kmax, f32x16 (&o)[2][2], float (&linv)[2]) {
;     ...
;     for (int kt = 0; kt < ntiles; ++kt) {
;         if (kt + 1 < ntiles) gload(kt + 1);
;         const unsigned char* Ks = smem + (kt & 1) * BUF; const unsigned char* Vs = Ks + KBYTES;
;         const unsigned char* kp = Ks + r32 * KP + hi * 16;
;         const unsigned char* vp = Vs + (4 * hi + q4) * VP + (16 * nhalf + 4 * p4) * 2;
; #pragma unroll
;         for (int kb = 0; kb < 2; ++kb) {
;             bf16x8 pf[2][2];
;             {
;                 f32x16 s0, s1;
; #pragma unroll
;                 for (int r = 0; r < 16; ++r) { s0[r] = nshift[0]; s1[r] = nshift[1]; }
; #pragma unroll
;                 for (int ds = 0; ds < 4; ++ds) {
;                     const bf16x8 kf = *(const bf16x8*)(kp + kb * 32 * KP + ds * 32);
;                     const bf16x8 q0 = *(const bf16x8*)(qs + ds * 32), q1 = *(const bf16x8*)(qs + 32 * KP + ds * 32);
;                     s0 = __builtin_amdgcn_mfma_f32_32x32x16_bf16(kf, q0, s0, 0, 0, 0);
;                     s1 = __builtin_amdgcn_mfma_f32_32x32x16_bf16(kf, q1, s1, 0, 0, 0);
;                 }
;                 float l0 = 0.f, l1 = 0.f;
; #pragma unroll
;                 for (int r = 0; r < 16; ++r) { s0[r] = __builtin_amdgcn_exp2f(s0[r]); l0 += s0[r]; }
; #pragma unroll
;                 for (int r = 0; r < 16; ++r) { s1[r] = __builtin_amdgcn_exp2f(s1[r]); l1 += s1[r]; }
;                 lsum[0] += l0; lsum[1] += l1;
; #pragma unroll
;                 for (int j = 0; j < 2; ++j) {
;                     u32x4 w0, w1;
;                     w0.x = cvt_pk_bf16(s0[8 * j + 0], s0[8 * j + 1]); w0.y = cvt_pk_bf16(s0[8 * j + 2], s0[8 * j + 3]); w0.z = cvt_pk_bf16(s0[8 * j + 4], s0[8 * j + 5]); w0.w = cvt_pk_bf16(s0[8 * j + 6], s0[8 * j + 7]);
;                     w1.x = cvt_pk_bf16(s1[8 * j + 0], s1[8 * j + 1]); w1.y = cvt_pk_bf16(s1[8 * j + 2], s1[8 * j + 3]); w1.z = cvt_pk_bf16(s1[8 * j + 4], s1[8 * j + 5]); w1.w = cvt_pk_bf16(s1[8 * j + 6], s1[8 * j + 7]);
;                     pf[0][j] = __builtin_bit_cast(bf16x8, w0); pf[1][j] = __builtin_bit_cast(bf16x8, w1);
;                 }
;             }
	v_mfma_f32_32x32x16_bf16 v[80:95], v[198:201], v[146:149], v[16:31]
	v_exp_f32_e32 v96, v96
	v_exp_f32_e32 v97, v97
	v_exp_f32_e32 v98, v98
	v_add_f32_e32 v145, v145, v96
	v_exp_f32_e32 v99, v99
	v_mfma_f32_32x32x16_bf16 v[80:95], v[202:205], v[150:153], v[80:95]
	s_add_i32 s70, s59, 3
	s_cmp_lt_u32 s70, 4
	s_cselect_b32 s2, s65, s32
	s_lshl_b32 s3, s70, 6
	s_add_i32 s2, s2, s3
	s_lshl_b32 s2, s2, 8
	s_add_u32 s60, s66, s2
	s_addc_u32 s61, s67, 0
	s_add_u32 s62, s68, s2
	s_addc_u32 s63, s69, 0
	v_add_f32_e32 v145, v145, v97
	v_cvt_pk_bf16_f32 v120, v96, v97
	v_exp_f32_e32 v100, v100
	v_add_f32_e32 v145, v145, v98
	v_exp_f32_e32 v101, v101
	v_mfma_f32_32x32x16_bf16 v[80:95], v[206:209], v[154:157], v[80:95]
	v_add_f32_e32 v145, v145, v99
	v_cvt_pk_bf16_f32 v121, v98, v99
	v_exp_f32_e32 v102, v102
	v_add_f32_e32 v145, v145, v100
	v_exp_f32_e32 v103, v103
	v_add_f32_e32 v145, v145, v101
	v_mfma_f32_32x32x16_bf16 v[80:95], v[128:131], v[158:161], v[80:95]
	s_add_i32 m0, s56, 0x4000
	s_nop 0
	global_load_lds_dwordx4 v236, s[60:61]
	v_cvt_pk_bf16_f32 v122, v100, v101
	v_exp_f32_e32 v104, v104
	v_add_f32_e32 v145, v145, v102
	v_exp_f32_e32 v105, v105
	v_add_f32_e32 v145, v145, v103
	v_cvt_pk_bf16_f32 v123, v102, v103
	s_waitcnt lgkmcnt(6)
	v_mfma_f32_32x32x16_bf16 v[64:79], v[162:165], v[112:115], v[64:79]
	v_exp_f32_e32 v106, v106
	v_add_f32_e32 v145, v145, v104
	v_exp_f32_e32 v107, v107
	v_add_f32_e32 v145, v145, v105
	v_cvt_pk_bf16_f32 v124, v104, v105
	v_exp_f32_e32 v108, v108
	s_waitcnt lgkmcnt(4)
	v_mfma_f32_32x32x16_bf16 v[48:63], v[166:169], v[112:115], v[48:63]
	s_add_i32 m0, s56, 0x6000
	s_nop 0
	global_load_lds_dwordx4 v234, s[62:63]
	v_add_f32_e32 v145, v145, v106
	v_exp_f32_e32 v109, v109
	v_add_f32_e32 v145, v145, v107
	v_cvt_pk_bf16_f32 v125, v106, v107
	v_exp_f32_e32 v110, v110
	s_waitcnt lgkmcnt(2)
	v_mfma_f32_32x32x16_bf16 v[64:79], v[214:217], v[116:119], v[64:79]
	v_add_f32_e32 v145, v145, v108
	v_exp_f32_e32 v111, v111
	v_add_f32_e32 v145, v145, v109
	v_cvt_pk_bf16_f32 v126, v108, v109
	v_add_f32_e32 v145, v145, v110
	v_add_f32_e32 v145, v145, v111
	v_cvt_pk_bf16_f32 v127, v110, v111
	s_waitcnt lgkmcnt(0)
	v_mfma_f32_32x32x16_bf16 v[48:63], v[218:221], v[116:119], v[48:63]
	v_mfma_f32_32x32x16_bf16 v[96:111], v[198:201], v[176:179], v[16:31]
	ds_read_b128 v[198:201], v170 offset:49152
	v_exp_f32_e32 v80, v80
	v_exp_f32_e32 v81, v81
	v_exp_f32_e32 v82, v82
	v_add_f32_e32 v144, v144, v80
	v_exp_f32_e32 v83, v83
	v_mfma_f32_32x32x16_bf16 v[96:111], v[202:205], v[180:183], v[96:111]
	ds_read_b128 v[202:205], v171 offset:49152
	v_add_f32_e32 v144, v144, v81
	v_cvt_pk_bf16_f32 v112, v80, v81
	v_exp_f32_e32 v84, v84
	v_add_f32_e32 v144, v144, v82
	v_exp_f32_e32 v85, v85
	v_mfma_f32_32x32x16_bf16 v[96:111], v[206:209], v[184:187], v[96:111]
	ds_read_b128 v[206:209], v210 offset:49152
	v_add_f32_e32 v144, v144, v83
	v_cvt_pk_bf16_f32 v113, v82, v83
	v_exp_f32_e32 v86, v86
	v_add_f32_e32 v144, v144, v84
	v_exp_f32_e32 v87, v87
	v_add_f32_e32 v144, v144, v85
	v_mfma_f32_32x32x16_bf16 v[96:111], v[128:131], v[188:191], v[96:111]
	ds_read_b128 v[128:131], v222 offset:49152
	v_cvt_pk_bf16_f32 v114, v84, v85
	v_exp_f32_e32 v88, v88
	v_add_f32_e32 v144, v144, v86
	v_exp_f32_e32 v89, v89
	v_add_f32_e32 v144, v144, v87
	v_cvt_pk_bf16_f32 v115, v86, v87
	v_mfma_f32_32x32x16_bf16 v[32:47], v[162:165], v[120:123], v[32:47]
	ds_read_b64_tr_b16 v[162:163], v223 offset:45056
	ds_read_b64_tr_b16 v[164:165], v223 offset:46080
	v_exp_f32_e32 v90, v90
	v_add_f32_e32 v144, v144, v88
	v_exp_f32_e32 v91, v91
	v_add_f32_e32 v144, v144, v89
	v_cvt_pk_bf16_f32 v116, v88, v89
	v_exp_f32_e32 v92, v92
	v_mfma_f32_32x32x16_bf16 v[0:15], v[166:169], v[120:123], v[0:15]
	ds_read_b64_tr_b16 v[166:167], v224 offset:45056
	ds_read_b64_tr_b16 v[168:169], v224 offset:46080
	v_add_f32_e32 v144, v144, v90
	v_exp_f32_e32 v93, v93
	v_add_f32_e32 v144, v144, v91
	v_cvt_pk_bf16_f32 v117, v90, v91
	v_exp_f32_e32 v94, v94
	v_mfma_f32_32x32x16_bf16 v[32:47], v[214:217], v[124:127], v[32:47]
	ds_read_b64_tr_b16 v[214:215], v223 offset:47104
	ds_read_b64_tr_b16 v[216:217], v223 offset:48128
	v_add_f32_e32 v144, v144, v92
	v_exp_f32_e32 v95, v95
	v_add_f32_e32 v144, v144, v93
	v_cvt_pk_bf16_f32 v118, v92, v93
	v_add_f32_e32 v144, v144, v94
	v_add_f32_e32 v144, v144, v95
	v_cvt_pk_bf16_f32 v119, v94, v95
	v_mfma_f32_32x32x16_bf16 v[0:15], v[218:221], v[124:127], v[0:15]
	ds_read_b64_tr_b16 v[218:219], v224 offset:47104
	ds_read_b64_tr_b16 v[220:221], v224 offset:48128
	s_waitcnt lgkmcnt(11)
	v_mfma_f32_32x32x16_bf16 v[80:95], v[198:201], v[146:149], v[16:31]
	v_exp_f32_e32 v96, v96
	v_exp_f32_e32 v97, v97
	v_exp_f32_e32 v98, v98
	v_add_f32_e32 v145, v145, v96
	v_exp_f32_e32 v99, v99
	s_waitcnt lgkmcnt(10)
	v_mfma_f32_32x32x16_bf16 v[80:95], v[202:205], v[150:153], v[80:95]
	v_add_f32_e32 v145, v145, v97
	v_cvt_pk_bf16_f32 v120, v96, v97
	v_exp_f32_e32 v100, v100
	v_add_f32_e32 v145, v145, v98
	v_exp_f32_e32 v101, v101
	s_waitcnt lgkmcnt(9)
	v_mfma_f32_32x32x16_bf16 v[80:95], v[206:209], v[154:157], v[80:95]
	v_add_f32_e32 v145, v145, v99
	v_cvt_pk_bf16_f32 v121, v98, v99
	v_exp_f32_e32 v102, v102
	v_add_f32_e32 v145, v145, v100
	v_exp_f32_e32 v103, v103
	v_add_f32_e32 v145, v145, v101
	s_waitcnt lgkmcnt(8)
	v_mfma_f32_32x32x16_bf16 v[80:95], v[128:131], v[158:161], v[80:95]
	v_cvt_pk_bf16_f32 v122, v100, v101
	v_exp_f32_e32 v104, v104
	v_add_f32_e32 v145, v145, v102
	v_exp_f32_e32 v105, v105
	v_add_f32_e32 v145, v145, v103
	v_cvt_pk_bf16_f32 v123, v102, v103
	s_waitcnt lgkmcnt(6)
; __device__ __forceinline__ void attn_pass_A2(const int tid, unsigned char* smem, const bf16_t* Q0w, int qpitch, const bf16_t* Kb, int kpitch, const bf16_t* Vb, int vpitch,
;                                              int b, int ntiles, float kmax, f32x16 (&o)[2][2], float (&linv)[2]) {
;     ...
;     for (int kt = 0; kt < ntiles; ++kt) {
;         if (kt + 1 < ntiles) gload(kt + 1);
;         const unsigned char* Ks = smem + (kt & 1) * BUF; const unsigned char* Vs = Ks + KBYTES;
;         const unsigned char* kp = Ks + r32 * KP + hi * 16;
;         const unsigned char* vp = Vs + (4 * hi + q4) * VP + (16 * nhalf + 4 * p4) * 2;
; #pragma unroll
;         for (int kb = 0; kb < 2; ++kb) {
;             bf16x8 pf[2][2];
;             {
;                 f32x16 s0, s1;
; #pragma unroll
;                 for (int r = 0; r < 16; ++r) { s0[r] = nshift[0]; s1[r] = nshift[1]; }
; #pragma unroll
;                 for (int ds = 0; ds < 4; ++ds) {
;                     const bf16x8 kf = *(const bf16x8*)(kp + kb * 32 * KP + ds * 32);
;                     const bf16x8 q0 = *(const bf16x8*)(qs + ds * 32), q1 = *(const bf16x8*)(qs + 32 * KP + ds * 32);
;                     s0 = __builtin_amdgcn_mfma_f32_32x32x16_bf16(kf, q0, s0, 0, 0, 0);
;                     s1 = __builtin_amdgcn_mfma_f32_32x32x16_bf16(kf, q1, s1, 0, 0, 0);
;                 }
;                 float l0 = 0.f, l1 = 0.f;
; #pragma unroll
;                 for (int r = 0; r < 16; ++r) { s0[r] = __builtin_amdgcn_exp2f(s0[r]); l0 += s0[r]; }
; #pragma unroll
;                 for (int r = 0; r < 16; ++r) { s1[r] = __builtin_amdgcn_exp2f(s1[r]); l1 += s1[r]; }
;                 lsum[0] += l0; lsum[1] += l1;
; #pragma unroll
;                 for (int j = 0; j < 2; ++j) {
;                     u32x4 w0, w1;
;                     w0.x = cvt_pk_bf16(s0[8 * j + 0], s0[8 * j + 1]); w0.y = cvt_pk_bf16(s0[8 * j + 2], s0[8 * j + 3]); w0.z = cvt_pk_bf16(s0[8 * j + 4], s0[8 * j + 5]); w0.w = cvt_pk_bf16(s0[8 * j + 6], s0[8 * j + 7]);
;                     w1.x = cvt_pk_bf16(s1[8 * j + 0], s1[8 * j + 1]); w1.y = cvt_pk_bf16(s1[8 * j + 2], s1[8 * j + 3]); w1.z = cvt_pk_bf16(s1[8 * j + 4], s1[8 * j + 5]); w1.w = cvt_pk_bf16(s1[8 * j + 6], s1[8 * j + 7]);
;                     pf[0][j] = __builtin_bit_cast(bf16x8, w0); pf[1][j] = __builtin_bit_cast(bf16x8, w1);
;                 }
;             }
	v_mfma_f32_32x32x16_bf16 v[64:79], v[162:165], v[112:115], v[64:79]
	v_exp_f32_e32 v106, v106
	v_add_f32_e32 v145, v145, v104
	v_exp_f32_e32 v107, v107
	v_add_f32_e32 v145, v145, v105
	v_cvt_pk_bf16_f32 v124, v104, v105
	v_exp_f32_e32 v108, v108
	s_waitcnt lgkmcnt(4)
	v_mfma_f32_32x32x16_bf16 v[48:63], v[166:169], v[112:115], v[48:63]
	v_add_f32_e32 v145, v145, v106
	v_exp_f32_e32 v109, v109
	v_add_f32_e32 v145, v145, v107
	v_cvt_pk_bf16_f32 v125, v106, v107
	v_exp_f32_e32 v110, v110
	s_waitcnt lgkmcnt(2)
	v_mfma_f32_32x32x16_bf16 v[64:79], v[214:217], v[116:119], v[64:79]
	v_add_f32_e32 v145, v145, v108
	v_exp_f32_e32 v111, v111
	v_add_f32_e32 v145, v145, v109
	v_cvt_pk_bf16_f32 v126, v108, v109
	v_add_f32_e32 v145, v145, v110
	v_add_f32_e32 v145, v145, v111
	v_cvt_pk_bf16_f32 v127, v110, v111
	s_waitcnt lgkmcnt(0)
	v_mfma_f32_32x32x16_bf16 v[48:63], v[218:221], v[116:119], v[48:63]
	v_mfma_f32_32x32x16_bf16 v[96:111], v[198:201], v[176:179], v[16:31]
	ds_read_b128 v[198:201], v170 offset:53248
	v_exp_f32_e32 v80, v80
	v_exp_f32_e32 v81, v81
	v_exp_f32_e32 v82, v82
	v_add_f32_e32 v144, v144, v80
	v_exp_f32_e32 v83, v83
	v_mfma_f32_32x32x16_bf16 v[96:111], v[202:205], v[180:183], v[96:111]
	ds_read_b128 v[202:205], v171 offset:53248
	v_add_f32_e32 v144, v144, v81
	v_cvt_pk_bf16_f32 v112, v80, v81
	v_exp_f32_e32 v84, v84
	v_add_f32_e32 v144, v144, v82
	v_exp_f32_e32 v85, v85
	v_mfma_f32_32x32x16_bf16 v[96:111], v[206:209], v[184:187], v[96:111]
	ds_read_b128 v[206:209], v210 offset:53248
	v_add_f32_e32 v144, v144, v83
	v_cvt_pk_bf16_f32 v113, v82, v83
	v_exp_f32_e32 v86, v86
	v_add_f32_e32 v144, v144, v84
	v_exp_f32_e32 v87, v87
	v_add_f32_e32 v144, v144, v85
	v_mfma_f32_32x32x16_bf16 v[96:111], v[128:131], v[188:191], v[96:111]
	ds_read_b128 v[128:131], v222 offset:53248
	v_cvt_pk_bf16_f32 v114, v84, v85
	v_exp_f32_e32 v88, v88
	v_add_f32_e32 v144, v144, v86
	v_exp_f32_e32 v89, v89
	v_add_f32_e32 v144, v144, v87
	v_cvt_pk_bf16_f32 v115, v86, v87
	v_mfma_f32_32x32x16_bf16 v[32:47], v[162:165], v[120:123], v[32:47]
	ds_read_b64_tr_b16 v[162:163], v223 offset:57344
	ds_read_b64_tr_b16 v[164:165], v223 offset:58368
	v_exp_f32_e32 v90, v90
	v_add_f32_e32 v144, v144, v88
	v_exp_f32_e32 v91, v91
	v_add_f32_e32 v144, v144, v89
	v_cvt_pk_bf16_f32 v116, v88, v89
	v_exp_f32_e32 v92, v92
	v_mfma_f32_32x32x16_bf16 v[0:15], v[166:169], v[120:123], v[0:15]
	ds_read_b64_tr_b16 v[166:167], v224 offset:57344
	ds_read_b64_tr_b16 v[168:169], v224 offset:58368
	s_add_i32 s59, s59, 1
	v_add_f32_e32 v144, v144, v90
	v_exp_f32_e32 v93, v93
	v_add_f32_e32 v144, v144, v91
	v_cvt_pk_bf16_f32 v117, v90, v91
	v_exp_f32_e32 v94, v94
	v_mfma_f32_32x32x16_bf16 v[32:47], v[214:217], v[124:127], v[32:47]
	ds_read_b64_tr_b16 v[214:215], v223 offset:59392
	ds_read_b64_tr_b16 v[216:217], v223 offset:60416
	v_add_f32_e32 v144, v144, v92
	v_exp_f32_e32 v95, v95
	v_add_f32_e32 v144, v144, v93
	v_cvt_pk_bf16_f32 v118, v92, v93
	v_add_f32_e32 v144, v144, v94
	v_add_f32_e32 v144, v144, v95
	v_cvt_pk_bf16_f32 v119, v94, v95
	v_mfma_f32_32x32x16_bf16 v[0:15], v[218:221], v[124:127], v[0:15]
	ds_read_b64_tr_b16 v[218:219], v224 offset:59392
	ds_read_b64_tr_b16 v[220:221], v224 offset:60416
	s_waitcnt vmcnt(2) lgkmcnt(8)
	s_barrier
	v_mfma_f32_32x32x16_bf16 v[80:95], v[198:201], v[146:149], v[16:31]
	v_exp_f32_e32 v96, v96
	v_exp_f32_e32 v97, v97
	v_exp_f32_e32 v98, v98
	v_add_f32_e32 v145, v145, v96
	v_exp_f32_e32 v99, v99
	v_mfma_f32_32x32x16_bf16 v[80:95], v[202:205], v[150:153], v[80:95]
	s_add_i32 s70, s59, 3
	s_cmp_lt_u32 s70, 4
	s_cselect_b32 s2, s65, s32
	s_lshl_b32 s3, s70, 6
	s_add_i32 s2, s2, s3
	s_lshl_b32 s2, s2, 8
	s_add_u32 s60, s66, s2
	s_addc_u32 s61, s67, 0
	s_add_u32 s62, s68, s2
	s_addc_u32 s63, s69, 0
	v_add_f32_e32 v145, v145, v97
	v_cvt_pk_bf16_f32 v120, v96, v97
	v_exp_f32_e32 v100, v100
	v_add_f32_e32 v145, v145, v98
	v_exp_f32_e32 v101, v101
	v_mfma_f32_32x32x16_bf16 v[80:95], v[206:209], v[154:157], v[80:95]
	v_add_f32_e32 v145, v145, v99
	v_cvt_pk_bf16_f32 v121, v98, v99
	v_exp_f32_e32 v102, v102
	v_add_f32_e32 v145, v145, v100
	v_exp_f32_e32 v103, v103
	v_add_f32_e32 v145, v145, v101
	v_mfma_f32_32x32x16_bf16 v[80:95], v[128:131], v[158:161], v[80:95]
	s_add_i32 m0, s56, 0x8000
	s_nop 0
	global_load_lds_dwordx4 v236, s[60:61]
	v_cvt_pk_bf16_f32 v122, v100, v101
	v_exp_f32_e32 v104, v104
	v_add_f32_e32 v145, v145, v102
	v_exp_f32_e32 v105, v105
	v_add_f32_e32 v145, v145, v103
	v_cvt_pk_bf16_f32 v123, v102, v103
	s_waitcnt lgkmcnt(6)
	v_mfma_f32_32x32x16_bf16 v[64:79], v[162:165], v[112:115], v[64:79]
	v_exp_f32_e32 v106, v106
	v_add_f32_e32 v145, v145, v104
	v_exp_f32_e32 v107, v107
	v_add_f32_e32 v145, v145, v105
	v_cvt_pk_bf16_f32 v124, v104, v105
	v_exp_f32_e32 v108, v108
	s_waitcnt lgkmcnt(4)
	v_mfma_f32_32x32x16_bf16 v[48:63], v[166:169], v[112:115], v[48:63]
	s_add_i32 m0, s56, 0xa000
	s_nop 0
	global_load_lds_dwordx4 v234, s[62:63]
	v_add_f32_e32 v145, v145, v106
	v_exp_f32_e32 v109, v109
	v_add_f32_e32 v145, v145, v107
	v_cvt_pk_bf16_f32 v125, v106, v107
	v_exp_f32_e32 v110, v110
	s_waitcnt lgkmcnt(2)
	v_mfma_f32_32x32x16_bf16 v[64:79], v[214:217], v[116:119], v[64:79]
	v_add_f32_e32 v145, v145, v108
	v_exp_f32_e32 v111, v111
	v_add_f32_e32 v145, v145, v109
	v_cvt_pk_bf16_f32 v126, v108, v109
	v_add_f32_e32 v145, v145, v110
	v_add_f32_e32 v145, v145, v111
	v_cvt_pk_bf16_f32 v127, v110, v111
	s_waitcnt lgkmcnt(0)
; __device__ __forceinline__ void attn_pass_A2(const int tid, unsigned char* smem, const bf16_t* Q0w, int qpitch, const bf16_t* Kb, int kpitch, const bf16_t* Vb, int vpitch,
;                                              int b, int ntiles, float kmax, f32x16 (&o)[2][2], float (&linv)[2]) {
;     ...
;     for (int kt = 0; kt < ntiles; ++kt) {
;         if (kt + 1 < ntiles) gload(kt + 1);
;         const unsigned char* Ks = smem + (kt & 1) * BUF; const unsigned char* Vs = Ks + KBYTES;
;         const unsigned char* kp = Ks + r32 * KP + hi * 16;
;         const unsigned char* vp = Vs + (4 * hi + q4) * VP + (16 * nhalf + 4 * p4) * 2;
; #pragma unroll
;         for (int kb = 0; kb < 2; ++kb) {
;             bf16x8 pf[2][2];
;             {
;                 f32x16 s0, s1;
; #pragma unroll
;                 for (int r = 0; r < 16; ++r) { s0[r] = nshift[0]; s1[r] = nshift[1]; }
; #pragma unroll
;                 for (int ds = 0; ds < 4; ++ds) {
;                     const bf16x8 kf = *(const bf16x8*)(kp + kb * 32 * KP + ds * 32);
;                     const bf16x8 q0 = *(const bf16x8*)(qs + ds * 32), q1 = *(const bf16x8*)(qs + 32 * KP + ds * 32);
;                     s0 = __builtin_amdgcn_mfma_f32_32x32x16_bf16(kf, q0, s0, 0, 0, 0);
;                     s1 = __builtin_amdgcn_mfma_f32_32x32x16_bf16(kf, q1, s1, 0, 0, 0);
;                 }
;                 float l0 = 0.f, l1 = 0.f;
; #pragma unroll
;                 for (int r = 0; r < 16; ++r) { s0[r] = __builtin_amdgcn_exp2f(s0[r]); l0 += s0[r]; }
; #pragma unroll
;                 for (int r = 0; r < 16; ++r) { s1[r] = __builtin_amdgcn_exp2f(s1[r]); l1 += s1[r]; }
;                 lsum[0] += l0; lsum[1] += l1;
; #pragma unroll
;                 for (int j = 0; j < 2; ++j) {
;                     u32x4 w0, w1;
;                     w0.x = cvt_pk_bf16(s0[8 * j + 0], s0[8 * j + 1]); w0.y = cvt_pk_bf16(s0[8 * j + 2], s0[8 * j + 3]); w0.z = cvt_pk_bf16(s0[8 * j + 4], s0[8 * j + 5]); w0.w = cvt_pk_bf16(s0[8 * j + 6], s0[8 * j + 7]);
;                     w1.x = cvt_pk_bf16(s1[8 * j + 0], s1[8 * j + 1]); w1.y = cvt_pk_bf16(s1[8 * j + 2], s1[8 * j + 3]); w1.z = cvt_pk_bf16(s1[8 * j + 4], s1[8 * j + 5]); w1.w = cvt_pk_bf16(s1[8 * j + 6], s1[8 * j + 7]);
;                     pf[0][j] = __builtin_bit_cast(bf16x8, w0); pf[1][j] = __builtin_bit_cast(bf16x8, w1);
;                 }
;             }
	v_mfma_f32_32x32x16_bf16 v[48:63], v[218:221], v[116:119], v[48:63]
	v_mfma_f32_32x32x16_bf16 v[96:111], v[198:201], v[176:179], v[16:31]
	ds_read_b128 v[198:201], v170
	v_exp_f32_e32 v80, v80
	v_exp_f32_e32 v81, v81
	v_exp_f32_e32 v82, v82
	v_add_f32_e32 v144, v144, v80
	v_exp_f32_e32 v83, v83
	v_mfma_f32_32x32x16_bf16 v[96:111], v[202:205], v[180:183], v[96:111]
	ds_read_b128 v[202:205], v171
	v_add_f32_e32 v144, v144, v81
	v_cvt_pk_bf16_f32 v112, v80, v81
	v_exp_f32_e32 v84, v84
	v_add_f32_e32 v144, v144, v82
	v_exp_f32_e32 v85, v85
	v_mfma_f32_32x32x16_bf16 v[96:111], v[206:209], v[184:187], v[96:111]
	ds_read_b128 v[206:209], v210
	v_add_f32_e32 v144, v144, v83
	v_cvt_pk_bf16_f32 v113, v82, v83
	v_exp_f32_e32 v86, v86
	v_add_f32_e32 v144, v144, v84
	v_exp_f32_e32 v87, v87
	v_add_f32_e32 v144, v144, v85
	v_mfma_f32_32x32x16_bf16 v[96:111], v[128:131], v[188:191], v[96:111]
	ds_read_b128 v[128:131], v222
	v_cvt_pk_bf16_f32 v114, v84, v85
	v_exp_f32_e32 v88, v88
	v_add_f32_e32 v144, v144, v86
	v_exp_f32_e32 v89, v89
	v_add_f32_e32 v144, v144, v87
	v_cvt_pk_bf16_f32 v115, v86, v87
	v_mfma_f32_32x32x16_bf16 v[32:47], v[162:165], v[120:123], v[32:47]
	ds_read_b64_tr_b16 v[162:163], v223 offset:61440
	ds_read_b64_tr_b16 v[164:165], v223 offset:62464
	v_exp_f32_e32 v90, v90
	v_add_f32_e32 v144, v144, v88
	v_exp_f32_e32 v91, v91
	v_add_f32_e32 v144, v144, v89
	v_cvt_pk_bf16_f32 v116, v88, v89
	v_exp_f32_e32 v92, v92
	v_mfma_f32_32x32x16_bf16 v[0:15], v[166:169], v[120:123], v[0:15]
	ds_read_b64_tr_b16 v[166:167], v224 offset:61440
	ds_read_b64_tr_b16 v[168:169], v224 offset:62464
	v_add_f32_e32 v144, v144, v90
	v_exp_f32_e32 v93, v93
	v_add_f32_e32 v144, v144, v91
	v_cvt_pk_bf16_f32 v117, v90, v91
	v_exp_f32_e32 v94, v94
	v_mfma_f32_32x32x16_bf16 v[32:47], v[214:217], v[124:127], v[32:47]
	ds_read_b64_tr_b16 v[214:215], v223 offset:63488
	ds_read_b64_tr_b16 v[216:217], v223 offset:64512
	v_add_f32_e32 v144, v144, v92
	v_exp_f32_e32 v95, v95
	v_add_f32_e32 v144, v144, v93
	v_cvt_pk_bf16_f32 v118, v92, v93
	v_add_f32_e32 v144, v144, v94
	v_add_f32_e32 v144, v144, v95
	v_cvt_pk_bf16_f32 v119, v94, v95
	v_mfma_f32_32x32x16_bf16 v[0:15], v[218:221], v[124:127], v[0:15]
	ds_read_b64_tr_b16 v[218:219], v224 offset:63488
	ds_read_b64_tr_b16 v[220:221], v224 offset:64512
	s_waitcnt lgkmcnt(11)
	v_mfma_f32_32x32x16_bf16 v[80:95], v[198:201], v[146:149], v[16:31]
	v_exp_f32_e32 v96, v96
	v_exp_f32_e32 v97, v97
	v_exp_f32_e32 v98, v98
	v_add_f32_e32 v145, v145, v96
	v_exp_f32_e32 v99, v99
	s_waitcnt lgkmcnt(10)
	v_mfma_f32_32x32x16_bf16 v[80:95], v[202:205], v[150:153], v[80:95]
	v_add_f32_e32 v145, v145, v97
	v_cvt_pk_bf16_f32 v120, v96, v97
	v_exp_f32_e32 v100, v100
	v_add_f32_e32 v145, v145, v98
	v_exp_f32_e32 v101, v101
	s_waitcnt lgkmcnt(9)
	v_mfma_f32_32x32x16_bf16 v[80:95], v[206:209], v[154:157], v[80:95]
	v_add_f32_e32 v145, v145, v99
	v_cvt_pk_bf16_f32 v121, v98, v99
	v_exp_f32_e32 v102, v102
	v_add_f32_e32 v145, v145, v100
	v_exp_f32_e32 v103, v103
	v_add_f32_e32 v145, v145, v101
	s_waitcnt lgkmcnt(8)
	v_mfma_f32_32x32x16_bf16 v[80:95], v[128:131], v[158:161], v[80:95]
	v_cvt_pk_bf16_f32 v122, v100, v101
	v_exp_f32_e32 v104, v104
	v_add_f32_e32 v145, v145, v102
	v_exp_f32_e32 v105, v105
	v_add_f32_e32 v145, v145, v103
	v_cvt_pk_bf16_f32 v123, v102, v103
	s_waitcnt lgkmcnt(6)
	v_mfma_f32_32x32x16_bf16 v[64:79], v[162:165], v[112:115], v[64:79]
	v_exp_f32_e32 v106, v106
	v_add_f32_e32 v145, v145, v104
	v_exp_f32_e32 v107, v107
	v_add_f32_e32 v145, v145, v105
	v_cvt_pk_bf16_f32 v124, v104, v105
	v_exp_f32_e32 v108, v108
	s_waitcnt lgkmcnt(4)
	v_mfma_f32_32x32x16_bf16 v[48:63], v[166:169], v[112:115], v[48:63]
	v_add_f32_e32 v145, v145, v106
	v_exp_f32_e32 v109, v109
	v_add_f32_e32 v145, v145, v107
	v_cvt_pk_bf16_f32 v125, v106, v107
	v_exp_f32_e32 v110, v110
	s_waitcnt lgkmcnt(2)
	v_mfma_f32_32x32x16_bf16 v[64:79], v[214:217], v[116:119], v[64:79]
	v_add_f32_e32 v145, v145, v108
	v_exp_f32_e32 v111, v111
	v_add_f32_e32 v145, v145, v109
	v_cvt_pk_bf16_f32 v126, v108, v109
	v_add_f32_e32 v145, v145, v110
	v_add_f32_e32 v145, v145, v111
	v_cvt_pk_bf16_f32 v127, v110, v111
	s_waitcnt lgkmcnt(0)
	v_mfma_f32_32x32x16_bf16 v[48:63], v[218:221], v[116:119], v[48:63]
	v_mfma_f32_32x32x16_bf16 v[96:111], v[198:201], v[176:179], v[16:31]
	ds_read_b128 v[198:201], v170 offset:4096
	v_exp_f32_e32 v80, v80
	v_exp_f32_e32 v81, v81
	v_exp_f32_e32 v82, v82
	v_add_f32_e32 v144, v144, v80
	v_exp_f32_e32 v83, v83
	v_mfma_f32_32x32x16_bf16 v[96:111], v[202:205], v[180:183], v[96:111]
	ds_read_b128 v[202:205], v171 offset:4096
	v_add_f32_e32 v144, v144, v81
	v_cvt_pk_bf16_f32 v112, v80, v81
	v_exp_f32_e32 v84, v84
	v_add_f32_e32 v144, v144, v82
	v_exp_f32_e32 v85, v85
	v_mfma_f32_32x32x16_bf16 v[96:111], v[206:209], v[184:187], v[96:111]
	ds_read_b128 v[206:209], v210 offset:4096
	v_add_f32_e32 v144, v144, v83
	v_cvt_pk_bf16_f32 v113, v82, v83
	v_exp_f32_e32 v86, v86
	v_add_f32_e32 v144, v144, v84
	v_exp_f32_e32 v87, v87
	v_add_f32_e32 v144, v144, v85
	v_mfma_f32_32x32x16_bf16 v[96:111], v[128:131], v[188:191], v[96:111]
	ds_read_b128 v[128:131], v222 offset:4096
	v_cvt_pk_bf16_f32 v114, v84, v85
	v_exp_f32_e32 v88, v88
	v_add_f32_e32 v144, v144, v86
	v_exp_f32_e32 v89, v89
	v_add_f32_e32 v144, v144, v87
	v_cvt_pk_bf16_f32 v115, v86, v87
	v_mfma_f32_32x32x16_bf16 v[32:47], v[162:165], v[120:123], v[32:47]
	ds_read_b64_tr_b16 v[162:163], v223 offset:8192
	ds_read_b64_tr_b16 v[164:165], v223 offset:9216
	v_exp_f32_e32 v90, v90
	v_add_f32_e32 v144, v144, v88
	v_exp_f32_e32 v91, v91
	v_add_f32_e32 v144, v144, v89
	v_cvt_pk_bf16_f32 v116, v88, v89
	v_exp_f32_e32 v92, v92
	v_mfma_f32_32x32x16_bf16 v[0:15], v[166:169], v[120:123], v[0:15]
	ds_read_b64_tr_b16 v[166:167], v224 offset:8192
	ds_read_b64_tr_b16 v[168:169], v224 offset:9216
	s_add_i32 s59, s59, 1
	v_add_f32_e32 v144, v144, v90
	v_exp_f32_e32 v93, v93
	v_add_f32_e32 v144, v144, v91
	v_cvt_pk_bf16_f32 v117, v90, v91
	v_exp_f32_e32 v94, v94
	v_mfma_f32_32x32x16_bf16 v[32:47], v[214:217], v[124:127], v[32:47]
	ds_read_b64_tr_b16 v[214:215], v223 offset:10240
	ds_read_b64_tr_b16 v[216:217], v223 offset:11264
	v_add_f32_e32 v144, v144, v92
	v_exp_f32_e32 v95, v95
	v_add_f32_e32 v144, v144, v93
	v_cvt_pk_bf16_f32 v118, v92, v93
	v_add_f32_e32 v144, v144, v94
	v_add_f32_e32 v144, v144, v95
	v_cvt_pk_bf16_f32 v119, v94, v95
	v_mfma_f32_32x32x16_bf16 v[0:15], v[218:221], v[124:127], v[0:15]
	ds_read_b64_tr_b16 v[218:219], v224 offset:10240
	ds_read_b64_tr_b16 v[220:221], v224 offset:11264
	s_add_i32 s71, s25, -7
	s_cmp_lt_i32 s59, s71
	s_waitcnt vmcnt(2) lgkmcnt(8)
	s_barrier
	s_cbranch_scc1 .Laattn_loop
; __device__ __forceinline__ void attn_pass_A2(const int tid, unsigned char* smem, const bf16_t* Q0w, int qpitch, const bf16_t* Kb, int kpitch, const bf16_t* Vb, int vpitch,
;                                              int b, int ntiles, float kmax, f32x16 (&o)[2][2], float (&linv)[2]) {
;     ...
;     for (int kt = 0; kt < ntiles; ++kt) {
;         if (kt + 1 < ntiles) gload(kt + 1);
;         const unsigned char* Ks = smem + (kt & 1) * BUF; const unsigned char* Vs = Ks + KBYTES;
;         const unsigned char* kp = Ks + r32 * KP + hi * 16;
;         const unsigned char* vp = Vs + (4 * hi + q4) * VP + (16 * nhalf + 4 * p4) * 2;
; #pragma unroll
;         for (int kb = 0; kb < 2; ++kb) {
;             bf16x8 pf[2][2];
;             {
;                 f32x16 s0, s1;
; #pragma unroll
;                 for (int r = 0; r < 16; ++r) { s0[r] = nshift[0]; s1[r] = nshift[1]; }
; #pragma unroll
;                 for (int ds = 0; ds < 4; ++ds) {
;                     const bf16x8 kf = *(const bf16x8*)(kp + kb * 32 * KP + ds * 32);
;                     const bf16x8 q0 = *(const bf16x8*)(qs + ds * 32), q1 = *(const bf16x8*)(qs + 32 * KP + ds * 32);
;                     s0 = __builtin_amdgcn_mfma_f32_32x32x16_bf16(kf, q0, s0, 0, 0, 0);
;                     s1 = __builtin_amdgcn_mfma_f32_32x32x16_bf16(kf, q1, s1, 0, 0, 0);
;                 }
;                 float l0 = 0.f, l1 = 0.f;
; #pragma unroll
;                 for (int r = 0; r < 16; ++r) { s0[r] = __builtin_amdgcn_exp2f(s0[r]); l0 += s0[r]; }
; #pragma unroll
;                 for (int r = 0; r < 16; ++r) { s1[r] = __builtin_amdgcn_exp2f(s1[r]); l1 += s1[r]; }
;                 lsum[0] += l0; lsum[1] += l1;
; #pragma unroll
;                 for (int j = 0; j < 2; ++j) {
;                     u32x4 w0, w1;
;                     w0.x = cvt_pk_bf16(s0[8 * j + 0], s0[8 * j + 1]); w0.y = cvt_pk_bf16(s0[8 * j + 2], s0[8 * j + 3]); w0.z = cvt_pk_bf16(s0[8 * j + 4], s0[8 * j + 5]); w0.w = cvt_pk_bf16(s0[8 * j + 6], s0[8 * j + 7]);
;                     w1.x = cvt_pk_bf16(s1[8 * j + 0], s1[8 * j + 1]); w1.y = cvt_pk_bf16(s1[8 * j + 2], s1[8 * j + 3]); w1.z = cvt_pk_bf16(s1[8 * j + 4], s1[8 * j + 5]); w1.w = cvt_pk_bf16(s1[8 * j + 6], s1[8 * j + 7]);
;                     pf[0][j] = __builtin_bit_cast(bf16x8, w0); pf[1][j] = __builtin_bit_cast(bf16x8, w1);
;                 }
;             }
.Laattn_tail:
	v_mfma_f32_32x32x16_bf16 v[80:95], v[198:201], v[146:149], v[16:31]
	v_exp_f32_e32 v96, v96
	v_exp_f32_e32 v97, v97
	v_exp_f32_e32 v98, v98
	v_add_f32_e32 v145, v145, v96
	v_exp_f32_e32 v99, v99
	v_mfma_f32_32x32x16_bf16 v[80:95], v[202:205], v[150:153], v[80:95]
	s_add_i32 s70, s59, 3
	s_cmp_lt_u32 s70, 4
	s_cselect_b32 s2, s65, s32
	s_lshl_b32 s3, s70, 6
	s_add_i32 s2, s2, s3
	s_lshl_b32 s2, s2, 8
	s_add_u32 s60, s66, s2
	s_addc_u32 s61, s67, 0
	s_add_u32 s62, s68, s2
	s_addc_u32 s63, s69, 0
	v_add_f32_e32 v145, v145, v97
	v_cvt_pk_bf16_f32 v120, v96, v97
	v_exp_f32_e32 v100, v100
	v_add_f32_e32 v145, v145, v98
	v_exp_f32_e32 v101, v101
	v_mfma_f32_32x32x16_bf16 v[80:95], v[206:209], v[154:157], v[80:95]
	v_add_f32_e32 v145, v145, v99
	v_cvt_pk_bf16_f32 v121, v98, v99
	v_exp_f32_e32 v102, v102
	v_add_f32_e32 v145, v145, v100
	v_exp_f32_e32 v103, v103
	v_add_f32_e32 v145, v145, v101
	v_mfma_f32_32x32x16_bf16 v[80:95], v[128:131], v[158:161], v[80:95]
	s_add_i32 m0, s56, 0xc000
	s_nop 0
	global_load_lds_dwordx4 v236, s[60:61]
	v_cvt_pk_bf16_f32 v122, v100, v101
	v_exp_f32_e32 v104, v104
	v_add_f32_e32 v145, v145, v102
	v_exp_f32_e32 v105, v105
	v_add_f32_e32 v145, v145, v103
	v_cvt_pk_bf16_f32 v123, v102, v103
	s_waitcnt lgkmcnt(6)
	v_mfma_f32_32x32x16_bf16 v[64:79], v[162:165], v[112:115], v[64:79]
	v_exp_f32_e32 v106, v106
	v_add_f32_e32 v145, v145, v104
	v_exp_f32_e32 v107, v107
	v_add_f32_e32 v145, v145, v105
	v_cvt_pk_bf16_f32 v124, v104, v105
	v_exp_f32_e32 v108, v108
	s_waitcnt lgkmcnt(4)
	v_mfma_f32_32x32x16_bf16 v[48:63], v[166:169], v[112:115], v[48:63]
	s_add_i32 m0, s56, 0xe000
	s_nop 0
	global_load_lds_dwordx4 v234, s[62:63]
	v_add_f32_e32 v145, v145, v106
	v_exp_f32_e32 v109, v109
	v_add_f32_e32 v145, v145, v107
	v_cvt_pk_bf16_f32 v125, v106, v107
	v_exp_f32_e32 v110, v110
	s_waitcnt lgkmcnt(2)
	v_mfma_f32_32x32x16_bf16 v[64:79], v[214:217], v[116:119], v[64:79]
	v_add_f32_e32 v145, v145, v108
	v_exp_f32_e32 v111, v111
	v_add_f32_e32 v145, v145, v109
	v_cvt_pk_bf16_f32 v126, v108, v109
	v_add_f32_e32 v145, v145, v110
	v_add_f32_e32 v145, v145, v111
	v_cvt_pk_bf16_f32 v127, v110, v111
	s_waitcnt lgkmcnt(0)
	v_mfma_f32_32x32x16_bf16 v[48:63], v[218:221], v[116:119], v[48:63]
	v_mfma_f32_32x32x16_bf16 v[96:111], v[198:201], v[176:179], v[16:31]
	ds_read_b128 v[198:201], v170 offset:16384
	v_exp_f32_e32 v80, v80
	v_exp_f32_e32 v81, v81
	v_exp_f32_e32 v82, v82
	v_add_f32_e32 v144, v144, v80
	v_exp_f32_e32 v83, v83
	v_mfma_f32_32x32x16_bf16 v[96:111], v[202:205], v[180:183], v[96:111]
	ds_read_b128 v[202:205], v171 offset:16384
	v_add_f32_e32 v144, v144, v81
	v_cvt_pk_bf16_f32 v112, v80, v81
	v_exp_f32_e32 v84, v84
	v_add_f32_e32 v144, v144, v82
	v_exp_f32_e32 v85, v85
	v_mfma_f32_32x32x16_bf16 v[96:111], v[206:209], v[184:187], v[96:111]
	ds_read_b128 v[206:209], v210 offset:16384
	v_add_f32_e32 v144, v144, v83
	v_cvt_pk_bf16_f32 v113, v82, v83
	v_exp_f32_e32 v86, v86
	v_add_f32_e32 v144, v144, v84
	v_exp_f32_e32 v87, v87
	v_add_f32_e32 v144, v144, v85
	v_mfma_f32_32x32x16_bf16 v[96:111], v[128:131], v[188:191], v[96:111]
	ds_read_b128 v[128:131], v222 offset:16384
	v_cvt_pk_bf16_f32 v114, v84, v85
	v_exp_f32_e32 v88, v88
	v_add_f32_e32 v144, v144, v86
	v_exp_f32_e32 v89, v89
	v_add_f32_e32 v144, v144, v87
	v_cvt_pk_bf16_f32 v115, v86, v87
	v_mfma_f32_32x32x16_bf16 v[32:47], v[162:165], v[120:123], v[32:47]
	ds_read_b64_tr_b16 v[162:163], v223 offset:12288
	ds_read_b64_tr_b16 v[164:165], v223 offset:13312
	v_exp_f32_e32 v90, v90
	v_add_f32_e32 v144, v144, v88
	v_exp_f32_e32 v91, v91
	v_add_f32_e32 v144, v144, v89
	v_cvt_pk_bf16_f32 v116, v88, v89
	v_exp_f32_e32 v92, v92
	v_mfma_f32_32x32x16_bf16 v[0:15], v[166:169], v[120:123], v[0:15]
	ds_read_b64_tr_b16 v[166:167], v224 offset:12288
	ds_read_b64_tr_b16 v[168:169], v224 offset:13312
	v_add_f32_e32 v144, v144, v90
	v_exp_f32_e32 v93, v93
	v_add_f32_e32 v144, v144, v91
	v_cvt_pk_bf16_f32 v117, v90, v91
	v_exp_f32_e32 v94, v94
	v_mfma_f32_32x32x16_bf16 v[32:47], v[214:217], v[124:127], v[32:47]
	ds_read_b64_tr_b16 v[214:215], v223 offset:14336
	ds_read_b64_tr_b16 v[216:217], v223 offset:15360
	v_add_f32_e32 v144, v144, v92
	v_exp_f32_e32 v95, v95
	v_add_f32_e32 v144, v144, v93
	v_cvt_pk_bf16_f32 v118, v92, v93
	v_add_f32_e32 v144, v144, v94
	v_add_f32_e32 v144, v144, v95
	v_cvt_pk_bf16_f32 v119, v94, v95
	v_mfma_f32_32x32x16_bf16 v[0:15], v[218:221], v[124:127], v[0:15]
	ds_read_b64_tr_b16 v[218:219], v224 offset:14336
	ds_read_b64_tr_b16 v[220:221], v224 offset:15360
	s_waitcnt lgkmcnt(11)
	v_mfma_f32_32x32x16_bf16 v[80:95], v[198:201], v[146:149], v[16:31]
	v_exp_f32_e32 v96, v96
	v_exp_f32_e32 v97, v97
	v_exp_f32_e32 v98, v98
	v_add_f32_e32 v145, v145, v96
	v_exp_f32_e32 v99, v99
	s_waitcnt lgkmcnt(10)
	v_mfma_f32_32x32x16_bf16 v[80:95], v[202:205], v[150:153], v[80:95]
	v_add_f32_e32 v145, v145, v97
	v_cvt_pk_bf16_f32 v120, v96, v97
	v_exp_f32_e32 v100, v100
	v_add_f32_e32 v145, v145, v98
	v_exp_f32_e32 v101, v101
	s_waitcnt lgkmcnt(9)
	v_mfma_f32_32x32x16_bf16 v[80:95], v[206:209], v[154:157], v[80:95]
	v_add_f32_e32 v145, v145, v99
	v_cvt_pk_bf16_f32 v121, v98, v99
	v_exp_f32_e32 v102, v102
	v_add_f32_e32 v145, v145, v100
	v_exp_f32_e32 v103, v103
	v_add_f32_e32 v145, v145, v101
	s_waitcnt lgkmcnt(8)
	v_mfma_f32_32x32x16_bf16 v[80:95], v[128:131], v[158:161], v[80:95]
	v_cvt_pk_bf16_f32 v122, v100, v101
	v_exp_f32_e32 v104, v104
	v_add_f32_e32 v145, v145, v102
	v_exp_f32_e32 v105, v105
	v_add_f32_e32 v145, v145, v103
	v_cvt_pk_bf16_f32 v123, v102, v103
	s_waitcnt lgkmcnt(6)
; __device__ __forceinline__ void attn_pass_A2(const int tid, unsigned char* smem, const bf16_t* Q0w, int qpitch, const bf16_t* Kb, int kpitch, const bf16_t* Vb, int vpitch,
;                                              int b, int ntiles, float kmax, f32x16 (&o)[2][2], float (&linv)[2]) {
;     ...
;     for (int kt = 0; kt < ntiles; ++kt) {
;         if (kt + 1 < ntiles) gload(kt + 1);
;         const unsigned char* Ks = smem + (kt & 1) * BUF; const unsigned char* Vs = Ks + KBYTES;
;         const unsigned char* kp = Ks + r32 * KP + hi * 16;
;         const unsigned char* vp = Vs + (4 * hi + q4) * VP + (16 * nhalf + 4 * p4) * 2;
; #pragma unroll
;         for (int kb = 0; kb < 2; ++kb) {
;             bf16x8 pf[2][2];
;             {
;                 f32x16 s0, s1;
; #pragma unroll
;                 for (int r = 0; r < 16; ++r) { s0[r] = nshift[0]; s1[r] = nshift[1]; }
; #pragma unroll
;                 for (int ds = 0; ds < 4; ++ds) {
;                     const bf16x8 kf = *(const bf16x8*)(kp + kb * 32 * KP + ds * 32);
;                     const bf16x8 q0 = *(const bf16x8*)(qs + ds * 32), q1 = *(const bf16x8*)(qs + 32 * KP + ds * 32);
;                     s0 = __builtin_amdgcn_mfma_f32_32x32x16_bf16(kf, q0, s0, 0, 0, 0);
;                     s1 = __builtin_amdgcn_mfma_f32_32x32x16_bf16(kf, q1, s1, 0, 0, 0);
;                 }
;                 float l0 = 0.f, l1 = 0.f;
; #pragma unroll
;                 for (int r = 0; r < 16; ++r) { s0[r] = __builtin_amdgcn_exp2f(s0[r]); l0 += s0[r]; }
; #pragma unroll
;                 for (int r = 0; r < 16; ++r) { s1[r] = __builtin_amdgcn_exp2f(s1[r]); l1 += s1[r]; }
;                 lsum[0] += l0; lsum[1] += l1;
; #pragma unroll
;                 for (int j = 0; j < 2; ++j) {
;                     u32x4 w0, w1;
;                     w0.x = cvt_pk_bf16(s0[8 * j + 0], s0[8 * j + 1]); w0.y = cvt_pk_bf16(s0[8 * j + 2], s0[8 * j + 3]); w0.z = cvt_pk_bf16(s0[8 * j + 4], s0[8 * j + 5]); w0.w = cvt_pk_bf16(s0[8 * j + 6], s0[8 * j + 7]);
;                     w1.x = cvt_pk_bf16(s1[8 * j + 0], s1[8 * j + 1]); w1.y = cvt_pk_bf16(s1[8 * j + 2], s1[8 * j + 3]); w1.z = cvt_pk_bf16(s1[8 * j + 4], s1[8 * j + 5]); w1.w = cvt_pk_bf16(s1[8 * j + 6], s1[8 * j + 7]);
;                     pf[0][j] = __builtin_bit_cast(bf16x8, w0); pf[1][j] = __builtin_bit_cast(bf16x8, w1);
;                 }
;             }
	v_mfma_f32_32x32x16_bf16 v[64:79], v[162:165], v[112:115], v[64:79]
	v_exp_f32_e32 v106, v106
	v_add_f32_e32 v145, v145, v104
	v_exp_f32_e32 v107, v107
	v_add_f32_e32 v145, v145, v105
	v_cvt_pk_bf16_f32 v124, v104, v105
	v_exp_f32_e32 v108, v108
	s_waitcnt lgkmcnt(4)
	v_mfma_f32_32x32x16_bf16 v[48:63], v[166:169], v[112:115], v[48:63]
	v_add_f32_e32 v145, v145, v106
	v_exp_f32_e32 v109, v109
	v_add_f32_e32 v145, v145, v107
	v_cvt_pk_bf16_f32 v125, v106, v107
	v_exp_f32_e32 v110, v110
	s_waitcnt lgkmcnt(2)
	v_mfma_f32_32x32x16_bf16 v[64:79], v[214:217], v[116:119], v[64:79]
	v_add_f32_e32 v145, v145, v108
	v_exp_f32_e32 v111, v111
	v_add_f32_e32 v145, v145, v109
	v_cvt_pk_bf16_f32 v126, v108, v109
	v_add_f32_e32 v145, v145, v110
	v_add_f32_e32 v145, v145, v111
	v_cvt_pk_bf16_f32 v127, v110, v111
	s_waitcnt lgkmcnt(0)
	v_mfma_f32_32x32x16_bf16 v[48:63], v[218:221], v[116:119], v[48:63]
	v_mfma_f32_32x32x16_bf16 v[96:111], v[198:201], v[176:179], v[16:31]
	ds_read_b128 v[198:201], v170 offset:20480
	v_exp_f32_e32 v80, v80
	v_exp_f32_e32 v81, v81
	v_exp_f32_e32 v82, v82
	v_add_f32_e32 v144, v144, v80
	v_exp_f32_e32 v83, v83
	v_mfma_f32_32x32x16_bf16 v[96:111], v[202:205], v[180:183], v[96:111]
	ds_read_b128 v[202:205], v171 offset:20480
	v_add_f32_e32 v144, v144, v81
	v_cvt_pk_bf16_f32 v112, v80, v81
	v_exp_f32_e32 v84, v84
	v_add_f32_e32 v144, v144, v82
	v_exp_f32_e32 v85, v85
	v_mfma_f32_32x32x16_bf16 v[96:111], v[206:209], v[184:187], v[96:111]
	ds_read_b128 v[206:209], v210 offset:20480
	v_add_f32_e32 v144, v144, v83
	v_cvt_pk_bf16_f32 v113, v82, v83
	v_exp_f32_e32 v86, v86
	v_add_f32_e32 v144, v144, v84
	v_exp_f32_e32 v87, v87
	v_add_f32_e32 v144, v144, v85
	v_mfma_f32_32x32x16_bf16 v[96:111], v[128:131], v[188:191], v[96:111]
	ds_read_b128 v[128:131], v222 offset:20480
	v_cvt_pk_bf16_f32 v114, v84, v85
	v_exp_f32_e32 v88, v88
	v_add_f32_e32 v144, v144, v86
	v_exp_f32_e32 v89, v89
	v_add_f32_e32 v144, v144, v87
	v_cvt_pk_bf16_f32 v115, v86, v87
	v_mfma_f32_32x32x16_bf16 v[32:47], v[162:165], v[120:123], v[32:47]
	ds_read_b64_tr_b16 v[162:163], v223 offset:24576
	ds_read_b64_tr_b16 v[164:165], v223 offset:25600
	v_exp_f32_e32 v90, v90
	v_add_f32_e32 v144, v144, v88
	v_exp_f32_e32 v91, v91
	v_add_f32_e32 v144, v144, v89
	v_cvt_pk_bf16_f32 v116, v88, v89
	v_exp_f32_e32 v92, v92
	v_mfma_f32_32x32x16_bf16 v[0:15], v[166:169], v[120:123], v[0:15]
	ds_read_b64_tr_b16 v[166:167], v224 offset:24576
	ds_read_b64_tr_b16 v[168:169], v224 offset:25600
	s_add_i32 s59, s59, 1
	v_add_f32_e32 v144, v144, v90
	v_exp_f32_e32 v93, v93
	v_add_f32_e32 v144, v144, v91
	v_cvt_pk_bf16_f32 v117, v90, v91
	v_exp_f32_e32 v94, v94
	v_mfma_f32_32x32x16_bf16 v[32:47], v[214:217], v[124:127], v[32:47]
	ds_read_b64_tr_b16 v[214:215], v223 offset:26624
	ds_read_b64_tr_b16 v[216:217], v223 offset:27648
	v_add_f32_e32 v144, v144, v92
	v_exp_f32_e32 v95, v95
	v_add_f32_e32 v144, v144, v93
	v_cvt_pk_bf16_f32 v118, v92, v93
	v_add_f32_e32 v144, v144, v94
	v_add_f32_e32 v144, v144, v95
	v_cvt_pk_bf16_f32 v119, v94, v95
	v_mfma_f32_32x32x16_bf16 v[0:15], v[218:221], v[124:127], v[0:15]
	ds_read_b64_tr_b16 v[218:219], v224 offset:26624
	ds_read_b64_tr_b16 v[220:221], v224 offset:27648
	s_waitcnt vmcnt(2) lgkmcnt(8)
	s_barrier
	v_mfma_f32_32x32x16_bf16 v[80:95], v[198:201], v[146:149], v[16:31]
	v_exp_f32_e32 v96, v96
	v_exp_f32_e32 v97, v97
	v_exp_f32_e32 v98, v98
	v_add_f32_e32 v145, v145, v96
	v_exp_f32_e32 v99, v99
	v_mfma_f32_32x32x16_bf16 v[80:95], v[202:205], v[150:153], v[80:95]
	v_add_f32_e32 v145, v145, v97
	v_cvt_pk_bf16_f32 v120, v96, v97
	v_exp_f32_e32 v100, v100
	v_add_f32_e32 v145, v145, v98
	v_exp_f32_e32 v101, v101
	v_mfma_f32_32x32x16_bf16 v[80:95], v[206:209], v[154:157], v[80:95]
	v_add_f32_e32 v145, v145, v99
	v_cvt_pk_bf16_f32 v121, v98, v99
	v_exp_f32_e32 v102, v102
	v_add_f32_e32 v145, v145, v100
	v_exp_f32_e32 v103, v103
	v_add_f32_e32 v145, v145, v101
	v_mfma_f32_32x32x16_bf16 v[80:95], v[128:131], v[158:161], v[80:95]
	v_cvt_pk_bf16_f32 v122, v100, v101
	v_exp_f32_e32 v104, v104
	v_add_f32_e32 v145, v145, v102
	v_exp_f32_e32 v105, v105
	v_add_f32_e32 v145, v145, v103
	v_cvt_pk_bf16_f32 v123, v102, v103
	s_waitcnt lgkmcnt(6)
	v_mfma_f32_32x32x16_bf16 v[64:79], v[162:165], v[112:115], v[64:79]
	v_exp_f32_e32 v106, v106
	v_add_f32_e32 v145, v145, v104
	v_exp_f32_e32 v107, v107
	v_add_f32_e32 v145, v145, v105
	v_cvt_pk_bf16_f32 v124, v104, v105
	v_exp_f32_e32 v108, v108
	s_waitcnt lgkmcnt(4)
	v_mfma_f32_32x32x16_bf16 v[48:63], v[166:169], v[112:115], v[48:63]
	v_add_f32_e32 v145, v145, v106
	v_exp_f32_e32 v109, v109
	v_add_f32_e32 v145, v145, v107
	v_cvt_pk_bf16_f32 v125, v106, v107
	v_exp_f32_e32 v110, v110
	s_waitcnt lgkmcnt(2)
	v_mfma_f32_32x32x16_bf16 v[64:79], v[214:217], v[116:119], v[64:79]
	v_add_f32_e32 v145, v145, v108
	v_exp_f32_e32 v111, v111
	v_add_f32_e32 v145, v145, v109
	v_cvt_pk_bf16_f32 v126, v108, v109
	v_add_f32_e32 v145, v145, v110
	v_add_f32_e32 v145, v145, v111
	v_cvt_pk_bf16_f32 v127, v110, v111
	s_waitcnt lgkmcnt(0)
; __device__ __forceinline__ void attn_pass_A2(const int tid, unsigned char* smem, const bf16_t* Q0w, int qpitch, const bf16_t* Kb, int kpitch, const bf16_t* Vb, int vpitch,
;                                              int b, int ntiles, float kmax, f32x16 (&o)[2][2], float (&linv)[2]) {
;     ...
;     for (int kt = 0; kt < ntiles; ++kt) {
;         if (kt + 1 < ntiles) gload(kt + 1);
;         const unsigned char* Ks = smem + (kt & 1) * BUF; const unsigned char* Vs = Ks + KBYTES;
;         const unsigned char* kp = Ks + r32 * KP + hi * 16;
;         const unsigned char* vp = Vs + (4 * hi + q4) * VP + (16 * nhalf + 4 * p4) * 2;
; #pragma unroll
;         for (int kb = 0; kb < 2; ++kb) {
;             bf16x8 pf[2][2];
;             {
;                 f32x16 s0, s1;
; #pragma unroll
;                 for (int r = 0; r < 16; ++r) { s0[r] = nshift[0]; s1[r] = nshift[1]; }
; #pragma unroll
;                 for (int ds = 0; ds < 4; ++ds) {
;                     const bf16x8 kf = *(const bf16x8*)(kp + kb * 32 * KP + ds * 32);
;                     const bf16x8 q0 = *(const bf16x8*)(qs + ds * 32), q1 = *(const bf16x8*)(qs + 32 * KP + ds * 32);
;                     s0 = __builtin_amdgcn_mfma_f32_32x32x16_bf16(kf, q0, s0, 0, 0, 0);
;                     s1 = __builtin_amdgcn_mfma_f32_32x32x16_bf16(kf, q1, s1, 0, 0, 0);
;                 }
;                 float l0 = 0.f, l1 = 0.f;
; #pragma unroll
;                 for (int r = 0; r < 16; ++r) { s0[r] = __builtin_amdgcn_exp2f(s0[r]); l0 += s0[r]; }
; #pragma unroll
;                 for (int r = 0; r < 16; ++r) { s1[r] = __builtin_amdgcn_exp2f(s1[r]); l1 += s1[r]; }
;                 lsum[0] += l0; lsum[1] += l1;
; #pragma unroll
;                 for (int j = 0; j < 2; ++j) {
;                     u32x4 w0, w1;
;                     w0.x = cvt_pk_bf16(s0[8 * j + 0], s0[8 * j + 1]); w0.y = cvt_pk_bf16(s0[8 * j + 2], s0[8 * j + 3]); w0.z = cvt_pk_bf16(s0[8 * j + 4], s0[8 * j + 5]); w0.w = cvt_pk_bf16(s0[8 * j + 6], s0[8 * j + 7]);
;                     w1.x = cvt_pk_bf16(s1[8 * j + 0], s1[8 * j + 1]); w1.y = cvt_pk_bf16(s1[8 * j + 2], s1[8 * j + 3]); w1.z = cvt_pk_bf16(s1[8 * j + 4], s1[8 * j + 5]); w1.w = cvt_pk_bf16(s1[8 * j + 6], s1[8 * j + 7]);
;                     pf[0][j] = __builtin_bit_cast(bf16x8, w0); pf[1][j] = __builtin_bit_cast(bf16x8, w1);
;                 }
;             }
	v_mfma_f32_32x32x16_bf16 v[48:63], v[218:221], v[116:119], v[48:63]
	v_mfma_f32_32x32x16_bf16 v[96:111], v[198:201], v[176:179], v[16:31]
	ds_read_b128 v[198:201], v170 offset:32768
	v_exp_f32_e32 v80, v80
	v_exp_f32_e32 v81, v81
	v_exp_f32_e32 v82, v82
	v_add_f32_e32 v144, v144, v80
	v_exp_f32_e32 v83, v83
	v_mfma_f32_32x32x16_bf16 v[96:111], v[202:205], v[180:183], v[96:111]
	ds_read_b128 v[202:205], v171 offset:32768
	v_add_f32_e32 v144, v144, v81
	v_cvt_pk_bf16_f32 v112, v80, v81
	v_exp_f32_e32 v84, v84
	v_add_f32_e32 v144, v144, v82
	v_exp_f32_e32 v85, v85
	v_mfma_f32_32x32x16_bf16 v[96:111], v[206:209], v[184:187], v[96:111]
	ds_read_b128 v[206:209], v210 offset:32768
	v_add_f32_e32 v144, v144, v83
	v_cvt_pk_bf16_f32 v113, v82, v83
	v_exp_f32_e32 v86, v86
	v_add_f32_e32 v144, v144, v84
	v_exp_f32_e32 v87, v87
	v_add_f32_e32 v144, v144, v85
	v_mfma_f32_32x32x16_bf16 v[96:111], v[128:131], v[188:191], v[96:111]
	ds_read_b128 v[128:131], v222 offset:32768
	v_cvt_pk_bf16_f32 v114, v84, v85
	v_exp_f32_e32 v88, v88
	v_add_f32_e32 v144, v144, v86
	v_exp_f32_e32 v89, v89
	v_add_f32_e32 v144, v144, v87
	v_cvt_pk_bf16_f32 v115, v86, v87
	v_mfma_f32_32x32x16_bf16 v[32:47], v[162:165], v[120:123], v[32:47]
	ds_read_b64_tr_b16 v[162:163], v223 offset:28672
	ds_read_b64_tr_b16 v[164:165], v223 offset:29696
	v_exp_f32_e32 v90, v90
	v_add_f32_e32 v144, v144, v88
	v_exp_f32_e32 v91, v91
	v_add_f32_e32 v144, v144, v89
	v_cvt_pk_bf16_f32 v116, v88, v89
	v_exp_f32_e32 v92, v92
	v_mfma_f32_32x32x16_bf16 v[0:15], v[166:169], v[120:123], v[0:15]
	ds_read_b64_tr_b16 v[166:167], v224 offset:28672
	ds_read_b64_tr_b16 v[168:169], v224 offset:29696
	v_add_f32_e32 v144, v144, v90
	v_exp_f32_e32 v93, v93
	v_add_f32_e32 v144, v144, v91
	v_cvt_pk_bf16_f32 v117, v90, v91
	v_exp_f32_e32 v94, v94
	v_mfma_f32_32x32x16_bf16 v[32:47], v[214:217], v[124:127], v[32:47]
	ds_read_b64_tr_b16 v[214:215], v223 offset:30720
	ds_read_b64_tr_b16 v[216:217], v223 offset:31744
	v_add_f32_e32 v144, v144, v92
	v_exp_f32_e32 v95, v95
	v_add_f32_e32 v144, v144, v93
	v_cvt_pk_bf16_f32 v118, v92, v93
	v_add_f32_e32 v144, v144, v94
	v_add_f32_e32 v144, v144, v95
	v_cvt_pk_bf16_f32 v119, v94, v95
	v_mfma_f32_32x32x16_bf16 v[0:15], v[218:221], v[124:127], v[0:15]
	ds_read_b64_tr_b16 v[218:219], v224 offset:30720
	ds_read_b64_tr_b16 v[220:221], v224 offset:31744
	s_waitcnt lgkmcnt(11)
	v_mfma_f32_32x32x16_bf16 v[80:95], v[198:201], v[146:149], v[16:31]
	v_exp_f32_e32 v96, v96
	v_exp_f32_e32 v97, v97
	v_exp_f32_e32 v98, v98
	v_add_f32_e32 v145, v145, v96
	v_exp_f32_e32 v99, v99
	s_waitcnt lgkmcnt(10)
	v_mfma_f32_32x32x16_bf16 v[80:95], v[202:205], v[150:153], v[80:95]
	v_add_f32_e32 v145, v145, v97
	v_cvt_pk_bf16_f32 v120, v96, v97
	v_exp_f32_e32 v100, v100
	v_add_f32_e32 v145, v145, v98
	v_exp_f32_e32 v101, v101
	s_waitcnt lgkmcnt(9)
	v_mfma_f32_32x32x16_bf16 v[80:95], v[206:209], v[154:157], v[80:95]
	v_add_f32_e32 v145, v145, v99
	v_cvt_pk_bf16_f32 v121, v98, v99
	v_exp_f32_e32 v102, v102
	v_add_f32_e32 v145, v145, v100
	v_exp_f32_e32 v103, v103
	v_add_f32_e32 v145, v145, v101
	s_waitcnt lgkmcnt(8)
	v_mfma_f32_32x32x16_bf16 v[80:95], v[128:131], v[158:161], v[80:95]
	v_cvt_pk_bf16_f32 v122, v100, v101
	v_exp_f32_e32 v104, v104
	v_add_f32_e32 v145, v145, v102
	v_exp_f32_e32 v105, v105
	v_add_f32_e32 v145, v145, v103
	v_cvt_pk_bf16_f32 v123, v102, v103
	s_waitcnt lgkmcnt(6)
	v_mfma_f32_32x32x16_bf16 v[64:79], v[162:165], v[112:115], v[64:79]
	v_exp_f32_e32 v106, v106
	v_add_f32_e32 v145, v145, v104
	v_exp_f32_e32 v107, v107
	v_add_f32_e32 v145, v145, v105
	v_cvt_pk_bf16_f32 v124, v104, v105
	v_exp_f32_e32 v108, v108
	s_waitcnt lgkmcnt(4)
	v_mfma_f32_32x32x16_bf16 v[48:63], v[166:169], v[112:115], v[48:63]
	v_add_f32_e32 v145, v145, v106
	v_exp_f32_e32 v109, v109
	v_add_f32_e32 v145, v145, v107
	v_cvt_pk_bf16_f32 v125, v106, v107
	v_exp_f32_e32 v110, v110
	s_waitcnt lgkmcnt(2)
	v_mfma_f32_32x32x16_bf16 v[64:79], v[214:217], v[116:119], v[64:79]
	v_add_f32_e32 v145, v145, v108
	v_exp_f32_e32 v111, v111
	v_add_f32_e32 v145, v145, v109
	v_cvt_pk_bf16_f32 v126, v108, v109
	v_add_f32_e32 v145, v145, v110
	v_add_f32_e32 v145, v145, v111
	v_cvt_pk_bf16_f32 v127, v110, v111
	s_waitcnt lgkmcnt(0)
	v_mfma_f32_32x32x16_bf16 v[48:63], v[218:221], v[116:119], v[48:63]
	v_mfma_f32_32x32x16_bf16 v[96:111], v[198:201], v[176:179], v[16:31]
	ds_read_b128 v[198:201], v170 offset:36864
	v_exp_f32_e32 v80, v80
	v_exp_f32_e32 v81, v81
	v_exp_f32_e32 v82, v82
	v_add_f32_e32 v144, v144, v80
	v_exp_f32_e32 v83, v83
	v_mfma_f32_32x32x16_bf16 v[96:111], v[202:205], v[180:183], v[96:111]
	ds_read_b128 v[202:205], v171 offset:36864
	v_add_f32_e32 v144, v144, v81
	v_cvt_pk_bf16_f32 v112, v80, v81
	v_exp_f32_e32 v84, v84
	v_add_f32_e32 v144, v144, v82
	v_exp_f32_e32 v85, v85
	v_mfma_f32_32x32x16_bf16 v[96:111], v[206:209], v[184:187], v[96:111]
	ds_read_b128 v[206:209], v210 offset:36864
	v_add_f32_e32 v144, v144, v83
	v_cvt_pk_bf16_f32 v113, v82, v83
	v_exp_f32_e32 v86, v86
	v_add_f32_e32 v144, v144, v84
	v_exp_f32_e32 v87, v87
	v_add_f32_e32 v144, v144, v85
	v_mfma_f32_32x32x16_bf16 v[96:111], v[128:131], v[188:191], v[96:111]
	ds_read_b128 v[128:131], v222 offset:36864
	v_cvt_pk_bf16_f32 v114, v84, v85
	v_exp_f32_e32 v88, v88
	v_add_f32_e32 v144, v144, v86
	v_exp_f32_e32 v89, v89
	v_add_f32_e32 v144, v144, v87
	v_cvt_pk_bf16_f32 v115, v86, v87
	v_mfma_f32_32x32x16_bf16 v[32:47], v[162:165], v[120:123], v[32:47]
	ds_read_b64_tr_b16 v[162:163], v223 offset:40960
	ds_read_b64_tr_b16 v[164:165], v223 offset:41984
	v_exp_f32_e32 v90, v90
	v_add_f32_e32 v144, v144, v88
	v_exp_f32_e32 v91, v91
	v_add_f32_e32 v144, v144, v89
	v_cvt_pk_bf16_f32 v116, v88, v89
	v_exp_f32_e32 v92, v92
	v_mfma_f32_32x32x16_bf16 v[0:15], v[166:169], v[120:123], v[0:15]
	ds_read_b64_tr_b16 v[166:167], v224 offset:40960
	ds_read_b64_tr_b16 v[168:169], v224 offset:41984
	s_add_i32 s59, s59, 1
	v_add_f32_e32 v144, v144, v90
	v_exp_f32_e32 v93, v93
	v_add_f32_e32 v144, v144, v91
	v_cvt_pk_bf16_f32 v117, v90, v91
	v_exp_f32_e32 v94, v94
	v_mfma_f32_32x32x16_bf16 v[32:47], v[214:217], v[124:127], v[32:47]
	ds_read_b64_tr_b16 v[214:215], v223 offset:43008
	ds_read_b64_tr_b16 v[216:217], v223 offset:44032
	v_add_f32_e32 v144, v144, v92
	v_exp_f32_e32 v95, v95
	v_add_f32_e32 v144, v144, v93
	v_cvt_pk_bf16_f32 v118, v92, v93
	v_add_f32_e32 v144, v144, v94
	v_add_f32_e32 v144, v144, v95
	v_cvt_pk_bf16_f32 v119, v94, v95
	v_mfma_f32_32x32x16_bf16 v[0:15], v[218:221], v[124:127], v[0:15]
	ds_read_b64_tr_b16 v[218:219], v224 offset:43008
	ds_read_b64_tr_b16 v[220:221], v224 offset:44032
	s_waitcnt vmcnt(0) lgkmcnt(8)
	s_barrier
; __device__ __forceinline__ void attn_pass_A2(const int tid, unsigned char* smem, const bf16_t* Q0w, int qpitch, const bf16_t* Kb, int kpitch, const bf16_t* Vb, int vpitch,
;                                              int b, int ntiles, float kmax, f32x16 (&o)[2][2], float (&linv)[2]) {
;     ...
;     for (int kt = 0; kt < ntiles; ++kt) {
;         if (kt + 1 < ntiles) gload(kt + 1);
;         const unsigned char* Ks = smem + (kt & 1) * BUF; const unsigned char* Vs = Ks + KBYTES;
;         const unsigned char* kp = Ks + r32 * KP + hi * 16;
;         const unsigned char* vp = Vs + (4 * hi + q4) * VP + (16 * nhalf + 4 * p4) * 2;
; #pragma unroll
;         for (int kb = 0; kb < 2; ++kb) {
;             bf16x8 pf[2][2];
;             {
;                 f32x16 s0, s1;
; #pragma unroll
;                 for (int r = 0; r < 16; ++r) { s0[r] = nshift[0]; s1[r] = nshift[1]; }
; #pragma unroll
;                 for (int ds = 0; ds < 4; ++ds) {
;                     const bf16x8 kf = *(const bf16x8*)(kp + kb * 32 * KP + ds * 32);
;                     const bf16x8 q0 = *(const bf16x8*)(qs + ds * 32), q1 = *(const bf16x8*)(qs + 32 * KP + ds * 32);
;                     s0 = __builtin_amdgcn_mfma_f32_32x32x16_bf16(kf, q0, s0, 0, 0, 0);
;                     s1 = __builtin_amdgcn_mfma_f32_32x32x16_bf16(kf, q1, s1, 0, 0, 0);
;                 }
;                 float l0 = 0.f, l1 = 0.f;
; #pragma unroll
;                 for (int r = 0; r < 16; ++r) { s0[r] = __builtin_amdgcn_exp2f(s0[r]); l0 += s0[r]; }
; #pragma unroll
;                 for (int r = 0; r < 16; ++r) { s1[r] = __builtin_amdgcn_exp2f(s1[r]); l1 += s1[r]; }
;                 lsum[0] += l0; lsum[1] += l1;
; #pragma unroll
;                 for (int j = 0; j < 2; ++j) {
;                     u32x4 w0, w1;
;                     w0.x = cvt_pk_bf16(s0[8 * j + 0], s0[8 * j + 1]); w0.y = cvt_pk_bf16(s0[8 * j + 2], s0[8 * j + 3]); w0.z = cvt_pk_bf16(s0[8 * j + 4], s0[8 * j + 5]); w0.w = cvt_pk_bf16(s0[8 * j + 6], s0[8 * j + 7]);
;                     w1.x = cvt_pk_bf16(s1[8 * j + 0], s1[8 * j + 1]); w1.y = cvt_pk_bf16(s1[8 * j + 2], s1[8 * j + 3]); w1.z = cvt_pk_bf16(s1[8 * j + 4], s1[8 * j + 5]); w1.w = cvt_pk_bf16(s1[8 * j + 6], s1[8 * j + 7]);
;                     pf[0][j] = __builtin_bit_cast(bf16x8, w0); pf[1][j] = __builtin_bit_cast(bf16x8, w1);
;                 }
;             }
	v_mfma_f32_32x32x16_bf16 v[80:95], v[198:201], v[146:149], v[16:31]
	v_exp_f32_e32 v96, v96
	v_exp_f32_e32 v97, v97
	v_exp_f32_e32 v98, v98
	v_add_f32_e32 v145, v145, v96
	v_exp_f32_e32 v99, v99
	v_mfma_f32_32x32x16_bf16 v[80:95], v[202:205], v[150:153], v[80:95]
	v_add_f32_e32 v145, v145, v97
	v_cvt_pk_bf16_f32 v120, v96, v97
	v_exp_f32_e32 v100, v100
	v_add_f32_e32 v145, v145, v98
	v_exp_f32_e32 v101, v101
	v_mfma_f32_32x32x16_bf16 v[80:95], v[206:209], v[154:157], v[80:95]
	v_add_f32_e32 v145, v145, v99
	v_cvt_pk_bf16_f32 v121, v98, v99
	v_exp_f32_e32 v102, v102
	v_add_f32_e32 v145, v145, v100
	v_exp_f32_e32 v103, v103
	v_add_f32_e32 v145, v145, v101
	v_mfma_f32_32x32x16_bf16 v[80:95], v[128:131], v[158:161], v[80:95]
	v_cvt_pk_bf16_f32 v122, v100, v101
	v_exp_f32_e32 v104, v104
	v_add_f32_e32 v145, v145, v102
	v_exp_f32_e32 v105, v105
	v_add_f32_e32 v145, v145, v103
	v_cvt_pk_bf16_f32 v123, v102, v103
	s_waitcnt lgkmcnt(6)
	v_mfma_f32_32x32x16_bf16 v[64:79], v[162:165], v[112:115], v[64:79]
	v_exp_f32_e32 v106, v106
	v_add_f32_e32 v145, v145, v104
	v_exp_f32_e32 v107, v107
	v_add_f32_e32 v145, v145, v105
	v_cvt_pk_bf16_f32 v124, v104, v105
	v_exp_f32_e32 v108, v108
	s_waitcnt lgkmcnt(4)
	v_mfma_f32_32x32x16_bf16 v[48:63], v[166:169], v[112:115], v[48:63]
	v_add_f32_e32 v145, v145, v106
	v_exp_f32_e32 v109, v109
	v_add_f32_e32 v145, v145, v107
	v_cvt_pk_bf16_f32 v125, v106, v107
	v_exp_f32_e32 v110, v110
	s_waitcnt lgkmcnt(2)
	v_mfma_f32_32x32x16_bf16 v[64:79], v[214:217], v[116:119], v[64:79]
	v_add_f32_e32 v145, v145, v108
	v_exp_f32_e32 v111, v111
	v_add_f32_e32 v145, v145, v109
	v_cvt_pk_bf16_f32 v126, v108, v109
	v_add_f32_e32 v145, v145, v110
	v_add_f32_e32 v145, v145, v111
	v_cvt_pk_bf16_f32 v127, v110, v111
	s_waitcnt lgkmcnt(0)
	v_mfma_f32_32x32x16_bf16 v[48:63], v[218:221], v[116:119], v[48:63]
	v_mfma_f32_32x32x16_bf16 v[96:111], v[198:201], v[176:179], v[16:31]
	ds_read_b128 v[198:201], v170 offset:49152
	v_exp_f32_e32 v80, v80
	v_exp_f32_e32 v81, v81
	v_exp_f32_e32 v82, v82
	v_add_f32_e32 v144, v144, v80
	v_exp_f32_e32 v83, v83
	v_mfma_f32_32x32x16_bf16 v[96:111], v[202:205], v[180:183], v[96:111]
	ds_read_b128 v[202:205], v171 offset:49152
	v_add_f32_e32 v144, v144, v81
	v_cvt_pk_bf16_f32 v112, v80, v81
	v_exp_f32_e32 v84, v84
	v_add_f32_e32 v144, v144, v82
	v_exp_f32_e32 v85, v85
	v_mfma_f32_32x32x16_bf16 v[96:111], v[206:209], v[184:187], v[96:111]
	ds_read_b128 v[206:209], v210 offset:49152
	v_add_f32_e32 v144, v144, v83
	v_cvt_pk_bf16_f32 v113, v82, v83
	v_exp_f32_e32 v86, v86
	v_add_f32_e32 v144, v144, v84
	v_exp_f32_e32 v87, v87
	v_add_f32_e32 v144, v144, v85
	v_mfma_f32_32x32x16_bf16 v[96:111], v[128:131], v[188:191], v[96:111]
	ds_read_b128 v[128:131], v222 offset:49152
	v_cvt_pk_bf16_f32 v114, v84, v85
	v_exp_f32_e32 v88, v88
	v_add_f32_e32 v144, v144, v86
	v_exp_f32_e32 v89, v89
	v_add_f32_e32 v144, v144, v87
	v_cvt_pk_bf16_f32 v115, v86, v87
	v_mfma_f32_32x32x16_bf16 v[32:47], v[162:165], v[120:123], v[32:47]
	ds_read_b64_tr_b16 v[162:163], v223 offset:45056
	ds_read_b64_tr_b16 v[164:165], v223 offset:46080
	v_exp_f32_e32 v90, v90
	v_add_f32_e32 v144, v144, v88
	v_exp_f32_e32 v91, v91
	v_add_f32_e32 v144, v144, v89
	v_cvt_pk_bf16_f32 v116, v88, v89
	v_exp_f32_e32 v92, v92
	v_mfma_f32_32x32x16_bf16 v[0:15], v[166:169], v[120:123], v[0:15]
	ds_read_b64_tr_b16 v[166:167], v224 offset:45056
	ds_read_b64_tr_b16 v[168:169], v224 offset:46080
	v_add_f32_e32 v144, v144, v90
	v_exp_f32_e32 v93, v93
	v_add_f32_e32 v144, v144, v91
	v_cvt_pk_bf16_f32 v117, v90, v91
	v_exp_f32_e32 v94, v94
	v_mfma_f32_32x32x16_bf16 v[32:47], v[214:217], v[124:127], v[32:47]
	ds_read_b64_tr_b16 v[214:215], v223 offset:47104
	ds_read_b64_tr_b16 v[216:217], v223 offset:48128
	v_add_f32_e32 v144, v144, v92
	v_exp_f32_e32 v95, v95
	v_add_f32_e32 v144, v144, v93
	v_cvt_pk_bf16_f32 v118, v92, v93
	v_add_f32_e32 v144, v144, v94
	v_add_f32_e32 v144, v144, v95
	v_cvt_pk_bf16_f32 v119, v94, v95
	v_mfma_f32_32x32x16_bf16 v[0:15], v[218:221], v[124:127], v[0:15]
	ds_read_b64_tr_b16 v[218:219], v224 offset:47104
	ds_read_b64_tr_b16 v[220:221], v224 offset:48128
	s_waitcnt lgkmcnt(11)
	v_mfma_f32_32x32x16_bf16 v[80:95], v[198:201], v[146:149], v[16:31]
	v_exp_f32_e32 v96, v96
	v_exp_f32_e32 v97, v97
	v_exp_f32_e32 v98, v98
	v_add_f32_e32 v145, v145, v96
	v_exp_f32_e32 v99, v99
	s_waitcnt lgkmcnt(10)
	v_mfma_f32_32x32x16_bf16 v[80:95], v[202:205], v[150:153], v[80:95]
	v_add_f32_e32 v145, v145, v97
	v_cvt_pk_bf16_f32 v120, v96, v97
	v_exp_f32_e32 v100, v100
	v_add_f32_e32 v145, v145, v98
	v_exp_f32_e32 v101, v101
	s_waitcnt lgkmcnt(9)
	v_mfma_f32_32x32x16_bf16 v[80:95], v[206:209], v[154:157], v[80:95]
	v_add_f32_e32 v145, v145, v99
	v_cvt_pk_bf16_f32 v121, v98, v99
	v_exp_f32_e32 v102, v102
	v_add_f32_e32 v145, v145, v100
	v_exp_f32_e32 v103, v103
	v_add_f32_e32 v145, v145, v101
	s_waitcnt lgkmcnt(8)
	v_mfma_f32_32x32x16_bf16 v[80:95], v[128:131], v[158:161], v[80:95]
	v_cvt_pk_bf16_f32 v122, v100, v101
	v_exp_f32_e32 v104, v104
	v_add_f32_e32 v145, v145, v102
	v_exp_f32_e32 v105, v105
	v_add_f32_e32 v145, v145, v103
	v_cvt_pk_bf16_f32 v123, v102, v103
	s_waitcnt lgkmcnt(6)
	v_mfma_f32_32x32x16_bf16 v[64:79], v[162:165], v[112:115], v[64:79]
	v_exp_f32_e32 v106, v106
	v_add_f32_e32 v145, v145, v104
	v_exp_f32_e32 v107, v107
	v_add_f32_e32 v145, v145, v105
	v_cvt_pk_bf16_f32 v124, v104, v105
	v_exp_f32_e32 v108, v108
	s_waitcnt lgkmcnt(4)
	v_mfma_f32_32x32x16_bf16 v[48:63], v[166:169], v[112:115], v[48:63]
	v_add_f32_e32 v145, v145, v106
	v_exp_f32_e32 v109, v109
	v_add_f32_e32 v145, v145, v107
	v_cvt_pk_bf16_f32 v125, v106, v107
	v_exp_f32_e32 v110, v110
	s_waitcnt lgkmcnt(2)
; __device__ __forceinline__ void attn_pass_A2(const int tid, unsigned char* smem, const bf16_t* Q0w, int qpitch, const bf16_t* Kb, int kpitch, const bf16_t* Vb, int vpitch,
;                                              int b, int ntiles, float kmax, f32x16 (&o)[2][2], float (&linv)[2]) {
;     ...
;     for (int kt = 0; kt < ntiles; ++kt) {
;         if (kt + 1 < ntiles) gload(kt + 1);
;         const unsigned char* Ks = smem + (kt & 1) * BUF; const unsigned char* Vs = Ks + KBYTES;
;         const unsigned char* kp = Ks + r32 * KP + hi * 16;
;         const unsigned char* vp = Vs + (4 * hi + q4) * VP + (16 * nhalf + 4 * p4) * 2;
; #pragma unroll
;         for (int kb = 0; kb < 2; ++kb) {
;             bf16x8 pf[2][2];
;             {
;                 f32x16 s0, s1;
; #pragma unroll
;                 for (int r = 0; r < 16; ++r) { s0[r] = nshift[0]; s1[r] = nshift[1]; }
; #pragma unroll
;                 for (int ds = 0; ds < 4; ++ds) {
;                     const bf16x8 kf = *(const bf16x8*)(kp + kb * 32 * KP + ds * 32);
;                     const bf16x8 q0 = *(const bf16x8*)(qs + ds * 32), q1 = *(const bf16x8*)(qs + 32 * KP + ds * 32);
;                     s0 = __builtin_amdgcn_mfma_f32_32x32x16_bf16(kf, q0, s0, 0, 0, 0);
;                     s1 = __builtin_amdgcn_mfma_f32_32x32x16_bf16(kf, q1, s1, 0, 0, 0);
;                 }
;                 float l0 = 0.f, l1 = 0.f;
; #pragma unroll
;                 for (int r = 0; r < 16; ++r) { s0[r] = __builtin_amdgcn_exp2f(s0[r]); l0 += s0[r]; }
; #pragma unroll
;                 for (int r = 0; r < 16; ++r) { s1[r] = __builtin_amdgcn_exp2f(s1[r]); l1 += s1[r]; }
;                 lsum[0] += l0; lsum[1] += l1;
; #pragma unroll
;                 for (int j = 0; j < 2; ++j) {
;                     u32x4 w0, w1;
;                     w0.x = cvt_pk_bf16(s0[8 * j + 0], s0[8 * j + 1]); w0.y = cvt_pk_bf16(s0[8 * j + 2], s0[8 * j + 3]); w0.z = cvt_pk_bf16(s0[8 * j + 4], s0[8 * j + 5]); w0.w = cvt_pk_bf16(s0[8 * j + 6], s0[8 * j + 7]);
;                     w1.x = cvt_pk_bf16(s1[8 * j + 0], s1[8 * j + 1]); w1.y = cvt_pk_bf16(s1[8 * j + 2], s1[8 * j + 3]); w1.z = cvt_pk_bf16(s1[8 * j + 4], s1[8 * j + 5]); w1.w = cvt_pk_bf16(s1[8 * j + 6], s1[8 * j + 7]);
;                     pf[0][j] = __builtin_bit_cast(bf16x8, w0); pf[1][j] = __builtin_bit_cast(bf16x8, w1);
;                 }
;             }
	v_mfma_f32_32x32x16_bf16 v[64:79], v[214:217], v[116:119], v[64:79]
	v_add_f32_e32 v145, v145, v108
	v_exp_f32_e32 v111, v111
	v_add_f32_e32 v145, v145, v109
	v_cvt_pk_bf16_f32 v126, v108, v109
	v_add_f32_e32 v145, v145, v110
	v_add_f32_e32 v145, v145, v111
	v_cvt_pk_bf16_f32 v127, v110, v111
	s_waitcnt lgkmcnt(0)
	v_mfma_f32_32x32x16_bf16 v[48:63], v[218:221], v[116:119], v[48:63]
	v_mfma_f32_32x32x16_bf16 v[96:111], v[198:201], v[176:179], v[16:31]
	ds_read_b128 v[198:201], v170 offset:53248
	v_exp_f32_e32 v80, v80
	v_exp_f32_e32 v81, v81
	v_exp_f32_e32 v82, v82
	v_add_f32_e32 v144, v144, v80
	v_exp_f32_e32 v83, v83
	v_mfma_f32_32x32x16_bf16 v[96:111], v[202:205], v[180:183], v[96:111]
	ds_read_b128 v[202:205], v171 offset:53248
	v_add_f32_e32 v144, v144, v81
	v_cvt_pk_bf16_f32 v112, v80, v81
	v_exp_f32_e32 v84, v84
	v_add_f32_e32 v144, v144, v82
	v_exp_f32_e32 v85, v85
	v_mfma_f32_32x32x16_bf16 v[96:111], v[206:209], v[184:187], v[96:111]
	ds_read_b128 v[206:209], v210 offset:53248
	v_add_f32_e32 v144, v144, v83
	v_cvt_pk_bf16_f32 v113, v82, v83
	v_exp_f32_e32 v86, v86
	v_add_f32_e32 v144, v144, v84
	v_exp_f32_e32 v87, v87
	v_add_f32_e32 v144, v144, v85
	v_mfma_f32_32x32x16_bf16 v[96:111], v[128:131], v[188:191], v[96:111]
	ds_read_b128 v[128:131], v222 offset:53248
	v_cvt_pk_bf16_f32 v114, v84, v85
	v_exp_f32_e32 v88, v88
	v_add_f32_e32 v144, v144, v86
	v_exp_f32_e32 v89, v89
	v_add_f32_e32 v144, v144, v87
	v_cvt_pk_bf16_f32 v115, v86, v87
	v_mfma_f32_32x32x16_bf16 v[32:47], v[162:165], v[120:123], v[32:47]
	ds_read_b64_tr_b16 v[162:163], v223 offset:57344
	ds_read_b64_tr_b16 v[164:165], v223 offset:58368
	v_exp_f32_e32 v90, v90
	v_add_f32_e32 v144, v144, v88
	v_exp_f32_e32 v91, v91
	v_add_f32_e32 v144, v144, v89
	v_cvt_pk_bf16_f32 v116, v88, v89
	v_exp_f32_e32 v92, v92
	v_mfma_f32_32x32x16_bf16 v[0:15], v[166:169], v[120:123], v[0:15]
	ds_read_b64_tr_b16 v[166:167], v224 offset:57344
	ds_read_b64_tr_b16 v[168:169], v224 offset:58368
	s_add_i32 s59, s59, 1
	v_add_f32_e32 v144, v144, v90
	v_exp_f32_e32 v93, v93
	v_add_f32_e32 v144, v144, v91
	v_cvt_pk_bf16_f32 v117, v90, v91
	v_exp_f32_e32 v94, v94
	v_mfma_f32_32x32x16_bf16 v[32:47], v[214:217], v[124:127], v[32:47]
	ds_read_b64_tr_b16 v[214:215], v223 offset:59392
	ds_read_b64_tr_b16 v[216:217], v223 offset:60416
	v_add_f32_e32 v144, v144, v92
	v_exp_f32_e32 v95, v95
	v_add_f32_e32 v144, v144, v93
	v_cvt_pk_bf16_f32 v118, v92, v93
	v_add_f32_e32 v144, v144, v94
	v_add_f32_e32 v144, v144, v95
	v_cvt_pk_bf16_f32 v119, v94, v95
	v_mfma_f32_32x32x16_bf16 v[0:15], v[218:221], v[124:127], v[0:15]
	ds_read_b64_tr_b16 v[218:219], v224 offset:59392
	ds_read_b64_tr_b16 v[220:221], v224 offset:60416
	s_waitcnt lgkmcnt(8)
	s_barrier
; __device__ __forceinline__ float sum_x32(float v) { auto rr = __builtin_amdgcn_permlane32_swap(__float_as_uint(v), __float_as_uint(v), false, false); return __uint_as_float(rr[0]) + __uint_as_float(rr[1]); }
; __device__ __forceinline__ s16x4 ld_tr(const unsigned char* p) { return __builtin_bit_cast(s16x4, __builtin_amdgcn_ds_read_tr16_b64_v4i16((LAS s16x4*)p)); }
; __device__ __forceinline__ void attn_pass_A2(const int tid, unsigned char* smem, const bf16_t* Q0w, int qpitch, const bf16_t* Kb, int kpitch, const bf16_t* Vb, int vpitch,
;                                              int b, int ntiles, float kmax, f32x16 (&o)[2][2], float (&linv)[2]) {
;     ...
; #pragma unroll
;             for (int d0 = 0; d0 < 2; ++d0)
; #pragma unroll
;                 for (int j = 0; j < 2; ++j) {
;                     const unsigned char* a = vp + (32 * kb + 16 * j) * VP + d0 * 64;
;                     const s16x4 lo = ld_tr(a), h4 = ld_tr(a + 8 * VP);
;                     const bf16x8 vf = (bf16x8){lo[0], lo[1], lo[2], lo[3], h4[0], h4[1], h4[2], h4[3]};
;                     o[0][d0] = __builtin_amdgcn_mfma_f32_32x32x16_bf16(vf, pf[0][j], o[0][d0], 0, 0, 0);
;                     o[1][d0] = __builtin_amdgcn_mfma_f32_32x32x16_bf16(vf, pf[1][j], o[1][d0], 0, 0, 0);
;                 }
;             __builtin_amdgcn_sched_barrier(0);
;         }
;         if (kt + 1 < ntiles) lwrite((kt + 1) & 1);
;         __syncthreads();
;     }
;     linv[0] = 1.0f / sum_x32(lsum[0]); linv[1] = 1.0f / sum_x32(lsum[1]);
	v_mfma_f32_32x32x16_bf16 v[80:95], v[198:201], v[146:149], v[16:31]
	v_exp_f32_e32 v96, v96
	v_exp_f32_e32 v97, v97
	v_exp_f32_e32 v98, v98
	v_add_f32_e32 v145, v145, v96
	v_exp_f32_e32 v99, v99
	v_mfma_f32_32x32x16_bf16 v[80:95], v[202:205], v[150:153], v[80:95]
	v_add_f32_e32 v145, v145, v97
	v_cvt_pk_bf16_f32 v120, v96, v97
	v_exp_f32_e32 v100, v100
	v_add_f32_e32 v145, v145, v98
	v_exp_f32_e32 v101, v101
	v_mfma_f32_32x32x16_bf16 v[80:95], v[206:209], v[154:157], v[80:95]
	v_add_f32_e32 v145, v145, v99
	v_cvt_pk_bf16_f32 v121, v98, v99
	v_exp_f32_e32 v102, v102
	v_add_f32_e32 v145, v145, v100
	v_exp_f32_e32 v103, v103
	v_add_f32_e32 v145, v145, v101
	v_mfma_f32_32x32x16_bf16 v[80:95], v[128:131], v[158:161], v[80:95]
	v_cvt_pk_bf16_f32 v122, v100, v101
	v_exp_f32_e32 v104, v104
	v_add_f32_e32 v145, v145, v102
	v_exp_f32_e32 v105, v105
	v_add_f32_e32 v145, v145, v103
	v_cvt_pk_bf16_f32 v123, v102, v103
	s_waitcnt lgkmcnt(6)
	v_mfma_f32_32x32x16_bf16 v[64:79], v[162:165], v[112:115], v[64:79]
	v_exp_f32_e32 v106, v106
	v_add_f32_e32 v145, v145, v104
	v_exp_f32_e32 v107, v107
	v_add_f32_e32 v145, v145, v105
	v_cvt_pk_bf16_f32 v124, v104, v105
	v_exp_f32_e32 v108, v108
	s_waitcnt lgkmcnt(4)
	v_mfma_f32_32x32x16_bf16 v[48:63], v[166:169], v[112:115], v[48:63]
	v_add_f32_e32 v145, v145, v106
	v_exp_f32_e32 v109, v109
	v_add_f32_e32 v145, v145, v107
	v_cvt_pk_bf16_f32 v125, v106, v107
	v_exp_f32_e32 v110, v110
	s_waitcnt lgkmcnt(2)
	v_mfma_f32_32x32x16_bf16 v[64:79], v[214:217], v[116:119], v[64:79]
	v_add_f32_e32 v145, v145, v108
	v_exp_f32_e32 v111, v111
	v_add_f32_e32 v145, v145, v109
	v_cvt_pk_bf16_f32 v126, v108, v109
	v_add_f32_e32 v145, v145, v110
	v_add_f32_e32 v145, v145, v111
	v_cvt_pk_bf16_f32 v127, v110, v111
	s_waitcnt lgkmcnt(0)
	v_mfma_f32_32x32x16_bf16 v[48:63], v[218:221], v[116:119], v[48:63]
	v_mfma_f32_32x32x16_bf16 v[96:111], v[198:201], v[176:179], v[16:31]
	v_exp_f32_e32 v80, v80
	v_exp_f32_e32 v81, v81
	v_exp_f32_e32 v82, v82
	v_add_f32_e32 v144, v144, v80
	v_exp_f32_e32 v83, v83
	v_mfma_f32_32x32x16_bf16 v[96:111], v[202:205], v[180:183], v[96:111]
	v_add_f32_e32 v144, v144, v81
	v_cvt_pk_bf16_f32 v112, v80, v81
	v_exp_f32_e32 v84, v84
	v_add_f32_e32 v144, v144, v82
	v_exp_f32_e32 v85, v85
	v_mfma_f32_32x32x16_bf16 v[96:111], v[206:209], v[184:187], v[96:111]
	v_add_f32_e32 v144, v144, v83
	v_cvt_pk_bf16_f32 v113, v82, v83
	v_exp_f32_e32 v86, v86
	v_add_f32_e32 v144, v144, v84
	v_exp_f32_e32 v87, v87
	v_add_f32_e32 v144, v144, v85
	v_mfma_f32_32x32x16_bf16 v[96:111], v[128:131], v[188:191], v[96:111]
	v_cvt_pk_bf16_f32 v114, v84, v85
	v_exp_f32_e32 v88, v88
	v_add_f32_e32 v144, v144, v86
	v_exp_f32_e32 v89, v89
	v_add_f32_e32 v144, v144, v87
	v_cvt_pk_bf16_f32 v115, v86, v87
	v_mfma_f32_32x32x16_bf16 v[32:47], v[162:165], v[120:123], v[32:47]
	ds_read_b64_tr_b16 v[162:163], v223 offset:61440
	ds_read_b64_tr_b16 v[164:165], v223 offset:62464
	v_exp_f32_e32 v90, v90
	v_add_f32_e32 v144, v144, v88
	v_exp_f32_e32 v91, v91
	v_add_f32_e32 v144, v144, v89
	v_cvt_pk_bf16_f32 v116, v88, v89
	v_exp_f32_e32 v92, v92
	v_mfma_f32_32x32x16_bf16 v[0:15], v[166:169], v[120:123], v[0:15]
	ds_read_b64_tr_b16 v[166:167], v224 offset:61440
	ds_read_b64_tr_b16 v[168:169], v224 offset:62464
	v_add_f32_e32 v144, v144, v90
	v_exp_f32_e32 v93, v93
	v_add_f32_e32 v144, v144, v91
	v_cvt_pk_bf16_f32 v117, v90, v91
	v_exp_f32_e32 v94, v94
	v_mfma_f32_32x32x16_bf16 v[32:47], v[214:217], v[124:127], v[32:47]
	ds_read_b64_tr_b16 v[214:215], v223 offset:63488
	ds_read_b64_tr_b16 v[216:217], v223 offset:64512
	v_add_f32_e32 v144, v144, v92
	v_exp_f32_e32 v95, v95
	v_add_f32_e32 v144, v144, v93
	v_cvt_pk_bf16_f32 v118, v92, v93
	v_add_f32_e32 v144, v144, v94
	v_add_f32_e32 v144, v144, v95
	v_cvt_pk_bf16_f32 v119, v94, v95
	v_mfma_f32_32x32x16_bf16 v[0:15], v[218:221], v[124:127], v[0:15]
	ds_read_b64_tr_b16 v[218:219], v224 offset:63488
	ds_read_b64_tr_b16 v[220:221], v224 offset:64512
	s_waitcnt lgkmcnt(6)
	v_mfma_f32_32x32x16_bf16 v[64:79], v[162:165], v[112:115], v[64:79]
	v_exp_f32_e32 v96, v96
	v_exp_f32_e32 v97, v97
	v_exp_f32_e32 v98, v98
	v_add_f32_e32 v145, v145, v96
	v_exp_f32_e32 v99, v99
	v_add_f32_e32 v145, v145, v97
	v_cvt_pk_bf16_f32 v120, v96, v97
	v_exp_f32_e32 v100, v100
	v_add_f32_e32 v145, v145, v98
	v_exp_f32_e32 v101, v101
	v_add_f32_e32 v145, v145, v99
	v_cvt_pk_bf16_f32 v121, v98, v99
	v_exp_f32_e32 v102, v102
	s_waitcnt lgkmcnt(4)
	v_mfma_f32_32x32x16_bf16 v[48:63], v[166:169], v[112:115], v[48:63]
	v_add_f32_e32 v145, v145, v100
	v_exp_f32_e32 v103, v103
	v_add_f32_e32 v145, v145, v101
	v_cvt_pk_bf16_f32 v122, v100, v101
	v_exp_f32_e32 v104, v104
	v_add_f32_e32 v145, v145, v102
	v_exp_f32_e32 v105, v105
	v_add_f32_e32 v145, v145, v103
	v_cvt_pk_bf16_f32 v123, v102, v103
	v_exp_f32_e32 v106, v106
	v_add_f32_e32 v145, v145, v104
	v_exp_f32_e32 v107, v107
	v_add_f32_e32 v145, v145, v105
	s_waitcnt lgkmcnt(2)
	v_mfma_f32_32x32x16_bf16 v[64:79], v[214:217], v[116:119], v[64:79]
	v_cvt_pk_bf16_f32 v124, v104, v105
	v_exp_f32_e32 v108, v108
	v_add_f32_e32 v145, v145, v106
	v_exp_f32_e32 v109, v109
	v_add_f32_e32 v145, v145, v107
	v_cvt_pk_bf16_f32 v125, v106, v107
	v_exp_f32_e32 v110, v110
	v_add_f32_e32 v145, v145, v108
	v_exp_f32_e32 v111, v111
	v_add_f32_e32 v145, v145, v109
	v_cvt_pk_bf16_f32 v126, v108, v109
	v_add_f32_e32 v145, v145, v110
	v_add_f32_e32 v145, v145, v111
	v_cvt_pk_bf16_f32 v127, v110, v111
	s_waitcnt lgkmcnt(0)
	v_mfma_f32_32x32x16_bf16 v[48:63], v[218:221], v[116:119], v[48:63]
	v_mfma_f32_32x32x16_bf16 v[32:47], v[162:165], v[120:123], v[32:47]
	v_mfma_f32_32x32x16_bf16 v[0:15], v[166:169], v[120:123], v[0:15]
	v_mfma_f32_32x32x16_bf16 v[32:47], v[214:217], v[124:127], v[32:47]
	v_mfma_f32_32x32x16_bf16 v[0:15], v[218:221], v[124:127], v[0:15]
	s_waitcnt lgkmcnt(0)
	s_barrier
	s_waitcnt vmcnt(0)

; __device__ __forceinline__ float sum_x32(float v) { auto rr = __builtin_amdgcn_permlane32_swap(__float_as_uint(v), __float_as_uint(v), false, false); return __uint_as_float(rr[0]) + __uint_as_float(rr[1]); }
;     __device__ __forceinline__ void operator()(const f32x4 (&acc)[2][2][4][2], const Unit& u, int wr, int wc, int fr, int fq) const {
;     ...
;                 const int row = 256 * u.pm + 128 * ai + 64 * wr + 16 * m + fr;
;                 f32x4 x[2][2]; float ss = 0.f;
; #pragma unroll
;                 for (int bj = 0; bj < 2; ++bj)
; #pragma unroll
;                     for (int n = 0; n < 2; ++n) { x[bj][n] = acc[ai][bj][m][n]; ss += (x[bj][n][0] * x[bj][n][0] + x[bj][n][1] * x[bj][n][1]) + (x[bj][n][2] * x[bj][n][2] + x[bj][n][3] * x[bj][n][3]); }
;                 ss += shx<16>(ss); ss = sum_x32(ss);
;                 const float rinv = rsqrtf(ss * (1.0f / 64.0f) + EPS);
; #pragma unroll
;                 for (int bj = 0; bj < 2; ++bj)
; #pragma unroll
;                     for (int n = 0; n < 2; ++n) x[bj][n] = x[bj][n] * rinv * g[bj][n];
;                 if (!isctx) {
;                     const int t = row & (SEQ - 1); const int p = (fq < 2) ? (t >> 6) : (t & 63);
;                     const float* tp = tab + (p * 16 + 8 * (fq & 1)) * 2;
; #pragma unroll
;                     for (int n = 0; n < 2; ++n) {
;                         const f32x4 cs0 = *(const f32x4*)(tp + 8 * n), cs1 = *(const f32x4*)(tp + 8 * n + 4);
;                         const float c[4] = {cs0[0], cs0[2], cs1[0], cs1[2]}, s[4] = {cs0[1], cs0[3], cs1[1], cs1[3]};
; #pragma unroll
;                         for (int e = 0; e < 4; ++e) { const float lo = x[0][n][e], hi = x[1][n][e]; x[0][n][e] = lo * c[e] - hi * s[e]; x[1][n][e] = hi * c[e] + lo * s[e]; }
;                     }
.LBB0_535:
	v_lshlrev_b32_e32 v144, 3, v210
	v_ashrrev_i32_e32 v145, 31, v144
	v_lshl_add_u64 v[56:57], v[144:145], 2, s[26:27]
	global_load_dwordx4 v[52:55], v[56:57], off offset:16
	global_load_dwordx4 v[60:63], v[56:57], off
	global_load_dwordx4 v[48:51], v[56:57], off offset:144
	s_nop 0
	global_load_dwordx4 v[56:59], v[56:57], off offset:128
	v_lshlrev_b32_e32 v146, 4, v210
	v_and_b32_e32 v151, 16, v146
	v_pk_mul_f32 v[146:147], v[142:143], v[142:143]
	v_pk_mul_f32 v[148:149], v[140:141], v[140:141]
	s_cmpk_lt_i32 s6, 0x80
	v_pk_mov_b32 v[154:155], v[148:149], v[146:147] op_sel:[1,0]
	v_mov_b32_e32 v149, v147
	v_pk_add_f32 v[146:147], v[154:155], v[148:149]
	v_pk_mul_f32 v[148:149], v[138:139], v[138:139]
	v_pk_add_f32 v[146:147], v[146:147], v[146:147] op_sel_hi:[0,1]
	v_pk_mul_f32 v[154:155], v[136:137], v[136:137]
	v_mul_f32_e32 v146, v132, v132
	v_pk_mov_b32 v[156:157], v[154:155], v[148:149] op_sel:[1,0]
	v_mov_b32_e32 v155, v149
	v_pk_add_f32 v[148:149], v[156:157], v[154:155]
	v_pk_fma_f32 v[154:155], v[132:133], v[132:133], v[146:147] op_sel_hi:[1,1,0]
	v_mul_f32_e32 v146, v134, v134
	v_pk_add_f32 v[148:149], v[148:149], v[148:149] op_sel_hi:[0,1]
	v_pk_fma_f32 v[156:157], v[134:135], v[134:135], v[146:147] op_sel_hi:[1,1,0]
	v_mul_f32_e32 v154, v128, v128
	v_mul_f32_e32 v156, v129, v129
	v_mul_f32_e32 v148, v130, v130
	v_mul_f32_e32 v146, v131, v131
	v_pk_add_f32 v[154:155], v[154:155], v[156:157]
	v_pk_add_f32 v[146:147], v[148:149], v[146:147]
	s_cselect_b64 s[18:19], -1, 0
	v_pk_add_f32 v[146:147], v[154:155], v[146:147]
	s_lshl_b32 s2, s6, 8
	v_add_f32_e32 v146, v146, v147
	ds_swizzle_b32 v147, v146 offset:swizzle(SWAP,16)
	s_add_i32 s2, s2, s61
	v_add_u32_e32 v150, s2, v209
	s_mov_b32 s2, 0x800000
	s_cmpk_gt_i32 s6, 0x7f
	s_waitcnt lgkmcnt(0)
	v_add_f32_e32 v146, v146, v147
	v_mov_b32_e32 v147, v146
	s_nop 1
	v_permlane32_swap_b32_e32 v146, v147
	v_add_f32_e32 v146, v146, v147
	v_fmamk_f32 v146, v146, 0x3c800000, v226
	v_cmp_gt_f32_e32 vcc, s2, v146
	v_mul_f32_e32 v147, 0x4b800000, v146
	v_cmp_gt_i32_e64 s[6:7], 2, v210
	v_cndmask_b32_e32 v146, v146, v147, vcc
	v_rsq_f32_e32 v146, v146
	v_and_b32_e32 v152, 63, v209
	v_lshlrev_b32_e32 v151, 2, v151
	v_mul_f32_e32 v147, 0x45800000, v146
	v_cndmask_b32_e32 v154, v146, v147, vcc
	v_pk_mul_f32 v[140:141], v[140:141], v[154:155] op_sel_hi:[1,0]
	v_pk_mul_f32 v[142:143], v[142:143], v[154:155] op_sel_hi:[1,0]
	v_pk_mul_f32 v[136:137], v[136:137], v[154:155] op_sel_hi:[1,0]
	v_pk_mul_f32 v[138:139], v[138:139], v[154:155] op_sel_hi:[1,0]
	v_pk_mul_f32 v[128:129], v[128:129], v[154:155] op_sel_hi:[1,0]
	v_pk_mul_f32 v[130:131], v[130:131], v[154:155] op_sel_hi:[1,0]
	s_waitcnt vmcnt(0)
	v_pk_mul_f32 v[138:139], v[54:55], v[138:139]
	v_pk_mul_f32 v[146:147], v[60:61], v[140:141]
	v_pk_mul_f32 v[140:141], v[132:133], v[154:155] op_sel_hi:[1,0]
	v_pk_mul_f32 v[132:133], v[134:135], v[154:155] op_sel_hi:[1,0]
	v_pk_mul_f32 v[148:149], v[62:63], v[142:143]
	v_pk_mul_f32 v[136:137], v[52:53], v[136:137]
	v_pk_mul_f32 v[132:133], v[58:59], v[132:133]
	v_pk_mul_f32 v[134:135], v[56:57], v[140:141]
	v_pk_mul_f32 v[130:131], v[50:51], v[130:131]
	v_pk_mul_f32 v[140:141], v[48:49], v[128:129]
	s_cbranch_scc1 .LBB0_537
	v_bfe_u32 v186, v150, 6, 7
	v_and_b32_e32 v187, 63, v209
	v_cndmask_b32_e64 v186, v187, v186, s[6:7]
	v_lshl_or_b32 v186, v186, 7, v151
	global_load_dwordx4 v[170:173], v186, s[10:11]
	global_load_dwordx4 v[174:177], v186, s[10:11] offset:16
	global_load_dwordx4 v[178:181], v186, s[10:11] offset:32
	global_load_dwordx4 v[182:185], v186, s[10:11] offset:48
	v_add_u32_e32 v186, 0x10, v150
	v_bfe_u32 v186, v186, 6, 7
	v_add_u32_e32 v187, 0x10, v209
	v_and_b32_e32 v187, 63, v187
	v_cndmask_b32_e64 v186, v187, v186, s[6:7]
	v_lshl_or_b32 v186, v186, 7, v151
	global_load_dwordx4 v[212:215], v186, s[10:11]
	global_load_dwordx4 v[216:219], v186, s[10:11] offset:16
	global_load_dwordx4 v[220:223], v186, s[10:11] offset:32
	global_load_dwordx4 v[230:233], v186, s[10:11] offset:48
	v_bfe_u32 v128, v150, 6, 7
	v_cndmask_b32_e64 v128, v152, v128, s[6:7]
	v_lshl_or_b32 v192, v128, 7, v151
	v_lshl_add_u64 v[162:163], s[10:11], 0, v[192:193]
	s_waitcnt vmcnt(4)
	v_mov_b32_e32 v154, v170
	v_mov_b32_e32 v155, v171
	v_mov_b32_e32 v156, v172
	v_mov_b32_e32 v157, v173
	v_mov_b32_e32 v158, v174
	v_mov_b32_e32 v159, v175
	v_mov_b32_e32 v160, v176
	v_mov_b32_e32 v161, v177
	v_mov_b32_e32 v128, v154
	v_mul_f32_e32 v154, v148, v158
	v_mul_f32_e32 v164, v132, v159
	v_mul_f32_e32 v158, v132, v158
	v_mov_b32_e32 v132, v149
	v_mov_b32_e32 v129, v156
	v_mov_b32_e32 v156, v155
	v_pk_mul_f32 v[168:169], v[132:133], v[160:161]
	v_pk_mul_f32 v[142:143], v[134:135], v[156:157]
	v_pk_mul_f32 v[134:135], v[134:135], v[128:129]
	v_mul_f32_e32 v166, v148, v159
	v_mov_b32_e32 v155, v168
	v_mov_b32_e32 v165, v169
	v_mov_b32_e32 v148, v133
	v_pk_fma_f32 v[142:143], v[146:147], v[128:129], v[142:143] neg_lo:[0,0,1] neg_hi:[0,0,1]
	v_pk_add_f32 v[128:129], v[154:155], v[164:165] neg_lo:[0,1] neg_hi:[0,1]
	v_pk_mul_f32 v[132:133], v[148:149], v[160:161]
	v_pk_fma_f32 v[134:135], v[146:147], v[156:157], v[134:135]
	v_mov_b32_e32 v167, v133
	v_mov_b32_e32 v159, v132
	v_pk_add_f32 v[132:133], v[166:167], v[158:159]
	v_mov_b32_e32 v146, v178
	v_mov_b32_e32 v147, v179
	v_mov_b32_e32 v148, v180
	v_mov_b32_e32 v149, v181
	v_mov_b32_e32 v154, v182
	v_mov_b32_e32 v155, v183
	v_mov_b32_e32 v156, v184
	v_mov_b32_e32 v157, v185
	v_mov_b32_e32 v159, v148
	v_mul_f32_e32 v160, v138, v154
	v_mul_f32_e32 v162, v130, v155
	v_mul_f32_e32 v154, v130, v154
	v_mov_b32_e32 v130, v139
	v_mov_b32_e32 v148, v147
	v_mul_f32_e32 v164, v138, v155
	v_pk_mul_f32 v[166:167], v[130:131], v[156:157]
	v_mov_b32_e32 v138, v131
	v_mov_b32_e32 v158, v146
	v_pk_mul_f32 v[146:147], v[140:141], v[148:149]
	v_mov_b32_e32 v161, v166
	v_mov_b32_e32 v163, v167
	v_pk_mul_f32 v[130:131], v[138:139], v[156:157]
	v_pk_mul_f32 v[140:141], v[140:141], v[158:159]
	v_pk_fma_f32 v[146:147], v[136:137], v[158:159], v[146:147] neg_lo:[0,0,1] neg_hi:[0,0,1]
	v_pk_add_f32 v[158:159], v[160:161], v[162:163] neg_lo:[0,1] neg_hi:[0,1]
	v_mov_b32_e32 v165, v131
	v_mov_b32_e32 v155, v130
	v_pk_fma_f32 v[140:141], v[136:137], v[148:149], v[140:141]
	v_pk_add_f32 v[130:131], v[164:165], v[154:155]
	v_mov_b32_e32 v136, v146
	v_mov_b32_e32 v137, v147
	v_mov_b32_e32 v138, v158
	v_mov_b32_e32 v139, v159
	v_mov_b32_e32 v146, v142
	v_mov_b32_e32 v147, v143
	v_mov_b32_e32 v148, v128
	v_mov_b32_e32 v149, v129
; __device__ __forceinline__ unsigned cvt_pk_bf16(float lo, float hi) { f32x2 v = {lo, hi}; bf16x2_t b = __builtin_convertvector(v, bf16x2_t); return __builtin_bit_cast(unsigned, b); }
;     __device__ __forceinline__ void operator()(const f32x4 (&acc)[2][2][4][2], const Unit& u, int wr, int wc, int fr, int fq) const {
;     ...
;                 const int row = 256 * u.pm + 128 * ai + 64 * wr + 16 * m + fr;
;                 f32x4 x[2][2]; float ss = 0.f;
; #pragma unroll
;                 for (int bj = 0; bj < 2; ++bj)
; #pragma unroll
;                     for (int n = 0; n < 2; ++n) { x[bj][n] = acc[ai][bj][m][n]; ss += (x[bj][n][0] * x[bj][n][0] + x[bj][n][1] * x[bj][n][1]) + (x[bj][n][2] * x[bj][n][2] + x[bj][n][3] * x[bj][n][3]); }
;                 ss += shx<16>(ss); ss = sum_x32(ss);
;                 const float rinv = rsqrtf(ss * (1.0f / 64.0f) + EPS);
; #pragma unroll
;                 for (int bj = 0; bj < 2; ++bj)
; #pragma unroll
;                     for (int n = 0; n < 2; ++n) x[bj][n] = x[bj][n] * rinv * g[bj][n];
;                 if (!isctx) {
;                     const int t = row & (SEQ - 1); const int p = (fq < 2) ? (t >> 6) : (t & 63);
;                     const float* tp = tab + (p * 16 + 8 * (fq & 1)) * 2;
; #pragma unroll
;                     for (int n = 0; n < 2; ++n) {
;                         const f32x4 cs0 = *(const f32x4*)(tp + 8 * n), cs1 = *(const f32x4*)(tp + 8 * n + 4);
;                         const float c[4] = {cs0[0], cs0[2], cs1[0], cs1[2]}, s[4] = {cs0[1], cs0[3], cs1[1], cs1[3]};
; #pragma unroll
;                         for (int e = 0; e < 4; ++e) { const float lo = x[0][n][e], hi = x[1][n][e]; x[0][n][e] = lo * c[e] - hi * s[e]; x[1][n][e] = hi * c[e] + lo * s[e]; }
;                     }
;                 }
; #pragma unroll
;                 for (int bj = 0; bj < 2; ++bj) {
;                     u32x4 w; w.x = cvt_pk_bf16(x[bj][0][0] * qs, x[bj][0][1] * qs); w.y = cvt_pk_bf16(x[bj][0][2] * qs, x[bj][0][3] * qs);
;                     w.z = cvt_pk_bf16(x[bj][1][0] * qs, x[bj][1][1] * qs); w.w = cvt_pk_bf16(x[bj][1][2] * qs, x[bj][1][3] * qs);
;                     *(u32x4*)(dst + (size_t)row * pitch + colbase + 32 * bj + 8 * fq) = w;
;                 }
.LBB0_537:
	s_ashr_i32 s9, s8, 31
	s_lshl_b64 s[2:3], s[8:9], 1
	s_add_u32 s2, s16, s2
	s_addc_u32 s3, s17, s3
	v_ashrrev_i32_e32 v143, 31, v150
	v_lshl_add_u64 v[128:129], v[144:145], 1, s[2:3]
	v_mul_lo_u32 v153, s25, v150
	v_mul_lo_u32 v143, s24, v143
	v_mad_u64_u32 v[144:145], s[2:3], s24, v150, 0
	v_add3_u32 v145, v145, v143, v153
	v_lshl_add_u64 v[154:155], v[144:145], 1, v[128:129]
	v_pk_mul_f32 v[144:145], s[96:97], v[146:147] op_sel_hi:[0,1]
	v_pk_mul_f32 v[146:147], s[96:97], v[148:149] op_sel_hi:[0,1]
	v_pk_mul_f32 v[136:137], s[96:97], v[136:137] op_sel_hi:[0,1]
	v_cvt_pk_bf16_f32 v144, v144, v145
	v_cvt_pk_bf16_f32 v145, v146, v147
	v_cvt_pk_bf16_f32 v146, v136, v137
	v_pk_mul_f32 v[136:137], s[96:97], v[138:139] op_sel_hi:[0,1]
	v_cvt_pk_bf16_f32 v147, v136, v137
	v_pk_mul_f32 v[136:137], v[126:127], v[126:127]
	v_pk_mul_f32 v[138:139], v[124:125], v[124:125]
	global_store_dwordx4 v[154:155], v[144:147], off
	v_pk_mul_f32 v[134:135], s[96:97], v[134:135] op_sel_hi:[0,1]
	v_pk_mul_f32 v[132:133], s[96:97], v[132:133] op_sel_hi:[0,1]
	v_pk_mov_b32 v[144:145], v[138:139], v[136:137] op_sel:[1,0]
	v_mov_b32_e32 v139, v137
	v_pk_add_f32 v[136:137], v[144:145], v[138:139]
	v_pk_mul_f32 v[138:139], v[122:123], v[122:123]
	v_pk_add_f32 v[136:137], v[136:137], v[136:137] op_sel_hi:[0,1]
	v_pk_mul_f32 v[144:145], v[120:121], v[120:121]
	v_mul_f32_e32 v136, v116, v116
	v_pk_mov_b32 v[146:147], v[144:145], v[138:139] op_sel:[1,0]
	v_mov_b32_e32 v145, v139
	v_pk_add_f32 v[138:139], v[146:147], v[144:145]
	v_pk_fma_f32 v[144:145], v[116:117], v[116:117], v[136:137] op_sel_hi:[1,1,0]
	v_mul_f32_e32 v136, v118, v118
	v_pk_add_f32 v[138:139], v[138:139], v[138:139] op_sel_hi:[0,1]
	v_pk_fma_f32 v[146:147], v[118:119], v[118:119], v[136:137] op_sel_hi:[1,1,0]
	v_mul_f32_e32 v144, v112, v112
	v_mul_f32_e32 v146, v113, v113
	v_mul_f32_e32 v138, v114, v114
	v_mul_f32_e32 v136, v115, v115
	v_pk_add_f32 v[144:145], v[144:145], v[146:147]
	v_pk_add_f32 v[136:137], v[138:139], v[136:137]
	v_cvt_pk_bf16_f32 v134, v134, v135
	v_pk_add_f32 v[136:137], v[144:145], v[136:137]
	v_cvt_pk_bf16_f32 v135, v132, v133
	v_add_f32_e32 v137, v136, v137
	ds_swizzle_b32 v138, v137 offset:swizzle(SWAP,16)
	v_pk_mul_f32 v[132:133], s[96:97], v[140:141] op_sel_hi:[0,1]
	v_cvt_pk_bf16_f32 v136, v132, v133
	s_mov_b32 s2, 0x800000
	v_pk_mul_f32 v[130:131], s[96:97], v[130:131] op_sel_hi:[0,1]
	s_waitcnt lgkmcnt(0)
	v_add_f32_e32 v132, v137, v138
	v_mov_b32_e32 v133, v132
	s_nop 1
	v_permlane32_swap_b32_e32 v132, v133
	v_add_f32_e32 v132, v132, v133
	v_fmamk_f32 v132, v132, 0x3c800000, v226
	v_mul_f32_e32 v133, 0x4b800000, v132
	v_cmp_gt_f32_e32 vcc, s2, v132
	v_cvt_pk_bf16_f32 v137, v130, v131
	global_store_dwordx4 v[154:155], v[134:137], off offset:64
	v_cndmask_b32_e32 v132, v132, v133, vcc
	v_rsq_f32_e32 v132, v132
	v_add_u32_e32 v142, 16, v209
	v_and_b32_e32 v142, 63, v142
	v_mul_f32_e32 v130, 0x45800000, v132
	v_cndmask_b32_e32 v134, v132, v130, vcc
	v_pk_mul_f32 v[124:125], v[124:125], v[134:135] op_sel_hi:[1,0]
	v_pk_mul_f32 v[126:127], v[126:127], v[134:135] op_sel_hi:[1,0]
	v_pk_mul_f32 v[130:131], v[60:61], v[124:125]
	v_pk_mul_f32 v[124:125], v[116:117], v[134:135] op_sel_hi:[1,0]
	v_pk_mul_f32 v[116:117], v[118:119], v[134:135] op_sel_hi:[1,0]
	v_pk_mul_f32 v[118:119], v[56:57], v[124:125]
	v_pk_mul_f32 v[124:125], v[112:113], v[134:135] op_sel_hi:[1,0]
	v_pk_mul_f32 v[120:121], v[120:121], v[134:135] op_sel_hi:[1,0]
	v_pk_mul_f32 v[122:123], v[122:123], v[134:135] op_sel_hi:[1,0]
	v_pk_mul_f32 v[112:113], v[114:115], v[134:135] op_sel_hi:[1,0]
	v_pk_mul_f32 v[114:115], v[48:49], v[124:125]
	v_cndmask_b32_e64 v124, 0, 1, s[18:19]
	v_pk_mul_f32 v[132:133], v[62:63], v[126:127]
	v_pk_mul_f32 v[122:123], v[54:55], v[122:123]
	v_pk_mul_f32 v[120:121], v[52:53], v[120:121]
	v_pk_mul_f32 v[116:117], v[58:59], v[116:117]
	v_pk_mul_f32 v[112:113], v[50:51], v[112:113]
	v_cmp_ne_u32_e64 s[8:9], 1, v124
	s_andn2_b64 vcc, exec, s[18:19]
	v_add_u32_e32 v134, 16, v150
	s_cbranch_vccnz .LBB0_539
	v_add_u32_e32 v186, 0x20, v150
	v_bfe_u32 v186, v186, 6, 7
	v_add_u32_e32 v187, 0x20, v209
	v_and_b32_e32 v187, 63, v187
	v_cndmask_b32_e64 v186, v187, v186, s[6:7]
	v_lshl_or_b32 v186, v186, 7, v151
	global_load_dwordx4 v[170:173], v186, s[10:11]
	global_load_dwordx4 v[174:177], v186, s[10:11] offset:16
	global_load_dwordx4 v[178:181], v186, s[10:11] offset:32
	global_load_dwordx4 v[182:185], v186, s[10:11] offset:48
	v_bfe_u32 v124, v134, 6, 7
	v_cndmask_b32_e64 v124, v142, v124, s[6:7]
	v_lshl_or_b32 v192, v124, 7, v151
	v_lshl_add_u64 v[140:141], s[10:11], 0, v[192:193]
	s_waitcnt vmcnt(6)
	v_mov_b32_e32 v136, v212
	v_mov_b32_e32 v137, v213
	v_mov_b32_e32 v138, v214
	v_mov_b32_e32 v139, v215
	v_mov_b32_e32 v144, v216
	v_mov_b32_e32 v145, v217
	v_mov_b32_e32 v146, v218
	v_mov_b32_e32 v147, v219
	v_mov_b32_e32 v124, v136
	v_mul_f32_e32 v136, v132, v144
	v_mul_f32_e32 v148, v116, v145
	v_mul_f32_e32 v144, v116, v144
	v_mov_b32_e32 v116, v133
	v_mov_b32_e32 v125, v138
	v_mov_b32_e32 v138, v137
	v_pk_mul_f32 v[156:157], v[116:117], v[146:147]
	v_pk_mul_f32 v[126:127], v[118:119], v[138:139]
	v_pk_mul_f32 v[118:119], v[118:119], v[124:125]
	v_mul_f32_e32 v154, v132, v145
	v_mov_b32_e32 v137, v156
	v_mov_b32_e32 v149, v157
	v_mov_b32_e32 v132, v117
	v_pk_fma_f32 v[126:127], v[130:131], v[124:125], v[126:127] neg_lo:[0,0,1] neg_hi:[0,0,1]
	v_pk_add_f32 v[124:125], v[136:137], v[148:149] neg_lo:[0,1] neg_hi:[0,1]
	v_pk_mul_f32 v[116:117], v[132:133], v[146:147]
	v_pk_fma_f32 v[118:119], v[130:131], v[138:139], v[118:119]
	v_mov_b32_e32 v155, v117
	v_mov_b32_e32 v145, v116
	v_pk_add_f32 v[116:117], v[154:155], v[144:145]
	v_mov_b32_e32 v130, v220
	v_mov_b32_e32 v131, v221
	v_mov_b32_e32 v132, v222
	v_mov_b32_e32 v133, v223
	v_mov_b32_e32 v136, v230
	v_mov_b32_e32 v137, v231
	v_mov_b32_e32 v138, v232
	v_mov_b32_e32 v139, v233
	v_mov_b32_e32 v141, v132
	v_mul_f32_e32 v144, v122, v136
	v_mul_f32_e32 v146, v112, v137
	v_mul_f32_e32 v136, v112, v136
	v_mov_b32_e32 v112, v123
	v_mov_b32_e32 v132, v131
	v_mul_f32_e32 v148, v122, v137
	v_pk_mul_f32 v[154:155], v[112:113], v[138:139]
	v_mov_b32_e32 v122, v113
	v_mov_b32_e32 v140, v130
	v_pk_mul_f32 v[130:131], v[114:115], v[132:133]
	v_mov_b32_e32 v145, v154
	v_mov_b32_e32 v147, v155
	v_pk_mul_f32 v[112:113], v[122:123], v[138:139]
	v_pk_mul_f32 v[114:115], v[114:115], v[140:141]
	v_pk_fma_f32 v[130:131], v[120:121], v[140:141], v[130:131] neg_lo:[0,0,1] neg_hi:[0,0,1]
	v_pk_add_f32 v[140:141], v[144:145], v[146:147] neg_lo:[0,1] neg_hi:[0,1]
	v_mov_b32_e32 v149, v113
	v_mov_b32_e32 v137, v112
	v_pk_fma_f32 v[114:115], v[120:121], v[132:133], v[114:115]
	v_pk_add_f32 v[112:113], v[148:149], v[136:137]
	v_mov_b32_e32 v120, v130
	v_mov_b32_e32 v121, v131
	v_mov_b32_e32 v122, v140
	v_mov_b32_e32 v123, v141
	v_mov_b32_e32 v130, v126
	v_mov_b32_e32 v131, v127
	v_mov_b32_e32 v132, v124
	v_mov_b32_e32 v133, v125
; __device__ __forceinline__ unsigned cvt_pk_bf16(float lo, float hi) { f32x2 v = {lo, hi}; bf16x2_t b = __builtin_convertvector(v, bf16x2_t); return __builtin_bit_cast(unsigned, b); }
;     __device__ __forceinline__ void operator()(const f32x4 (&acc)[2][2][4][2], const Unit& u, int wr, int wc, int fr, int fq) const {
;     ...
;                 const int row = 256 * u.pm + 128 * ai + 64 * wr + 16 * m + fr;
;                 f32x4 x[2][2]; float ss = 0.f;
; #pragma unroll
;                 for (int bj = 0; bj < 2; ++bj)
; #pragma unroll
;                     for (int n = 0; n < 2; ++n) { x[bj][n] = acc[ai][bj][m][n]; ss += (x[bj][n][0] * x[bj][n][0] + x[bj][n][1] * x[bj][n][1]) + (x[bj][n][2] * x[bj][n][2] + x[bj][n][3] * x[bj][n][3]); }
;                 ss += shx<16>(ss); ss = sum_x32(ss);
;                 const float rinv = rsqrtf(ss * (1.0f / 64.0f) + EPS);
; #pragma unroll
;                 for (int bj = 0; bj < 2; ++bj)
; #pragma unroll
;                     for (int n = 0; n < 2; ++n) x[bj][n] = x[bj][n] * rinv * g[bj][n];
;                 if (!isctx) {
;                     const int t = row & (SEQ - 1); const int p = (fq < 2) ? (t >> 6) : (t & 63);
;                     const float* tp = tab + (p * 16 + 8 * (fq & 1)) * 2;
; #pragma unroll
;                     for (int n = 0; n < 2; ++n) {
;                         const f32x4 cs0 = *(const f32x4*)(tp + 8 * n), cs1 = *(const f32x4*)(tp + 8 * n + 4);
;                         const float c[4] = {cs0[0], cs0[2], cs1[0], cs1[2]}, s[4] = {cs0[1], cs0[3], cs1[1], cs1[3]};
; #pragma unroll
;                         for (int e = 0; e < 4; ++e) { const float lo = x[0][n][e], hi = x[1][n][e]; x[0][n][e] = lo * c[e] - hi * s[e]; x[1][n][e] = hi * c[e] + lo * s[e]; }
;                     }
;                 }
; #pragma unroll
;                 for (int bj = 0; bj < 2; ++bj) {
;                     u32x4 w; w.x = cvt_pk_bf16(x[bj][0][0] * qs, x[bj][0][1] * qs); w.y = cvt_pk_bf16(x[bj][0][2] * qs, x[bj][0][3] * qs);
;                     w.z = cvt_pk_bf16(x[bj][1][0] * qs, x[bj][1][1] * qs); w.w = cvt_pk_bf16(x[bj][1][2] * qs, x[bj][1][3] * qs);
;                     *(u32x4*)(dst + (size_t)row * pitch + colbase + 32 * bj + 8 * fq) = w;
;                 }
.LBB0_539:
	s_mov_b32 s97, s96
	v_ashrrev_i32_e32 v125, 31, v134
	v_mul_lo_u32 v135, s25, v134
	v_mul_lo_u32 v125, s24, v125
	v_mad_u64_u32 v[126:127], s[2:3], s24, v134, 0
	v_pk_mul_f32 v[130:131], s[96:97], v[130:131]
	v_pk_mul_f32 v[132:133], s[96:97], v[132:133]
	v_pk_mul_f32 v[120:121], s[96:97], v[120:121]
	v_add3_u32 v127, v127, v125, v135
	v_cvt_pk_bf16_f32 v130, v130, v131
	v_cvt_pk_bf16_f32 v131, v132, v133
	v_cvt_pk_bf16_f32 v132, v120, v121
	v_pk_mul_f32 v[120:121], s[96:97], v[122:123]
	v_lshl_add_u64 v[126:127], v[126:127], 1, v[128:129]
	v_cvt_pk_bf16_f32 v133, v120, v121
	v_pk_mul_f32 v[120:121], v[110:111], v[110:111]
	v_pk_mul_f32 v[122:123], v[108:109], v[108:109]
	global_store_dwordx4 v[126:127], v[130:133], off
	v_pk_mul_f32 v[114:115], s[96:97], v[114:115]
	s_mov_b32 s2, 0x800000
	v_pk_mov_b32 v[130:131], v[122:123], v[120:121] op_sel:[1,0]
	v_mov_b32_e32 v123, v121
	v_pk_add_f32 v[120:121], v[130:131], v[122:123]
	v_pk_mul_f32 v[122:123], v[106:107], v[106:107]
	v_pk_add_f32 v[120:121], v[120:121], v[120:121] op_sel_hi:[0,1]
	v_pk_mul_f32 v[130:131], v[104:105], v[104:105]
	v_mul_f32_e32 v120, v100, v100
	v_pk_mov_b32 v[132:133], v[130:131], v[122:123] op_sel:[1,0]
	v_mov_b32_e32 v131, v123
	v_pk_add_f32 v[122:123], v[132:133], v[130:131]
	v_pk_fma_f32 v[130:131], v[100:101], v[100:101], v[120:121] op_sel_hi:[1,1,0]
	v_mul_f32_e32 v120, v102, v102
	v_pk_add_f32 v[122:123], v[122:123], v[122:123] op_sel_hi:[0,1]
	v_pk_fma_f32 v[132:133], v[102:103], v[102:103], v[120:121] op_sel_hi:[1,1,0]
	v_mul_f32_e32 v130, v96, v96
	v_mul_f32_e32 v132, v97, v97
	v_mul_f32_e32 v122, v98, v98
	v_mul_f32_e32 v120, v99, v99
	v_pk_add_f32 v[130:131], v[130:131], v[132:133]
	v_pk_add_f32 v[120:121], v[122:123], v[120:121]
	v_pk_mul_f32 v[112:113], s[96:97], v[112:113]
	v_pk_add_f32 v[120:121], v[130:131], v[120:121]
	v_pk_mul_f32 v[118:119], s[96:97], v[118:119]
	v_add_f32_e32 v121, v120, v121
	ds_swizzle_b32 v122, v121 offset:swizzle(SWAP,16)
	v_cvt_pk_bf16_f32 v120, v114, v115
	v_pk_mul_f32 v[116:117], s[96:97], v[116:117]
	v_cvt_pk_bf16_f32 v118, v118, v119
	v_cvt_pk_bf16_f32 v119, v116, v117
	s_waitcnt lgkmcnt(0)
	v_add_f32_e32 v114, v121, v122
	v_mov_b32_e32 v115, v114
	s_nop 1
	v_permlane32_swap_b32_e32 v114, v115
	v_add_f32_e32 v114, v114, v115
	v_fmamk_f32 v114, v114, 0x3c800000, v226
	v_mul_f32_e32 v115, 0x4b800000, v114
	v_cmp_gt_f32_e32 vcc, s2, v114
	v_cvt_pk_bf16_f32 v121, v112, v113
	v_xor_b32_e32 v124, 32, v152
	v_cndmask_b32_e32 v114, v114, v115, vcc
	v_rsq_f32_e32 v114, v114
	global_store_dwordx4 v[126:127], v[118:121], off offset:64
	v_mul_f32_e32 v112, 0x45800000, v114
	v_cndmask_b32_e32 v116, v114, v112, vcc
	v_pk_mul_f32 v[108:109], v[108:109], v[116:117] op_sel_hi:[1,0]
	v_pk_mul_f32 v[110:111], v[110:111], v[116:117] op_sel_hi:[1,0]
	v_pk_mul_f32 v[112:113], v[60:61], v[108:109]
	v_pk_mul_f32 v[108:109], v[100:101], v[116:117] op_sel_hi:[1,0]
	v_pk_mul_f32 v[104:105], v[104:105], v[116:117] op_sel_hi:[1,0]
	v_pk_mul_f32 v[106:107], v[106:107], v[116:117] op_sel_hi:[1,0]
	v_pk_mul_f32 v[100:101], v[102:103], v[116:117] op_sel_hi:[1,0]
	v_pk_mul_f32 v[102:103], v[56:57], v[108:109]
	v_pk_mul_f32 v[108:109], v[96:97], v[116:117] op_sel_hi:[1,0]
	v_pk_mul_f32 v[96:97], v[98:99], v[116:117] op_sel_hi:[1,0]
	v_pk_mul_f32 v[114:115], v[62:63], v[110:111]
	v_pk_mul_f32 v[106:107], v[54:55], v[106:107]
	v_pk_mul_f32 v[104:105], v[52:53], v[104:105]
	v_pk_mul_f32 v[100:101], v[58:59], v[100:101]
	v_pk_mul_f32 v[96:97], v[50:51], v[96:97]
	v_pk_mul_f32 v[98:99], v[48:49], v[108:109]
	s_and_b64 vcc, exec, s[8:9]
	v_add_u32_e32 v116, 32, v150
	s_cbranch_vccnz .LBB0_541
	v_add_u32_e32 v186, 0x30, v150
	v_bfe_u32 v186, v186, 6, 7
	v_add_u32_e32 v187, 0x30, v209
	v_and_b32_e32 v187, 63, v187
	v_cndmask_b32_e64 v186, v187, v186, s[6:7]
	v_lshl_or_b32 v186, v186, 7, v151
	global_load_dwordx4 v[212:215], v186, s[10:11]
	global_load_dwordx4 v[216:219], v186, s[10:11] offset:16
	global_load_dwordx4 v[220:223], v186, s[10:11] offset:32
	global_load_dwordx4 v[230:233], v186, s[10:11] offset:48
	v_bfe_u32 v108, v116, 6, 7
	v_cndmask_b32_e64 v108, v124, v108, s[6:7]
	v_lshl_or_b32 v192, v108, 7, v151
	v_lshl_add_u64 v[122:123], s[10:11], 0, v[192:193]
	s_waitcnt vmcnt(6)
	v_mov_b32_e32 v118, v170
	v_mov_b32_e32 v119, v171
	v_mov_b32_e32 v120, v172
	v_mov_b32_e32 v121, v173
	v_mov_b32_e32 v130, v174
	v_mov_b32_e32 v131, v175
	v_mov_b32_e32 v132, v176
	v_mov_b32_e32 v133, v177
	v_mov_b32_e32 v108, v118
	v_mul_f32_e32 v118, v114, v130
	v_mul_f32_e32 v126, v100, v131
	v_mul_f32_e32 v130, v100, v130
	v_mov_b32_e32 v100, v115
	v_mov_b32_e32 v109, v120
	v_mov_b32_e32 v120, v119
	v_pk_mul_f32 v[136:137], v[100:101], v[132:133]
	v_pk_mul_f32 v[110:111], v[102:103], v[120:121]
	v_pk_mul_f32 v[102:103], v[102:103], v[108:109]
	v_mul_f32_e32 v134, v114, v131
	v_mov_b32_e32 v119, v136
	v_mov_b32_e32 v127, v137
	v_mov_b32_e32 v114, v101
	v_pk_fma_f32 v[110:111], v[112:113], v[108:109], v[110:111] neg_lo:[0,0,1] neg_hi:[0,0,1]
	v_pk_add_f32 v[108:109], v[118:119], v[126:127] neg_lo:[0,1] neg_hi:[0,1]
	v_pk_mul_f32 v[100:101], v[114:115], v[132:133]
	v_pk_fma_f32 v[102:103], v[112:113], v[120:121], v[102:103]
	v_mov_b32_e32 v135, v101
	v_mov_b32_e32 v131, v100
	v_pk_add_f32 v[100:101], v[134:135], v[130:131]
	v_mov_b32_e32 v112, v178
	v_mov_b32_e32 v113, v179
	v_mov_b32_e32 v114, v180
	v_mov_b32_e32 v115, v181
	v_mov_b32_e32 v118, v182
	v_mov_b32_e32 v119, v183
	v_mov_b32_e32 v120, v184
	v_mov_b32_e32 v121, v185
	v_mov_b32_e32 v123, v114
	v_mul_f32_e32 v126, v106, v118
	v_mul_f32_e32 v130, v96, v119
	v_mul_f32_e32 v118, v96, v118
	v_mov_b32_e32 v96, v107
	v_mov_b32_e32 v114, v113
	v_mul_f32_e32 v132, v106, v119
	v_pk_mul_f32 v[134:135], v[96:97], v[120:121]
	v_mov_b32_e32 v106, v97
	v_mov_b32_e32 v122, v112
	v_pk_mul_f32 v[112:113], v[98:99], v[114:115]
	v_mov_b32_e32 v127, v134
	v_mov_b32_e32 v131, v135
	v_pk_mul_f32 v[96:97], v[106:107], v[120:121]
	v_pk_mul_f32 v[98:99], v[98:99], v[122:123]
	v_pk_fma_f32 v[112:113], v[104:105], v[122:123], v[112:113] neg_lo:[0,0,1] neg_hi:[0,0,1]
	v_pk_add_f32 v[122:123], v[126:127], v[130:131] neg_lo:[0,1] neg_hi:[0,1]
	v_mov_b32_e32 v133, v97
	v_mov_b32_e32 v119, v96
	v_pk_fma_f32 v[98:99], v[104:105], v[114:115], v[98:99]
	v_pk_add_f32 v[96:97], v[132:133], v[118:119]
	v_mov_b32_e32 v104, v112
	v_mov_b32_e32 v105, v113
	v_mov_b32_e32 v106, v122
	v_mov_b32_e32 v107, v123
	v_mov_b32_e32 v112, v110
	v_mov_b32_e32 v113, v111
	v_mov_b32_e32 v114, v108
	v_mov_b32_e32 v115, v109
; __device__ __forceinline__ unsigned cvt_pk_bf16(float lo, float hi) { f32x2 v = {lo, hi}; bf16x2_t b = __builtin_convertvector(v, bf16x2_t); return __builtin_bit_cast(unsigned, b); }
;     __device__ __forceinline__ void operator()(const f32x4 (&acc)[2][2][4][2], const Unit& u, int wr, int wc, int fr, int fq) const {
;     ...
;                 const int row = 256 * u.pm + 128 * ai + 64 * wr + 16 * m + fr;
;                 f32x4 x[2][2]; float ss = 0.f;
; #pragma unroll
;                 for (int bj = 0; bj < 2; ++bj)
; #pragma unroll
;                     for (int n = 0; n < 2; ++n) { x[bj][n] = acc[ai][bj][m][n]; ss += (x[bj][n][0] * x[bj][n][0] + x[bj][n][1] * x[bj][n][1]) + (x[bj][n][2] * x[bj][n][2] + x[bj][n][3] * x[bj][n][3]); }
;                 ss += shx<16>(ss); ss = sum_x32(ss);
;                 const float rinv = rsqrtf(ss * (1.0f / 64.0f) + EPS);
; #pragma unroll
;                 for (int bj = 0; bj < 2; ++bj)
; #pragma unroll
;                     for (int n = 0; n < 2; ++n) x[bj][n] = x[bj][n] * rinv * g[bj][n];
;                 if (!isctx) {
;                     const int t = row & (SEQ - 1); const int p = (fq < 2) ? (t >> 6) : (t & 63);
;                     const float* tp = tab + (p * 16 + 8 * (fq & 1)) * 2;
; #pragma unroll
;                     for (int n = 0; n < 2; ++n) {
;                         const f32x4 cs0 = *(const f32x4*)(tp + 8 * n), cs1 = *(const f32x4*)(tp + 8 * n + 4);
;                         const float c[4] = {cs0[0], cs0[2], cs1[0], cs1[2]}, s[4] = {cs0[1], cs0[3], cs1[1], cs1[3]};
; #pragma unroll
;                         for (int e = 0; e < 4; ++e) { const float lo = x[0][n][e], hi = x[1][n][e]; x[0][n][e] = lo * c[e] - hi * s[e]; x[1][n][e] = hi * c[e] + lo * s[e]; }
;                     }
;                 }
; #pragma unroll
;                 for (int bj = 0; bj < 2; ++bj) {
;                     u32x4 w; w.x = cvt_pk_bf16(x[bj][0][0] * qs, x[bj][0][1] * qs); w.y = cvt_pk_bf16(x[bj][0][2] * qs, x[bj][0][3] * qs);
;                     w.z = cvt_pk_bf16(x[bj][1][0] * qs, x[bj][1][1] * qs); w.w = cvt_pk_bf16(x[bj][1][2] * qs, x[bj][1][3] * qs);
;                     *(u32x4*)(dst + (size_t)row * pitch + colbase + 32 * bj + 8 * fq) = w;
;                 }
.LBB0_541:
	v_ashrrev_i32_e32 v109, 31, v116
	v_mul_lo_u32 v117, s25, v116
	v_mul_lo_u32 v109, s24, v109
	v_mad_u64_u32 v[110:111], s[2:3], s24, v116, 0
	v_add3_u32 v111, v111, v109, v117
	v_lshl_add_u64 v[116:117], v[110:111], 1, v[128:129]
	v_pk_mul_f32 v[110:111], s[96:97], v[112:113]
	v_pk_mul_f32 v[112:113], s[96:97], v[114:115]
	v_pk_mul_f32 v[104:105], s[96:97], v[104:105]
	v_cvt_pk_bf16_f32 v110, v110, v111
	v_cvt_pk_bf16_f32 v111, v112, v113
	v_cvt_pk_bf16_f32 v112, v104, v105
	v_pk_mul_f32 v[104:105], s[96:97], v[106:107]
	v_pk_mul_f32 v[106:107], v[92:93], v[92:93]
	v_cvt_pk_bf16_f32 v113, v104, v105
	v_pk_mul_f32 v[104:105], v[94:95], v[94:95]
	global_store_dwordx4 v[116:117], v[110:113], off
	v_pk_mul_f32 v[98:99], s[96:97], v[98:99]
	s_mov_b32 s2, 0x800000
	v_pk_mov_b32 v[110:111], v[106:107], v[104:105] op_sel:[1,0]
	v_mov_b32_e32 v107, v105
	v_pk_add_f32 v[104:105], v[110:111], v[106:107]
	v_pk_mul_f32 v[106:107], v[90:91], v[90:91]
	v_pk_add_f32 v[104:105], v[104:105], v[104:105] op_sel_hi:[0,1]
	v_pk_mul_f32 v[110:111], v[88:89], v[88:89]
	v_mul_f32_e32 v104, v84, v84
	v_pk_mov_b32 v[112:113], v[110:111], v[106:107] op_sel:[1,0]
	v_mov_b32_e32 v111, v107
	v_pk_add_f32 v[106:107], v[112:113], v[110:111]
	v_pk_fma_f32 v[110:111], v[84:85], v[84:85], v[104:105] op_sel_hi:[1,1,0]
	v_mul_f32_e32 v104, v86, v86
	v_pk_add_f32 v[106:107], v[106:107], v[106:107] op_sel_hi:[0,1]
	v_pk_fma_f32 v[112:113], v[86:87], v[86:87], v[104:105] op_sel_hi:[1,1,0]
	v_mul_f32_e32 v110, v80, v80
	v_mul_f32_e32 v112, v81, v81
	v_mul_f32_e32 v106, v82, v82
	v_mul_f32_e32 v104, v83, v83
	v_pk_add_f32 v[110:111], v[110:111], v[112:113]
	v_pk_add_f32 v[104:105], v[106:107], v[104:105]
	v_pk_mul_f32 v[96:97], s[96:97], v[96:97]
	v_pk_add_f32 v[104:105], v[110:111], v[104:105]
	v_pk_mul_f32 v[102:103], s[96:97], v[102:103]
	v_add_f32_e32 v105, v104, v105
	ds_swizzle_b32 v106, v105 offset:swizzle(SWAP,16)
	v_cvt_pk_bf16_f32 v104, v98, v99
	v_pk_mul_f32 v[100:101], s[96:97], v[100:101]
	v_cvt_pk_bf16_f32 v102, v102, v103
	v_cvt_pk_bf16_f32 v103, v100, v101
	s_waitcnt lgkmcnt(0)
	v_add_f32_e32 v98, v105, v106
	v_mov_b32_e32 v99, v98
	s_nop 1
	v_permlane32_swap_b32_e32 v98, v99
	v_add_f32_e32 v98, v98, v99
	v_fmamk_f32 v98, v98, 0x3c800000, v226
	v_mul_f32_e32 v99, 0x4b800000, v98
	v_cmp_gt_f32_e32 vcc, s2, v98
	v_cvt_pk_bf16_f32 v105, v96, v97
	v_add_u32_e32 v108, 48, v209
	v_cndmask_b32_e32 v98, v98, v99, vcc
	v_rsq_f32_e32 v98, v98
	v_and_b32_e32 v108, 63, v108
	global_store_dwordx4 v[116:117], v[102:105], off offset:64
	v_mul_f32_e32 v96, 0x45800000, v98
	v_cndmask_b32_e32 v100, v98, v96, vcc
	v_pk_mul_f32 v[92:93], v[92:93], v[100:101] op_sel_hi:[1,0]
	v_pk_mul_f32 v[94:95], v[94:95], v[100:101] op_sel_hi:[1,0]
	v_pk_mul_f32 v[96:97], v[60:61], v[92:93]
	v_pk_mul_f32 v[92:93], v[84:85], v[100:101] op_sel_hi:[1,0]
	v_pk_mul_f32 v[88:89], v[88:89], v[100:101] op_sel_hi:[1,0]
	v_pk_mul_f32 v[90:91], v[90:91], v[100:101] op_sel_hi:[1,0]
	v_pk_mul_f32 v[84:85], v[86:87], v[100:101] op_sel_hi:[1,0]
	v_pk_mul_f32 v[86:87], v[56:57], v[92:93]
	v_pk_mul_f32 v[92:93], v[80:81], v[100:101] op_sel_hi:[1,0]
	v_pk_mul_f32 v[80:81], v[82:83], v[100:101] op_sel_hi:[1,0]
	v_pk_mul_f32 v[98:99], v[62:63], v[94:95]
	v_pk_mul_f32 v[90:91], v[54:55], v[90:91]
	v_pk_mul_f32 v[88:89], v[52:53], v[88:89]
	v_pk_mul_f32 v[84:85], v[58:59], v[84:85]
	v_pk_mul_f32 v[80:81], v[50:51], v[80:81]
	v_pk_mul_f32 v[82:83], v[48:49], v[92:93]
	s_and_b64 vcc, exec, s[8:9]
	v_add_u32_e32 v100, 48, v150
	s_cbranch_vccnz .LBB0_543
	v_add_u32_e32 v186, 0x80, v150
	v_bfe_u32 v186, v186, 6, 7
	v_add_u32_e32 v187, 0x80, v209
	v_and_b32_e32 v187, 63, v187
	v_cndmask_b32_e64 v186, v187, v186, s[6:7]
	v_lshl_or_b32 v186, v186, 7, v151
	global_load_dwordx4 v[170:173], v186, s[10:11]
	global_load_dwordx4 v[174:177], v186, s[10:11] offset:16
	global_load_dwordx4 v[178:181], v186, s[10:11] offset:32
	global_load_dwordx4 v[182:185], v186, s[10:11] offset:48
	v_bfe_u32 v92, v100, 6, 7
	v_cndmask_b32_e64 v92, v108, v92, s[6:7]
	v_lshl_or_b32 v192, v92, 7, v151
	v_lshl_add_u64 v[106:107], s[10:11], 0, v[192:193]
	s_waitcnt vmcnt(6)
	v_mov_b32_e32 v102, v212
	v_mov_b32_e32 v103, v213
	v_mov_b32_e32 v104, v214
	v_mov_b32_e32 v105, v215
	v_mov_b32_e32 v110, v216
	v_mov_b32_e32 v111, v217
	v_mov_b32_e32 v112, v218
	v_mov_b32_e32 v113, v219
	v_mov_b32_e32 v92, v102
	v_mul_f32_e32 v102, v98, v110
	v_mul_f32_e32 v114, v84, v111
	v_mul_f32_e32 v110, v84, v110
	v_mov_b32_e32 v84, v99
	v_mov_b32_e32 v93, v104
	v_mov_b32_e32 v104, v103
	v_pk_mul_f32 v[118:119], v[84:85], v[112:113]
	v_pk_mul_f32 v[94:95], v[86:87], v[104:105]
	v_pk_mul_f32 v[86:87], v[86:87], v[92:93]
	v_mul_f32_e32 v116, v98, v111
	v_mov_b32_e32 v103, v118
	v_mov_b32_e32 v115, v119
	v_mov_b32_e32 v98, v85
	v_pk_fma_f32 v[94:95], v[96:97], v[92:93], v[94:95] neg_lo:[0,0,1] neg_hi:[0,0,1]
	v_pk_add_f32 v[92:93], v[102:103], v[114:115] neg_lo:[0,1] neg_hi:[0,1]
	v_pk_mul_f32 v[84:85], v[98:99], v[112:113]
	v_pk_fma_f32 v[86:87], v[96:97], v[104:105], v[86:87]
	v_mov_b32_e32 v117, v85
	v_mov_b32_e32 v111, v84
	v_pk_add_f32 v[84:85], v[116:117], v[110:111]
	v_mov_b32_e32 v96, v220
	v_mov_b32_e32 v97, v221
	v_mov_b32_e32 v98, v222
	v_mov_b32_e32 v99, v223
	v_mov_b32_e32 v102, v230
	v_mov_b32_e32 v103, v231
	v_mov_b32_e32 v104, v232
	v_mov_b32_e32 v105, v233
	v_mov_b32_e32 v107, v98
	v_mul_f32_e32 v110, v90, v102
	v_mul_f32_e32 v112, v80, v103
	v_mul_f32_e32 v102, v80, v102
	v_mov_b32_e32 v80, v91
	v_mov_b32_e32 v98, v97
	v_mul_f32_e32 v114, v90, v103
	v_pk_mul_f32 v[116:117], v[80:81], v[104:105]
	v_mov_b32_e32 v90, v81
	v_mov_b32_e32 v106, v96
	v_pk_mul_f32 v[96:97], v[82:83], v[98:99]
	v_mov_b32_e32 v111, v116
	v_mov_b32_e32 v113, v117
	v_pk_mul_f32 v[80:81], v[90:91], v[104:105]
	v_pk_mul_f32 v[82:83], v[82:83], v[106:107]
	v_pk_fma_f32 v[96:97], v[88:89], v[106:107], v[96:97] neg_lo:[0,0,1] neg_hi:[0,0,1]
	v_pk_add_f32 v[106:107], v[110:111], v[112:113] neg_lo:[0,1] neg_hi:[0,1]
	v_mov_b32_e32 v115, v81
	v_mov_b32_e32 v103, v80
	v_pk_fma_f32 v[82:83], v[88:89], v[98:99], v[82:83]
	v_pk_add_f32 v[80:81], v[114:115], v[102:103]
	v_mov_b32_e32 v88, v96
	v_mov_b32_e32 v89, v97
	v_mov_b32_e32 v90, v106
	v_mov_b32_e32 v91, v107
	v_mov_b32_e32 v96, v94
	v_mov_b32_e32 v97, v95
	v_mov_b32_e32 v98, v92
	v_mov_b32_e32 v99, v93
; __device__ __forceinline__ unsigned cvt_pk_bf16(float lo, float hi) { f32x2 v = {lo, hi}; bf16x2_t b = __builtin_convertvector(v, bf16x2_t); return __builtin_bit_cast(unsigned, b); }
;     __device__ __forceinline__ void operator()(const f32x4 (&acc)[2][2][4][2], const Unit& u, int wr, int wc, int fr, int fq) const {
;     ...
;                 const int row = 256 * u.pm + 128 * ai + 64 * wr + 16 * m + fr;
;                 f32x4 x[2][2]; float ss = 0.f;
; #pragma unroll
;                 for (int bj = 0; bj < 2; ++bj)
; #pragma unroll
;                     for (int n = 0; n < 2; ++n) { x[bj][n] = acc[ai][bj][m][n]; ss += (x[bj][n][0] * x[bj][n][0] + x[bj][n][1] * x[bj][n][1]) + (x[bj][n][2] * x[bj][n][2] + x[bj][n][3] * x[bj][n][3]); }
;                 ss += shx<16>(ss); ss = sum_x32(ss);
;                 const float rinv = rsqrtf(ss * (1.0f / 64.0f) + EPS);
; #pragma unroll
;                 for (int bj = 0; bj < 2; ++bj)
; #pragma unroll
;                     for (int n = 0; n < 2; ++n) x[bj][n] = x[bj][n] * rinv * g[bj][n];
;                 if (!isctx) {
;                     const int t = row & (SEQ - 1); const int p = (fq < 2) ? (t >> 6) : (t & 63);
;                     const float* tp = tab + (p * 16 + 8 * (fq & 1)) * 2;
; #pragma unroll
;                     for (int n = 0; n < 2; ++n) {
;                         const f32x4 cs0 = *(const f32x4*)(tp + 8 * n), cs1 = *(const f32x4*)(tp + 8 * n + 4);
;                         const float c[4] = {cs0[0], cs0[2], cs1[0], cs1[2]}, s[4] = {cs0[1], cs0[3], cs1[1], cs1[3]};
; #pragma unroll
;                         for (int e = 0; e < 4; ++e) { const float lo = x[0][n][e], hi = x[1][n][e]; x[0][n][e] = lo * c[e] - hi * s[e]; x[1][n][e] = hi * c[e] + lo * s[e]; }
;                     }
;                 }
; #pragma unroll
;                 for (int bj = 0; bj < 2; ++bj) {
;                     u32x4 w; w.x = cvt_pk_bf16(x[bj][0][0] * qs, x[bj][0][1] * qs); w.y = cvt_pk_bf16(x[bj][0][2] * qs, x[bj][0][3] * qs);
;                     w.z = cvt_pk_bf16(x[bj][1][0] * qs, x[bj][1][1] * qs); w.w = cvt_pk_bf16(x[bj][1][2] * qs, x[bj][1][3] * qs);
;                     *(u32x4*)(dst + (size_t)row * pitch + colbase + 32 * bj + 8 * fq) = w;
;                 }
.LBB0_543:
	v_ashrrev_i32_e32 v92, 31, v100
	v_mul_lo_u32 v94, s25, v100
	v_mul_lo_u32 v95, s24, v92
	v_mad_u64_u32 v[92:93], s[2:3], s24, v100, 0
	v_add3_u32 v93, v93, v95, v94
	v_lshl_add_u64 v[100:101], v[92:93], 1, v[128:129]
	v_pk_mul_f32 v[92:93], s[96:97], v[96:97]
	v_pk_mul_f32 v[94:95], s[96:97], v[98:99]
	v_pk_mul_f32 v[88:89], s[96:97], v[88:89]
	v_cvt_pk_bf16_f32 v92, v92, v93
	v_cvt_pk_bf16_f32 v93, v94, v95
	v_cvt_pk_bf16_f32 v94, v88, v89
	v_pk_mul_f32 v[88:89], s[96:97], v[90:91]
	v_pk_mul_f32 v[90:91], v[76:77], v[76:77]
	v_cvt_pk_bf16_f32 v95, v88, v89
	v_pk_mul_f32 v[88:89], v[78:79], v[78:79]
	global_store_dwordx4 v[100:101], v[92:95], off
	v_pk_mul_f32 v[82:83], s[96:97], v[82:83]
	s_mov_b32 s2, 0x800000
	v_pk_mov_b32 v[92:93], v[90:91], v[88:89] op_sel:[1,0]
	v_mov_b32_e32 v91, v89
	v_pk_add_f32 v[88:89], v[92:93], v[90:91]
	v_pk_mul_f32 v[90:91], v[74:75], v[74:75]
	v_pk_add_f32 v[88:89], v[88:89], v[88:89] op_sel_hi:[0,1]
	v_pk_mul_f32 v[92:93], v[72:73], v[72:73]
	v_mul_f32_e32 v88, v68, v68
	v_pk_mov_b32 v[94:95], v[92:93], v[90:91] op_sel:[1,0]
	v_mov_b32_e32 v93, v91
	v_pk_add_f32 v[90:91], v[94:95], v[92:93]
	v_pk_fma_f32 v[92:93], v[68:69], v[68:69], v[88:89] op_sel_hi:[1,1,0]
	v_mul_f32_e32 v88, v70, v70
	v_pk_add_f32 v[90:91], v[90:91], v[90:91] op_sel_hi:[0,1]
	v_pk_fma_f32 v[94:95], v[70:71], v[70:71], v[88:89] op_sel_hi:[1,1,0]
	v_mul_f32_e32 v92, v64, v64
	v_mul_f32_e32 v94, v65, v65
	v_mul_f32_e32 v90, v66, v66
	v_mul_f32_e32 v88, v67, v67
	v_pk_add_f32 v[92:93], v[92:93], v[94:95]
	v_pk_add_f32 v[88:89], v[90:91], v[88:89]
	v_pk_mul_f32 v[86:87], s[96:97], v[86:87]
	v_pk_add_f32 v[88:89], v[92:93], v[88:89]
	v_pk_mul_f32 v[84:85], s[96:97], v[84:85]
	v_add_f32_e32 v89, v88, v89
	ds_swizzle_b32 v90, v89 offset:swizzle(SWAP,16)
	v_cvt_pk_bf16_f32 v88, v82, v83
	v_pk_mul_f32 v[80:81], s[96:97], v[80:81]
	v_cvt_pk_bf16_f32 v86, v86, v87
	v_cvt_pk_bf16_f32 v87, v84, v85
	s_waitcnt lgkmcnt(0)
	v_add_f32_e32 v82, v89, v90
	v_mov_b32_e32 v83, v82
	s_nop 1
	v_permlane32_swap_b32_e32 v82, v83
	v_add_f32_e32 v82, v82, v83
	v_fmamk_f32 v82, v82, 0x3c800000, v226
	v_mul_f32_e32 v83, 0x4b800000, v82
	v_cmp_gt_f32_e32 vcc, s2, v82
	v_cvt_pk_bf16_f32 v89, v80, v81
	global_store_dwordx4 v[100:101], v[86:89], off offset:64
	v_cndmask_b32_e32 v82, v82, v83, vcc
	v_rsq_f32_e32 v82, v82
	v_add_u32_e32 v84, 0x80, v150
	v_mul_f32_e32 v80, 0x45800000, v82
	v_cndmask_b32_e32 v86, v82, v80, vcc
	v_pk_mul_f32 v[76:77], v[76:77], v[86:87] op_sel_hi:[1,0]
	v_pk_mul_f32 v[78:79], v[78:79], v[86:87] op_sel_hi:[1,0]
	v_pk_mul_f32 v[80:81], v[60:61], v[76:77]
	v_pk_mul_f32 v[76:77], v[68:69], v[86:87] op_sel_hi:[1,0]
	v_pk_mul_f32 v[72:73], v[72:73], v[86:87] op_sel_hi:[1,0]
	v_pk_mul_f32 v[74:75], v[74:75], v[86:87] op_sel_hi:[1,0]
	v_pk_mul_f32 v[68:69], v[70:71], v[86:87] op_sel_hi:[1,0]
	v_pk_mul_f32 v[70:71], v[56:57], v[76:77]
	v_pk_mul_f32 v[76:77], v[64:65], v[86:87] op_sel_hi:[1,0]
	v_pk_mul_f32 v[64:65], v[66:67], v[86:87] op_sel_hi:[1,0]
	v_pk_mul_f32 v[82:83], v[62:63], v[78:79]
	v_pk_mul_f32 v[74:75], v[54:55], v[74:75]
	v_pk_mul_f32 v[72:73], v[52:53], v[72:73]
	v_pk_mul_f32 v[68:69], v[58:59], v[68:69]
	v_pk_mul_f32 v[64:65], v[50:51], v[64:65]
	s_and_b64 vcc, exec, s[8:9]
	v_pk_mul_f32 v[66:67], v[48:49], v[76:77]
	s_cbranch_vccnz .LBB0_545
	v_add_u32_e32 v186, 0x90, v150
	v_bfe_u32 v186, v186, 6, 7
	v_add_u32_e32 v187, 0x90, v209
	v_and_b32_e32 v187, 63, v187
	v_cndmask_b32_e64 v186, v187, v186, s[6:7]
	v_lshl_or_b32 v186, v186, 7, v151
	global_load_dwordx4 v[212:215], v186, s[10:11]
	global_load_dwordx4 v[216:219], v186, s[10:11] offset:16
	global_load_dwordx4 v[220:223], v186, s[10:11] offset:32
	global_load_dwordx4 v[230:233], v186, s[10:11] offset:48
	v_bfe_u32 v76, v84, 6, 7
	v_cndmask_b32_e64 v76, v152, v76, s[6:7]
	v_lshl_or_b32 v192, v76, 7, v151
	v_lshl_add_u64 v[94:95], s[10:11], 0, v[192:193]
	s_waitcnt vmcnt(6)
	v_mov_b32_e32 v86, v170
	v_mov_b32_e32 v87, v171
	v_mov_b32_e32 v88, v172
	v_mov_b32_e32 v89, v173
	v_mov_b32_e32 v90, v174
	v_mov_b32_e32 v91, v175
	v_mov_b32_e32 v92, v176
	v_mov_b32_e32 v93, v177
	v_mov_b32_e32 v76, v86
	v_mul_f32_e32 v86, v82, v90
	v_mul_f32_e32 v96, v68, v91
	v_mul_f32_e32 v90, v68, v90
	v_mov_b32_e32 v68, v83
	v_mov_b32_e32 v77, v88
	v_mov_b32_e32 v88, v87
	v_pk_mul_f32 v[100:101], v[68:69], v[92:93]
	v_pk_mul_f32 v[78:79], v[70:71], v[88:89]
	v_pk_mul_f32 v[70:71], v[70:71], v[76:77]
	v_mul_f32_e32 v98, v82, v91
	v_mov_b32_e32 v87, v100
	v_mov_b32_e32 v97, v101
	v_mov_b32_e32 v82, v69
	v_pk_fma_f32 v[78:79], v[80:81], v[76:77], v[78:79] neg_lo:[0,0,1] neg_hi:[0,0,1]
	v_pk_add_f32 v[76:77], v[86:87], v[96:97] neg_lo:[0,1] neg_hi:[0,1]
	v_pk_mul_f32 v[68:69], v[82:83], v[92:93]
	v_pk_fma_f32 v[70:71], v[80:81], v[88:89], v[70:71]
	v_mov_b32_e32 v99, v69
	v_mov_b32_e32 v91, v68
	v_pk_add_f32 v[68:69], v[98:99], v[90:91]
	v_mov_b32_e32 v80, v178
	v_mov_b32_e32 v81, v179
	v_mov_b32_e32 v82, v180
	v_mov_b32_e32 v83, v181
	v_mov_b32_e32 v86, v182
	v_mov_b32_e32 v87, v183
	v_mov_b32_e32 v88, v184
	v_mov_b32_e32 v89, v185
	v_mov_b32_e32 v91, v82
	v_mul_f32_e32 v92, v74, v86
	v_mul_f32_e32 v94, v64, v87
	v_mul_f32_e32 v86, v64, v86
	v_mov_b32_e32 v64, v75
	v_mov_b32_e32 v82, v81
	v_mul_f32_e32 v96, v74, v87
	v_pk_mul_f32 v[98:99], v[64:65], v[88:89]
	v_mov_b32_e32 v74, v65
	v_mov_b32_e32 v90, v80
	v_pk_mul_f32 v[80:81], v[66:67], v[82:83]
	v_mov_b32_e32 v93, v98
	v_mov_b32_e32 v95, v99
	v_pk_mul_f32 v[64:65], v[74:75], v[88:89]
	v_pk_mul_f32 v[66:67], v[66:67], v[90:91]
	v_pk_fma_f32 v[80:81], v[72:73], v[90:91], v[80:81] neg_lo:[0,0,1] neg_hi:[0,0,1]
	v_pk_add_f32 v[90:91], v[92:93], v[94:95] neg_lo:[0,1] neg_hi:[0,1]
	v_mov_b32_e32 v97, v65
	v_mov_b32_e32 v87, v64
	v_pk_fma_f32 v[66:67], v[72:73], v[82:83], v[66:67]
	v_pk_add_f32 v[64:65], v[96:97], v[86:87]
	v_mov_b32_e32 v72, v80
	v_mov_b32_e32 v73, v81
	v_mov_b32_e32 v74, v90
	v_mov_b32_e32 v75, v91
	v_mov_b32_e32 v80, v78
	v_mov_b32_e32 v81, v79
	v_mov_b32_e32 v82, v76
	v_mov_b32_e32 v83, v77
; __device__ __forceinline__ unsigned cvt_pk_bf16(float lo, float hi) { f32x2 v = {lo, hi}; bf16x2_t b = __builtin_convertvector(v, bf16x2_t); return __builtin_bit_cast(unsigned, b); }
;     __device__ __forceinline__ void operator()(const f32x4 (&acc)[2][2][4][2], const Unit& u, int wr, int wc, int fr, int fq) const {
;     ...
;                 const int row = 256 * u.pm + 128 * ai + 64 * wr + 16 * m + fr;
;                 f32x4 x[2][2]; float ss = 0.f;
; #pragma unroll
;                 for (int bj = 0; bj < 2; ++bj)
; #pragma unroll
;                     for (int n = 0; n < 2; ++n) { x[bj][n] = acc[ai][bj][m][n]; ss += (x[bj][n][0] * x[bj][n][0] + x[bj][n][1] * x[bj][n][1]) + (x[bj][n][2] * x[bj][n][2] + x[bj][n][3] * x[bj][n][3]); }
;                 ss += shx<16>(ss); ss = sum_x32(ss);
;                 const float rinv = rsqrtf(ss * (1.0f / 64.0f) + EPS);
; #pragma unroll
;                 for (int bj = 0; bj < 2; ++bj)
; #pragma unroll
;                     for (int n = 0; n < 2; ++n) x[bj][n] = x[bj][n] * rinv * g[bj][n];
;                 if (!isctx) {
;                     const int t = row & (SEQ - 1); const int p = (fq < 2) ? (t >> 6) : (t & 63);
;                     const float* tp = tab + (p * 16 + 8 * (fq & 1)) * 2;
; #pragma unroll
;                     for (int n = 0; n < 2; ++n) {
;                         const f32x4 cs0 = *(const f32x4*)(tp + 8 * n), cs1 = *(const f32x4*)(tp + 8 * n + 4);
;                         const float c[4] = {cs0[0], cs0[2], cs1[0], cs1[2]}, s[4] = {cs0[1], cs0[3], cs1[1], cs1[3]};
; #pragma unroll
;                         for (int e = 0; e < 4; ++e) { const float lo = x[0][n][e], hi = x[1][n][e]; x[0][n][e] = lo * c[e] - hi * s[e]; x[1][n][e] = hi * c[e] + lo * s[e]; }
;                     }
;                 }
; #pragma unroll
;                 for (int bj = 0; bj < 2; ++bj) {
;                     u32x4 w; w.x = cvt_pk_bf16(x[bj][0][0] * qs, x[bj][0][1] * qs); w.y = cvt_pk_bf16(x[bj][0][2] * qs, x[bj][0][3] * qs);
;                     w.z = cvt_pk_bf16(x[bj][1][0] * qs, x[bj][1][1] * qs); w.w = cvt_pk_bf16(x[bj][1][2] * qs, x[bj][1][3] * qs);
;                     *(u32x4*)(dst + (size_t)row * pitch + colbase + 32 * bj + 8 * fq) = w;
;                 }
.LBB0_545:
	v_ashrrev_i32_e32 v76, 31, v84
	v_mul_lo_u32 v78, s25, v84
	v_mul_lo_u32 v79, s24, v76
	v_mad_u64_u32 v[76:77], s[2:3], s24, v84, 0
	v_add3_u32 v77, v77, v79, v78
	v_lshl_add_u64 v[84:85], v[76:77], 1, v[128:129]
	v_pk_mul_f32 v[76:77], s[96:97], v[80:81]
	v_pk_mul_f32 v[78:79], s[96:97], v[82:83]
	v_pk_mul_f32 v[72:73], s[96:97], v[72:73]
	v_cvt_pk_bf16_f32 v76, v76, v77
	v_cvt_pk_bf16_f32 v77, v78, v79
	v_cvt_pk_bf16_f32 v78, v72, v73
	v_pk_mul_f32 v[72:73], s[96:97], v[74:75]
	v_pk_mul_f32 v[74:75], v[44:45], v[44:45]
	v_cvt_pk_bf16_f32 v79, v72, v73
	v_pk_mul_f32 v[72:73], v[46:47], v[46:47]
	global_store_dwordx4 v[84:85], v[76:79], off
	v_pk_mul_f32 v[66:67], s[96:97], v[66:67]
	s_mov_b32 s2, 0x800000
	v_pk_mov_b32 v[76:77], v[74:75], v[72:73] op_sel:[1,0]
	v_mov_b32_e32 v75, v73
	v_pk_add_f32 v[72:73], v[76:77], v[74:75]
	v_pk_mul_f32 v[74:75], v[42:43], v[42:43]
	v_pk_add_f32 v[72:73], v[72:73], v[72:73] op_sel_hi:[0,1]
	v_pk_mul_f32 v[76:77], v[40:41], v[40:41]
	v_mul_f32_e32 v72, v36, v36
	v_pk_mov_b32 v[78:79], v[76:77], v[74:75] op_sel:[1,0]
	v_mov_b32_e32 v77, v75
	v_pk_add_f32 v[74:75], v[78:79], v[76:77]
	v_pk_fma_f32 v[76:77], v[36:37], v[36:37], v[72:73] op_sel_hi:[1,1,0]
	v_mul_f32_e32 v72, v38, v38
	v_pk_add_f32 v[74:75], v[74:75], v[74:75] op_sel_hi:[0,1]
	v_pk_fma_f32 v[78:79], v[38:39], v[38:39], v[72:73] op_sel_hi:[1,1,0]
	v_mul_f32_e32 v76, v32, v32
	v_mul_f32_e32 v78, v33, v33
	v_mul_f32_e32 v74, v34, v34
	v_mul_f32_e32 v72, v35, v35
	v_pk_add_f32 v[76:77], v[76:77], v[78:79]
	v_pk_add_f32 v[72:73], v[74:75], v[72:73]
	v_pk_mul_f32 v[64:65], s[96:97], v[64:65]
	v_pk_add_f32 v[72:73], v[76:77], v[72:73]
	v_pk_mul_f32 v[70:71], s[96:97], v[70:71]
	v_add_f32_e32 v73, v72, v73
	ds_swizzle_b32 v74, v73 offset:swizzle(SWAP,16)
	v_cvt_pk_bf16_f32 v72, v66, v67
	v_pk_mul_f32 v[68:69], s[96:97], v[68:69]
	v_cvt_pk_bf16_f32 v70, v70, v71
	v_cvt_pk_bf16_f32 v71, v68, v69
	s_waitcnt lgkmcnt(0)
	v_add_f32_e32 v66, v73, v74
	v_mov_b32_e32 v67, v66
	s_nop 1
	v_permlane32_swap_b32_e32 v66, v67
	v_add_f32_e32 v66, v66, v67
	v_fmamk_f32 v66, v66, 0x3c800000, v226
	v_mul_f32_e32 v67, 0x4b800000, v66
	v_cmp_gt_f32_e32 vcc, s2, v66
	v_cvt_pk_bf16_f32 v73, v64, v65
	global_store_dwordx4 v[84:85], v[70:73], off offset:64
	v_cndmask_b32_e32 v66, v66, v67, vcc
	v_rsq_f32_e32 v66, v66
	s_nop 0
	v_mul_f32_e32 v64, 0x45800000, v66
	v_cndmask_b32_e32 v68, v66, v64, vcc
	v_pk_mul_f32 v[44:45], v[44:45], v[68:69] op_sel_hi:[1,0]
	v_pk_mul_f32 v[46:47], v[46:47], v[68:69] op_sel_hi:[1,0]
	v_pk_mul_f32 v[64:65], v[60:61], v[44:45]
	v_pk_mul_f32 v[44:45], v[36:37], v[68:69] op_sel_hi:[1,0]
	v_pk_mul_f32 v[40:41], v[40:41], v[68:69] op_sel_hi:[1,0]
	v_pk_mul_f32 v[42:43], v[42:43], v[68:69] op_sel_hi:[1,0]
	v_pk_mul_f32 v[36:37], v[38:39], v[68:69] op_sel_hi:[1,0]
	v_pk_mul_f32 v[38:39], v[56:57], v[44:45]
	v_pk_mul_f32 v[44:45], v[32:33], v[68:69] op_sel_hi:[1,0]
	v_pk_mul_f32 v[32:33], v[34:35], v[68:69] op_sel_hi:[1,0]
	v_pk_mul_f32 v[66:67], v[62:63], v[46:47]
	v_pk_mul_f32 v[42:43], v[54:55], v[42:43]
	v_pk_mul_f32 v[40:41], v[52:53], v[40:41]
	v_pk_mul_f32 v[36:37], v[58:59], v[36:37]
	v_pk_mul_f32 v[32:33], v[50:51], v[32:33]
	v_pk_mul_f32 v[34:35], v[48:49], v[44:45]
	s_and_b64 vcc, exec, s[8:9]
	v_add_u32_e32 v68, 0x90, v150
	s_cbranch_vccnz .LBB0_547
	v_add_u32_e32 v186, 0xa0, v150
	v_bfe_u32 v186, v186, 6, 7
	v_add_u32_e32 v187, 0xa0, v209
	v_and_b32_e32 v187, 63, v187
	v_cndmask_b32_e64 v186, v187, v186, s[6:7]
	v_lshl_or_b32 v186, v186, 7, v151
	global_load_dwordx4 v[170:173], v186, s[10:11]
	global_load_dwordx4 v[174:177], v186, s[10:11] offset:16
	global_load_dwordx4 v[178:181], v186, s[10:11] offset:32
	global_load_dwordx4 v[182:185], v186, s[10:11] offset:48
	v_bfe_u32 v44, v68, 6, 7
	v_cndmask_b32_e64 v44, v142, v44, s[6:7]
	v_lshl_or_b32 v192, v44, 7, v151
	v_lshl_add_u64 v[78:79], s[10:11], 0, v[192:193]
	s_waitcnt vmcnt(6)
	v_mov_b32_e32 v70, v212
	v_mov_b32_e32 v71, v213
	v_mov_b32_e32 v72, v214
	v_mov_b32_e32 v73, v215
	v_mov_b32_e32 v74, v216
	v_mov_b32_e32 v75, v217
	v_mov_b32_e32 v76, v218
	v_mov_b32_e32 v77, v219
	v_mov_b32_e32 v44, v70
	v_mul_f32_e32 v70, v66, v74
	v_mul_f32_e32 v80, v36, v75
	v_mul_f32_e32 v74, v36, v74
	v_mov_b32_e32 v36, v67
	v_mov_b32_e32 v45, v72
	v_mov_b32_e32 v72, v71
	v_pk_mul_f32 v[84:85], v[36:37], v[76:77]
	v_pk_mul_f32 v[46:47], v[38:39], v[72:73]
	v_pk_mul_f32 v[38:39], v[38:39], v[44:45]
	v_mul_f32_e32 v82, v66, v75
	v_mov_b32_e32 v71, v84
	v_mov_b32_e32 v81, v85
	v_mov_b32_e32 v66, v37
	v_pk_fma_f32 v[46:47], v[64:65], v[44:45], v[46:47] neg_lo:[0,0,1] neg_hi:[0,0,1]
	v_pk_add_f32 v[44:45], v[70:71], v[80:81] neg_lo:[0,1] neg_hi:[0,1]
	v_pk_mul_f32 v[36:37], v[66:67], v[76:77]
	v_pk_fma_f32 v[38:39], v[64:65], v[72:73], v[38:39]
	v_mov_b32_e32 v83, v37
	v_mov_b32_e32 v75, v36
	v_pk_add_f32 v[36:37], v[82:83], v[74:75]
	v_mov_b32_e32 v64, v220
	v_mov_b32_e32 v65, v221
	v_mov_b32_e32 v66, v222
	v_mov_b32_e32 v67, v223
	v_mov_b32_e32 v70, v230
	v_mov_b32_e32 v71, v231
	v_mov_b32_e32 v72, v232
	v_mov_b32_e32 v73, v233
	v_mov_b32_e32 v75, v66
	v_mul_f32_e32 v76, v42, v70
	v_mul_f32_e32 v78, v32, v71
	v_mul_f32_e32 v70, v32, v70
	v_mov_b32_e32 v32, v43
	v_mov_b32_e32 v66, v65
	v_mul_f32_e32 v80, v42, v71
	v_pk_mul_f32 v[82:83], v[32:33], v[72:73]
	v_mov_b32_e32 v42, v33
	v_mov_b32_e32 v74, v64
	v_pk_mul_f32 v[64:65], v[34:35], v[66:67]
	v_mov_b32_e32 v77, v82
	v_mov_b32_e32 v79, v83
	v_pk_mul_f32 v[32:33], v[42:43], v[72:73]
	v_pk_mul_f32 v[34:35], v[34:35], v[74:75]
	v_pk_fma_f32 v[64:65], v[40:41], v[74:75], v[64:65] neg_lo:[0,0,1] neg_hi:[0,0,1]
	v_pk_add_f32 v[74:75], v[76:77], v[78:79] neg_lo:[0,1] neg_hi:[0,1]
	v_mov_b32_e32 v81, v33
	v_mov_b32_e32 v71, v32
	v_pk_fma_f32 v[34:35], v[40:41], v[66:67], v[34:35]
	v_pk_add_f32 v[32:33], v[80:81], v[70:71]
	v_mov_b32_e32 v40, v64
	v_mov_b32_e32 v41, v65
	v_mov_b32_e32 v42, v74
	v_mov_b32_e32 v43, v75
	v_mov_b32_e32 v64, v46
	v_mov_b32_e32 v65, v47
	v_mov_b32_e32 v66, v44
	v_mov_b32_e32 v67, v45
; __device__ __forceinline__ unsigned cvt_pk_bf16(float lo, float hi) { f32x2 v = {lo, hi}; bf16x2_t b = __builtin_convertvector(v, bf16x2_t); return __builtin_bit_cast(unsigned, b); }
;     __device__ __forceinline__ void operator()(const f32x4 (&acc)[2][2][4][2], const Unit& u, int wr, int wc, int fr, int fq) const {
;     ...
;                 const int row = 256 * u.pm + 128 * ai + 64 * wr + 16 * m + fr;
;                 f32x4 x[2][2]; float ss = 0.f;
; #pragma unroll
;                 for (int bj = 0; bj < 2; ++bj)
; #pragma unroll
;                     for (int n = 0; n < 2; ++n) { x[bj][n] = acc[ai][bj][m][n]; ss += (x[bj][n][0] * x[bj][n][0] + x[bj][n][1] * x[bj][n][1]) + (x[bj][n][2] * x[bj][n][2] + x[bj][n][3] * x[bj][n][3]); }
;                 ss += shx<16>(ss); ss = sum_x32(ss);
;                 const float rinv = rsqrtf(ss * (1.0f / 64.0f) + EPS);
; #pragma unroll
;                 for (int bj = 0; bj < 2; ++bj)
; #pragma unroll
;                     for (int n = 0; n < 2; ++n) x[bj][n] = x[bj][n] * rinv * g[bj][n];
;                 if (!isctx) {
;                     const int t = row & (SEQ - 1); const int p = (fq < 2) ? (t >> 6) : (t & 63);
;                     const float* tp = tab + (p * 16 + 8 * (fq & 1)) * 2;
; #pragma unroll
;                     for (int n = 0; n < 2; ++n) {
;                         const f32x4 cs0 = *(const f32x4*)(tp + 8 * n), cs1 = *(const f32x4*)(tp + 8 * n + 4);
;                         const float c[4] = {cs0[0], cs0[2], cs1[0], cs1[2]}, s[4] = {cs0[1], cs0[3], cs1[1], cs1[3]};
; #pragma unroll
;                         for (int e = 0; e < 4; ++e) { const float lo = x[0][n][e], hi = x[1][n][e]; x[0][n][e] = lo * c[e] - hi * s[e]; x[1][n][e] = hi * c[e] + lo * s[e]; }
;                     }
;                 }
; #pragma unroll
;                 for (int bj = 0; bj < 2; ++bj) {
;                     u32x4 w; w.x = cvt_pk_bf16(x[bj][0][0] * qs, x[bj][0][1] * qs); w.y = cvt_pk_bf16(x[bj][0][2] * qs, x[bj][0][3] * qs);
;                     w.z = cvt_pk_bf16(x[bj][1][0] * qs, x[bj][1][1] * qs); w.w = cvt_pk_bf16(x[bj][1][2] * qs, x[bj][1][3] * qs);
;                     *(u32x4*)(dst + (size_t)row * pitch + colbase + 32 * bj + 8 * fq) = w;
;                 }
.LBB0_547:
	v_ashrrev_i32_e32 v44, 31, v68
	v_mul_lo_u32 v46, s25, v68
	v_mul_lo_u32 v47, s24, v44
	v_mad_u64_u32 v[44:45], s[2:3], s24, v68, 0
	v_add3_u32 v45, v45, v47, v46
	v_lshl_add_u64 v[68:69], v[44:45], 1, v[128:129]
	v_pk_mul_f32 v[44:45], s[96:97], v[64:65]
	v_pk_mul_f32 v[46:47], s[96:97], v[66:67]
	v_pk_mul_f32 v[40:41], s[96:97], v[40:41]
	v_cvt_pk_bf16_f32 v44, v44, v45
	v_cvt_pk_bf16_f32 v45, v46, v47
	v_cvt_pk_bf16_f32 v46, v40, v41
	v_pk_mul_f32 v[40:41], s[96:97], v[42:43]
	v_pk_mul_f32 v[42:43], v[28:29], v[28:29]
	v_cvt_pk_bf16_f32 v47, v40, v41
	v_pk_mul_f32 v[40:41], v[30:31], v[30:31]
	global_store_dwordx4 v[68:69], v[44:47], off
	v_pk_mul_f32 v[34:35], s[96:97], v[34:35]
	s_mov_b32 s2, 0x800000
	v_pk_mov_b32 v[44:45], v[42:43], v[40:41] op_sel:[1,0]
	v_mov_b32_e32 v43, v41
	v_pk_add_f32 v[40:41], v[44:45], v[42:43]
	v_pk_mul_f32 v[42:43], v[26:27], v[26:27]
	v_pk_add_f32 v[40:41], v[40:41], v[40:41] op_sel_hi:[0,1]
	v_pk_mul_f32 v[44:45], v[24:25], v[24:25]
	v_mul_f32_e32 v40, v20, v20
	v_pk_mov_b32 v[46:47], v[44:45], v[42:43] op_sel:[1,0]
	v_mov_b32_e32 v45, v43
	v_pk_add_f32 v[42:43], v[46:47], v[44:45]
	v_pk_fma_f32 v[44:45], v[20:21], v[20:21], v[40:41] op_sel_hi:[1,1,0]
	v_mul_f32_e32 v40, v22, v22
	v_pk_add_f32 v[42:43], v[42:43], v[42:43] op_sel_hi:[0,1]
	v_pk_fma_f32 v[46:47], v[22:23], v[22:23], v[40:41] op_sel_hi:[1,1,0]
	v_mul_f32_e32 v44, v16, v16
	v_mul_f32_e32 v46, v17, v17
	v_mul_f32_e32 v42, v18, v18
	v_mul_f32_e32 v40, v19, v19
	v_pk_add_f32 v[44:45], v[44:45], v[46:47]
	v_pk_add_f32 v[40:41], v[42:43], v[40:41]
	v_pk_mul_f32 v[32:33], s[96:97], v[32:33]
	v_pk_add_f32 v[40:41], v[44:45], v[40:41]
	v_pk_mul_f32 v[38:39], s[96:97], v[38:39]
	v_add_f32_e32 v41, v40, v41
	ds_swizzle_b32 v42, v41 offset:swizzle(SWAP,16)
	v_cvt_pk_bf16_f32 v40, v34, v35
	v_pk_mul_f32 v[36:37], s[96:97], v[36:37]
	v_cvt_pk_bf16_f32 v38, v38, v39
	v_cvt_pk_bf16_f32 v39, v36, v37
	s_waitcnt lgkmcnt(0)
	v_add_f32_e32 v34, v41, v42
	v_mov_b32_e32 v35, v34
	s_nop 1
	v_permlane32_swap_b32_e32 v34, v35
	v_add_f32_e32 v34, v34, v35
	v_fmamk_f32 v34, v34, 0x3c800000, v226
	v_mul_f32_e32 v35, 0x4b800000, v34
	v_cmp_gt_f32_e32 vcc, s2, v34
	v_cvt_pk_bf16_f32 v41, v32, v33
	global_store_dwordx4 v[68:69], v[38:41], off offset:64
	v_cndmask_b32_e32 v34, v34, v35, vcc
	v_rsq_f32_e32 v34, v34
	s_nop 0
	v_mul_f32_e32 v32, 0x45800000, v34
	v_cndmask_b32_e32 v36, v34, v32, vcc
	v_pk_mul_f32 v[28:29], v[28:29], v[36:37] op_sel_hi:[1,0]
	v_pk_mul_f32 v[30:31], v[30:31], v[36:37] op_sel_hi:[1,0]
	v_pk_mul_f32 v[32:33], v[60:61], v[28:29]
	v_pk_mul_f32 v[28:29], v[20:21], v[36:37] op_sel_hi:[1,0]
	v_pk_mul_f32 v[24:25], v[24:25], v[36:37] op_sel_hi:[1,0]
	v_pk_mul_f32 v[26:27], v[26:27], v[36:37] op_sel_hi:[1,0]
	v_pk_mul_f32 v[20:21], v[22:23], v[36:37] op_sel_hi:[1,0]
	v_pk_mul_f32 v[22:23], v[56:57], v[28:29]
	v_pk_mul_f32 v[28:29], v[16:17], v[36:37] op_sel_hi:[1,0]
	v_pk_mul_f32 v[16:17], v[18:19], v[36:37] op_sel_hi:[1,0]
	v_pk_mul_f32 v[34:35], v[62:63], v[30:31]
	v_pk_mul_f32 v[26:27], v[54:55], v[26:27]
	v_pk_mul_f32 v[24:25], v[52:53], v[24:25]
	v_pk_mul_f32 v[20:21], v[58:59], v[20:21]
	v_pk_mul_f32 v[16:17], v[50:51], v[16:17]
	v_pk_mul_f32 v[18:19], v[48:49], v[28:29]
	s_and_b64 vcc, exec, s[8:9]
	v_add_u32_e32 v36, 0xa0, v150
	s_cbranch_vccnz .LBB0_549
	v_add_u32_e32 v186, 0xb0, v150
	v_bfe_u32 v186, v186, 6, 7
	v_add_u32_e32 v187, 0xb0, v209
	v_and_b32_e32 v187, 63, v187
	v_cndmask_b32_e64 v186, v187, v186, s[6:7]
	v_lshl_or_b32 v186, v186, 7, v151
	global_load_dwordx4 v[212:215], v186, s[10:11]
	global_load_dwordx4 v[216:219], v186, s[10:11] offset:16
	global_load_dwordx4 v[220:223], v186, s[10:11] offset:32
	global_load_dwordx4 v[230:233], v186, s[10:11] offset:48
	v_bfe_u32 v28, v36, 6, 7
	v_cndmask_b32_e64 v28, v124, v28, s[6:7]
	v_lshl_or_b32 v192, v28, 7, v151
	v_lshl_add_u64 v[46:47], s[10:11], 0, v[192:193]
	s_waitcnt vmcnt(6)
	v_mov_b32_e32 v38, v170
	v_mov_b32_e32 v39, v171
	v_mov_b32_e32 v40, v172
	v_mov_b32_e32 v41, v173
	v_mov_b32_e32 v42, v174
	v_mov_b32_e32 v43, v175
	v_mov_b32_e32 v44, v176
	v_mov_b32_e32 v45, v177
	v_mov_b32_e32 v28, v38
	v_mul_f32_e32 v38, v34, v42
	v_mul_f32_e32 v64, v20, v43
	v_mul_f32_e32 v42, v20, v42
	v_mov_b32_e32 v20, v35
	v_mov_b32_e32 v29, v40
	v_mov_b32_e32 v40, v39
	v_pk_mul_f32 v[68:69], v[20:21], v[44:45]
	v_pk_mul_f32 v[30:31], v[22:23], v[40:41]
	v_pk_mul_f32 v[22:23], v[22:23], v[28:29]
	v_mul_f32_e32 v66, v34, v43
	v_mov_b32_e32 v39, v68
	v_mov_b32_e32 v65, v69
	v_mov_b32_e32 v34, v21
	v_pk_fma_f32 v[30:31], v[32:33], v[28:29], v[30:31] neg_lo:[0,0,1] neg_hi:[0,0,1]
	v_pk_add_f32 v[28:29], v[38:39], v[64:65] neg_lo:[0,1] neg_hi:[0,1]
	v_pk_mul_f32 v[20:21], v[34:35], v[44:45]
	v_pk_fma_f32 v[22:23], v[32:33], v[40:41], v[22:23]
	v_mov_b32_e32 v67, v21
	v_mov_b32_e32 v43, v20
	v_pk_add_f32 v[20:21], v[66:67], v[42:43]
	v_mov_b32_e32 v32, v178
	v_mov_b32_e32 v33, v179
	v_mov_b32_e32 v34, v180
	v_mov_b32_e32 v35, v181
	v_mov_b32_e32 v38, v182
	v_mov_b32_e32 v39, v183
	v_mov_b32_e32 v40, v184
	v_mov_b32_e32 v41, v185
	v_mov_b32_e32 v43, v34
	v_mul_f32_e32 v44, v26, v38
	v_mul_f32_e32 v46, v16, v39
	v_mul_f32_e32 v38, v16, v38
	v_mov_b32_e32 v16, v27
	v_mov_b32_e32 v34, v33
	v_mul_f32_e32 v64, v26, v39
	v_pk_mul_f32 v[66:67], v[16:17], v[40:41]
	v_mov_b32_e32 v26, v17
	v_mov_b32_e32 v42, v32
	v_pk_mul_f32 v[32:33], v[18:19], v[34:35]
	v_mov_b32_e32 v45, v66
	v_mov_b32_e32 v47, v67
	v_pk_mul_f32 v[16:17], v[26:27], v[40:41]
	v_pk_mul_f32 v[18:19], v[18:19], v[42:43]
	v_pk_fma_f32 v[32:33], v[24:25], v[42:43], v[32:33] neg_lo:[0,0,1] neg_hi:[0,0,1]
	v_pk_add_f32 v[42:43], v[44:45], v[46:47] neg_lo:[0,1] neg_hi:[0,1]
	v_mov_b32_e32 v65, v17
	v_mov_b32_e32 v39, v16
	v_pk_fma_f32 v[18:19], v[24:25], v[34:35], v[18:19]
	v_pk_add_f32 v[16:17], v[64:65], v[38:39]
	v_mov_b32_e32 v24, v32
	v_mov_b32_e32 v25, v33
	v_mov_b32_e32 v26, v42
	v_mov_b32_e32 v27, v43
	v_mov_b32_e32 v32, v30
	v_mov_b32_e32 v33, v31
	v_mov_b32_e32 v34, v28
	v_mov_b32_e32 v35, v29
; __device__ __forceinline__ unsigned cvt_pk_bf16(float lo, float hi) { f32x2 v = {lo, hi}; bf16x2_t b = __builtin_convertvector(v, bf16x2_t); return __builtin_bit_cast(unsigned, b); }
;     __device__ __forceinline__ void operator()(const f32x4 (&acc)[2][2][4][2], const Unit& u, int wr, int wc, int fr, int fq) const {
;     ...
;                 const int row = 256 * u.pm + 128 * ai + 64 * wr + 16 * m + fr;
;                 f32x4 x[2][2]; float ss = 0.f;
; #pragma unroll
;                 for (int bj = 0; bj < 2; ++bj)
; #pragma unroll
;                     for (int n = 0; n < 2; ++n) { x[bj][n] = acc[ai][bj][m][n]; ss += (x[bj][n][0] * x[bj][n][0] + x[bj][n][1] * x[bj][n][1]) + (x[bj][n][2] * x[bj][n][2] + x[bj][n][3] * x[bj][n][3]); }
;                 ss += shx<16>(ss); ss = sum_x32(ss);
;                 const float rinv = rsqrtf(ss * (1.0f / 64.0f) + EPS);
; #pragma unroll
;                 for (int bj = 0; bj < 2; ++bj)
; #pragma unroll
;                     for (int n = 0; n < 2; ++n) x[bj][n] = x[bj][n] * rinv * g[bj][n];
;                 if (!isctx) {
;                     const int t = row & (SEQ - 1); const int p = (fq < 2) ? (t >> 6) : (t & 63);
;                     const float* tp = tab + (p * 16 + 8 * (fq & 1)) * 2;
; #pragma unroll
;                     for (int n = 0; n < 2; ++n) {
;                         const f32x4 cs0 = *(const f32x4*)(tp + 8 * n), cs1 = *(const f32x4*)(tp + 8 * n + 4);
;                         const float c[4] = {cs0[0], cs0[2], cs1[0], cs1[2]}, s[4] = {cs0[1], cs0[3], cs1[1], cs1[3]};
; #pragma unroll
;                         for (int e = 0; e < 4; ++e) { const float lo = x[0][n][e], hi = x[1][n][e]; x[0][n][e] = lo * c[e] - hi * s[e]; x[1][n][e] = hi * c[e] + lo * s[e]; }
;                     }
;                 }
; #pragma unroll
;                 for (int bj = 0; bj < 2; ++bj) {
;                     u32x4 w; w.x = cvt_pk_bf16(x[bj][0][0] * qs, x[bj][0][1] * qs); w.y = cvt_pk_bf16(x[bj][0][2] * qs, x[bj][0][3] * qs);
;                     w.z = cvt_pk_bf16(x[bj][1][0] * qs, x[bj][1][1] * qs); w.w = cvt_pk_bf16(x[bj][1][2] * qs, x[bj][1][3] * qs);
;                     *(u32x4*)(dst + (size_t)row * pitch + colbase + 32 * bj + 8 * fq) = w;
;                 }
.LBB0_549:
	v_ashrrev_i32_e32 v28, 31, v36
	v_mul_lo_u32 v30, s25, v36
	v_mul_lo_u32 v31, s24, v28
	v_mad_u64_u32 v[28:29], s[2:3], s24, v36, 0
	v_add3_u32 v29, v29, v31, v30
	v_lshl_add_u64 v[36:37], v[28:29], 1, v[128:129]
	v_pk_mul_f32 v[28:29], s[96:97], v[32:33]
	v_pk_mul_f32 v[30:31], s[96:97], v[34:35]
	v_pk_mul_f32 v[24:25], s[96:97], v[24:25]
	v_cvt_pk_bf16_f32 v28, v28, v29
	v_cvt_pk_bf16_f32 v29, v30, v31
	v_cvt_pk_bf16_f32 v30, v24, v25
	v_pk_mul_f32 v[24:25], s[96:97], v[26:27]
	v_pk_mul_f32 v[26:27], v[12:13], v[12:13]
	v_cvt_pk_bf16_f32 v31, v24, v25
	v_pk_mul_f32 v[24:25], v[14:15], v[14:15]
	global_store_dwordx4 v[36:37], v[28:31], off
	v_pk_mul_f32 v[18:19], s[96:97], v[18:19]
	s_mov_b32 s2, 0x800000
	v_pk_mov_b32 v[28:29], v[26:27], v[24:25] op_sel:[1,0]
	v_mov_b32_e32 v27, v25
	v_pk_add_f32 v[24:25], v[28:29], v[26:27]
	v_pk_mul_f32 v[26:27], v[10:11], v[10:11]
	v_pk_add_f32 v[24:25], v[24:25], v[24:25] op_sel_hi:[0,1]
	v_pk_mul_f32 v[28:29], v[8:9], v[8:9]
	v_mul_f32_e32 v24, v4, v4
	v_pk_mov_b32 v[30:31], v[28:29], v[26:27] op_sel:[1,0]
	v_mov_b32_e32 v29, v27
	v_pk_add_f32 v[26:27], v[30:31], v[28:29]
	v_pk_fma_f32 v[28:29], v[4:5], v[4:5], v[24:25] op_sel_hi:[1,1,0]
	v_mul_f32_e32 v24, v6, v6
	v_pk_add_f32 v[26:27], v[26:27], v[26:27] op_sel_hi:[0,1]
	v_pk_fma_f32 v[30:31], v[6:7], v[6:7], v[24:25] op_sel_hi:[1,1,0]
	v_mul_f32_e32 v28, v0, v0
	v_mul_f32_e32 v30, v1, v1
	v_mul_f32_e32 v26, v2, v2
	v_mul_f32_e32 v24, v3, v3
	v_pk_add_f32 v[28:29], v[28:29], v[30:31]
	v_pk_add_f32 v[24:25], v[26:27], v[24:25]
	v_pk_mul_f32 v[16:17], s[96:97], v[16:17]
	v_pk_add_f32 v[24:25], v[28:29], v[24:25]
	v_pk_mul_f32 v[22:23], s[96:97], v[22:23]
	v_add_f32_e32 v25, v24, v25
	ds_swizzle_b32 v26, v25 offset:swizzle(SWAP,16)
	v_cvt_pk_bf16_f32 v24, v18, v19
	v_pk_mul_f32 v[20:21], s[96:97], v[20:21]
	v_cvt_pk_bf16_f32 v22, v22, v23
	v_cvt_pk_bf16_f32 v23, v20, v21
	s_waitcnt lgkmcnt(0)
	v_add_f32_e32 v18, v25, v26
	v_mov_b32_e32 v19, v18
	s_nop 1
	v_permlane32_swap_b32_e32 v18, v19
	v_add_f32_e32 v18, v18, v19
	v_fmamk_f32 v18, v18, 0x3c800000, v226
	v_mul_f32_e32 v19, 0x4b800000, v18
	v_cmp_gt_f32_e32 vcc, s2, v18
	v_cvt_pk_bf16_f32 v25, v16, v17
	global_store_dwordx4 v[36:37], v[22:25], off offset:64
	v_cndmask_b32_e32 v18, v18, v19, vcc
	v_rsq_f32_e32 v18, v18
	s_nop 0
	v_mul_f32_e32 v16, 0x45800000, v18
	v_cndmask_b32_e32 v20, v18, v16, vcc
	v_pk_mul_f32 v[12:13], v[12:13], v[20:21] op_sel_hi:[1,0]
	v_pk_mul_f32 v[14:15], v[14:15], v[20:21] op_sel_hi:[1,0]
	v_pk_mul_f32 v[16:17], v[60:61], v[12:13]
	v_pk_mul_f32 v[12:13], v[4:5], v[20:21] op_sel_hi:[1,0]
	v_pk_mul_f32 v[8:9], v[8:9], v[20:21] op_sel_hi:[1,0]
	v_pk_mul_f32 v[10:11], v[10:11], v[20:21] op_sel_hi:[1,0]
	v_pk_mul_f32 v[4:5], v[6:7], v[20:21] op_sel_hi:[1,0]
	v_pk_mul_f32 v[6:7], v[56:57], v[12:13]
	v_pk_mul_f32 v[12:13], v[0:1], v[20:21] op_sel_hi:[1,0]
	v_pk_mul_f32 v[0:1], v[2:3], v[20:21] op_sel_hi:[1,0]
	v_pk_mul_f32 v[18:19], v[62:63], v[14:15]
	v_pk_mul_f32 v[10:11], v[54:55], v[10:11]
	v_pk_mul_f32 v[8:9], v[52:53], v[8:9]
	v_pk_mul_f32 v[4:5], v[58:59], v[4:5]
	v_pk_mul_f32 v[0:1], v[50:51], v[0:1]
	v_pk_mul_f32 v[12:13], v[48:49], v[12:13]
	s_and_b64 vcc, exec, s[8:9]
	v_add_u32_e32 v20, 0xb0, v150
	s_cbranch_vccnz .LBB0_551
	v_bfe_u32 v2, v20, 6, 7
	v_cndmask_b32_e64 v2, v108, v2, s[6:7]
	v_lshl_or_b32 v192, v2, 7, v151
	v_lshl_add_u64 v[30:31], s[10:11], 0, v[192:193]
	s_waitcnt vmcnt(2)
	v_mov_b32_e32 v22, v212
	v_mov_b32_e32 v23, v213
	v_mov_b32_e32 v24, v214
	v_mov_b32_e32 v25, v215
	v_mov_b32_e32 v26, v216
	v_mov_b32_e32 v27, v217
	v_mov_b32_e32 v28, v218
	v_mov_b32_e32 v29, v219
	v_mov_b32_e32 v2, v22
	v_mul_f32_e32 v22, v18, v26
	v_mul_f32_e32 v32, v4, v27
	v_mul_f32_e32 v26, v4, v26
	v_mov_b32_e32 v4, v19
	v_mov_b32_e32 v3, v24
	v_mov_b32_e32 v24, v23
	v_pk_mul_f32 v[36:37], v[4:5], v[28:29]
	v_pk_mul_f32 v[14:15], v[6:7], v[24:25]
	v_pk_mul_f32 v[6:7], v[6:7], v[2:3]
	v_mul_f32_e32 v34, v18, v27
	v_mov_b32_e32 v23, v36
	v_mov_b32_e32 v33, v37
	v_mov_b32_e32 v18, v5
	v_pk_fma_f32 v[14:15], v[16:17], v[2:3], v[14:15] neg_lo:[0,0,1] neg_hi:[0,0,1]
	v_pk_add_f32 v[2:3], v[22:23], v[32:33] neg_lo:[0,1] neg_hi:[0,1]
	v_pk_mul_f32 v[4:5], v[18:19], v[28:29]
	v_pk_fma_f32 v[6:7], v[16:17], v[24:25], v[6:7]
	v_mov_b32_e32 v35, v5
	v_mov_b32_e32 v27, v4
	v_pk_add_f32 v[4:5], v[34:35], v[26:27]
	v_mov_b32_e32 v16, v220
	v_mov_b32_e32 v17, v221
	v_mov_b32_e32 v18, v222
	v_mov_b32_e32 v19, v223
	v_mov_b32_e32 v22, v230
	v_mov_b32_e32 v23, v231
	v_mov_b32_e32 v24, v232
	v_mov_b32_e32 v25, v233
	v_mov_b32_e32 v27, v18
	v_mul_f32_e32 v28, v10, v22
	v_mul_f32_e32 v30, v0, v23
	v_mul_f32_e32 v22, v0, v22
	v_mov_b32_e32 v0, v11
	v_mov_b32_e32 v18, v17
	v_mul_f32_e32 v32, v10, v23
	v_pk_mul_f32 v[34:35], v[0:1], v[24:25]
	v_mov_b32_e32 v10, v1
	v_mov_b32_e32 v26, v16
	v_pk_mul_f32 v[16:17], v[12:13], v[18:19]
	v_mov_b32_e32 v29, v34
	v_mov_b32_e32 v31, v35
	v_pk_mul_f32 v[0:1], v[10:11], v[24:25]
	v_pk_mul_f32 v[12:13], v[12:13], v[26:27]
	v_pk_fma_f32 v[16:17], v[8:9], v[26:27], v[16:17] neg_lo:[0,0,1] neg_hi:[0,0,1]
	v_pk_add_f32 v[26:27], v[28:29], v[30:31] neg_lo:[0,1] neg_hi:[0,1]
	v_mov_b32_e32 v33, v1
	v_mov_b32_e32 v23, v0
	v_pk_fma_f32 v[12:13], v[8:9], v[18:19], v[12:13]
	v_pk_add_f32 v[0:1], v[32:33], v[22:23]
	v_mov_b32_e32 v8, v16
	v_mov_b32_e32 v9, v17
	v_mov_b32_e32 v10, v26
	v_mov_b32_e32 v11, v27
	v_mov_b32_e32 v16, v14
	v_mov_b32_e32 v17, v15
	v_mov_b32_e32 v18, v2
	v_mov_b32_e32 v19, v3
